# expert gather phases: one static s_setprio 1 for the younger half (waves 4..7) of every workgroup, reset at the phase end
# speedup vs baseline: 1.0031x; 1.0031x over previous
.LBB0_594:
	s_cmp_lt_i32 s56, 8
	s_cselect_b64 s[0:1], -1, 0
	s_and_b64 s[0:1], s[0:1], s[4:5]
	s_andn2_b64 vcc, exec, s[0:1]
	s_cbranch_vccnz .LBB0_619
	s_cmpk_gt_i32 s33, 0x7ff
	v_mbcnt_lo_u32_b32 v0, -1, 0
	v_mbcnt_hi_u32_b32 v0, -1, v0
	s_cbranch_scc1 .LBB0_619
	s_mov_b32 s63, s33
	v_readlane_b32 s64, v248, 0
	s_lshr_b32 s64, s64, 6
	s_cmp_ge_u32 s64, 4
	s_cbranch_scc0 .LpgL0_noprio
	s_setprio 1
.LpgL0_noprio:
.LpgL0_group:
	v_mbcnt_lo_u32_b32 v249, -1, 0
	v_mbcnt_hi_u32_b32 v249, -1, v249
	v_and_b32_e32 v250, 15, v249
	v_lshrrev_b32_e32 v251, 4, v249
	v_and_b32_e32 v252, 3, v250
	v_cmp_eq_u32_e64 s[4:5], 1, v252
	v_cmp_eq_u32_e64 s[6:7], 2, v252
	v_cmp_eq_u32_e64 s[8:9], 3, v252
	v_cmp_eq_u32_e64 s[10:11], 0, v249
	s_add_u32 s12, s54, 0x29800000
	s_addc_u32 s13, s55, 0
	s_and_b32 s13, s13, 0xffff
	s_mov_b32 s14, 0x2000000
	s_mov_b32 s15, 0x20000
	s_add_u32 s16, s54, 0x8000000
	s_addc_u32 s17, s55, 0
	s_and_b32 s17, s17, 0xffff
	s_mov_b32 s18, 0x1000000
	s_mov_b32 s19, 0x20000
	s_add_u32 s20, s54, 0xc000000
	s_addc_u32 s21, s55, 0
	s_and_b32 s21, s21, 0xffff
	s_mov_b32 s22, 0x1000000
	s_mov_b32 s23, 0x20000
	s_add_u32 s30, s54, 0x80000
	s_addc_u32 s31, s55, 0
	s_add_u32 s34, s54, 0xc0000
	s_addc_u32 s35, s55, 0
	s_mov_b32 s94, 0xc3e00000
	s_mov_b32 s96, 0x800000
	s_mov_b32 s81, 0x1010101
	v_lshrrev_b32_e32 v253, 2, v250
	v_lshrrev_b32_e32 v254, 1, v251
	v_lshl_add_u32 v255, v253, 1, v254
	v_lshl_add_u32 v237, v255, 2, s91
	v_and_b32_e32 v255, 1, v251
	v_lshl_add_u32 v236, v255, 2, v252
	v_lshlrev_b32_e32 v236, 4, v236
	v_lshlrev_b32_e32 v254, 7, v254
	v_lshl_add_u32 v254, v252, 5, v254
	v_lshl_add_u32 v254, v255, 4, v254
	v_and_b32_e32 v253, 1, v253
	v_mov_b32_e32 v255, 0x7fff0000
	v_cmp_eq_u32_e32 vcc, 0, v253
	s_nop 1
	v_cndmask_b32_e32 v238, v255, v254, vcc
	v_cndmask_b32_e32 v239, v254, v255, vcc
	v_mov_b32_e32 v240, 0x7f7f7f7f
	v_mov_b32_e32 v255, 0x20202020
	v_cmp_gt_u32_e32 vcc, 8, v250
	s_nop 1
	v_cndmask_b32_e32 v241, v255, v240, vcc
	v_cndmask_b32_e32 v242, v240, v255, vcc
	v_lshrrev_b32_e32 v254, 3, v250
	v_lshl_add_u32 v254, v252, 1, v254
	v_lshl_add_u32 v255, v251, 1, v253
	v_lshl_add_u32 v244, v254, 3, v255
	v_lshlrev_b32_e32 v244, 2, v244
	v_add_u32_e32 v243, s91, v244
	v_and_b32_e32 v253, 3, v255
	v_lshrrev_b32_e32 v255, 2, v255
	v_lshl_add_u32 v253, v253, 1, v255
	v_lshl_add_u32 v253, v254, 3, v253
	v_lshlrev_b32_e32 v253, 2, v253
	v_add_u32_e32 v245, s91, v253
	v_add_u32_e32 v245, 0x1000, v245
	v_mov_b32_e32 v246, 0
	s_lshl_b32 s64, s63, 12
	s_add_u32 s24, s54, 0x28000000
	s_addc_u32 s25, s55, 0
	s_add_u32 s24, s24, s64
	s_addc_u32 s25, s25, 0
	s_lshl_b32 s64, s63, 12
	s_add_u32 s26, s54, 0x28800000
	s_addc_u32 s27, s55, 0
	s_add_u32 s26, s26, s64
	s_addc_u32 s27, s27, 0
	s_lshl_b32 s64, s63, 15
	s_add_u32 s28, s54, 0x18000000
	s_addc_u32 s29, s55, 0
	s_add_u32 s28, s28, s64
	s_addc_u32 s29, s29, 0
	s_lshl_b32 s64, s63, 5
	s_add_u32 s40, s54, 0x40000
	s_addc_u32 s41, s55, 0
	s_add_u32 s40, s40, s64
	s_addc_u32 s41, s41, 0
	s_lshl_b32 s64, s63, 5
	s_add_u32 s44, s54, 0x50000
	s_addc_u32 s45, s55, 0
	s_add_u32 s44, s44, s64
	s_addc_u32 s45, s45, 0
	s_lshl_b32 s61, s63, 14
	s_add_u32 s62, s61, 0x100
	v_mbcnt_lo_u32_b32 v253, -1, 0
	v_mbcnt_hi_u32_b32 v253, -1, v253
	v_lshlrev_b32_e32 v253, 2, v253
	global_load_dword v0, v253, s[24:25] offset:0 nt
	global_load_dword v1, v253, s[24:25] offset:256 nt
	global_load_dword v2, v253, s[24:25] offset:512 nt
	global_load_dword v3, v253, s[24:25] offset:768 nt
	global_load_dword v4, v253, s[24:25] offset:1024 nt
	global_load_dword v5, v253, s[24:25] offset:1280 nt
	global_load_dword v6, v253, s[24:25] offset:1536 nt
	global_load_dword v7, v253, s[24:25] offset:1792 nt
	global_load_dword v8, v253, s[24:25] offset:2048 nt
	global_load_dword v9, v253, s[24:25] offset:2304 nt
	global_load_dword v10, v253, s[24:25] offset:2560 nt
	global_load_dword v11, v253, s[24:25] offset:2816 nt
	global_load_dword v12, v253, s[24:25] offset:3072 nt
	global_load_dword v13, v253, s[24:25] offset:3328 nt
	global_load_dword v14, v253, s[24:25] offset:3584 nt
	global_load_dword v15, v253, s[24:25] offset:3840 nt
	v_add_u32_e32 v254, s91, v253
	s_waitcnt vmcnt(0)
	ds_write_b32 v254, v0 offset:0
	ds_write_b32 v254, v1 offset:256
	ds_write_b32 v254, v2 offset:512
	ds_write_b32 v254, v3 offset:768
	ds_write_b32 v254, v4 offset:1024
	ds_write_b32 v254, v5 offset:1280
	ds_write_b32 v254, v6 offset:1536
	ds_write_b32 v254, v7 offset:1792
	ds_write_b32 v254, v8 offset:2048
	ds_write_b32 v254, v9 offset:2304
	ds_write_b32 v254, v10 offset:2560
	ds_write_b32 v254, v11 offset:2816
	ds_write_b32 v254, v12 offset:3072
	ds_write_b32 v254, v13 offset:3328
	ds_write_b32 v254, v14 offset:3584
	ds_write_b32 v254, v15 offset:3840
	s_waitcnt lgkmcnt(0)
	s_lshl_b32 s61, s63, 14
	s_add_u32 s62, s61, 0x100
	v_mov_b32_e32 v204, 0
	v_mov_b32_e32 v205, 0
	v_mov_b32_e32 v206, 0
	v_mov_b32_e32 v207, 0
	v_mov_b32_e32 v208, 0
	v_mov_b32_e32 v209, 0
	v_mov_b32_e32 v210, 0
	v_mov_b32_e32 v211, 0
	v_mov_b32_e32 v212, 0
	v_mov_b32_e32 v213, 0
	v_mov_b32_e32 v214, 0
	v_mov_b32_e32 v215, 0
	v_mov_b32_e32 v216, 0
	v_mov_b32_e32 v217, 0
	v_mov_b32_e32 v218, 0
	v_mov_b32_e32 v219, 0
	v_mov_b32_e32 v176, 0
	v_mov_b32_e32 v177, 0
	v_mov_b32_e32 v178, 0
	v_mov_b32_e32 v179, 0
	v_mov_b32_e32 v180, 0
	v_mov_b32_e32 v181, 0
	v_mov_b32_e32 v182, 0
	v_mov_b32_e32 v183, 0
	v_mov_b32_e32 v184, 0
	v_mov_b32_e32 v185, 0
	v_mov_b32_e32 v186, 0
	v_mov_b32_e32 v187, 0
	v_mov_b32_e32 v188, 0
	v_mov_b32_e32 v189, 0
	v_mov_b32_e32 v190, 0
	v_mov_b32_e32 v191, 0
	s_mov_b32 s0, 0
	s_mov_b32 s1, 0
	s_mov_b32 s60, 0x200000
	ds_read_b32 v144, v237 offset:0
	ds_read_b32 v145, v237 offset:32
	ds_read_b32 v146, v237 offset:64
	ds_read_b32 v147, v237 offset:96
	ds_read_b32 v148, v237 offset:128
	ds_read_b32 v149, v237 offset:160
	ds_read_b32 v150, v237 offset:192
	ds_read_b32 v151, v237 offset:224
	s_waitcnt lgkmcnt(0)
	v_lshl_or_b32 v144, v144, 7, v236
	v_lshl_or_b32 v145, v145, 7, v236
	v_lshl_or_b32 v146, v146, 7, v236
	v_lshl_or_b32 v147, v147, 7, v236
	v_lshl_or_b32 v148, v148, 7, v236
	v_lshl_or_b32 v149, v149, 7, v236
	v_lshl_or_b32 v150, v150, 7, v236
	v_lshl_or_b32 v151, v151, 7, v236
	buffer_load_dwordx4 v[0:3], v144, s[16:19], s1 offen
	buffer_load_dwordx4 v[4:7], v145, s[16:19], s1 offen
	buffer_load_dwordx4 v[8:11], v146, s[16:19], s1 offen
	buffer_load_dwordx4 v[12:15], v147, s[16:19], s1 offen
	buffer_load_dwordx4 v[16:19], v148, s[16:19], s1 offen
	buffer_load_dwordx4 v[20:23], v149, s[16:19], s1 offen
	buffer_load_dwordx4 v[24:27], v150, s[16:19], s1 offen
	buffer_load_dwordx4 v[28:31], v151, s[16:19], s1 offen
	ds_read_b32 v144, v237 offset:256
	ds_read_b32 v145, v237 offset:288
	ds_read_b32 v146, v237 offset:320
	ds_read_b32 v147, v237 offset:352
	ds_read_b32 v148, v237 offset:384
	ds_read_b32 v149, v237 offset:416
	ds_read_b32 v150, v237 offset:448
	ds_read_b32 v151, v237 offset:480
	s_add_u32 s80, s61, 0x0
	buffer_load_dwordx4 v[128:131], v238, s[12:15], s80 offen nt
	buffer_load_dwordx4 v[132:135], v239, s[12:15], s80 offen nt
	s_waitcnt lgkmcnt(0)
	v_lshl_or_b32 v144, v144, 7, v236
	v_lshl_or_b32 v145, v145, 7, v236
	v_lshl_or_b32 v146, v146, 7, v236
	v_lshl_or_b32 v147, v147, 7, v236
	v_lshl_or_b32 v148, v148, 7, v236
	v_lshl_or_b32 v149, v149, 7, v236
	v_lshl_or_b32 v150, v150, 7, v236
	v_lshl_or_b32 v151, v151, 7, v236
	buffer_load_dwordx4 v[32:35], v144, s[16:19], s1 offen
	buffer_load_dwordx4 v[36:39], v145, s[16:19], s1 offen
	buffer_load_dwordx4 v[40:43], v146, s[16:19], s1 offen
	buffer_load_dwordx4 v[44:47], v147, s[16:19], s1 offen
	buffer_load_dwordx4 v[48:51], v148, s[16:19], s1 offen
	buffer_load_dwordx4 v[52:55], v149, s[16:19], s1 offen
	buffer_load_dwordx4 v[56:59], v150, s[16:19], s1 offen
	buffer_load_dwordx4 v[60:63], v151, s[16:19], s1 offen
	ds_read_b32 v144, v237 offset:512
	ds_read_b32 v145, v237 offset:544
	ds_read_b32 v146, v237 offset:576
	ds_read_b32 v147, v237 offset:608
	ds_read_b32 v148, v237 offset:640
	ds_read_b32 v149, v237 offset:672
	ds_read_b32 v150, v237 offset:704
	ds_read_b32 v151, v237 offset:736
	s_waitcnt lgkmcnt(0)
	v_lshl_or_b32 v144, v144, 7, v236
	v_lshl_or_b32 v145, v145, 7, v236
	v_lshl_or_b32 v146, v146, 7, v236
	v_lshl_or_b32 v147, v147, 7, v236
	v_lshl_or_b32 v148, v148, 7, v236
	v_lshl_or_b32 v149, v149, 7, v236
	v_lshl_or_b32 v150, v150, 7, v236
	v_lshl_or_b32 v151, v151, 7, v236
	buffer_load_dwordx4 v[64:67], v144, s[16:19], s1 offen
	buffer_load_dwordx4 v[68:71], v145, s[16:19], s1 offen
	buffer_load_dwordx4 v[72:75], v146, s[16:19], s1 offen
	buffer_load_dwordx4 v[76:79], v147, s[16:19], s1 offen
	buffer_load_dwordx4 v[80:83], v148, s[16:19], s1 offen
	buffer_load_dwordx4 v[84:87], v149, s[16:19], s1 offen
	buffer_load_dwordx4 v[88:91], v150, s[16:19], s1 offen
	buffer_load_dwordx4 v[92:95], v151, s[16:19], s1 offen
	ds_read_b32 v144, v237 offset:768
	ds_read_b32 v145, v237 offset:800
	ds_read_b32 v146, v237 offset:832
	ds_read_b32 v147, v237 offset:864
	ds_read_b32 v148, v237 offset:896
	ds_read_b32 v149, v237 offset:928
	ds_read_b32 v150, v237 offset:960
	ds_read_b32 v151, v237 offset:992

.LpgL0_vjoinv0:
	s_lshl_b32 s64, s0, 9
	s_add_u32 s64, s64, 0x1000
	s_add_u32 s70, s28, s64
	s_addc_u32 s71, s29, 0
	global_load_dwordx2 v[230:231], v239, s[70:71]
	s_waitcnt lgkmcnt(0)
	v_lshl_or_b32 v128, v128, 7, v232
	v_lshl_or_b32 v129, v129, 7, v232
	v_lshl_or_b32 v130, v130, 7, v232
	v_lshl_or_b32 v131, v131, 7, v232
	v_lshl_or_b32 v132, v132, 7, v232
	v_lshl_or_b32 v133, v133, 7, v232
	v_lshl_or_b32 v134, v134, 7, v232
	v_lshl_or_b32 v135, v135, 7, v232
	buffer_load_dwordx4 v[32:35], v128, s[20:23], s1 offen
	buffer_load_dwordx4 v[36:39], v129, s[20:23], s1 offen
	buffer_load_dwordx4 v[40:43], v130, s[20:23], s1 offen
	buffer_load_dwordx4 v[44:47], v131, s[20:23], s1 offen
	buffer_load_dwordx4 v[48:51], v132, s[20:23], s1 offen
	buffer_load_dwordx4 v[52:55], v133, s[20:23], s1 offen
	buffer_load_dwordx4 v[56:59], v134, s[20:23], s1 offen
	buffer_load_dwordx4 v[60:63], v135, s[20:23], s1 offen
	ds_read_b32 v128, v243 offset:1536
	ds_read_b32 v129, v243 offset:1568
	ds_read_b32 v130, v243 offset:1600
	ds_read_b32 v131, v243 offset:1632
	ds_read_b32 v132, v243 offset:1664
	ds_read_b32 v133, v243 offset:1696
	ds_read_b32 v134, v243 offset:1728
	ds_read_b32 v135, v243 offset:1760
	ds_read_b64 v[176:177], v234 offset:768
	ds_read_b64 v[178:179], v234 offset:800
	ds_read_b64 v[180:181], v234 offset:832
	ds_read_b64 v[182:183], v234 offset:864
	ds_read_b64 v[184:185], v234 offset:896
	ds_read_b64 v[186:187], v234 offset:928
	ds_read_b64 v[188:189], v234 offset:960
	ds_read_b64 v[190:191], v234 offset:992
	s_waitcnt vmcnt(28)
	v_and_b32_e32 v144, v160, v235
	v_and_b32_e32 v145, v160, v236
	v_and_b32_e32 v146, v160, v237
	v_and_b32_e32 v147, v160, v238
	v_and_b32_e32 v148, v161, v235
	v_and_b32_e32 v149, v161, v236
	v_and_b32_e32 v150, v161, v237
	v_and_b32_e32 v151, v161, v238
	s_mov_b64 vcc, s[4:5]
	v_cndmask_b32_dpp v138, v64, v66, vcc row_shl:4 row_mask:0xf bank_mask:0xf bound_ctrl:1
	v_cndmask_b32_dpp v139, v65, v67, vcc row_shl:4 row_mask:0xf bank_mask:0xf bound_ctrl:1
	s_mov_b64 vcc, s[6:7]
	v_cndmask_b32_dpp v136, v66, v64, vcc row_shr:4 row_mask:0xf bank_mask:0xf bound_ctrl:1
	v_cndmask_b32_dpp v137, v67, v65, vcc row_shr:4 row_mask:0xf bank_mask:0xf bound_ctrl:1
	v_and_b32_e32 v204, v162, v235
	v_and_b32_e32 v205, v162, v236
	v_and_b32_e32 v206, v162, v237
	v_and_b32_e32 v207, v162, v238
	v_and_b32_e32 v208, v163, v235
	v_and_b32_e32 v209, v163, v236
	v_and_b32_e32 v210, v163, v237
	v_and_b32_e32 v211, v163, v238
	s_mov_b64 vcc, s[6:7]
	v_cndmask_b32_dpp v140, v70, v68, vcc row_shr:4 row_mask:0xf bank_mask:0xf bound_ctrl:1
	v_cndmask_b32_dpp v141, v71, v69, vcc row_shr:4 row_mask:0xf bank_mask:0xf bound_ctrl:1
	s_mov_b64 vcc, s[4:5]
	v_cndmask_b32_dpp v142, v68, v70, vcc row_shl:4 row_mask:0xf bank_mask:0xf bound_ctrl:1
	v_cndmask_b32_dpp v143, v69, v71, vcc row_shl:4 row_mask:0xf bank_mask:0xf bound_ctrl:1
	v_mfma_scale_f32_16x16x128_f8f6f4 v[216:219], v[136:139], v[144:151], 0, v240, v241 op_sel_hi:[0,0,0] cbsz:4
	v_and_b32_e32 v144, v164, v235
	v_and_b32_e32 v145, v164, v236
	v_and_b32_e32 v146, v164, v237
	v_and_b32_e32 v147, v164, v238
	v_and_b32_e32 v148, v165, v235
	v_and_b32_e32 v149, v165, v236
	v_and_b32_e32 v150, v165, v237
	v_and_b32_e32 v151, v165, v238
	s_mov_b64 vcc, s[4:5]
	v_cndmask_b32_dpp v138, v72, v74, vcc row_shl:4 row_mask:0xf bank_mask:0xf bound_ctrl:1
	v_cndmask_b32_dpp v139, v73, v75, vcc row_shl:4 row_mask:0xf bank_mask:0xf bound_ctrl:1
	s_mov_b64 vcc, s[6:7]
	v_cndmask_b32_dpp v136, v74, v72, vcc row_shr:4 row_mask:0xf bank_mask:0xf bound_ctrl:1
	v_cndmask_b32_dpp v137, v75, v73, vcc row_shr:4 row_mask:0xf bank_mask:0xf bound_ctrl:1
	v_mfma_scale_f32_16x16x128_f8f6f4 v[216:219], v[140:143], v[204:211], v[216:219], v240, v241 op_sel_hi:[0,0,0] cbsz:4
	v_and_b32_e32 v204, v166, v235
	v_and_b32_e32 v205, v166, v236
	v_and_b32_e32 v206, v166, v237
	v_and_b32_e32 v207, v166, v238
	v_and_b32_e32 v208, v167, v235
	v_and_b32_e32 v209, v167, v236
	v_and_b32_e32 v210, v167, v237
	v_and_b32_e32 v211, v167, v238
	s_mov_b64 vcc, s[6:7]
	v_cndmask_b32_dpp v140, v78, v76, vcc row_shr:4 row_mask:0xf bank_mask:0xf bound_ctrl:1
	v_cndmask_b32_dpp v141, v79, v77, vcc row_shr:4 row_mask:0xf bank_mask:0xf bound_ctrl:1
	s_mov_b64 vcc, s[4:5]
	v_cndmask_b32_dpp v142, v76, v78, vcc row_shl:4 row_mask:0xf bank_mask:0xf bound_ctrl:1
	v_cndmask_b32_dpp v143, v77, v79, vcc row_shl:4 row_mask:0xf bank_mask:0xf bound_ctrl:1
	v_mfma_scale_f32_16x16x128_f8f6f4 v[216:219], v[136:139], v[144:151], v[216:219], v240, v241 op_sel_hi:[0,0,0] cbsz:4
	v_and_b32_e32 v144, v168, v235
	v_and_b32_e32 v145, v168, v236
	v_and_b32_e32 v146, v168, v237
	v_and_b32_e32 v147, v168, v238
	v_and_b32_e32 v148, v169, v235
	v_and_b32_e32 v149, v169, v236
	v_and_b32_e32 v150, v169, v237
	v_and_b32_e32 v151, v169, v238
	s_mov_b64 vcc, s[4:5]
	v_cndmask_b32_dpp v138, v80, v82, vcc row_shl:4 row_mask:0xf bank_mask:0xf bound_ctrl:1
	v_cndmask_b32_dpp v139, v81, v83, vcc row_shl:4 row_mask:0xf bank_mask:0xf bound_ctrl:1
	s_mov_b64 vcc, s[6:7]
	v_cndmask_b32_dpp v136, v82, v80, vcc row_shr:4 row_mask:0xf bank_mask:0xf bound_ctrl:1
	v_cndmask_b32_dpp v137, v83, v81, vcc row_shr:4 row_mask:0xf bank_mask:0xf bound_ctrl:1
	v_mfma_scale_f32_16x16x128_f8f6f4 v[216:219], v[140:143], v[204:211], v[216:219], v240, v241 op_sel_hi:[0,0,0] cbsz:4
	v_and_b32_e32 v204, v170, v235
	v_and_b32_e32 v205, v170, v236
	v_and_b32_e32 v206, v170, v237
	v_and_b32_e32 v207, v170, v238
	v_and_b32_e32 v208, v171, v235
	v_and_b32_e32 v209, v171, v236
	v_and_b32_e32 v210, v171, v237
	v_and_b32_e32 v211, v171, v238
	s_mov_b64 vcc, s[6:7]
	v_cndmask_b32_dpp v140, v86, v84, vcc row_shr:4 row_mask:0xf bank_mask:0xf bound_ctrl:1
	v_cndmask_b32_dpp v141, v87, v85, vcc row_shr:4 row_mask:0xf bank_mask:0xf bound_ctrl:1
	s_mov_b64 vcc, s[4:5]
	v_cndmask_b32_dpp v142, v84, v86, vcc row_shl:4 row_mask:0xf bank_mask:0xf bound_ctrl:1
	v_cndmask_b32_dpp v143, v85, v87, vcc row_shl:4 row_mask:0xf bank_mask:0xf bound_ctrl:1
	v_mfma_scale_f32_16x16x128_f8f6f4 v[216:219], v[136:139], v[144:151], v[216:219], v240, v241 op_sel_hi:[0,0,0] cbsz:4
	v_and_b32_e32 v144, v172, v235
	v_and_b32_e32 v145, v172, v236
	v_and_b32_e32 v146, v172, v237
	v_and_b32_e32 v147, v172, v238
	v_and_b32_e32 v148, v173, v235
	v_and_b32_e32 v149, v173, v236
	v_and_b32_e32 v150, v173, v237
	v_and_b32_e32 v151, v173, v238
	s_mov_b64 vcc, s[4:5]
	v_cndmask_b32_dpp v138, v88, v90, vcc row_shl:4 row_mask:0xf bank_mask:0xf bound_ctrl:1
	v_cndmask_b32_dpp v139, v89, v91, vcc row_shl:4 row_mask:0xf bank_mask:0xf bound_ctrl:1
	s_mov_b64 vcc, s[6:7]
	v_cndmask_b32_dpp v136, v90, v88, vcc row_shr:4 row_mask:0xf bank_mask:0xf bound_ctrl:1
	v_cndmask_b32_dpp v137, v91, v89, vcc row_shr:4 row_mask:0xf bank_mask:0xf bound_ctrl:1
	v_mfma_scale_f32_16x16x128_f8f6f4 v[216:219], v[140:143], v[204:211], v[216:219], v240, v241 op_sel_hi:[0,0,0] cbsz:4
	v_and_b32_e32 v204, v174, v235
	v_and_b32_e32 v205, v174, v236
	v_and_b32_e32 v206, v174, v237
	v_and_b32_e32 v207, v174, v238
	v_and_b32_e32 v208, v175, v235
	v_and_b32_e32 v209, v175, v236
	v_and_b32_e32 v210, v175, v237
	v_and_b32_e32 v211, v175, v238
	s_mov_b64 vcc, s[6:7]
	v_cndmask_b32_dpp v140, v94, v92, vcc row_shr:4 row_mask:0xf bank_mask:0xf bound_ctrl:1
	v_cndmask_b32_dpp v141, v95, v93, vcc row_shr:4 row_mask:0xf bank_mask:0xf bound_ctrl:1
	s_mov_b64 vcc, s[4:5]
	v_cndmask_b32_dpp v142, v92, v94, vcc row_shl:4 row_mask:0xf bank_mask:0xf bound_ctrl:1
	v_cndmask_b32_dpp v143, v93, v95, vcc row_shl:4 row_mask:0xf bank_mask:0xf bound_ctrl:1
	v_mfma_scale_f32_16x16x128_f8f6f4 v[216:219], v[136:139], v[144:151], v[216:219], v240, v241 op_sel_hi:[0,0,0] cbsz:4
	s_nop 0
	v_mfma_scale_f32_16x16x128_f8f6f4 v[216:219], v[140:143], v[204:211], v[216:219], v240, v241 op_sel_hi:[0,0,0] cbsz:4
	s_waitcnt lgkmcnt(0)
	v_lshl_or_b32 v128, v128, 7, v232
	v_lshl_or_b32 v129, v129, 7, v232
	v_lshl_or_b32 v130, v130, 7, v232
	v_lshl_or_b32 v131, v131, 7, v232
	v_lshl_or_b32 v132, v132, 7, v232
	v_lshl_or_b32 v133, v133, 7, v232
	v_lshl_or_b32 v134, v134, 7, v232
	v_lshl_or_b32 v135, v135, 7, v232
	buffer_load_dwordx4 v[64:67], v128, s[20:23], s1 offen
	buffer_load_dwordx4 v[68:71], v129, s[20:23], s1 offen
	buffer_load_dwordx4 v[72:75], v130, s[20:23], s1 offen
	buffer_load_dwordx4 v[76:79], v131, s[20:23], s1 offen
	buffer_load_dwordx4 v[80:83], v132, s[20:23], s1 offen
	buffer_load_dwordx4 v[84:87], v133, s[20:23], s1 offen
	buffer_load_dwordx4 v[88:91], v134, s[20:23], s1 offen
	buffer_load_dwordx4 v[92:95], v135, s[20:23], s1 offen
	ds_read_b32 v128, v243 offset:1792
	ds_read_b32 v129, v243 offset:1824
	ds_read_b32 v130, v243 offset:1856
	ds_read_b32 v131, v243 offset:1888
	ds_read_b32 v132, v243 offset:1920
	ds_read_b32 v133, v243 offset:1952
	ds_read_b32 v134, v243 offset:1984
	ds_read_b32 v135, v243 offset:2016
	ds_read_b64 v[160:161], v234 offset:1024
	ds_read_b64 v[162:163], v234 offset:1056
	ds_read_b64 v[164:165], v234 offset:1088
	ds_read_b64 v[166:167], v234 offset:1120
	ds_read_b64 v[168:169], v234 offset:1152
	ds_read_b64 v[170:171], v234 offset:1184
	ds_read_b64 v[172:173], v234 offset:1216
	ds_read_b64 v[174:175], v234 offset:1248
	s_waitcnt vmcnt(26)
	v_and_b32_e32 v144, v176, v235
	v_and_b32_e32 v145, v176, v236
	v_and_b32_e32 v146, v176, v237
	v_and_b32_e32 v147, v176, v238
	v_and_b32_e32 v148, v177, v235
	v_and_b32_e32 v149, v177, v236
	v_and_b32_e32 v150, v177, v237
	v_and_b32_e32 v151, v177, v238
	s_mov_b64 vcc, s[4:5]
	v_cndmask_b32_dpp v138, v96, v98, vcc row_shl:4 row_mask:0xf bank_mask:0xf bound_ctrl:1
	v_cndmask_b32_dpp v139, v97, v99, vcc row_shl:4 row_mask:0xf bank_mask:0xf bound_ctrl:1
	s_mov_b64 vcc, s[6:7]
	v_cndmask_b32_dpp v136, v98, v96, vcc row_shr:4 row_mask:0xf bank_mask:0xf bound_ctrl:1
	v_cndmask_b32_dpp v137, v99, v97, vcc row_shr:4 row_mask:0xf bank_mask:0xf bound_ctrl:1
	v_and_b32_e32 v204, v178, v235
	v_and_b32_e32 v205, v178, v236
	v_and_b32_e32 v206, v178, v237
	v_and_b32_e32 v207, v178, v238
	v_and_b32_e32 v208, v179, v235
	v_and_b32_e32 v209, v179, v236
	v_and_b32_e32 v210, v179, v237
	v_and_b32_e32 v211, v179, v238
	s_mov_b64 vcc, s[6:7]
	v_cndmask_b32_dpp v140, v102, v100, vcc row_shr:4 row_mask:0xf bank_mask:0xf bound_ctrl:1
	v_cndmask_b32_dpp v141, v103, v101, vcc row_shr:4 row_mask:0xf bank_mask:0xf bound_ctrl:1
	s_mov_b64 vcc, s[4:5]
	v_cndmask_b32_dpp v142, v100, v102, vcc row_shl:4 row_mask:0xf bank_mask:0xf bound_ctrl:1
	v_cndmask_b32_dpp v143, v101, v103, vcc row_shl:4 row_mask:0xf bank_mask:0xf bound_ctrl:1
	v_mfma_scale_f32_16x16x128_f8f6f4 v[216:219], v[136:139], v[144:151], v[216:219], v240, v241 op_sel_hi:[0,0,0] cbsz:4
	v_permlane16_swap_b32_e32 v212, v214
	v_permlane16_swap_b32_e32 v213, v215
	v_lshlrev_b32_e32 v252, 16, v228
	v_and_b32_e32 v144, v180, v235
	v_and_b32_e32 v145, v180, v236
	v_and_b32_e32 v146, v180, v237
	v_and_b32_e32 v147, v180, v238
	v_and_b32_e32 v148, v181, v235
	v_and_b32_e32 v149, v181, v236
	v_and_b32_e32 v150, v181, v237
	v_and_b32_e32 v151, v181, v238
	s_mov_b64 vcc, s[4:5]
	v_cndmask_b32_dpp v138, v104, v106, vcc row_shl:4 row_mask:0xf bank_mask:0xf bound_ctrl:1
	v_cndmask_b32_dpp v139, v105, v107, vcc row_shl:4 row_mask:0xf bank_mask:0xf bound_ctrl:1
	s_mov_b64 vcc, s[6:7]
	v_cndmask_b32_dpp v136, v106, v104, vcc row_shr:4 row_mask:0xf bank_mask:0xf bound_ctrl:1
	v_cndmask_b32_dpp v137, v107, v105, vcc row_shr:4 row_mask:0xf bank_mask:0xf bound_ctrl:1
	v_mfma_scale_f32_16x16x128_f8f6f4 v[216:219], v[140:143], v[204:211], v[216:219], v240, v241 op_sel_hi:[0,0,0] cbsz:4
	v_and_b32_e32 v253, 0xffff0000, v228
	v_lshlrev_b32_e32 v254, 16, v229
	v_and_b32_e32 v255, 0xffff0000, v229
	v_and_b32_e32 v204, v182, v235
	v_and_b32_e32 v205, v182, v236
	v_and_b32_e32 v206, v182, v237
	v_and_b32_e32 v207, v182, v238
	v_and_b32_e32 v208, v183, v235
	v_and_b32_e32 v209, v183, v236
	v_and_b32_e32 v210, v183, v237
	v_and_b32_e32 v211, v183, v238
	s_mov_b64 vcc, s[6:7]
	v_cndmask_b32_dpp v140, v110, v108, vcc row_shr:4 row_mask:0xf bank_mask:0xf bound_ctrl:1
	v_cndmask_b32_dpp v141, v111, v109, vcc row_shr:4 row_mask:0xf bank_mask:0xf bound_ctrl:1
	s_mov_b64 vcc, s[4:5]
	v_cndmask_b32_dpp v142, v108, v110, vcc row_shl:4 row_mask:0xf bank_mask:0xf bound_ctrl:1
	v_cndmask_b32_dpp v143, v109, v111, vcc row_shl:4 row_mask:0xf bank_mask:0xf bound_ctrl:1
	v_mfma_scale_f32_16x16x128_f8f6f4 v[216:219], v[136:139], v[144:151], v[216:219], v240, v241 op_sel_hi:[0,0,0] cbsz:4
	v_add_f32_e32 v252, v212, v252
	v_add_f32_e32 v253, v214, v253
	v_add_f32_e32 v254, v213, v254
	v_and_b32_e32 v144, v184, v235
	v_and_b32_e32 v145, v184, v236
	v_and_b32_e32 v146, v184, v237
	v_and_b32_e32 v147, v184, v238
	v_and_b32_e32 v148, v185, v235
	v_and_b32_e32 v149, v185, v236
	v_and_b32_e32 v150, v185, v237
	v_and_b32_e32 v151, v185, v238
	s_mov_b64 vcc, s[4:5]
	v_cndmask_b32_dpp v138, v112, v114, vcc row_shl:4 row_mask:0xf bank_mask:0xf bound_ctrl:1
	v_cndmask_b32_dpp v139, v113, v115, vcc row_shl:4 row_mask:0xf bank_mask:0xf bound_ctrl:1
	s_mov_b64 vcc, s[6:7]
	v_cndmask_b32_dpp v136, v114, v112, vcc row_shr:4 row_mask:0xf bank_mask:0xf bound_ctrl:1
	v_cndmask_b32_dpp v137, v115, v113, vcc row_shr:4 row_mask:0xf bank_mask:0xf bound_ctrl:1
	v_mfma_scale_f32_16x16x128_f8f6f4 v[216:219], v[140:143], v[204:211], v[216:219], v240, v241 op_sel_hi:[0,0,0] cbsz:4
	v_add_f32_e32 v255, v215, v255
	v_mul_f32_e32 v192, v252, v252
	v_mul_f32_e32 v193, v254, v254
	v_and_b32_e32 v204, v186, v235
	v_and_b32_e32 v205, v186, v236
	v_and_b32_e32 v206, v186, v237
	v_and_b32_e32 v207, v186, v238
	v_and_b32_e32 v208, v187, v235
	v_and_b32_e32 v209, v187, v236
	v_and_b32_e32 v210, v187, v237
	v_and_b32_e32 v211, v187, v238
	s_mov_b64 vcc, s[6:7]
	v_cndmask_b32_dpp v140, v118, v116, vcc row_shr:4 row_mask:0xf bank_mask:0xf bound_ctrl:1
	v_cndmask_b32_dpp v141, v119, v117, vcc row_shr:4 row_mask:0xf bank_mask:0xf bound_ctrl:1
	s_mov_b64 vcc, s[4:5]
	v_cndmask_b32_dpp v142, v116, v118, vcc row_shl:4 row_mask:0xf bank_mask:0xf bound_ctrl:1
	v_cndmask_b32_dpp v143, v117, v119, vcc row_shl:4 row_mask:0xf bank_mask:0xf bound_ctrl:1
	v_mfma_scale_f32_16x16x128_f8f6f4 v[216:219], v[136:139], v[144:151], v[216:219], v240, v241 op_sel_hi:[0,0,0] cbsz:4
	v_fmac_f32_e32 v192, v253, v253
	v_fmac_f32_e32 v193, v255, v255
	v_cvt_pk_bf16_f32 v250, v252, v253
	v_and_b32_e32 v144, v188, v235
	v_and_b32_e32 v145, v188, v236
	v_and_b32_e32 v146, v188, v237
	v_and_b32_e32 v147, v188, v238
	v_and_b32_e32 v148, v189, v235
	v_and_b32_e32 v149, v189, v236
	v_and_b32_e32 v150, v189, v237
	v_and_b32_e32 v151, v189, v238
	s_mov_b64 vcc, s[4:5]
	v_cndmask_b32_dpp v138, v120, v122, vcc row_shl:4 row_mask:0xf bank_mask:0xf bound_ctrl:1
	v_cndmask_b32_dpp v139, v121, v123, vcc row_shl:4 row_mask:0xf bank_mask:0xf bound_ctrl:1
	s_mov_b64 vcc, s[6:7]
	v_cndmask_b32_dpp v136, v122, v120, vcc row_shr:4 row_mask:0xf bank_mask:0xf bound_ctrl:1
	v_cndmask_b32_dpp v137, v123, v121, vcc row_shr:4 row_mask:0xf bank_mask:0xf bound_ctrl:1
	v_mfma_scale_f32_16x16x128_f8f6f4 v[216:219], v[140:143], v[204:211], v[216:219], v240, v241 op_sel_hi:[0,0,0] cbsz:4
	v_cvt_pk_bf16_f32 v251, v254, v255
	v_add_f32_e32 v192, v192, v193
	v_add_f32_e32 v220, v220, v192
	v_and_b32_e32 v204, v190, v235
	v_and_b32_e32 v205, v190, v236
	v_and_b32_e32 v206, v190, v237
	v_and_b32_e32 v207, v190, v238
	v_and_b32_e32 v208, v191, v235
	v_and_b32_e32 v209, v191, v236
	v_and_b32_e32 v210, v191, v237
	v_and_b32_e32 v211, v191, v238
	s_mov_b64 vcc, s[6:7]
	v_cndmask_b32_dpp v140, v126, v124, vcc row_shr:4 row_mask:0xf bank_mask:0xf bound_ctrl:1
	v_cndmask_b32_dpp v141, v127, v125, vcc row_shr:4 row_mask:0xf bank_mask:0xf bound_ctrl:1
	s_mov_b64 vcc, s[4:5]
	v_cndmask_b32_dpp v142, v124, v126, vcc row_shl:4 row_mask:0xf bank_mask:0xf bound_ctrl:1
	v_cndmask_b32_dpp v143, v125, v127, vcc row_shl:4 row_mask:0xf bank_mask:0xf bound_ctrl:1
	v_mfma_scale_f32_16x16x128_f8f6f4 v[216:219], v[136:139], v[144:151], v[216:219], v240, v241 op_sel_hi:[0,0,0] cbsz:4
	s_nop 0
	v_mfma_scale_f32_16x16x128_f8f6f4 v[216:219], v[140:143], v[204:211], v[216:219], v240, v241 op_sel_hi:[0,0,0] cbsz:4
	s_lshl_b32 s64, s0, 9
	s_add_u32 s64, s64, 0x0
	s_add_u32 s76, s28, s64
	s_addc_u32 s77, s29, 0
	global_store_dwordx2 v239, v[250:251], s[76:77]
	s_lshl_b32 s64, s0, 9
	s_add_u32 s64, s64, 0x2000
	s_add_u32 s70, s28, s64
	s_addc_u32 s71, s29, 0
	global_load_dwordx2 v[228:229], v239, s[70:71]
	s_waitcnt lgkmcnt(0)
	v_lshl_or_b32 v128, v128, 7, v232
	v_lshl_or_b32 v129, v129, 7, v232
	v_lshl_or_b32 v130, v130, 7, v232
	v_lshl_or_b32 v131, v131, 7, v232
	v_lshl_or_b32 v132, v132, 7, v232
	v_lshl_or_b32 v133, v133, 7, v232
	v_lshl_or_b32 v134, v134, 7, v232
	v_lshl_or_b32 v135, v135, 7, v232
	buffer_load_dwordx4 v[96:99], v128, s[20:23], s1 offen
	buffer_load_dwordx4 v[100:103], v129, s[20:23], s1 offen
	buffer_load_dwordx4 v[104:107], v130, s[20:23], s1 offen
	buffer_load_dwordx4 v[108:111], v131, s[20:23], s1 offen
	buffer_load_dwordx4 v[112:115], v132, s[20:23], s1 offen
	buffer_load_dwordx4 v[116:119], v133, s[20:23], s1 offen
	buffer_load_dwordx4 v[120:123], v134, s[20:23], s1 offen
	buffer_load_dwordx4 v[124:127], v135, s[20:23], s1 offen
	ds_read_b32 v128, v243 offset:2048
	ds_read_b32 v129, v243 offset:2080
	ds_read_b32 v130, v243 offset:2112
	ds_read_b32 v131, v243 offset:2144
	ds_read_b32 v132, v243 offset:2176
	ds_read_b32 v133, v243 offset:2208
	ds_read_b32 v134, v243 offset:2240
	ds_read_b32 v135, v243 offset:2272
	ds_read_b64 v[176:177], v234 offset:1280
	ds_read_b64 v[178:179], v234 offset:1312
	ds_read_b64 v[180:181], v234 offset:1344
	ds_read_b64 v[182:183], v234 offset:1376
	ds_read_b64 v[184:185], v234 offset:1408
	ds_read_b64 v[186:187], v234 offset:1440
	ds_read_b64 v[188:189], v234 offset:1472
	ds_read_b64 v[190:191], v234 offset:1504
	s_waitcnt vmcnt(28)
	v_and_b32_e32 v144, v160, v235
	v_and_b32_e32 v145, v160, v236
	v_and_b32_e32 v146, v160, v237
	v_and_b32_e32 v147, v160, v238
	v_and_b32_e32 v148, v161, v235
	v_and_b32_e32 v149, v161, v236
	v_and_b32_e32 v150, v161, v237
	v_and_b32_e32 v151, v161, v238
	s_mov_b64 vcc, s[4:5]
	v_cndmask_b32_dpp v138, v0, v2, vcc row_shl:4 row_mask:0xf bank_mask:0xf bound_ctrl:1
	v_cndmask_b32_dpp v139, v1, v3, vcc row_shl:4 row_mask:0xf bank_mask:0xf bound_ctrl:1
	s_mov_b64 vcc, s[6:7]
	v_cndmask_b32_dpp v136, v2, v0, vcc row_shr:4 row_mask:0xf bank_mask:0xf bound_ctrl:1
	v_cndmask_b32_dpp v137, v3, v1, vcc row_shr:4 row_mask:0xf bank_mask:0xf bound_ctrl:1
	v_and_b32_e32 v204, v162, v235
	v_and_b32_e32 v205, v162, v236
	v_and_b32_e32 v206, v162, v237
	v_and_b32_e32 v207, v162, v238
	v_and_b32_e32 v208, v163, v235
	v_and_b32_e32 v209, v163, v236
	v_and_b32_e32 v210, v163, v237
	v_and_b32_e32 v211, v163, v238
	s_mov_b64 vcc, s[6:7]
	v_cndmask_b32_dpp v140, v6, v4, vcc row_shr:4 row_mask:0xf bank_mask:0xf bound_ctrl:1
	v_cndmask_b32_dpp v141, v7, v5, vcc row_shr:4 row_mask:0xf bank_mask:0xf bound_ctrl:1
	s_mov_b64 vcc, s[4:5]
	v_cndmask_b32_dpp v142, v4, v6, vcc row_shl:4 row_mask:0xf bank_mask:0xf bound_ctrl:1
	v_cndmask_b32_dpp v143, v5, v7, vcc row_shl:4 row_mask:0xf bank_mask:0xf bound_ctrl:1
	v_mfma_scale_f32_16x16x128_f8f6f4 v[212:215], v[136:139], v[144:151], 0, v240, v241 op_sel_hi:[0,0,0] cbsz:4
	v_and_b32_e32 v144, v164, v235
	v_and_b32_e32 v145, v164, v236
	v_and_b32_e32 v146, v164, v237
	v_and_b32_e32 v147, v164, v238
	v_and_b32_e32 v148, v165, v235
	v_and_b32_e32 v149, v165, v236
	v_and_b32_e32 v150, v165, v237
	v_and_b32_e32 v151, v165, v238
	s_mov_b64 vcc, s[4:5]
	v_cndmask_b32_dpp v138, v8, v10, vcc row_shl:4 row_mask:0xf bank_mask:0xf bound_ctrl:1
	v_cndmask_b32_dpp v139, v9, v11, vcc row_shl:4 row_mask:0xf bank_mask:0xf bound_ctrl:1
	s_mov_b64 vcc, s[6:7]
	v_cndmask_b32_dpp v136, v10, v8, vcc row_shr:4 row_mask:0xf bank_mask:0xf bound_ctrl:1
	v_cndmask_b32_dpp v137, v11, v9, vcc row_shr:4 row_mask:0xf bank_mask:0xf bound_ctrl:1
	v_mfma_scale_f32_16x16x128_f8f6f4 v[212:215], v[140:143], v[204:211], v[212:215], v240, v241 op_sel_hi:[0,0,0] cbsz:4
	v_and_b32_e32 v204, v166, v235
	v_and_b32_e32 v205, v166, v236
	v_and_b32_e32 v206, v166, v237
	v_and_b32_e32 v207, v166, v238
	v_and_b32_e32 v208, v167, v235
	v_and_b32_e32 v209, v167, v236
	v_and_b32_e32 v210, v167, v237
	v_and_b32_e32 v211, v167, v238
	s_mov_b64 vcc, s[6:7]
	v_cndmask_b32_dpp v140, v14, v12, vcc row_shr:4 row_mask:0xf bank_mask:0xf bound_ctrl:1
	v_cndmask_b32_dpp v141, v15, v13, vcc row_shr:4 row_mask:0xf bank_mask:0xf bound_ctrl:1
	s_mov_b64 vcc, s[4:5]
	v_cndmask_b32_dpp v142, v12, v14, vcc row_shl:4 row_mask:0xf bank_mask:0xf bound_ctrl:1
	v_cndmask_b32_dpp v143, v13, v15, vcc row_shl:4 row_mask:0xf bank_mask:0xf bound_ctrl:1
	v_mfma_scale_f32_16x16x128_f8f6f4 v[212:215], v[136:139], v[144:151], v[212:215], v240, v241 op_sel_hi:[0,0,0] cbsz:4
	v_and_b32_e32 v144, v168, v235
	v_and_b32_e32 v145, v168, v236
	v_and_b32_e32 v146, v168, v237
	v_and_b32_e32 v147, v168, v238
	v_and_b32_e32 v148, v169, v235
	v_and_b32_e32 v149, v169, v236
	v_and_b32_e32 v150, v169, v237
	v_and_b32_e32 v151, v169, v238
	s_mov_b64 vcc, s[4:5]
	v_cndmask_b32_dpp v138, v16, v18, vcc row_shl:4 row_mask:0xf bank_mask:0xf bound_ctrl:1
	v_cndmask_b32_dpp v139, v17, v19, vcc row_shl:4 row_mask:0xf bank_mask:0xf bound_ctrl:1
	s_mov_b64 vcc, s[6:7]
	v_cndmask_b32_dpp v136, v18, v16, vcc row_shr:4 row_mask:0xf bank_mask:0xf bound_ctrl:1
	v_cndmask_b32_dpp v137, v19, v17, vcc row_shr:4 row_mask:0xf bank_mask:0xf bound_ctrl:1
	v_mfma_scale_f32_16x16x128_f8f6f4 v[212:215], v[140:143], v[204:211], v[212:215], v240, v241 op_sel_hi:[0,0,0] cbsz:4
	v_and_b32_e32 v204, v170, v235
	v_and_b32_e32 v205, v170, v236
	v_and_b32_e32 v206, v170, v237
	v_and_b32_e32 v207, v170, v238
	v_and_b32_e32 v208, v171, v235
	v_and_b32_e32 v209, v171, v236
	v_and_b32_e32 v210, v171, v237
	v_and_b32_e32 v211, v171, v238
	s_mov_b64 vcc, s[6:7]
	v_cndmask_b32_dpp v140, v22, v20, vcc row_shr:4 row_mask:0xf bank_mask:0xf bound_ctrl:1
	v_cndmask_b32_dpp v141, v23, v21, vcc row_shr:4 row_mask:0xf bank_mask:0xf bound_ctrl:1
	s_mov_b64 vcc, s[4:5]
	v_cndmask_b32_dpp v142, v20, v22, vcc row_shl:4 row_mask:0xf bank_mask:0xf bound_ctrl:1
	v_cndmask_b32_dpp v143, v21, v23, vcc row_shl:4 row_mask:0xf bank_mask:0xf bound_ctrl:1
	v_mfma_scale_f32_16x16x128_f8f6f4 v[212:215], v[136:139], v[144:151], v[212:215], v240, v241 op_sel_hi:[0,0,0] cbsz:4
	v_and_b32_e32 v144, v172, v235
	v_and_b32_e32 v145, v172, v236
	v_and_b32_e32 v146, v172, v237
	v_and_b32_e32 v147, v172, v238
	v_and_b32_e32 v148, v173, v235
	v_and_b32_e32 v149, v173, v236
	v_and_b32_e32 v150, v173, v237
	v_and_b32_e32 v151, v173, v238
	s_mov_b64 vcc, s[4:5]
	v_cndmask_b32_dpp v138, v24, v26, vcc row_shl:4 row_mask:0xf bank_mask:0xf bound_ctrl:1
	v_cndmask_b32_dpp v139, v25, v27, vcc row_shl:4 row_mask:0xf bank_mask:0xf bound_ctrl:1
	s_mov_b64 vcc, s[6:7]
	v_cndmask_b32_dpp v136, v26, v24, vcc row_shr:4 row_mask:0xf bank_mask:0xf bound_ctrl:1
	v_cndmask_b32_dpp v137, v27, v25, vcc row_shr:4 row_mask:0xf bank_mask:0xf bound_ctrl:1
	v_mfma_scale_f32_16x16x128_f8f6f4 v[212:215], v[140:143], v[204:211], v[212:215], v240, v241 op_sel_hi:[0,0,0] cbsz:4
	v_and_b32_e32 v204, v174, v235
	v_and_b32_e32 v205, v174, v236
	v_and_b32_e32 v206, v174, v237
	v_and_b32_e32 v207, v174, v238
	v_and_b32_e32 v208, v175, v235
	v_and_b32_e32 v209, v175, v236
	v_and_b32_e32 v210, v175, v237
	v_and_b32_e32 v211, v175, v238
	s_mov_b64 vcc, s[6:7]
	v_cndmask_b32_dpp v140, v30, v28, vcc row_shr:4 row_mask:0xf bank_mask:0xf bound_ctrl:1
	v_cndmask_b32_dpp v141, v31, v29, vcc row_shr:4 row_mask:0xf bank_mask:0xf bound_ctrl:1
	s_mov_b64 vcc, s[4:5]
	v_cndmask_b32_dpp v142, v28, v30, vcc row_shl:4 row_mask:0xf bank_mask:0xf bound_ctrl:1
	v_cndmask_b32_dpp v143, v29, v31, vcc row_shl:4 row_mask:0xf bank_mask:0xf bound_ctrl:1
	v_mfma_scale_f32_16x16x128_f8f6f4 v[212:215], v[136:139], v[144:151], v[212:215], v240, v241 op_sel_hi:[0,0,0] cbsz:4
	s_nop 0
	v_mfma_scale_f32_16x16x128_f8f6f4 v[212:215], v[140:143], v[204:211], v[212:215], v240, v241 op_sel_hi:[0,0,0] cbsz:4
	s_waitcnt lgkmcnt(0)
	v_lshl_or_b32 v128, v128, 7, v232
	v_lshl_or_b32 v129, v129, 7, v232
	v_lshl_or_b32 v130, v130, 7, v232
	v_lshl_or_b32 v131, v131, 7, v232
	v_lshl_or_b32 v132, v132, 7, v232
	v_lshl_or_b32 v133, v133, 7, v232
	v_lshl_or_b32 v134, v134, 7, v232
	v_lshl_or_b32 v135, v135, 7, v232
	buffer_load_dwordx4 v[0:3], v128, s[20:23], s1 offen
	buffer_load_dwordx4 v[4:7], v129, s[20:23], s1 offen
	buffer_load_dwordx4 v[8:11], v130, s[20:23], s1 offen
	buffer_load_dwordx4 v[12:15], v131, s[20:23], s1 offen
	buffer_load_dwordx4 v[16:19], v132, s[20:23], s1 offen
	buffer_load_dwordx4 v[20:23], v133, s[20:23], s1 offen
	buffer_load_dwordx4 v[24:27], v134, s[20:23], s1 offen
	buffer_load_dwordx4 v[28:31], v135, s[20:23], s1 offen
	ds_read_b32 v128, v243 offset:2304
	ds_read_b32 v129, v243 offset:2336
	ds_read_b32 v130, v243 offset:2368
	ds_read_b32 v131, v243 offset:2400
	ds_read_b32 v132, v243 offset:2432
	ds_read_b32 v133, v243 offset:2464
	ds_read_b32 v134, v243 offset:2496
	ds_read_b32 v135, v243 offset:2528
	ds_read_b64 v[160:161], v234 offset:1536
	ds_read_b64 v[162:163], v234 offset:1568
	ds_read_b64 v[164:165], v234 offset:1600
	ds_read_b64 v[166:167], v234 offset:1632
	ds_read_b64 v[168:169], v234 offset:1664
	ds_read_b64 v[170:171], v234 offset:1696
	ds_read_b64 v[172:173], v234 offset:1728
	ds_read_b64 v[174:175], v234 offset:1760
	s_waitcnt vmcnt(26)
	v_and_b32_e32 v144, v176, v235
	v_and_b32_e32 v145, v176, v236
	v_and_b32_e32 v146, v176, v237
	v_and_b32_e32 v147, v176, v238
	v_and_b32_e32 v148, v177, v235
	v_and_b32_e32 v149, v177, v236
	v_and_b32_e32 v150, v177, v237
	v_and_b32_e32 v151, v177, v238
	s_mov_b64 vcc, s[4:5]
	v_cndmask_b32_dpp v138, v32, v34, vcc row_shl:4 row_mask:0xf bank_mask:0xf bound_ctrl:1
	v_cndmask_b32_dpp v139, v33, v35, vcc row_shl:4 row_mask:0xf bank_mask:0xf bound_ctrl:1
	s_mov_b64 vcc, s[6:7]
	v_cndmask_b32_dpp v136, v34, v32, vcc row_shr:4 row_mask:0xf bank_mask:0xf bound_ctrl:1
	v_cndmask_b32_dpp v137, v35, v33, vcc row_shr:4 row_mask:0xf bank_mask:0xf bound_ctrl:1
	v_and_b32_e32 v204, v178, v235
	v_and_b32_e32 v205, v178, v236
	v_and_b32_e32 v206, v178, v237
	v_and_b32_e32 v207, v178, v238
	v_and_b32_e32 v208, v179, v235
	v_and_b32_e32 v209, v179, v236
	v_and_b32_e32 v210, v179, v237
	v_and_b32_e32 v211, v179, v238
	s_mov_b64 vcc, s[6:7]
	v_cndmask_b32_dpp v140, v38, v36, vcc row_shr:4 row_mask:0xf bank_mask:0xf bound_ctrl:1
	v_cndmask_b32_dpp v141, v39, v37, vcc row_shr:4 row_mask:0xf bank_mask:0xf bound_ctrl:1
	s_mov_b64 vcc, s[4:5]
	v_cndmask_b32_dpp v142, v36, v38, vcc row_shl:4 row_mask:0xf bank_mask:0xf bound_ctrl:1
	v_cndmask_b32_dpp v143, v37, v39, vcc row_shl:4 row_mask:0xf bank_mask:0xf bound_ctrl:1
	v_mfma_scale_f32_16x16x128_f8f6f4 v[212:215], v[136:139], v[144:151], v[212:215], v240, v241 op_sel_hi:[0,0,0] cbsz:4
	v_permlane16_swap_b32_e32 v216, v218
	v_permlane16_swap_b32_e32 v217, v219
	v_lshlrev_b32_e32 v252, 16, v230
	v_and_b32_e32 v144, v180, v235
	v_and_b32_e32 v145, v180, v236
	v_and_b32_e32 v146, v180, v237
	v_and_b32_e32 v147, v180, v238
	v_and_b32_e32 v148, v181, v235
	v_and_b32_e32 v149, v181, v236
	v_and_b32_e32 v150, v181, v237
	v_and_b32_e32 v151, v181, v238
	s_mov_b64 vcc, s[4:5]
	v_cndmask_b32_dpp v138, v40, v42, vcc row_shl:4 row_mask:0xf bank_mask:0xf bound_ctrl:1
	v_cndmask_b32_dpp v139, v41, v43, vcc row_shl:4 row_mask:0xf bank_mask:0xf bound_ctrl:1
	s_mov_b64 vcc, s[6:7]
	v_cndmask_b32_dpp v136, v42, v40, vcc row_shr:4 row_mask:0xf bank_mask:0xf bound_ctrl:1
	v_cndmask_b32_dpp v137, v43, v41, vcc row_shr:4 row_mask:0xf bank_mask:0xf bound_ctrl:1
	v_mfma_scale_f32_16x16x128_f8f6f4 v[212:215], v[140:143], v[204:211], v[212:215], v240, v241 op_sel_hi:[0,0,0] cbsz:4
	v_and_b32_e32 v253, 0xffff0000, v230
	v_lshlrev_b32_e32 v254, 16, v231
	v_and_b32_e32 v255, 0xffff0000, v231
	v_and_b32_e32 v204, v182, v235
	v_and_b32_e32 v205, v182, v236
	v_and_b32_e32 v206, v182, v237
	v_and_b32_e32 v207, v182, v238
	v_and_b32_e32 v208, v183, v235
	v_and_b32_e32 v209, v183, v236
	v_and_b32_e32 v210, v183, v237
	v_and_b32_e32 v211, v183, v238
	s_mov_b64 vcc, s[6:7]
	v_cndmask_b32_dpp v140, v46, v44, vcc row_shr:4 row_mask:0xf bank_mask:0xf bound_ctrl:1
	v_cndmask_b32_dpp v141, v47, v45, vcc row_shr:4 row_mask:0xf bank_mask:0xf bound_ctrl:1
	s_mov_b64 vcc, s[4:5]
	v_cndmask_b32_dpp v142, v44, v46, vcc row_shl:4 row_mask:0xf bank_mask:0xf bound_ctrl:1
	v_cndmask_b32_dpp v143, v45, v47, vcc row_shl:4 row_mask:0xf bank_mask:0xf bound_ctrl:1
	v_mfma_scale_f32_16x16x128_f8f6f4 v[212:215], v[136:139], v[144:151], v[212:215], v240, v241 op_sel_hi:[0,0,0] cbsz:4
	v_add_f32_e32 v252, v216, v252
	v_add_f32_e32 v253, v218, v253
	v_add_f32_e32 v254, v217, v254
	v_and_b32_e32 v144, v184, v235
	v_and_b32_e32 v145, v184, v236
	v_and_b32_e32 v146, v184, v237
	v_and_b32_e32 v147, v184, v238
	v_and_b32_e32 v148, v185, v235
	v_and_b32_e32 v149, v185, v236
	v_and_b32_e32 v150, v185, v237
	v_and_b32_e32 v151, v185, v238
	s_mov_b64 vcc, s[4:5]
	v_cndmask_b32_dpp v138, v48, v50, vcc row_shl:4 row_mask:0xf bank_mask:0xf bound_ctrl:1
	v_cndmask_b32_dpp v139, v49, v51, vcc row_shl:4 row_mask:0xf bank_mask:0xf bound_ctrl:1
	s_mov_b64 vcc, s[6:7]
	v_cndmask_b32_dpp v136, v50, v48, vcc row_shr:4 row_mask:0xf bank_mask:0xf bound_ctrl:1
	v_cndmask_b32_dpp v137, v51, v49, vcc row_shr:4 row_mask:0xf bank_mask:0xf bound_ctrl:1
	v_mfma_scale_f32_16x16x128_f8f6f4 v[212:215], v[140:143], v[204:211], v[212:215], v240, v241 op_sel_hi:[0,0,0] cbsz:4
	v_add_f32_e32 v255, v219, v255
	v_mul_f32_e32 v192, v252, v252
	v_mul_f32_e32 v193, v254, v254
	v_and_b32_e32 v204, v186, v235
	v_and_b32_e32 v205, v186, v236
	v_and_b32_e32 v206, v186, v237
	v_and_b32_e32 v207, v186, v238
	v_and_b32_e32 v208, v187, v235
	v_and_b32_e32 v209, v187, v236
	v_and_b32_e32 v210, v187, v237
	v_and_b32_e32 v211, v187, v238
	s_mov_b64 vcc, s[6:7]
	v_cndmask_b32_dpp v140, v54, v52, vcc row_shr:4 row_mask:0xf bank_mask:0xf bound_ctrl:1
	v_cndmask_b32_dpp v141, v55, v53, vcc row_shr:4 row_mask:0xf bank_mask:0xf bound_ctrl:1
	s_mov_b64 vcc, s[4:5]
	v_cndmask_b32_dpp v142, v52, v54, vcc row_shl:4 row_mask:0xf bank_mask:0xf bound_ctrl:1
	v_cndmask_b32_dpp v143, v53, v55, vcc row_shl:4 row_mask:0xf bank_mask:0xf bound_ctrl:1
	v_mfma_scale_f32_16x16x128_f8f6f4 v[212:215], v[136:139], v[144:151], v[212:215], v240, v241 op_sel_hi:[0,0,0] cbsz:4
	v_fmac_f32_e32 v192, v253, v253
	v_fmac_f32_e32 v193, v255, v255
	v_cvt_pk_bf16_f32 v250, v252, v253
	v_and_b32_e32 v144, v188, v235
	v_and_b32_e32 v145, v188, v236
	v_and_b32_e32 v146, v188, v237
	v_and_b32_e32 v147, v188, v238
	v_and_b32_e32 v148, v189, v235
	v_and_b32_e32 v149, v189, v236
	v_and_b32_e32 v150, v189, v237
	v_and_b32_e32 v151, v189, v238
	s_mov_b64 vcc, s[4:5]
	v_cndmask_b32_dpp v138, v56, v58, vcc row_shl:4 row_mask:0xf bank_mask:0xf bound_ctrl:1
	v_cndmask_b32_dpp v139, v57, v59, vcc row_shl:4 row_mask:0xf bank_mask:0xf bound_ctrl:1
	s_mov_b64 vcc, s[6:7]
	v_cndmask_b32_dpp v136, v58, v56, vcc row_shr:4 row_mask:0xf bank_mask:0xf bound_ctrl:1
	v_cndmask_b32_dpp v137, v59, v57, vcc row_shr:4 row_mask:0xf bank_mask:0xf bound_ctrl:1
	v_mfma_scale_f32_16x16x128_f8f6f4 v[212:215], v[140:143], v[204:211], v[212:215], v240, v241 op_sel_hi:[0,0,0] cbsz:4
	v_cvt_pk_bf16_f32 v251, v254, v255
	v_add_f32_e32 v192, v192, v193
	v_add_f32_e32 v221, v221, v192
	v_and_b32_e32 v204, v190, v235
	v_and_b32_e32 v205, v190, v236
	v_and_b32_e32 v206, v190, v237
	v_and_b32_e32 v207, v190, v238
	v_and_b32_e32 v208, v191, v235
	v_and_b32_e32 v209, v191, v236
	v_and_b32_e32 v210, v191, v237
	v_and_b32_e32 v211, v191, v238
	s_mov_b64 vcc, s[6:7]
	v_cndmask_b32_dpp v140, v62, v60, vcc row_shr:4 row_mask:0xf bank_mask:0xf bound_ctrl:1
	v_cndmask_b32_dpp v141, v63, v61, vcc row_shr:4 row_mask:0xf bank_mask:0xf bound_ctrl:1
	s_mov_b64 vcc, s[4:5]
	v_cndmask_b32_dpp v142, v60, v62, vcc row_shl:4 row_mask:0xf bank_mask:0xf bound_ctrl:1
	v_cndmask_b32_dpp v143, v61, v63, vcc row_shl:4 row_mask:0xf bank_mask:0xf bound_ctrl:1
	v_mfma_scale_f32_16x16x128_f8f6f4 v[212:215], v[136:139], v[144:151], v[212:215], v240, v241 op_sel_hi:[0,0,0] cbsz:4
	s_nop 0
	v_mfma_scale_f32_16x16x128_f8f6f4 v[212:215], v[140:143], v[204:211], v[212:215], v240, v241 op_sel_hi:[0,0,0] cbsz:4
	s_lshl_b32 s64, s0, 9
	s_add_u32 s64, s64, 0x1000
	s_add_u32 s76, s28, s64
	s_addc_u32 s77, s29, 0
	global_store_dwordx2 v239, v[250:251], s[76:77]
	s_lshl_b32 s64, s0, 9
	s_add_u32 s64, s64, 0x3000
	s_add_u32 s70, s28, s64
	s_addc_u32 s71, s29, 0
	global_load_dwordx2 v[230:231], v239, s[70:71]
	s_waitcnt lgkmcnt(0)
	v_lshl_or_b32 v128, v128, 7, v232
	v_lshl_or_b32 v129, v129, 7, v232
	v_lshl_or_b32 v130, v130, 7, v232
	v_lshl_or_b32 v131, v131, 7, v232
	v_lshl_or_b32 v132, v132, 7, v232
	v_lshl_or_b32 v133, v133, 7, v232
	v_lshl_or_b32 v134, v134, 7, v232
	v_lshl_or_b32 v135, v135, 7, v232
	buffer_load_dwordx4 v[32:35], v128, s[20:23], s1 offen
	buffer_load_dwordx4 v[36:39], v129, s[20:23], s1 offen
	buffer_load_dwordx4 v[40:43], v130, s[20:23], s1 offen
	buffer_load_dwordx4 v[44:47], v131, s[20:23], s1 offen
	buffer_load_dwordx4 v[48:51], v132, s[20:23], s1 offen
	buffer_load_dwordx4 v[52:55], v133, s[20:23], s1 offen
	buffer_load_dwordx4 v[56:59], v134, s[20:23], s1 offen
	buffer_load_dwordx4 v[60:63], v135, s[20:23], s1 offen
	ds_read_b32 v128, v243 offset:2560
	ds_read_b32 v129, v243 offset:2592
	ds_read_b32 v130, v243 offset:2624
	ds_read_b32 v131, v243 offset:2656
	ds_read_b32 v132, v243 offset:2688
	ds_read_b32 v133, v243 offset:2720
	ds_read_b32 v134, v243 offset:2752
	ds_read_b32 v135, v243 offset:2784
	ds_read_b64 v[176:177], v234 offset:1792
	ds_read_b64 v[178:179], v234 offset:1824
	ds_read_b64 v[180:181], v234 offset:1856
	ds_read_b64 v[182:183], v234 offset:1888
	ds_read_b64 v[184:185], v234 offset:1920
	ds_read_b64 v[186:187], v234 offset:1952
	ds_read_b64 v[188:189], v234 offset:1984
	ds_read_b64 v[190:191], v234 offset:2016
	s_waitcnt vmcnt(28)
	v_and_b32_e32 v144, v160, v235
	v_and_b32_e32 v145, v160, v236
	v_and_b32_e32 v146, v160, v237
	v_and_b32_e32 v147, v160, v238
	v_and_b32_e32 v148, v161, v235
	v_and_b32_e32 v149, v161, v236
	v_and_b32_e32 v150, v161, v237
	v_and_b32_e32 v151, v161, v238
	s_mov_b64 vcc, s[4:5]
	v_cndmask_b32_dpp v138, v64, v66, vcc row_shl:4 row_mask:0xf bank_mask:0xf bound_ctrl:1
	v_cndmask_b32_dpp v139, v65, v67, vcc row_shl:4 row_mask:0xf bank_mask:0xf bound_ctrl:1
	s_mov_b64 vcc, s[6:7]
	v_cndmask_b32_dpp v136, v66, v64, vcc row_shr:4 row_mask:0xf bank_mask:0xf bound_ctrl:1
	v_cndmask_b32_dpp v137, v67, v65, vcc row_shr:4 row_mask:0xf bank_mask:0xf bound_ctrl:1
	v_and_b32_e32 v204, v162, v235
	v_and_b32_e32 v205, v162, v236
	v_and_b32_e32 v206, v162, v237
	v_and_b32_e32 v207, v162, v238
	v_and_b32_e32 v208, v163, v235
	v_and_b32_e32 v209, v163, v236
	v_and_b32_e32 v210, v163, v237
	v_and_b32_e32 v211, v163, v238
	s_mov_b64 vcc, s[6:7]
	v_cndmask_b32_dpp v140, v70, v68, vcc row_shr:4 row_mask:0xf bank_mask:0xf bound_ctrl:1
	v_cndmask_b32_dpp v141, v71, v69, vcc row_shr:4 row_mask:0xf bank_mask:0xf bound_ctrl:1
	s_mov_b64 vcc, s[4:5]
	v_cndmask_b32_dpp v142, v68, v70, vcc row_shl:4 row_mask:0xf bank_mask:0xf bound_ctrl:1
	v_cndmask_b32_dpp v143, v69, v71, vcc row_shl:4 row_mask:0xf bank_mask:0xf bound_ctrl:1
	v_mfma_scale_f32_16x16x128_f8f6f4 v[216:219], v[136:139], v[144:151], 0, v240, v241 op_sel_hi:[0,0,0] cbsz:4
	v_and_b32_e32 v144, v164, v235
	v_and_b32_e32 v145, v164, v236
	v_and_b32_e32 v146, v164, v237
	v_and_b32_e32 v147, v164, v238
	v_and_b32_e32 v148, v165, v235
	v_and_b32_e32 v149, v165, v236
	v_and_b32_e32 v150, v165, v237
	v_and_b32_e32 v151, v165, v238
	s_mov_b64 vcc, s[4:5]
	v_cndmask_b32_dpp v138, v72, v74, vcc row_shl:4 row_mask:0xf bank_mask:0xf bound_ctrl:1
	v_cndmask_b32_dpp v139, v73, v75, vcc row_shl:4 row_mask:0xf bank_mask:0xf bound_ctrl:1
	s_mov_b64 vcc, s[6:7]
	v_cndmask_b32_dpp v136, v74, v72, vcc row_shr:4 row_mask:0xf bank_mask:0xf bound_ctrl:1
	v_cndmask_b32_dpp v137, v75, v73, vcc row_shr:4 row_mask:0xf bank_mask:0xf bound_ctrl:1
	v_mfma_scale_f32_16x16x128_f8f6f4 v[216:219], v[140:143], v[204:211], v[216:219], v240, v241 op_sel_hi:[0,0,0] cbsz:4
	v_and_b32_e32 v204, v166, v235
	v_and_b32_e32 v205, v166, v236
	v_and_b32_e32 v206, v166, v237
	v_and_b32_e32 v207, v166, v238
	v_and_b32_e32 v208, v167, v235
	v_and_b32_e32 v209, v167, v236
	v_and_b32_e32 v210, v167, v237
	v_and_b32_e32 v211, v167, v238
	s_mov_b64 vcc, s[6:7]
	v_cndmask_b32_dpp v140, v78, v76, vcc row_shr:4 row_mask:0xf bank_mask:0xf bound_ctrl:1
	v_cndmask_b32_dpp v141, v79, v77, vcc row_shr:4 row_mask:0xf bank_mask:0xf bound_ctrl:1
	s_mov_b64 vcc, s[4:5]
	v_cndmask_b32_dpp v142, v76, v78, vcc row_shl:4 row_mask:0xf bank_mask:0xf bound_ctrl:1
	v_cndmask_b32_dpp v143, v77, v79, vcc row_shl:4 row_mask:0xf bank_mask:0xf bound_ctrl:1
	v_mfma_scale_f32_16x16x128_f8f6f4 v[216:219], v[136:139], v[144:151], v[216:219], v240, v241 op_sel_hi:[0,0,0] cbsz:4
	v_and_b32_e32 v144, v168, v235
	v_and_b32_e32 v145, v168, v236
	v_and_b32_e32 v146, v168, v237
	v_and_b32_e32 v147, v168, v238
	v_and_b32_e32 v148, v169, v235
	v_and_b32_e32 v149, v169, v236
	v_and_b32_e32 v150, v169, v237
	v_and_b32_e32 v151, v169, v238
	s_mov_b64 vcc, s[4:5]
	v_cndmask_b32_dpp v138, v80, v82, vcc row_shl:4 row_mask:0xf bank_mask:0xf bound_ctrl:1
	v_cndmask_b32_dpp v139, v81, v83, vcc row_shl:4 row_mask:0xf bank_mask:0xf bound_ctrl:1
	s_mov_b64 vcc, s[6:7]
	v_cndmask_b32_dpp v136, v82, v80, vcc row_shr:4 row_mask:0xf bank_mask:0xf bound_ctrl:1
	v_cndmask_b32_dpp v137, v83, v81, vcc row_shr:4 row_mask:0xf bank_mask:0xf bound_ctrl:1
	v_mfma_scale_f32_16x16x128_f8f6f4 v[216:219], v[140:143], v[204:211], v[216:219], v240, v241 op_sel_hi:[0,0,0] cbsz:4
	v_and_b32_e32 v204, v170, v235
	v_and_b32_e32 v205, v170, v236
	v_and_b32_e32 v206, v170, v237
	v_and_b32_e32 v207, v170, v238
	v_and_b32_e32 v208, v171, v235
	v_and_b32_e32 v209, v171, v236
	v_and_b32_e32 v210, v171, v237
	v_and_b32_e32 v211, v171, v238
	s_mov_b64 vcc, s[6:7]
	v_cndmask_b32_dpp v140, v86, v84, vcc row_shr:4 row_mask:0xf bank_mask:0xf bound_ctrl:1
	v_cndmask_b32_dpp v141, v87, v85, vcc row_shr:4 row_mask:0xf bank_mask:0xf bound_ctrl:1
	s_mov_b64 vcc, s[4:5]
	v_cndmask_b32_dpp v142, v84, v86, vcc row_shl:4 row_mask:0xf bank_mask:0xf bound_ctrl:1
	v_cndmask_b32_dpp v143, v85, v87, vcc row_shl:4 row_mask:0xf bank_mask:0xf bound_ctrl:1
	v_mfma_scale_f32_16x16x128_f8f6f4 v[216:219], v[136:139], v[144:151], v[216:219], v240, v241 op_sel_hi:[0,0,0] cbsz:4
	v_and_b32_e32 v144, v172, v235
	v_and_b32_e32 v145, v172, v236
	v_and_b32_e32 v146, v172, v237
	v_and_b32_e32 v147, v172, v238
	v_and_b32_e32 v148, v173, v235
	v_and_b32_e32 v149, v173, v236
	v_and_b32_e32 v150, v173, v237
	v_and_b32_e32 v151, v173, v238
	s_mov_b64 vcc, s[4:5]
	v_cndmask_b32_dpp v138, v88, v90, vcc row_shl:4 row_mask:0xf bank_mask:0xf bound_ctrl:1
	v_cndmask_b32_dpp v139, v89, v91, vcc row_shl:4 row_mask:0xf bank_mask:0xf bound_ctrl:1
	s_mov_b64 vcc, s[6:7]
	v_cndmask_b32_dpp v136, v90, v88, vcc row_shr:4 row_mask:0xf bank_mask:0xf bound_ctrl:1
	v_cndmask_b32_dpp v137, v91, v89, vcc row_shr:4 row_mask:0xf bank_mask:0xf bound_ctrl:1
	v_mfma_scale_f32_16x16x128_f8f6f4 v[216:219], v[140:143], v[204:211], v[216:219], v240, v241 op_sel_hi:[0,0,0] cbsz:4
	v_and_b32_e32 v204, v174, v235
	v_and_b32_e32 v205, v174, v236
	v_and_b32_e32 v206, v174, v237
	v_and_b32_e32 v207, v174, v238
	v_and_b32_e32 v208, v175, v235
	v_and_b32_e32 v209, v175, v236
	v_and_b32_e32 v210, v175, v237
	v_and_b32_e32 v211, v175, v238
	s_mov_b64 vcc, s[6:7]
	v_cndmask_b32_dpp v140, v94, v92, vcc row_shr:4 row_mask:0xf bank_mask:0xf bound_ctrl:1
	v_cndmask_b32_dpp v141, v95, v93, vcc row_shr:4 row_mask:0xf bank_mask:0xf bound_ctrl:1
	s_mov_b64 vcc, s[4:5]
	v_cndmask_b32_dpp v142, v92, v94, vcc row_shl:4 row_mask:0xf bank_mask:0xf bound_ctrl:1
	v_cndmask_b32_dpp v143, v93, v95, vcc row_shl:4 row_mask:0xf bank_mask:0xf bound_ctrl:1
	v_mfma_scale_f32_16x16x128_f8f6f4 v[216:219], v[136:139], v[144:151], v[216:219], v240, v241 op_sel_hi:[0,0,0] cbsz:4
	s_nop 0
	v_mfma_scale_f32_16x16x128_f8f6f4 v[216:219], v[140:143], v[204:211], v[216:219], v240, v241 op_sel_hi:[0,0,0] cbsz:4
	s_waitcnt lgkmcnt(0)
	v_lshl_or_b32 v128, v128, 7, v232
	v_lshl_or_b32 v129, v129, 7, v232
	v_lshl_or_b32 v130, v130, 7, v232
	v_lshl_or_b32 v131, v131, 7, v232
	v_lshl_or_b32 v132, v132, 7, v232
	v_lshl_or_b32 v133, v133, 7, v232
	v_lshl_or_b32 v134, v134, 7, v232
	v_lshl_or_b32 v135, v135, 7, v232
	buffer_load_dwordx4 v[64:67], v128, s[20:23], s1 offen
	buffer_load_dwordx4 v[68:71], v129, s[20:23], s1 offen
	buffer_load_dwordx4 v[72:75], v130, s[20:23], s1 offen
	buffer_load_dwordx4 v[76:79], v131, s[20:23], s1 offen
	buffer_load_dwordx4 v[80:83], v132, s[20:23], s1 offen
	buffer_load_dwordx4 v[84:87], v133, s[20:23], s1 offen
	buffer_load_dwordx4 v[88:91], v134, s[20:23], s1 offen
	buffer_load_dwordx4 v[92:95], v135, s[20:23], s1 offen
	ds_read_b32 v128, v243 offset:2816
	ds_read_b32 v129, v243 offset:2848
	ds_read_b32 v130, v243 offset:2880
	ds_read_b32 v131, v243 offset:2912
	ds_read_b32 v132, v243 offset:2944
	ds_read_b32 v133, v243 offset:2976
	ds_read_b32 v134, v243 offset:3008
	ds_read_b32 v135, v243 offset:3040
	ds_read_b64 v[160:161], v234 offset:2048
	ds_read_b64 v[162:163], v234 offset:2080
	ds_read_b64 v[164:165], v234 offset:2112
	ds_read_b64 v[166:167], v234 offset:2144
	ds_read_b64 v[168:169], v234 offset:2176
	ds_read_b64 v[170:171], v234 offset:2208
	ds_read_b64 v[172:173], v234 offset:2240
	ds_read_b64 v[174:175], v234 offset:2272
	s_waitcnt vmcnt(26)
	v_and_b32_e32 v144, v176, v235
	v_and_b32_e32 v145, v176, v236
	v_and_b32_e32 v146, v176, v237
	v_and_b32_e32 v147, v176, v238
	v_and_b32_e32 v148, v177, v235
	v_and_b32_e32 v149, v177, v236
	v_and_b32_e32 v150, v177, v237
	v_and_b32_e32 v151, v177, v238
	s_mov_b64 vcc, s[4:5]
	v_cndmask_b32_dpp v138, v96, v98, vcc row_shl:4 row_mask:0xf bank_mask:0xf bound_ctrl:1
	v_cndmask_b32_dpp v139, v97, v99, vcc row_shl:4 row_mask:0xf bank_mask:0xf bound_ctrl:1
	s_mov_b64 vcc, s[6:7]
	v_cndmask_b32_dpp v136, v98, v96, vcc row_shr:4 row_mask:0xf bank_mask:0xf bound_ctrl:1
	v_cndmask_b32_dpp v137, v99, v97, vcc row_shr:4 row_mask:0xf bank_mask:0xf bound_ctrl:1
	v_and_b32_e32 v204, v178, v235
	v_and_b32_e32 v205, v178, v236
	v_and_b32_e32 v206, v178, v237
	v_and_b32_e32 v207, v178, v238
	v_and_b32_e32 v208, v179, v235
	v_and_b32_e32 v209, v179, v236
	v_and_b32_e32 v210, v179, v237
	v_and_b32_e32 v211, v179, v238
	s_mov_b64 vcc, s[6:7]
	v_cndmask_b32_dpp v140, v102, v100, vcc row_shr:4 row_mask:0xf bank_mask:0xf bound_ctrl:1
	v_cndmask_b32_dpp v141, v103, v101, vcc row_shr:4 row_mask:0xf bank_mask:0xf bound_ctrl:1
	s_mov_b64 vcc, s[4:5]
	v_cndmask_b32_dpp v142, v100, v102, vcc row_shl:4 row_mask:0xf bank_mask:0xf bound_ctrl:1
	v_cndmask_b32_dpp v143, v101, v103, vcc row_shl:4 row_mask:0xf bank_mask:0xf bound_ctrl:1
	v_mfma_scale_f32_16x16x128_f8f6f4 v[216:219], v[136:139], v[144:151], v[216:219], v240, v241 op_sel_hi:[0,0,0] cbsz:4
	v_permlane16_swap_b32_e32 v212, v214
	v_permlane16_swap_b32_e32 v213, v215
	v_lshlrev_b32_e32 v252, 16, v228
	v_and_b32_e32 v144, v180, v235
	v_and_b32_e32 v145, v180, v236
	v_and_b32_e32 v146, v180, v237
	v_and_b32_e32 v147, v180, v238
	v_and_b32_e32 v148, v181, v235
	v_and_b32_e32 v149, v181, v236
	v_and_b32_e32 v150, v181, v237
	v_and_b32_e32 v151, v181, v238
	s_mov_b64 vcc, s[4:5]
	v_cndmask_b32_dpp v138, v104, v106, vcc row_shl:4 row_mask:0xf bank_mask:0xf bound_ctrl:1
	v_cndmask_b32_dpp v139, v105, v107, vcc row_shl:4 row_mask:0xf bank_mask:0xf bound_ctrl:1
	s_mov_b64 vcc, s[6:7]
	v_cndmask_b32_dpp v136, v106, v104, vcc row_shr:4 row_mask:0xf bank_mask:0xf bound_ctrl:1
	v_cndmask_b32_dpp v137, v107, v105, vcc row_shr:4 row_mask:0xf bank_mask:0xf bound_ctrl:1
	v_mfma_scale_f32_16x16x128_f8f6f4 v[216:219], v[140:143], v[204:211], v[216:219], v240, v241 op_sel_hi:[0,0,0] cbsz:4
	v_and_b32_e32 v253, 0xffff0000, v228
	v_lshlrev_b32_e32 v254, 16, v229
	v_and_b32_e32 v255, 0xffff0000, v229
	v_and_b32_e32 v204, v182, v235
	v_and_b32_e32 v205, v182, v236
	v_and_b32_e32 v206, v182, v237
	v_and_b32_e32 v207, v182, v238
	v_and_b32_e32 v208, v183, v235
	v_and_b32_e32 v209, v183, v236
	v_and_b32_e32 v210, v183, v237
	v_and_b32_e32 v211, v183, v238
	s_mov_b64 vcc, s[6:7]
	v_cndmask_b32_dpp v140, v110, v108, vcc row_shr:4 row_mask:0xf bank_mask:0xf bound_ctrl:1
	v_cndmask_b32_dpp v141, v111, v109, vcc row_shr:4 row_mask:0xf bank_mask:0xf bound_ctrl:1
	s_mov_b64 vcc, s[4:5]
	v_cndmask_b32_dpp v142, v108, v110, vcc row_shl:4 row_mask:0xf bank_mask:0xf bound_ctrl:1
	v_cndmask_b32_dpp v143, v109, v111, vcc row_shl:4 row_mask:0xf bank_mask:0xf bound_ctrl:1
	v_mfma_scale_f32_16x16x128_f8f6f4 v[216:219], v[136:139], v[144:151], v[216:219], v240, v241 op_sel_hi:[0,0,0] cbsz:4
	v_add_f32_e32 v252, v212, v252
	v_add_f32_e32 v253, v214, v253
	v_add_f32_e32 v254, v213, v254
	v_and_b32_e32 v144, v184, v235
	v_and_b32_e32 v145, v184, v236
	v_and_b32_e32 v146, v184, v237
	v_and_b32_e32 v147, v184, v238
	v_and_b32_e32 v148, v185, v235
	v_and_b32_e32 v149, v185, v236
	v_and_b32_e32 v150, v185, v237
	v_and_b32_e32 v151, v185, v238
	s_mov_b64 vcc, s[4:5]
	v_cndmask_b32_dpp v138, v112, v114, vcc row_shl:4 row_mask:0xf bank_mask:0xf bound_ctrl:1
	v_cndmask_b32_dpp v139, v113, v115, vcc row_shl:4 row_mask:0xf bank_mask:0xf bound_ctrl:1
	s_mov_b64 vcc, s[6:7]
	v_cndmask_b32_dpp v136, v114, v112, vcc row_shr:4 row_mask:0xf bank_mask:0xf bound_ctrl:1
	v_cndmask_b32_dpp v137, v115, v113, vcc row_shr:4 row_mask:0xf bank_mask:0xf bound_ctrl:1
	v_mfma_scale_f32_16x16x128_f8f6f4 v[216:219], v[140:143], v[204:211], v[216:219], v240, v241 op_sel_hi:[0,0,0] cbsz:4
	v_add_f32_e32 v255, v215, v255
	v_mul_f32_e32 v192, v252, v252
	v_mul_f32_e32 v193, v254, v254
	v_and_b32_e32 v204, v186, v235
	v_and_b32_e32 v205, v186, v236
	v_and_b32_e32 v206, v186, v237
	v_and_b32_e32 v207, v186, v238
	v_and_b32_e32 v208, v187, v235
	v_and_b32_e32 v209, v187, v236
	v_and_b32_e32 v210, v187, v237
	v_and_b32_e32 v211, v187, v238
	s_mov_b64 vcc, s[6:7]
	v_cndmask_b32_dpp v140, v118, v116, vcc row_shr:4 row_mask:0xf bank_mask:0xf bound_ctrl:1
	v_cndmask_b32_dpp v141, v119, v117, vcc row_shr:4 row_mask:0xf bank_mask:0xf bound_ctrl:1
	s_mov_b64 vcc, s[4:5]
	v_cndmask_b32_dpp v142, v116, v118, vcc row_shl:4 row_mask:0xf bank_mask:0xf bound_ctrl:1
	v_cndmask_b32_dpp v143, v117, v119, vcc row_shl:4 row_mask:0xf bank_mask:0xf bound_ctrl:1
	v_mfma_scale_f32_16x16x128_f8f6f4 v[216:219], v[136:139], v[144:151], v[216:219], v240, v241 op_sel_hi:[0,0,0] cbsz:4
	v_fmac_f32_e32 v192, v253, v253
	v_fmac_f32_e32 v193, v255, v255
	v_cvt_pk_bf16_f32 v250, v252, v253
	v_and_b32_e32 v144, v188, v235
	v_and_b32_e32 v145, v188, v236
	v_and_b32_e32 v146, v188, v237
	v_and_b32_e32 v147, v188, v238
	v_and_b32_e32 v148, v189, v235
	v_and_b32_e32 v149, v189, v236
	v_and_b32_e32 v150, v189, v237
	v_and_b32_e32 v151, v189, v238
	s_mov_b64 vcc, s[4:5]
	v_cndmask_b32_dpp v138, v120, v122, vcc row_shl:4 row_mask:0xf bank_mask:0xf bound_ctrl:1
	v_cndmask_b32_dpp v139, v121, v123, vcc row_shl:4 row_mask:0xf bank_mask:0xf bound_ctrl:1
	s_mov_b64 vcc, s[6:7]
	v_cndmask_b32_dpp v136, v122, v120, vcc row_shr:4 row_mask:0xf bank_mask:0xf bound_ctrl:1
	v_cndmask_b32_dpp v137, v123, v121, vcc row_shr:4 row_mask:0xf bank_mask:0xf bound_ctrl:1
	v_mfma_scale_f32_16x16x128_f8f6f4 v[216:219], v[140:143], v[204:211], v[216:219], v240, v241 op_sel_hi:[0,0,0] cbsz:4
	v_cvt_pk_bf16_f32 v251, v254, v255
	v_add_f32_e32 v192, v192, v193
	v_add_f32_e32 v222, v222, v192
	v_and_b32_e32 v204, v190, v235
	v_and_b32_e32 v205, v190, v236
	v_and_b32_e32 v206, v190, v237
	v_and_b32_e32 v207, v190, v238
	v_and_b32_e32 v208, v191, v235
	v_and_b32_e32 v209, v191, v236
	v_and_b32_e32 v210, v191, v237
	v_and_b32_e32 v211, v191, v238
	s_mov_b64 vcc, s[6:7]
	v_cndmask_b32_dpp v140, v126, v124, vcc row_shr:4 row_mask:0xf bank_mask:0xf bound_ctrl:1
	v_cndmask_b32_dpp v141, v127, v125, vcc row_shr:4 row_mask:0xf bank_mask:0xf bound_ctrl:1
	s_mov_b64 vcc, s[4:5]
	v_cndmask_b32_dpp v142, v124, v126, vcc row_shl:4 row_mask:0xf bank_mask:0xf bound_ctrl:1
	v_cndmask_b32_dpp v143, v125, v127, vcc row_shl:4 row_mask:0xf bank_mask:0xf bound_ctrl:1
	v_mfma_scale_f32_16x16x128_f8f6f4 v[216:219], v[136:139], v[144:151], v[216:219], v240, v241 op_sel_hi:[0,0,0] cbsz:4
	s_nop 0
	v_mfma_scale_f32_16x16x128_f8f6f4 v[216:219], v[140:143], v[204:211], v[216:219], v240, v241 op_sel_hi:[0,0,0] cbsz:4
	s_lshl_b32 s64, s0, 9
	s_add_u32 s64, s64, 0x2000
	s_add_u32 s76, s28, s64
	s_addc_u32 s77, s29, 0
	global_store_dwordx2 v239, v[250:251], s[76:77]
	s_lshl_b32 s64, s0, 9
	s_add_u32 s64, s64, 0x4000
	s_add_u32 s70, s28, s64
	s_addc_u32 s71, s29, 0
	global_load_dwordx2 v[228:229], v239, s[70:71]
	s_waitcnt lgkmcnt(0)
	v_lshl_or_b32 v128, v128, 7, v232
	v_lshl_or_b32 v129, v129, 7, v232
	v_lshl_or_b32 v130, v130, 7, v232
	v_lshl_or_b32 v131, v131, 7, v232
	v_lshl_or_b32 v132, v132, 7, v232
	v_lshl_or_b32 v133, v133, 7, v232
	v_lshl_or_b32 v134, v134, 7, v232
	v_lshl_or_b32 v135, v135, 7, v232
	buffer_load_dwordx4 v[96:99], v128, s[20:23], s1 offen
	buffer_load_dwordx4 v[100:103], v129, s[20:23], s1 offen
	buffer_load_dwordx4 v[104:107], v130, s[20:23], s1 offen
	buffer_load_dwordx4 v[108:111], v131, s[20:23], s1 offen
	buffer_load_dwordx4 v[112:115], v132, s[20:23], s1 offen
	buffer_load_dwordx4 v[116:119], v133, s[20:23], s1 offen
	buffer_load_dwordx4 v[120:123], v134, s[20:23], s1 offen
	buffer_load_dwordx4 v[124:127], v135, s[20:23], s1 offen
	ds_read_b32 v128, v243 offset:3072
	ds_read_b32 v129, v243 offset:3104
	ds_read_b32 v130, v243 offset:3136
	ds_read_b32 v131, v243 offset:3168
	ds_read_b32 v132, v243 offset:3200
	ds_read_b32 v133, v243 offset:3232
	ds_read_b32 v134, v243 offset:3264
	ds_read_b32 v135, v243 offset:3296
	ds_read_b64 v[176:177], v234 offset:2304
	ds_read_b64 v[178:179], v234 offset:2336
	ds_read_b64 v[180:181], v234 offset:2368
	ds_read_b64 v[182:183], v234 offset:2400
	ds_read_b64 v[184:185], v234 offset:2432
	ds_read_b64 v[186:187], v234 offset:2464
	ds_read_b64 v[188:189], v234 offset:2496
	ds_read_b64 v[190:191], v234 offset:2528
	s_waitcnt vmcnt(28)
	v_and_b32_e32 v144, v160, v235
	v_and_b32_e32 v145, v160, v236
	v_and_b32_e32 v146, v160, v237
	v_and_b32_e32 v147, v160, v238
	v_and_b32_e32 v148, v161, v235
	v_and_b32_e32 v149, v161, v236
	v_and_b32_e32 v150, v161, v237
	v_and_b32_e32 v151, v161, v238
	s_mov_b64 vcc, s[4:5]
	v_cndmask_b32_dpp v138, v0, v2, vcc row_shl:4 row_mask:0xf bank_mask:0xf bound_ctrl:1
	v_cndmask_b32_dpp v139, v1, v3, vcc row_shl:4 row_mask:0xf bank_mask:0xf bound_ctrl:1
	s_mov_b64 vcc, s[6:7]
	v_cndmask_b32_dpp v136, v2, v0, vcc row_shr:4 row_mask:0xf bank_mask:0xf bound_ctrl:1
	v_cndmask_b32_dpp v137, v3, v1, vcc row_shr:4 row_mask:0xf bank_mask:0xf bound_ctrl:1
	v_and_b32_e32 v204, v162, v235
	v_and_b32_e32 v205, v162, v236
	v_and_b32_e32 v206, v162, v237
	v_and_b32_e32 v207, v162, v238
	v_and_b32_e32 v208, v163, v235
	v_and_b32_e32 v209, v163, v236
	v_and_b32_e32 v210, v163, v237
	v_and_b32_e32 v211, v163, v238
	s_mov_b64 vcc, s[6:7]
	v_cndmask_b32_dpp v140, v6, v4, vcc row_shr:4 row_mask:0xf bank_mask:0xf bound_ctrl:1
	v_cndmask_b32_dpp v141, v7, v5, vcc row_shr:4 row_mask:0xf bank_mask:0xf bound_ctrl:1
	s_mov_b64 vcc, s[4:5]
	v_cndmask_b32_dpp v142, v4, v6, vcc row_shl:4 row_mask:0xf bank_mask:0xf bound_ctrl:1
	v_cndmask_b32_dpp v143, v5, v7, vcc row_shl:4 row_mask:0xf bank_mask:0xf bound_ctrl:1
	v_mfma_scale_f32_16x16x128_f8f6f4 v[212:215], v[136:139], v[144:151], 0, v240, v241 op_sel_hi:[0,0,0] cbsz:4
	v_and_b32_e32 v144, v164, v235
	v_and_b32_e32 v145, v164, v236
	v_and_b32_e32 v146, v164, v237
	v_and_b32_e32 v147, v164, v238
	v_and_b32_e32 v148, v165, v235
	v_and_b32_e32 v149, v165, v236
	v_and_b32_e32 v150, v165, v237
	v_and_b32_e32 v151, v165, v238
	s_mov_b64 vcc, s[4:5]
	v_cndmask_b32_dpp v138, v8, v10, vcc row_shl:4 row_mask:0xf bank_mask:0xf bound_ctrl:1
	v_cndmask_b32_dpp v139, v9, v11, vcc row_shl:4 row_mask:0xf bank_mask:0xf bound_ctrl:1
	s_mov_b64 vcc, s[6:7]
	v_cndmask_b32_dpp v136, v10, v8, vcc row_shr:4 row_mask:0xf bank_mask:0xf bound_ctrl:1
	v_cndmask_b32_dpp v137, v11, v9, vcc row_shr:4 row_mask:0xf bank_mask:0xf bound_ctrl:1
	v_mfma_scale_f32_16x16x128_f8f6f4 v[212:215], v[140:143], v[204:211], v[212:215], v240, v241 op_sel_hi:[0,0,0] cbsz:4
	v_and_b32_e32 v204, v166, v235
	v_and_b32_e32 v205, v166, v236
	v_and_b32_e32 v206, v166, v237
	v_and_b32_e32 v207, v166, v238
	v_and_b32_e32 v208, v167, v235
	v_and_b32_e32 v209, v167, v236
	v_and_b32_e32 v210, v167, v237
	v_and_b32_e32 v211, v167, v238
	s_mov_b64 vcc, s[6:7]
	v_cndmask_b32_dpp v140, v14, v12, vcc row_shr:4 row_mask:0xf bank_mask:0xf bound_ctrl:1
	v_cndmask_b32_dpp v141, v15, v13, vcc row_shr:4 row_mask:0xf bank_mask:0xf bound_ctrl:1
	s_mov_b64 vcc, s[4:5]
	v_cndmask_b32_dpp v142, v12, v14, vcc row_shl:4 row_mask:0xf bank_mask:0xf bound_ctrl:1
	v_cndmask_b32_dpp v143, v13, v15, vcc row_shl:4 row_mask:0xf bank_mask:0xf bound_ctrl:1
	v_mfma_scale_f32_16x16x128_f8f6f4 v[212:215], v[136:139], v[144:151], v[212:215], v240, v241 op_sel_hi:[0,0,0] cbsz:4
	v_and_b32_e32 v144, v168, v235
	v_and_b32_e32 v145, v168, v236
	v_and_b32_e32 v146, v168, v237
	v_and_b32_e32 v147, v168, v238
	v_and_b32_e32 v148, v169, v235
	v_and_b32_e32 v149, v169, v236
	v_and_b32_e32 v150, v169, v237
	v_and_b32_e32 v151, v169, v238
	s_mov_b64 vcc, s[4:5]
	v_cndmask_b32_dpp v138, v16, v18, vcc row_shl:4 row_mask:0xf bank_mask:0xf bound_ctrl:1
	v_cndmask_b32_dpp v139, v17, v19, vcc row_shl:4 row_mask:0xf bank_mask:0xf bound_ctrl:1
	s_mov_b64 vcc, s[6:7]
	v_cndmask_b32_dpp v136, v18, v16, vcc row_shr:4 row_mask:0xf bank_mask:0xf bound_ctrl:1
	v_cndmask_b32_dpp v137, v19, v17, vcc row_shr:4 row_mask:0xf bank_mask:0xf bound_ctrl:1
	v_mfma_scale_f32_16x16x128_f8f6f4 v[212:215], v[140:143], v[204:211], v[212:215], v240, v241 op_sel_hi:[0,0,0] cbsz:4
	v_and_b32_e32 v204, v170, v235
	v_and_b32_e32 v205, v170, v236
	v_and_b32_e32 v206, v170, v237
	v_and_b32_e32 v207, v170, v238
	v_and_b32_e32 v208, v171, v235
	v_and_b32_e32 v209, v171, v236
	v_and_b32_e32 v210, v171, v237
	v_and_b32_e32 v211, v171, v238
	s_mov_b64 vcc, s[6:7]
	v_cndmask_b32_dpp v140, v22, v20, vcc row_shr:4 row_mask:0xf bank_mask:0xf bound_ctrl:1
	v_cndmask_b32_dpp v141, v23, v21, vcc row_shr:4 row_mask:0xf bank_mask:0xf bound_ctrl:1
	s_mov_b64 vcc, s[4:5]
	v_cndmask_b32_dpp v142, v20, v22, vcc row_shl:4 row_mask:0xf bank_mask:0xf bound_ctrl:1
	v_cndmask_b32_dpp v143, v21, v23, vcc row_shl:4 row_mask:0xf bank_mask:0xf bound_ctrl:1
	v_mfma_scale_f32_16x16x128_f8f6f4 v[212:215], v[136:139], v[144:151], v[212:215], v240, v241 op_sel_hi:[0,0,0] cbsz:4
	v_and_b32_e32 v144, v172, v235
	v_and_b32_e32 v145, v172, v236
	v_and_b32_e32 v146, v172, v237
	v_and_b32_e32 v147, v172, v238
	v_and_b32_e32 v148, v173, v235
	v_and_b32_e32 v149, v173, v236
	v_and_b32_e32 v150, v173, v237
	v_and_b32_e32 v151, v173, v238
	s_mov_b64 vcc, s[4:5]
	v_cndmask_b32_dpp v138, v24, v26, vcc row_shl:4 row_mask:0xf bank_mask:0xf bound_ctrl:1
	v_cndmask_b32_dpp v139, v25, v27, vcc row_shl:4 row_mask:0xf bank_mask:0xf bound_ctrl:1
	s_mov_b64 vcc, s[6:7]
	v_cndmask_b32_dpp v136, v26, v24, vcc row_shr:4 row_mask:0xf bank_mask:0xf bound_ctrl:1
	v_cndmask_b32_dpp v137, v27, v25, vcc row_shr:4 row_mask:0xf bank_mask:0xf bound_ctrl:1
	v_mfma_scale_f32_16x16x128_f8f6f4 v[212:215], v[140:143], v[204:211], v[212:215], v240, v241 op_sel_hi:[0,0,0] cbsz:4
	v_and_b32_e32 v204, v174, v235
	v_and_b32_e32 v205, v174, v236
	v_and_b32_e32 v206, v174, v237
	v_and_b32_e32 v207, v174, v238
	v_and_b32_e32 v208, v175, v235
	v_and_b32_e32 v209, v175, v236
	v_and_b32_e32 v210, v175, v237
	v_and_b32_e32 v211, v175, v238
	s_mov_b64 vcc, s[6:7]
	v_cndmask_b32_dpp v140, v30, v28, vcc row_shr:4 row_mask:0xf bank_mask:0xf bound_ctrl:1
	v_cndmask_b32_dpp v141, v31, v29, vcc row_shr:4 row_mask:0xf bank_mask:0xf bound_ctrl:1
	s_mov_b64 vcc, s[4:5]
	v_cndmask_b32_dpp v142, v28, v30, vcc row_shl:4 row_mask:0xf bank_mask:0xf bound_ctrl:1
	v_cndmask_b32_dpp v143, v29, v31, vcc row_shl:4 row_mask:0xf bank_mask:0xf bound_ctrl:1
	v_mfma_scale_f32_16x16x128_f8f6f4 v[212:215], v[136:139], v[144:151], v[212:215], v240, v241 op_sel_hi:[0,0,0] cbsz:4
	s_nop 0
	v_mfma_scale_f32_16x16x128_f8f6f4 v[212:215], v[140:143], v[204:211], v[212:215], v240, v241 op_sel_hi:[0,0,0] cbsz:4
	s_waitcnt lgkmcnt(0)
	v_lshl_or_b32 v128, v128, 7, v232
	v_lshl_or_b32 v129, v129, 7, v232
	v_lshl_or_b32 v130, v130, 7, v232
	v_lshl_or_b32 v131, v131, 7, v232
	v_lshl_or_b32 v132, v132, 7, v232
	v_lshl_or_b32 v133, v133, 7, v232
	v_lshl_or_b32 v134, v134, 7, v232
	v_lshl_or_b32 v135, v135, 7, v232
	buffer_load_dwordx4 v[0:3], v128, s[20:23], s1 offen
	buffer_load_dwordx4 v[4:7], v129, s[20:23], s1 offen
	buffer_load_dwordx4 v[8:11], v130, s[20:23], s1 offen
	buffer_load_dwordx4 v[12:15], v131, s[20:23], s1 offen
	buffer_load_dwordx4 v[16:19], v132, s[20:23], s1 offen
	buffer_load_dwordx4 v[20:23], v133, s[20:23], s1 offen
	buffer_load_dwordx4 v[24:27], v134, s[20:23], s1 offen
	buffer_load_dwordx4 v[28:31], v135, s[20:23], s1 offen
	ds_read_b32 v128, v243 offset:3328
	ds_read_b32 v129, v243 offset:3360
	ds_read_b32 v130, v243 offset:3392
	ds_read_b32 v131, v243 offset:3424
	ds_read_b32 v132, v243 offset:3456
	ds_read_b32 v133, v243 offset:3488
	ds_read_b32 v134, v243 offset:3520
	ds_read_b32 v135, v243 offset:3552
	ds_read_b64 v[160:161], v234 offset:2560
	ds_read_b64 v[162:163], v234 offset:2592
	ds_read_b64 v[164:165], v234 offset:2624
	ds_read_b64 v[166:167], v234 offset:2656
	ds_read_b64 v[168:169], v234 offset:2688
	ds_read_b64 v[170:171], v234 offset:2720
	ds_read_b64 v[172:173], v234 offset:2752
	ds_read_b64 v[174:175], v234 offset:2784
	s_waitcnt vmcnt(26)
	v_and_b32_e32 v144, v176, v235
	v_and_b32_e32 v145, v176, v236
	v_and_b32_e32 v146, v176, v237
	v_and_b32_e32 v147, v176, v238
	v_and_b32_e32 v148, v177, v235
	v_and_b32_e32 v149, v177, v236
	v_and_b32_e32 v150, v177, v237
	v_and_b32_e32 v151, v177, v238
	s_mov_b64 vcc, s[4:5]
	v_cndmask_b32_dpp v138, v32, v34, vcc row_shl:4 row_mask:0xf bank_mask:0xf bound_ctrl:1
	v_cndmask_b32_dpp v139, v33, v35, vcc row_shl:4 row_mask:0xf bank_mask:0xf bound_ctrl:1
	s_mov_b64 vcc, s[6:7]
	v_cndmask_b32_dpp v136, v34, v32, vcc row_shr:4 row_mask:0xf bank_mask:0xf bound_ctrl:1
	v_cndmask_b32_dpp v137, v35, v33, vcc row_shr:4 row_mask:0xf bank_mask:0xf bound_ctrl:1
	v_and_b32_e32 v204, v178, v235
	v_and_b32_e32 v205, v178, v236
	v_and_b32_e32 v206, v178, v237
	v_and_b32_e32 v207, v178, v238
	v_and_b32_e32 v208, v179, v235
	v_and_b32_e32 v209, v179, v236
	v_and_b32_e32 v210, v179, v237
	v_and_b32_e32 v211, v179, v238
	s_mov_b64 vcc, s[6:7]
	v_cndmask_b32_dpp v140, v38, v36, vcc row_shr:4 row_mask:0xf bank_mask:0xf bound_ctrl:1
	v_cndmask_b32_dpp v141, v39, v37, vcc row_shr:4 row_mask:0xf bank_mask:0xf bound_ctrl:1
	s_mov_b64 vcc, s[4:5]
	v_cndmask_b32_dpp v142, v36, v38, vcc row_shl:4 row_mask:0xf bank_mask:0xf bound_ctrl:1
	v_cndmask_b32_dpp v143, v37, v39, vcc row_shl:4 row_mask:0xf bank_mask:0xf bound_ctrl:1
	v_mfma_scale_f32_16x16x128_f8f6f4 v[212:215], v[136:139], v[144:151], v[212:215], v240, v241 op_sel_hi:[0,0,0] cbsz:4
	v_permlane16_swap_b32_e32 v216, v218
	v_permlane16_swap_b32_e32 v217, v219
	v_lshlrev_b32_e32 v252, 16, v230
	v_and_b32_e32 v144, v180, v235
	v_and_b32_e32 v145, v180, v236
	v_and_b32_e32 v146, v180, v237
	v_and_b32_e32 v147, v180, v238
	v_and_b32_e32 v148, v181, v235
	v_and_b32_e32 v149, v181, v236
	v_and_b32_e32 v150, v181, v237
	v_and_b32_e32 v151, v181, v238
	s_mov_b64 vcc, s[4:5]
	v_cndmask_b32_dpp v138, v40, v42, vcc row_shl:4 row_mask:0xf bank_mask:0xf bound_ctrl:1
	v_cndmask_b32_dpp v139, v41, v43, vcc row_shl:4 row_mask:0xf bank_mask:0xf bound_ctrl:1
	s_mov_b64 vcc, s[6:7]
	v_cndmask_b32_dpp v136, v42, v40, vcc row_shr:4 row_mask:0xf bank_mask:0xf bound_ctrl:1
	v_cndmask_b32_dpp v137, v43, v41, vcc row_shr:4 row_mask:0xf bank_mask:0xf bound_ctrl:1
	v_mfma_scale_f32_16x16x128_f8f6f4 v[212:215], v[140:143], v[204:211], v[212:215], v240, v241 op_sel_hi:[0,0,0] cbsz:4
	v_and_b32_e32 v253, 0xffff0000, v230
	v_lshlrev_b32_e32 v254, 16, v231
	v_and_b32_e32 v255, 0xffff0000, v231
	v_and_b32_e32 v204, v182, v235
	v_and_b32_e32 v205, v182, v236
	v_and_b32_e32 v206, v182, v237
	v_and_b32_e32 v207, v182, v238
	v_and_b32_e32 v208, v183, v235
	v_and_b32_e32 v209, v183, v236
	v_and_b32_e32 v210, v183, v237
	v_and_b32_e32 v211, v183, v238
	s_mov_b64 vcc, s[6:7]
	v_cndmask_b32_dpp v140, v46, v44, vcc row_shr:4 row_mask:0xf bank_mask:0xf bound_ctrl:1
	v_cndmask_b32_dpp v141, v47, v45, vcc row_shr:4 row_mask:0xf bank_mask:0xf bound_ctrl:1
	s_mov_b64 vcc, s[4:5]
	v_cndmask_b32_dpp v142, v44, v46, vcc row_shl:4 row_mask:0xf bank_mask:0xf bound_ctrl:1
	v_cndmask_b32_dpp v143, v45, v47, vcc row_shl:4 row_mask:0xf bank_mask:0xf bound_ctrl:1
	v_mfma_scale_f32_16x16x128_f8f6f4 v[212:215], v[136:139], v[144:151], v[212:215], v240, v241 op_sel_hi:[0,0,0] cbsz:4
	v_add_f32_e32 v252, v216, v252
	v_add_f32_e32 v253, v218, v253
	v_add_f32_e32 v254, v217, v254
	v_and_b32_e32 v144, v184, v235
	v_and_b32_e32 v145, v184, v236
	v_and_b32_e32 v146, v184, v237
	v_and_b32_e32 v147, v184, v238
	v_and_b32_e32 v148, v185, v235
	v_and_b32_e32 v149, v185, v236
	v_and_b32_e32 v150, v185, v237
	v_and_b32_e32 v151, v185, v238
	s_mov_b64 vcc, s[4:5]
	v_cndmask_b32_dpp v138, v48, v50, vcc row_shl:4 row_mask:0xf bank_mask:0xf bound_ctrl:1
	v_cndmask_b32_dpp v139, v49, v51, vcc row_shl:4 row_mask:0xf bank_mask:0xf bound_ctrl:1
	s_mov_b64 vcc, s[6:7]
	v_cndmask_b32_dpp v136, v50, v48, vcc row_shr:4 row_mask:0xf bank_mask:0xf bound_ctrl:1
	v_cndmask_b32_dpp v137, v51, v49, vcc row_shr:4 row_mask:0xf bank_mask:0xf bound_ctrl:1
	v_mfma_scale_f32_16x16x128_f8f6f4 v[212:215], v[140:143], v[204:211], v[212:215], v240, v241 op_sel_hi:[0,0,0] cbsz:4
	v_add_f32_e32 v255, v219, v255
	v_mul_f32_e32 v192, v252, v252
	v_mul_f32_e32 v193, v254, v254
	v_and_b32_e32 v204, v186, v235
	v_and_b32_e32 v205, v186, v236
	v_and_b32_e32 v206, v186, v237
	v_and_b32_e32 v207, v186, v238
	v_and_b32_e32 v208, v187, v235
	v_and_b32_e32 v209, v187, v236
	v_and_b32_e32 v210, v187, v237
	v_and_b32_e32 v211, v187, v238
	s_mov_b64 vcc, s[6:7]
	v_cndmask_b32_dpp v140, v54, v52, vcc row_shr:4 row_mask:0xf bank_mask:0xf bound_ctrl:1
	v_cndmask_b32_dpp v141, v55, v53, vcc row_shr:4 row_mask:0xf bank_mask:0xf bound_ctrl:1
	s_mov_b64 vcc, s[4:5]
	v_cndmask_b32_dpp v142, v52, v54, vcc row_shl:4 row_mask:0xf bank_mask:0xf bound_ctrl:1
	v_cndmask_b32_dpp v143, v53, v55, vcc row_shl:4 row_mask:0xf bank_mask:0xf bound_ctrl:1
	v_mfma_scale_f32_16x16x128_f8f6f4 v[212:215], v[136:139], v[144:151], v[212:215], v240, v241 op_sel_hi:[0,0,0] cbsz:4
	v_fmac_f32_e32 v192, v253, v253
	v_fmac_f32_e32 v193, v255, v255
	v_cvt_pk_bf16_f32 v250, v252, v253
	v_and_b32_e32 v144, v188, v235
	v_and_b32_e32 v145, v188, v236
	v_and_b32_e32 v146, v188, v237
	v_and_b32_e32 v147, v188, v238
	v_and_b32_e32 v148, v189, v235
	v_and_b32_e32 v149, v189, v236
	v_and_b32_e32 v150, v189, v237
	v_and_b32_e32 v151, v189, v238
	s_mov_b64 vcc, s[4:5]
	v_cndmask_b32_dpp v138, v56, v58, vcc row_shl:4 row_mask:0xf bank_mask:0xf bound_ctrl:1
	v_cndmask_b32_dpp v139, v57, v59, vcc row_shl:4 row_mask:0xf bank_mask:0xf bound_ctrl:1
	s_mov_b64 vcc, s[6:7]
	v_cndmask_b32_dpp v136, v58, v56, vcc row_shr:4 row_mask:0xf bank_mask:0xf bound_ctrl:1
	v_cndmask_b32_dpp v137, v59, v57, vcc row_shr:4 row_mask:0xf bank_mask:0xf bound_ctrl:1
	v_mfma_scale_f32_16x16x128_f8f6f4 v[212:215], v[140:143], v[204:211], v[212:215], v240, v241 op_sel_hi:[0,0,0] cbsz:4
	v_cvt_pk_bf16_f32 v251, v254, v255
	v_add_f32_e32 v192, v192, v193
	v_add_f32_e32 v223, v223, v192
	v_and_b32_e32 v204, v190, v235
	v_and_b32_e32 v205, v190, v236
	v_and_b32_e32 v206, v190, v237
	v_and_b32_e32 v207, v190, v238
	v_and_b32_e32 v208, v191, v235
	v_and_b32_e32 v209, v191, v236
	v_and_b32_e32 v210, v191, v237
	v_and_b32_e32 v211, v191, v238
	s_mov_b64 vcc, s[6:7]
	v_cndmask_b32_dpp v140, v62, v60, vcc row_shr:4 row_mask:0xf bank_mask:0xf bound_ctrl:1
	v_cndmask_b32_dpp v141, v63, v61, vcc row_shr:4 row_mask:0xf bank_mask:0xf bound_ctrl:1
	s_mov_b64 vcc, s[4:5]
	v_cndmask_b32_dpp v142, v60, v62, vcc row_shl:4 row_mask:0xf bank_mask:0xf bound_ctrl:1
	v_cndmask_b32_dpp v143, v61, v63, vcc row_shl:4 row_mask:0xf bank_mask:0xf bound_ctrl:1
	v_mfma_scale_f32_16x16x128_f8f6f4 v[212:215], v[136:139], v[144:151], v[212:215], v240, v241 op_sel_hi:[0,0,0] cbsz:4
	s_nop 0
	v_mfma_scale_f32_16x16x128_f8f6f4 v[212:215], v[140:143], v[204:211], v[212:215], v240, v241 op_sel_hi:[0,0,0] cbsz:4
	s_lshl_b32 s64, s0, 9
	s_add_u32 s64, s64, 0x3000
	s_add_u32 s76, s28, s64
	s_addc_u32 s77, s29, 0
	global_store_dwordx2 v239, v[250:251], s[76:77]
	s_lshl_b32 s64, s0, 9
	s_add_u32 s64, s64, 0x5000
	s_add_u32 s70, s28, s64
	s_addc_u32 s71, s29, 0
	global_load_dwordx2 v[230:231], v239, s[70:71]
	s_waitcnt lgkmcnt(0)
	v_lshl_or_b32 v128, v128, 7, v232
	v_lshl_or_b32 v129, v129, 7, v232
	v_lshl_or_b32 v130, v130, 7, v232
	v_lshl_or_b32 v131, v131, 7, v232
	v_lshl_or_b32 v132, v132, 7, v232
	v_lshl_or_b32 v133, v133, 7, v232
	v_lshl_or_b32 v134, v134, 7, v232
	v_lshl_or_b32 v135, v135, 7, v232
	buffer_load_dwordx4 v[32:35], v128, s[20:23], s1 offen
	buffer_load_dwordx4 v[36:39], v129, s[20:23], s1 offen
	buffer_load_dwordx4 v[40:43], v130, s[20:23], s1 offen
	buffer_load_dwordx4 v[44:47], v131, s[20:23], s1 offen
	buffer_load_dwordx4 v[48:51], v132, s[20:23], s1 offen
	buffer_load_dwordx4 v[52:55], v133, s[20:23], s1 offen
	buffer_load_dwordx4 v[56:59], v134, s[20:23], s1 offen
	buffer_load_dwordx4 v[60:63], v135, s[20:23], s1 offen
	ds_read_b32 v128, v243 offset:3584
	ds_read_b32 v129, v243 offset:3616
	ds_read_b32 v130, v243 offset:3648
	ds_read_b32 v131, v243 offset:3680
	ds_read_b32 v132, v243 offset:3712
	ds_read_b32 v133, v243 offset:3744
	ds_read_b32 v134, v243 offset:3776
	ds_read_b32 v135, v243 offset:3808
	ds_read_b64 v[176:177], v234 offset:2816
	ds_read_b64 v[178:179], v234 offset:2848
	ds_read_b64 v[180:181], v234 offset:2880
	ds_read_b64 v[182:183], v234 offset:2912
	ds_read_b64 v[184:185], v234 offset:2944
	ds_read_b64 v[186:187], v234 offset:2976
	ds_read_b64 v[188:189], v234 offset:3008
	ds_read_b64 v[190:191], v234 offset:3040
	s_waitcnt vmcnt(28)
	v_and_b32_e32 v144, v160, v235
	v_and_b32_e32 v145, v160, v236
	v_and_b32_e32 v146, v160, v237
	v_and_b32_e32 v147, v160, v238
	v_and_b32_e32 v148, v161, v235
	v_and_b32_e32 v149, v161, v236
	v_and_b32_e32 v150, v161, v237
	v_and_b32_e32 v151, v161, v238
	s_mov_b64 vcc, s[4:5]
	v_cndmask_b32_dpp v138, v64, v66, vcc row_shl:4 row_mask:0xf bank_mask:0xf bound_ctrl:1
	v_cndmask_b32_dpp v139, v65, v67, vcc row_shl:4 row_mask:0xf bank_mask:0xf bound_ctrl:1
	s_mov_b64 vcc, s[6:7]
	v_cndmask_b32_dpp v136, v66, v64, vcc row_shr:4 row_mask:0xf bank_mask:0xf bound_ctrl:1
	v_cndmask_b32_dpp v137, v67, v65, vcc row_shr:4 row_mask:0xf bank_mask:0xf bound_ctrl:1
	v_and_b32_e32 v204, v162, v235
	v_and_b32_e32 v205, v162, v236
	v_and_b32_e32 v206, v162, v237
	v_and_b32_e32 v207, v162, v238
	v_and_b32_e32 v208, v163, v235
	v_and_b32_e32 v209, v163, v236
	v_and_b32_e32 v210, v163, v237
	v_and_b32_e32 v211, v163, v238
	s_mov_b64 vcc, s[6:7]
	v_cndmask_b32_dpp v140, v70, v68, vcc row_shr:4 row_mask:0xf bank_mask:0xf bound_ctrl:1
	v_cndmask_b32_dpp v141, v71, v69, vcc row_shr:4 row_mask:0xf bank_mask:0xf bound_ctrl:1
	s_mov_b64 vcc, s[4:5]
	v_cndmask_b32_dpp v142, v68, v70, vcc row_shl:4 row_mask:0xf bank_mask:0xf bound_ctrl:1
	v_cndmask_b32_dpp v143, v69, v71, vcc row_shl:4 row_mask:0xf bank_mask:0xf bound_ctrl:1
	v_mfma_scale_f32_16x16x128_f8f6f4 v[216:219], v[136:139], v[144:151], 0, v240, v241 op_sel_hi:[0,0,0] cbsz:4
	v_and_b32_e32 v144, v164, v235
	v_and_b32_e32 v145, v164, v236
	v_and_b32_e32 v146, v164, v237
	v_and_b32_e32 v147, v164, v238
	v_and_b32_e32 v148, v165, v235
	v_and_b32_e32 v149, v165, v236
	v_and_b32_e32 v150, v165, v237
	v_and_b32_e32 v151, v165, v238
	s_mov_b64 vcc, s[4:5]
	v_cndmask_b32_dpp v138, v72, v74, vcc row_shl:4 row_mask:0xf bank_mask:0xf bound_ctrl:1
	v_cndmask_b32_dpp v139, v73, v75, vcc row_shl:4 row_mask:0xf bank_mask:0xf bound_ctrl:1
	s_mov_b64 vcc, s[6:7]
	v_cndmask_b32_dpp v136, v74, v72, vcc row_shr:4 row_mask:0xf bank_mask:0xf bound_ctrl:1
	v_cndmask_b32_dpp v137, v75, v73, vcc row_shr:4 row_mask:0xf bank_mask:0xf bound_ctrl:1
	v_mfma_scale_f32_16x16x128_f8f6f4 v[216:219], v[140:143], v[204:211], v[216:219], v240, v241 op_sel_hi:[0,0,0] cbsz:4
	v_and_b32_e32 v204, v166, v235
	v_and_b32_e32 v205, v166, v236
	v_and_b32_e32 v206, v166, v237
	v_and_b32_e32 v207, v166, v238
	v_and_b32_e32 v208, v167, v235
	v_and_b32_e32 v209, v167, v236
	v_and_b32_e32 v210, v167, v237
	v_and_b32_e32 v211, v167, v238
	s_mov_b64 vcc, s[6:7]
	v_cndmask_b32_dpp v140, v78, v76, vcc row_shr:4 row_mask:0xf bank_mask:0xf bound_ctrl:1
	v_cndmask_b32_dpp v141, v79, v77, vcc row_shr:4 row_mask:0xf bank_mask:0xf bound_ctrl:1
	s_mov_b64 vcc, s[4:5]
	v_cndmask_b32_dpp v142, v76, v78, vcc row_shl:4 row_mask:0xf bank_mask:0xf bound_ctrl:1
	v_cndmask_b32_dpp v143, v77, v79, vcc row_shl:4 row_mask:0xf bank_mask:0xf bound_ctrl:1
	v_mfma_scale_f32_16x16x128_f8f6f4 v[216:219], v[136:139], v[144:151], v[216:219], v240, v241 op_sel_hi:[0,0,0] cbsz:4
	v_and_b32_e32 v144, v168, v235
	v_and_b32_e32 v145, v168, v236
	v_and_b32_e32 v146, v168, v237
	v_and_b32_e32 v147, v168, v238
	v_and_b32_e32 v148, v169, v235
	v_and_b32_e32 v149, v169, v236
	v_and_b32_e32 v150, v169, v237
	v_and_b32_e32 v151, v169, v238
	s_mov_b64 vcc, s[4:5]
	v_cndmask_b32_dpp v138, v80, v82, vcc row_shl:4 row_mask:0xf bank_mask:0xf bound_ctrl:1
	v_cndmask_b32_dpp v139, v81, v83, vcc row_shl:4 row_mask:0xf bank_mask:0xf bound_ctrl:1
	s_mov_b64 vcc, s[6:7]
	v_cndmask_b32_dpp v136, v82, v80, vcc row_shr:4 row_mask:0xf bank_mask:0xf bound_ctrl:1
	v_cndmask_b32_dpp v137, v83, v81, vcc row_shr:4 row_mask:0xf bank_mask:0xf bound_ctrl:1
	v_mfma_scale_f32_16x16x128_f8f6f4 v[216:219], v[140:143], v[204:211], v[216:219], v240, v241 op_sel_hi:[0,0,0] cbsz:4
	v_and_b32_e32 v204, v170, v235
	v_and_b32_e32 v205, v170, v236
	v_and_b32_e32 v206, v170, v237
	v_and_b32_e32 v207, v170, v238
	v_and_b32_e32 v208, v171, v235
	v_and_b32_e32 v209, v171, v236
	v_and_b32_e32 v210, v171, v237
	v_and_b32_e32 v211, v171, v238
	s_mov_b64 vcc, s[6:7]
	v_cndmask_b32_dpp v140, v86, v84, vcc row_shr:4 row_mask:0xf bank_mask:0xf bound_ctrl:1
	v_cndmask_b32_dpp v141, v87, v85, vcc row_shr:4 row_mask:0xf bank_mask:0xf bound_ctrl:1
	s_mov_b64 vcc, s[4:5]
	v_cndmask_b32_dpp v142, v84, v86, vcc row_shl:4 row_mask:0xf bank_mask:0xf bound_ctrl:1
	v_cndmask_b32_dpp v143, v85, v87, vcc row_shl:4 row_mask:0xf bank_mask:0xf bound_ctrl:1
	v_mfma_scale_f32_16x16x128_f8f6f4 v[216:219], v[136:139], v[144:151], v[216:219], v240, v241 op_sel_hi:[0,0,0] cbsz:4
	v_and_b32_e32 v144, v172, v235
	v_and_b32_e32 v145, v172, v236
	v_and_b32_e32 v146, v172, v237
	v_and_b32_e32 v147, v172, v238
	v_and_b32_e32 v148, v173, v235
	v_and_b32_e32 v149, v173, v236
	v_and_b32_e32 v150, v173, v237
	v_and_b32_e32 v151, v173, v238
	s_mov_b64 vcc, s[4:5]
	v_cndmask_b32_dpp v138, v88, v90, vcc row_shl:4 row_mask:0xf bank_mask:0xf bound_ctrl:1
	v_cndmask_b32_dpp v139, v89, v91, vcc row_shl:4 row_mask:0xf bank_mask:0xf bound_ctrl:1
	s_mov_b64 vcc, s[6:7]
	v_cndmask_b32_dpp v136, v90, v88, vcc row_shr:4 row_mask:0xf bank_mask:0xf bound_ctrl:1
	v_cndmask_b32_dpp v137, v91, v89, vcc row_shr:4 row_mask:0xf bank_mask:0xf bound_ctrl:1
	v_mfma_scale_f32_16x16x128_f8f6f4 v[216:219], v[140:143], v[204:211], v[216:219], v240, v241 op_sel_hi:[0,0,0] cbsz:4
	v_and_b32_e32 v204, v174, v235
	v_and_b32_e32 v205, v174, v236
	v_and_b32_e32 v206, v174, v237
	v_and_b32_e32 v207, v174, v238
	v_and_b32_e32 v208, v175, v235
	v_and_b32_e32 v209, v175, v236
	v_and_b32_e32 v210, v175, v237
	v_and_b32_e32 v211, v175, v238
	s_mov_b64 vcc, s[6:7]
	v_cndmask_b32_dpp v140, v94, v92, vcc row_shr:4 row_mask:0xf bank_mask:0xf bound_ctrl:1
	v_cndmask_b32_dpp v141, v95, v93, vcc row_shr:4 row_mask:0xf bank_mask:0xf bound_ctrl:1
	s_mov_b64 vcc, s[4:5]
	v_cndmask_b32_dpp v142, v92, v94, vcc row_shl:4 row_mask:0xf bank_mask:0xf bound_ctrl:1
	v_cndmask_b32_dpp v143, v93, v95, vcc row_shl:4 row_mask:0xf bank_mask:0xf bound_ctrl:1
	v_mfma_scale_f32_16x16x128_f8f6f4 v[216:219], v[136:139], v[144:151], v[216:219], v240, v241 op_sel_hi:[0,0,0] cbsz:4
	s_nop 0
	v_mfma_scale_f32_16x16x128_f8f6f4 v[216:219], v[140:143], v[204:211], v[216:219], v240, v241 op_sel_hi:[0,0,0] cbsz:4
	s_waitcnt lgkmcnt(0)
	v_lshl_or_b32 v128, v128, 7, v232
	v_lshl_or_b32 v129, v129, 7, v232
	v_lshl_or_b32 v130, v130, 7, v232
	v_lshl_or_b32 v131, v131, 7, v232
	v_lshl_or_b32 v132, v132, 7, v232
	v_lshl_or_b32 v133, v133, 7, v232
	v_lshl_or_b32 v134, v134, 7, v232
	v_lshl_or_b32 v135, v135, 7, v232
	buffer_load_dwordx4 v[64:67], v128, s[20:23], s1 offen
	buffer_load_dwordx4 v[68:71], v129, s[20:23], s1 offen
	buffer_load_dwordx4 v[72:75], v130, s[20:23], s1 offen
	buffer_load_dwordx4 v[76:79], v131, s[20:23], s1 offen
	buffer_load_dwordx4 v[80:83], v132, s[20:23], s1 offen
	buffer_load_dwordx4 v[84:87], v133, s[20:23], s1 offen
	buffer_load_dwordx4 v[88:91], v134, s[20:23], s1 offen
	buffer_load_dwordx4 v[92:95], v135, s[20:23], s1 offen
	ds_read_b32 v128, v243 offset:3840
	ds_read_b32 v129, v243 offset:3872
	ds_read_b32 v130, v243 offset:3904
	ds_read_b32 v131, v243 offset:3936
	ds_read_b32 v132, v243 offset:3968
	ds_read_b32 v133, v243 offset:4000
	ds_read_b32 v134, v243 offset:4032
	ds_read_b32 v135, v243 offset:4064
	ds_read_b64 v[160:161], v234 offset:3072
	ds_read_b64 v[162:163], v234 offset:3104
	ds_read_b64 v[164:165], v234 offset:3136
	ds_read_b64 v[166:167], v234 offset:3168
	ds_read_b64 v[168:169], v234 offset:3200
	ds_read_b64 v[170:171], v234 offset:3232
	ds_read_b64 v[172:173], v234 offset:3264
	ds_read_b64 v[174:175], v234 offset:3296
	s_waitcnt vmcnt(26)
	v_and_b32_e32 v144, v176, v235
	v_and_b32_e32 v145, v176, v236
	v_and_b32_e32 v146, v176, v237
	v_and_b32_e32 v147, v176, v238
	v_and_b32_e32 v148, v177, v235
	v_and_b32_e32 v149, v177, v236
	v_and_b32_e32 v150, v177, v237
	v_and_b32_e32 v151, v177, v238
	s_mov_b64 vcc, s[4:5]
	v_cndmask_b32_dpp v138, v96, v98, vcc row_shl:4 row_mask:0xf bank_mask:0xf bound_ctrl:1
	v_cndmask_b32_dpp v139, v97, v99, vcc row_shl:4 row_mask:0xf bank_mask:0xf bound_ctrl:1
	s_mov_b64 vcc, s[6:7]
	v_cndmask_b32_dpp v136, v98, v96, vcc row_shr:4 row_mask:0xf bank_mask:0xf bound_ctrl:1
	v_cndmask_b32_dpp v137, v99, v97, vcc row_shr:4 row_mask:0xf bank_mask:0xf bound_ctrl:1
	v_and_b32_e32 v204, v178, v235
	v_and_b32_e32 v205, v178, v236
	v_and_b32_e32 v206, v178, v237
	v_and_b32_e32 v207, v178, v238
	v_and_b32_e32 v208, v179, v235
	v_and_b32_e32 v209, v179, v236
	v_and_b32_e32 v210, v179, v237
	v_and_b32_e32 v211, v179, v238
	s_mov_b64 vcc, s[6:7]
	v_cndmask_b32_dpp v140, v102, v100, vcc row_shr:4 row_mask:0xf bank_mask:0xf bound_ctrl:1
	v_cndmask_b32_dpp v141, v103, v101, vcc row_shr:4 row_mask:0xf bank_mask:0xf bound_ctrl:1
	s_mov_b64 vcc, s[4:5]
	v_cndmask_b32_dpp v142, v100, v102, vcc row_shl:4 row_mask:0xf bank_mask:0xf bound_ctrl:1
	v_cndmask_b32_dpp v143, v101, v103, vcc row_shl:4 row_mask:0xf bank_mask:0xf bound_ctrl:1
	v_mfma_scale_f32_16x16x128_f8f6f4 v[216:219], v[136:139], v[144:151], v[216:219], v240, v241 op_sel_hi:[0,0,0] cbsz:4
	v_permlane16_swap_b32_e32 v212, v214
	v_permlane16_swap_b32_e32 v213, v215
	v_lshlrev_b32_e32 v252, 16, v228
	v_and_b32_e32 v144, v180, v235
	v_and_b32_e32 v145, v180, v236
	v_and_b32_e32 v146, v180, v237
	v_and_b32_e32 v147, v180, v238
	v_and_b32_e32 v148, v181, v235
	v_and_b32_e32 v149, v181, v236
	v_and_b32_e32 v150, v181, v237
	v_and_b32_e32 v151, v181, v238
	s_mov_b64 vcc, s[4:5]
	v_cndmask_b32_dpp v138, v104, v106, vcc row_shl:4 row_mask:0xf bank_mask:0xf bound_ctrl:1
	v_cndmask_b32_dpp v139, v105, v107, vcc row_shl:4 row_mask:0xf bank_mask:0xf bound_ctrl:1
	s_mov_b64 vcc, s[6:7]
	v_cndmask_b32_dpp v136, v106, v104, vcc row_shr:4 row_mask:0xf bank_mask:0xf bound_ctrl:1
	v_cndmask_b32_dpp v137, v107, v105, vcc row_shr:4 row_mask:0xf bank_mask:0xf bound_ctrl:1
	v_mfma_scale_f32_16x16x128_f8f6f4 v[216:219], v[140:143], v[204:211], v[216:219], v240, v241 op_sel_hi:[0,0,0] cbsz:4
	v_and_b32_e32 v253, 0xffff0000, v228
	v_lshlrev_b32_e32 v254, 16, v229
	v_and_b32_e32 v255, 0xffff0000, v229
	v_and_b32_e32 v204, v182, v235
	v_and_b32_e32 v205, v182, v236
	v_and_b32_e32 v206, v182, v237
	v_and_b32_e32 v207, v182, v238
	v_and_b32_e32 v208, v183, v235
	v_and_b32_e32 v209, v183, v236
	v_and_b32_e32 v210, v183, v237
	v_and_b32_e32 v211, v183, v238
	s_mov_b64 vcc, s[6:7]
	v_cndmask_b32_dpp v140, v110, v108, vcc row_shr:4 row_mask:0xf bank_mask:0xf bound_ctrl:1
	v_cndmask_b32_dpp v141, v111, v109, vcc row_shr:4 row_mask:0xf bank_mask:0xf bound_ctrl:1
	s_mov_b64 vcc, s[4:5]
	v_cndmask_b32_dpp v142, v108, v110, vcc row_shl:4 row_mask:0xf bank_mask:0xf bound_ctrl:1
	v_cndmask_b32_dpp v143, v109, v111, vcc row_shl:4 row_mask:0xf bank_mask:0xf bound_ctrl:1
	v_mfma_scale_f32_16x16x128_f8f6f4 v[216:219], v[136:139], v[144:151], v[216:219], v240, v241 op_sel_hi:[0,0,0] cbsz:4
	v_add_f32_e32 v252, v212, v252
	v_add_f32_e32 v253, v214, v253
	v_add_f32_e32 v254, v213, v254
	v_and_b32_e32 v144, v184, v235
	v_and_b32_e32 v145, v184, v236
	v_and_b32_e32 v146, v184, v237
	v_and_b32_e32 v147, v184, v238
	v_and_b32_e32 v148, v185, v235
	v_and_b32_e32 v149, v185, v236
	v_and_b32_e32 v150, v185, v237
	v_and_b32_e32 v151, v185, v238
	s_mov_b64 vcc, s[4:5]
	v_cndmask_b32_dpp v138, v112, v114, vcc row_shl:4 row_mask:0xf bank_mask:0xf bound_ctrl:1
	v_cndmask_b32_dpp v139, v113, v115, vcc row_shl:4 row_mask:0xf bank_mask:0xf bound_ctrl:1
	s_mov_b64 vcc, s[6:7]
	v_cndmask_b32_dpp v136, v114, v112, vcc row_shr:4 row_mask:0xf bank_mask:0xf bound_ctrl:1
	v_cndmask_b32_dpp v137, v115, v113, vcc row_shr:4 row_mask:0xf bank_mask:0xf bound_ctrl:1
	v_mfma_scale_f32_16x16x128_f8f6f4 v[216:219], v[140:143], v[204:211], v[216:219], v240, v241 op_sel_hi:[0,0,0] cbsz:4
	v_add_f32_e32 v255, v215, v255
	v_mul_f32_e32 v192, v252, v252
	v_mul_f32_e32 v193, v254, v254
	v_and_b32_e32 v204, v186, v235
	v_and_b32_e32 v205, v186, v236
	v_and_b32_e32 v206, v186, v237
	v_and_b32_e32 v207, v186, v238
	v_and_b32_e32 v208, v187, v235
	v_and_b32_e32 v209, v187, v236
	v_and_b32_e32 v210, v187, v237
	v_and_b32_e32 v211, v187, v238
	s_mov_b64 vcc, s[6:7]
	v_cndmask_b32_dpp v140, v118, v116, vcc row_shr:4 row_mask:0xf bank_mask:0xf bound_ctrl:1
	v_cndmask_b32_dpp v141, v119, v117, vcc row_shr:4 row_mask:0xf bank_mask:0xf bound_ctrl:1
	s_mov_b64 vcc, s[4:5]
	v_cndmask_b32_dpp v142, v116, v118, vcc row_shl:4 row_mask:0xf bank_mask:0xf bound_ctrl:1
	v_cndmask_b32_dpp v143, v117, v119, vcc row_shl:4 row_mask:0xf bank_mask:0xf bound_ctrl:1
	v_mfma_scale_f32_16x16x128_f8f6f4 v[216:219], v[136:139], v[144:151], v[216:219], v240, v241 op_sel_hi:[0,0,0] cbsz:4
	v_fmac_f32_e32 v192, v253, v253
	v_fmac_f32_e32 v193, v255, v255
	v_cvt_pk_bf16_f32 v250, v252, v253
	v_and_b32_e32 v144, v188, v235
	v_and_b32_e32 v145, v188, v236
	v_and_b32_e32 v146, v188, v237
	v_and_b32_e32 v147, v188, v238
	v_and_b32_e32 v148, v189, v235
	v_and_b32_e32 v149, v189, v236
	v_and_b32_e32 v150, v189, v237
	v_and_b32_e32 v151, v189, v238
	s_mov_b64 vcc, s[4:5]
	v_cndmask_b32_dpp v138, v120, v122, vcc row_shl:4 row_mask:0xf bank_mask:0xf bound_ctrl:1
	v_cndmask_b32_dpp v139, v121, v123, vcc row_shl:4 row_mask:0xf bank_mask:0xf bound_ctrl:1
	s_mov_b64 vcc, s[6:7]
	v_cndmask_b32_dpp v136, v122, v120, vcc row_shr:4 row_mask:0xf bank_mask:0xf bound_ctrl:1
	v_cndmask_b32_dpp v137, v123, v121, vcc row_shr:4 row_mask:0xf bank_mask:0xf bound_ctrl:1
	v_mfma_scale_f32_16x16x128_f8f6f4 v[216:219], v[140:143], v[204:211], v[216:219], v240, v241 op_sel_hi:[0,0,0] cbsz:4
	v_cvt_pk_bf16_f32 v251, v254, v255
	v_add_f32_e32 v192, v192, v193
	v_add_f32_e32 v224, v224, v192
	v_and_b32_e32 v204, v190, v235
	v_and_b32_e32 v205, v190, v236
	v_and_b32_e32 v206, v190, v237
	v_and_b32_e32 v207, v190, v238
	v_and_b32_e32 v208, v191, v235
	v_and_b32_e32 v209, v191, v236
	v_and_b32_e32 v210, v191, v237
	v_and_b32_e32 v211, v191, v238
	s_mov_b64 vcc, s[6:7]
	v_cndmask_b32_dpp v140, v126, v124, vcc row_shr:4 row_mask:0xf bank_mask:0xf bound_ctrl:1
	v_cndmask_b32_dpp v141, v127, v125, vcc row_shr:4 row_mask:0xf bank_mask:0xf bound_ctrl:1
	s_mov_b64 vcc, s[4:5]
	v_cndmask_b32_dpp v142, v124, v126, vcc row_shl:4 row_mask:0xf bank_mask:0xf bound_ctrl:1
	v_cndmask_b32_dpp v143, v125, v127, vcc row_shl:4 row_mask:0xf bank_mask:0xf bound_ctrl:1
	v_mfma_scale_f32_16x16x128_f8f6f4 v[216:219], v[136:139], v[144:151], v[216:219], v240, v241 op_sel_hi:[0,0,0] cbsz:4
	s_nop 0
	v_mfma_scale_f32_16x16x128_f8f6f4 v[216:219], v[140:143], v[204:211], v[216:219], v240, v241 op_sel_hi:[0,0,0] cbsz:4
	s_lshl_b32 s64, s0, 9
	s_add_u32 s64, s64, 0x4000
	s_add_u32 s76, s28, s64
	s_addc_u32 s77, s29, 0
	global_store_dwordx2 v239, v[250:251], s[76:77]
	s_lshl_b32 s64, s0, 9
	s_add_u32 s64, s64, 0x6000
	s_add_u32 s70, s28, s64
	s_addc_u32 s71, s29, 0
	global_load_dwordx2 v[228:229], v239, s[70:71]
	s_waitcnt lgkmcnt(0)
	v_lshl_or_b32 v128, v128, 7, v232
	v_lshl_or_b32 v129, v129, 7, v232
	v_lshl_or_b32 v130, v130, 7, v232
	v_lshl_or_b32 v131, v131, 7, v232
	v_lshl_or_b32 v132, v132, 7, v232
	v_lshl_or_b32 v133, v133, 7, v232
	v_lshl_or_b32 v134, v134, 7, v232
	v_lshl_or_b32 v135, v135, 7, v232
	buffer_load_dwordx4 v[96:99], v128, s[20:23], s1 offen
	buffer_load_dwordx4 v[100:103], v129, s[20:23], s1 offen
	buffer_load_dwordx4 v[104:107], v130, s[20:23], s1 offen
	buffer_load_dwordx4 v[108:111], v131, s[20:23], s1 offen
	buffer_load_dwordx4 v[112:115], v132, s[20:23], s1 offen
	buffer_load_dwordx4 v[116:119], v133, s[20:23], s1 offen
	buffer_load_dwordx4 v[120:123], v134, s[20:23], s1 offen
	buffer_load_dwordx4 v[124:127], v135, s[20:23], s1 offen
	ds_read_b32 v128, v243 offset:0
	ds_read_b32 v129, v243 offset:32
	ds_read_b32 v130, v243 offset:64
	ds_read_b32 v131, v243 offset:96
	ds_read_b32 v132, v243 offset:128
	ds_read_b32 v133, v243 offset:160
	ds_read_b32 v134, v243 offset:192
	ds_read_b32 v135, v243 offset:224
	ds_read_b64 v[176:177], v234 offset:3328
	ds_read_b64 v[178:179], v234 offset:3360
	ds_read_b64 v[180:181], v234 offset:3392
	ds_read_b64 v[182:183], v234 offset:3424
	ds_read_b64 v[184:185], v234 offset:3456
	ds_read_b64 v[186:187], v234 offset:3488
	ds_read_b64 v[188:189], v234 offset:3520
	ds_read_b64 v[190:191], v234 offset:3552
	s_waitcnt vmcnt(28)
	v_and_b32_e32 v144, v160, v235
	v_and_b32_e32 v145, v160, v236
	v_and_b32_e32 v146, v160, v237
	v_and_b32_e32 v147, v160, v238
	v_and_b32_e32 v148, v161, v235
	v_and_b32_e32 v149, v161, v236
	v_and_b32_e32 v150, v161, v237
	v_and_b32_e32 v151, v161, v238
	s_mov_b64 vcc, s[4:5]
	v_cndmask_b32_dpp v138, v0, v2, vcc row_shl:4 row_mask:0xf bank_mask:0xf bound_ctrl:1
	v_cndmask_b32_dpp v139, v1, v3, vcc row_shl:4 row_mask:0xf bank_mask:0xf bound_ctrl:1
	s_mov_b64 vcc, s[6:7]
	v_cndmask_b32_dpp v136, v2, v0, vcc row_shr:4 row_mask:0xf bank_mask:0xf bound_ctrl:1
	v_cndmask_b32_dpp v137, v3, v1, vcc row_shr:4 row_mask:0xf bank_mask:0xf bound_ctrl:1
	v_and_b32_e32 v204, v162, v235
	v_and_b32_e32 v205, v162, v236
	v_and_b32_e32 v206, v162, v237
	v_and_b32_e32 v207, v162, v238
	v_and_b32_e32 v208, v163, v235
	v_and_b32_e32 v209, v163, v236
	v_and_b32_e32 v210, v163, v237
	v_and_b32_e32 v211, v163, v238
	s_mov_b64 vcc, s[6:7]
	v_cndmask_b32_dpp v140, v6, v4, vcc row_shr:4 row_mask:0xf bank_mask:0xf bound_ctrl:1
	v_cndmask_b32_dpp v141, v7, v5, vcc row_shr:4 row_mask:0xf bank_mask:0xf bound_ctrl:1
	s_mov_b64 vcc, s[4:5]
	v_cndmask_b32_dpp v142, v4, v6, vcc row_shl:4 row_mask:0xf bank_mask:0xf bound_ctrl:1
	v_cndmask_b32_dpp v143, v5, v7, vcc row_shl:4 row_mask:0xf bank_mask:0xf bound_ctrl:1
	v_mfma_scale_f32_16x16x128_f8f6f4 v[212:215], v[136:139], v[144:151], 0, v240, v241 op_sel_hi:[0,0,0] cbsz:4
	v_and_b32_e32 v144, v164, v235
	v_and_b32_e32 v145, v164, v236
	v_and_b32_e32 v146, v164, v237
	v_and_b32_e32 v147, v164, v238
	v_and_b32_e32 v148, v165, v235
	v_and_b32_e32 v149, v165, v236
	v_and_b32_e32 v150, v165, v237
	v_and_b32_e32 v151, v165, v238
	s_mov_b64 vcc, s[4:5]
	v_cndmask_b32_dpp v138, v8, v10, vcc row_shl:4 row_mask:0xf bank_mask:0xf bound_ctrl:1
	v_cndmask_b32_dpp v139, v9, v11, vcc row_shl:4 row_mask:0xf bank_mask:0xf bound_ctrl:1
	s_mov_b64 vcc, s[6:7]
	v_cndmask_b32_dpp v136, v10, v8, vcc row_shr:4 row_mask:0xf bank_mask:0xf bound_ctrl:1
	v_cndmask_b32_dpp v137, v11, v9, vcc row_shr:4 row_mask:0xf bank_mask:0xf bound_ctrl:1
	v_mfma_scale_f32_16x16x128_f8f6f4 v[212:215], v[140:143], v[204:211], v[212:215], v240, v241 op_sel_hi:[0,0,0] cbsz:4
	v_and_b32_e32 v204, v166, v235
	v_and_b32_e32 v205, v166, v236
	v_and_b32_e32 v206, v166, v237
	v_and_b32_e32 v207, v166, v238
	v_and_b32_e32 v208, v167, v235
	v_and_b32_e32 v209, v167, v236
	v_and_b32_e32 v210, v167, v237
	v_and_b32_e32 v211, v167, v238
	s_mov_b64 vcc, s[6:7]
	v_cndmask_b32_dpp v140, v14, v12, vcc row_shr:4 row_mask:0xf bank_mask:0xf bound_ctrl:1
	v_cndmask_b32_dpp v141, v15, v13, vcc row_shr:4 row_mask:0xf bank_mask:0xf bound_ctrl:1
	s_mov_b64 vcc, s[4:5]
	v_cndmask_b32_dpp v142, v12, v14, vcc row_shl:4 row_mask:0xf bank_mask:0xf bound_ctrl:1
	v_cndmask_b32_dpp v143, v13, v15, vcc row_shl:4 row_mask:0xf bank_mask:0xf bound_ctrl:1
	v_mfma_scale_f32_16x16x128_f8f6f4 v[212:215], v[136:139], v[144:151], v[212:215], v240, v241 op_sel_hi:[0,0,0] cbsz:4
	v_and_b32_e32 v144, v168, v235
	v_and_b32_e32 v145, v168, v236
	v_and_b32_e32 v146, v168, v237
	v_and_b32_e32 v147, v168, v238
	v_and_b32_e32 v148, v169, v235
	v_and_b32_e32 v149, v169, v236
	v_and_b32_e32 v150, v169, v237
	v_and_b32_e32 v151, v169, v238
	s_mov_b64 vcc, s[4:5]
	v_cndmask_b32_dpp v138, v16, v18, vcc row_shl:4 row_mask:0xf bank_mask:0xf bound_ctrl:1
	v_cndmask_b32_dpp v139, v17, v19, vcc row_shl:4 row_mask:0xf bank_mask:0xf bound_ctrl:1
	s_mov_b64 vcc, s[6:7]
	v_cndmask_b32_dpp v136, v18, v16, vcc row_shr:4 row_mask:0xf bank_mask:0xf bound_ctrl:1
	v_cndmask_b32_dpp v137, v19, v17, vcc row_shr:4 row_mask:0xf bank_mask:0xf bound_ctrl:1
	v_mfma_scale_f32_16x16x128_f8f6f4 v[212:215], v[140:143], v[204:211], v[212:215], v240, v241 op_sel_hi:[0,0,0] cbsz:4
	v_and_b32_e32 v204, v170, v235
	v_and_b32_e32 v205, v170, v236
	v_and_b32_e32 v206, v170, v237
	v_and_b32_e32 v207, v170, v238
	v_and_b32_e32 v208, v171, v235
	v_and_b32_e32 v209, v171, v236
	v_and_b32_e32 v210, v171, v237
	v_and_b32_e32 v211, v171, v238
	s_mov_b64 vcc, s[6:7]
	v_cndmask_b32_dpp v140, v22, v20, vcc row_shr:4 row_mask:0xf bank_mask:0xf bound_ctrl:1
	v_cndmask_b32_dpp v141, v23, v21, vcc row_shr:4 row_mask:0xf bank_mask:0xf bound_ctrl:1
	s_mov_b64 vcc, s[4:5]
	v_cndmask_b32_dpp v142, v20, v22, vcc row_shl:4 row_mask:0xf bank_mask:0xf bound_ctrl:1
	v_cndmask_b32_dpp v143, v21, v23, vcc row_shl:4 row_mask:0xf bank_mask:0xf bound_ctrl:1
	v_mfma_scale_f32_16x16x128_f8f6f4 v[212:215], v[136:139], v[144:151], v[212:215], v240, v241 op_sel_hi:[0,0,0] cbsz:4
	v_and_b32_e32 v144, v172, v235
	v_and_b32_e32 v145, v172, v236
	v_and_b32_e32 v146, v172, v237
	v_and_b32_e32 v147, v172, v238
	v_and_b32_e32 v148, v173, v235
	v_and_b32_e32 v149, v173, v236
	v_and_b32_e32 v150, v173, v237
	v_and_b32_e32 v151, v173, v238
	s_mov_b64 vcc, s[4:5]
	v_cndmask_b32_dpp v138, v24, v26, vcc row_shl:4 row_mask:0xf bank_mask:0xf bound_ctrl:1
	v_cndmask_b32_dpp v139, v25, v27, vcc row_shl:4 row_mask:0xf bank_mask:0xf bound_ctrl:1
	s_mov_b64 vcc, s[6:7]
	v_cndmask_b32_dpp v136, v26, v24, vcc row_shr:4 row_mask:0xf bank_mask:0xf bound_ctrl:1
	v_cndmask_b32_dpp v137, v27, v25, vcc row_shr:4 row_mask:0xf bank_mask:0xf bound_ctrl:1
	v_mfma_scale_f32_16x16x128_f8f6f4 v[212:215], v[140:143], v[204:211], v[212:215], v240, v241 op_sel_hi:[0,0,0] cbsz:4
	v_and_b32_e32 v204, v174, v235
	v_and_b32_e32 v205, v174, v236
	v_and_b32_e32 v206, v174, v237
	v_and_b32_e32 v207, v174, v238
	v_and_b32_e32 v208, v175, v235
	v_and_b32_e32 v209, v175, v236
	v_and_b32_e32 v210, v175, v237
	v_and_b32_e32 v211, v175, v238
	s_mov_b64 vcc, s[6:7]
	v_cndmask_b32_dpp v140, v30, v28, vcc row_shr:4 row_mask:0xf bank_mask:0xf bound_ctrl:1
	v_cndmask_b32_dpp v141, v31, v29, vcc row_shr:4 row_mask:0xf bank_mask:0xf bound_ctrl:1
	s_mov_b64 vcc, s[4:5]
	v_cndmask_b32_dpp v142, v28, v30, vcc row_shl:4 row_mask:0xf bank_mask:0xf bound_ctrl:1
	v_cndmask_b32_dpp v143, v29, v31, vcc row_shl:4 row_mask:0xf bank_mask:0xf bound_ctrl:1
	v_mfma_scale_f32_16x16x128_f8f6f4 v[212:215], v[136:139], v[144:151], v[212:215], v240, v241 op_sel_hi:[0,0,0] cbsz:4
	s_nop 0
	v_mfma_scale_f32_16x16x128_f8f6f4 v[212:215], v[140:143], v[204:211], v[212:215], v240, v241 op_sel_hi:[0,0,0] cbsz:4
	s_waitcnt lgkmcnt(0)
	v_lshl_or_b32 v128, v128, 7, v232
	v_lshl_or_b32 v129, v129, 7, v232
	v_lshl_or_b32 v130, v130, 7, v232
	v_lshl_or_b32 v131, v131, 7, v232
	v_lshl_or_b32 v132, v132, 7, v232
	v_lshl_or_b32 v133, v133, 7, v232
	v_lshl_or_b32 v134, v134, 7, v232
	v_lshl_or_b32 v135, v135, 7, v232
	buffer_load_dwordx4 v[0:3], v128, s[20:23], s60 offen
	buffer_load_dwordx4 v[4:7], v129, s[20:23], s60 offen
	buffer_load_dwordx4 v[8:11], v130, s[20:23], s60 offen
	buffer_load_dwordx4 v[12:15], v131, s[20:23], s60 offen
	buffer_load_dwordx4 v[16:19], v132, s[20:23], s60 offen
	buffer_load_dwordx4 v[20:23], v133, s[20:23], s60 offen
	buffer_load_dwordx4 v[24:27], v134, s[20:23], s60 offen
	buffer_load_dwordx4 v[28:31], v135, s[20:23], s60 offen
	ds_read_b32 v128, v243 offset:256
	ds_read_b32 v129, v243 offset:288
	ds_read_b32 v130, v243 offset:320
	ds_read_b32 v131, v243 offset:352
	ds_read_b32 v132, v243 offset:384
	ds_read_b32 v133, v243 offset:416
	ds_read_b32 v134, v243 offset:448
	ds_read_b32 v135, v243 offset:480
	ds_read_b64 v[160:161], v234 offset:3584
	ds_read_b64 v[162:163], v234 offset:3616
	ds_read_b64 v[164:165], v234 offset:3648
	ds_read_b64 v[166:167], v234 offset:3680
	ds_read_b64 v[168:169], v234 offset:3712
	ds_read_b64 v[170:171], v234 offset:3744
	ds_read_b64 v[172:173], v234 offset:3776
	ds_read_b64 v[174:175], v234 offset:3808
	s_waitcnt vmcnt(26)
	v_and_b32_e32 v144, v176, v235
	v_and_b32_e32 v145, v176, v236
	v_and_b32_e32 v146, v176, v237
	v_and_b32_e32 v147, v176, v238
	v_and_b32_e32 v148, v177, v235
	v_and_b32_e32 v149, v177, v236
	v_and_b32_e32 v150, v177, v237
	v_and_b32_e32 v151, v177, v238
	s_mov_b64 vcc, s[4:5]
	v_cndmask_b32_dpp v138, v32, v34, vcc row_shl:4 row_mask:0xf bank_mask:0xf bound_ctrl:1
	v_cndmask_b32_dpp v139, v33, v35, vcc row_shl:4 row_mask:0xf bank_mask:0xf bound_ctrl:1
	s_mov_b64 vcc, s[6:7]
	v_cndmask_b32_dpp v136, v34, v32, vcc row_shr:4 row_mask:0xf bank_mask:0xf bound_ctrl:1
	v_cndmask_b32_dpp v137, v35, v33, vcc row_shr:4 row_mask:0xf bank_mask:0xf bound_ctrl:1
	v_and_b32_e32 v204, v178, v235
	v_and_b32_e32 v205, v178, v236
	v_and_b32_e32 v206, v178, v237
	v_and_b32_e32 v207, v178, v238
	v_and_b32_e32 v208, v179, v235
	v_and_b32_e32 v209, v179, v236
	v_and_b32_e32 v210, v179, v237
	v_and_b32_e32 v211, v179, v238
	s_mov_b64 vcc, s[6:7]
	v_cndmask_b32_dpp v140, v38, v36, vcc row_shr:4 row_mask:0xf bank_mask:0xf bound_ctrl:1
	v_cndmask_b32_dpp v141, v39, v37, vcc row_shr:4 row_mask:0xf bank_mask:0xf bound_ctrl:1
	s_mov_b64 vcc, s[4:5]
	v_cndmask_b32_dpp v142, v36, v38, vcc row_shl:4 row_mask:0xf bank_mask:0xf bound_ctrl:1
	v_cndmask_b32_dpp v143, v37, v39, vcc row_shl:4 row_mask:0xf bank_mask:0xf bound_ctrl:1
	v_mfma_scale_f32_16x16x128_f8f6f4 v[212:215], v[136:139], v[144:151], v[212:215], v240, v241 op_sel_hi:[0,0,0] cbsz:4
	v_permlane16_swap_b32_e32 v216, v218
	v_permlane16_swap_b32_e32 v217, v219
	v_lshlrev_b32_e32 v252, 16, v230
	v_and_b32_e32 v144, v180, v235
	v_and_b32_e32 v145, v180, v236
	v_and_b32_e32 v146, v180, v237
	v_and_b32_e32 v147, v180, v238
	v_and_b32_e32 v148, v181, v235
	v_and_b32_e32 v149, v181, v236
	v_and_b32_e32 v150, v181, v237
	v_and_b32_e32 v151, v181, v238
	s_mov_b64 vcc, s[4:5]
	v_cndmask_b32_dpp v138, v40, v42, vcc row_shl:4 row_mask:0xf bank_mask:0xf bound_ctrl:1
	v_cndmask_b32_dpp v139, v41, v43, vcc row_shl:4 row_mask:0xf bank_mask:0xf bound_ctrl:1
	s_mov_b64 vcc, s[6:7]
	v_cndmask_b32_dpp v136, v42, v40, vcc row_shr:4 row_mask:0xf bank_mask:0xf bound_ctrl:1
	v_cndmask_b32_dpp v137, v43, v41, vcc row_shr:4 row_mask:0xf bank_mask:0xf bound_ctrl:1
	v_mfma_scale_f32_16x16x128_f8f6f4 v[212:215], v[140:143], v[204:211], v[212:215], v240, v241 op_sel_hi:[0,0,0] cbsz:4
	v_and_b32_e32 v253, 0xffff0000, v230
	v_lshlrev_b32_e32 v254, 16, v231
	v_and_b32_e32 v255, 0xffff0000, v231
	v_and_b32_e32 v204, v182, v235
	v_and_b32_e32 v205, v182, v236
	v_and_b32_e32 v206, v182, v237
	v_and_b32_e32 v207, v182, v238
	v_and_b32_e32 v208, v183, v235
	v_and_b32_e32 v209, v183, v236
	v_and_b32_e32 v210, v183, v237
	v_and_b32_e32 v211, v183, v238
	s_mov_b64 vcc, s[6:7]
	v_cndmask_b32_dpp v140, v46, v44, vcc row_shr:4 row_mask:0xf bank_mask:0xf bound_ctrl:1
	v_cndmask_b32_dpp v141, v47, v45, vcc row_shr:4 row_mask:0xf bank_mask:0xf bound_ctrl:1
	s_mov_b64 vcc, s[4:5]
	v_cndmask_b32_dpp v142, v44, v46, vcc row_shl:4 row_mask:0xf bank_mask:0xf bound_ctrl:1
	v_cndmask_b32_dpp v143, v45, v47, vcc row_shl:4 row_mask:0xf bank_mask:0xf bound_ctrl:1
	v_mfma_scale_f32_16x16x128_f8f6f4 v[212:215], v[136:139], v[144:151], v[212:215], v240, v241 op_sel_hi:[0,0,0] cbsz:4
	v_add_f32_e32 v252, v216, v252
	v_add_f32_e32 v253, v218, v253
	v_add_f32_e32 v254, v217, v254
	v_and_b32_e32 v144, v184, v235
	v_and_b32_e32 v145, v184, v236
	v_and_b32_e32 v146, v184, v237
	v_and_b32_e32 v147, v184, v238
	v_and_b32_e32 v148, v185, v235
	v_and_b32_e32 v149, v185, v236
	v_and_b32_e32 v150, v185, v237
	v_and_b32_e32 v151, v185, v238
	s_mov_b64 vcc, s[4:5]
	v_cndmask_b32_dpp v138, v48, v50, vcc row_shl:4 row_mask:0xf bank_mask:0xf bound_ctrl:1
	v_cndmask_b32_dpp v139, v49, v51, vcc row_shl:4 row_mask:0xf bank_mask:0xf bound_ctrl:1
	s_mov_b64 vcc, s[6:7]
	v_cndmask_b32_dpp v136, v50, v48, vcc row_shr:4 row_mask:0xf bank_mask:0xf bound_ctrl:1
	v_cndmask_b32_dpp v137, v51, v49, vcc row_shr:4 row_mask:0xf bank_mask:0xf bound_ctrl:1
	v_mfma_scale_f32_16x16x128_f8f6f4 v[212:215], v[140:143], v[204:211], v[212:215], v240, v241 op_sel_hi:[0,0,0] cbsz:4
	v_add_f32_e32 v255, v219, v255
	v_mul_f32_e32 v192, v252, v252
	v_mul_f32_e32 v193, v254, v254
	v_and_b32_e32 v204, v186, v235
	v_and_b32_e32 v205, v186, v236
	v_and_b32_e32 v206, v186, v237
	v_and_b32_e32 v207, v186, v238
	v_and_b32_e32 v208, v187, v235
	v_and_b32_e32 v209, v187, v236
	v_and_b32_e32 v210, v187, v237
	v_and_b32_e32 v211, v187, v238
	s_mov_b64 vcc, s[6:7]
	v_cndmask_b32_dpp v140, v54, v52, vcc row_shr:4 row_mask:0xf bank_mask:0xf bound_ctrl:1
	v_cndmask_b32_dpp v141, v55, v53, vcc row_shr:4 row_mask:0xf bank_mask:0xf bound_ctrl:1
	s_mov_b64 vcc, s[4:5]
	v_cndmask_b32_dpp v142, v52, v54, vcc row_shl:4 row_mask:0xf bank_mask:0xf bound_ctrl:1
	v_cndmask_b32_dpp v143, v53, v55, vcc row_shl:4 row_mask:0xf bank_mask:0xf bound_ctrl:1
	v_mfma_scale_f32_16x16x128_f8f6f4 v[212:215], v[136:139], v[144:151], v[212:215], v240, v241 op_sel_hi:[0,0,0] cbsz:4
	v_fmac_f32_e32 v192, v253, v253
	v_fmac_f32_e32 v193, v255, v255
	v_cvt_pk_bf16_f32 v250, v252, v253
	v_and_b32_e32 v144, v188, v235
	v_and_b32_e32 v145, v188, v236
	v_and_b32_e32 v146, v188, v237
	v_and_b32_e32 v147, v188, v238
	v_and_b32_e32 v148, v189, v235
	v_and_b32_e32 v149, v189, v236
	v_and_b32_e32 v150, v189, v237
	v_and_b32_e32 v151, v189, v238
	s_mov_b64 vcc, s[4:5]
	v_cndmask_b32_dpp v138, v56, v58, vcc row_shl:4 row_mask:0xf bank_mask:0xf bound_ctrl:1
	v_cndmask_b32_dpp v139, v57, v59, vcc row_shl:4 row_mask:0xf bank_mask:0xf bound_ctrl:1
	s_mov_b64 vcc, s[6:7]
	v_cndmask_b32_dpp v136, v58, v56, vcc row_shr:4 row_mask:0xf bank_mask:0xf bound_ctrl:1
	v_cndmask_b32_dpp v137, v59, v57, vcc row_shr:4 row_mask:0xf bank_mask:0xf bound_ctrl:1
	v_mfma_scale_f32_16x16x128_f8f6f4 v[212:215], v[140:143], v[204:211], v[212:215], v240, v241 op_sel_hi:[0,0,0] cbsz:4
	v_cvt_pk_bf16_f32 v251, v254, v255
	v_add_f32_e32 v192, v192, v193
	v_add_f32_e32 v225, v225, v192
	v_and_b32_e32 v204, v190, v235
	v_and_b32_e32 v205, v190, v236
	v_and_b32_e32 v206, v190, v237
	v_and_b32_e32 v207, v190, v238
	v_and_b32_e32 v208, v191, v235
	v_and_b32_e32 v209, v191, v236
	v_and_b32_e32 v210, v191, v237
	v_and_b32_e32 v211, v191, v238
	s_mov_b64 vcc, s[6:7]
	v_cndmask_b32_dpp v140, v62, v60, vcc row_shr:4 row_mask:0xf bank_mask:0xf bound_ctrl:1
	v_cndmask_b32_dpp v141, v63, v61, vcc row_shr:4 row_mask:0xf bank_mask:0xf bound_ctrl:1
	s_mov_b64 vcc, s[4:5]
	v_cndmask_b32_dpp v142, v60, v62, vcc row_shl:4 row_mask:0xf bank_mask:0xf bound_ctrl:1
	v_cndmask_b32_dpp v143, v61, v63, vcc row_shl:4 row_mask:0xf bank_mask:0xf bound_ctrl:1
	v_mfma_scale_f32_16x16x128_f8f6f4 v[212:215], v[136:139], v[144:151], v[212:215], v240, v241 op_sel_hi:[0,0,0] cbsz:4
	s_nop 0
	v_mfma_scale_f32_16x16x128_f8f6f4 v[212:215], v[140:143], v[204:211], v[212:215], v240, v241 op_sel_hi:[0,0,0] cbsz:4
	s_lshl_b32 s64, s0, 9
	s_add_u32 s64, s64, 0x5000
	s_add_u32 s76, s28, s64
	s_addc_u32 s77, s29, 0
	global_store_dwordx2 v239, v[250:251], s[76:77]
	s_lshl_b32 s64, s0, 9
	s_add_u32 s64, s64, 0x7000
	s_add_u32 s70, s28, s64
	s_addc_u32 s71, s29, 0
	global_load_dwordx2 v[230:231], v239, s[70:71]
	s_waitcnt lgkmcnt(0)
	v_lshl_or_b32 v128, v128, 7, v232
	v_lshl_or_b32 v129, v129, 7, v232
	v_lshl_or_b32 v130, v130, 7, v232
	v_lshl_or_b32 v131, v131, 7, v232
	v_lshl_or_b32 v132, v132, 7, v232
	v_lshl_or_b32 v133, v133, 7, v232
	v_lshl_or_b32 v134, v134, 7, v232
	v_lshl_or_b32 v135, v135, 7, v232
	buffer_load_dwordx4 v[32:35], v128, s[20:23], s60 offen
	buffer_load_dwordx4 v[36:39], v129, s[20:23], s60 offen
	buffer_load_dwordx4 v[40:43], v130, s[20:23], s60 offen
	buffer_load_dwordx4 v[44:47], v131, s[20:23], s60 offen
	buffer_load_dwordx4 v[48:51], v132, s[20:23], s60 offen
	buffer_load_dwordx4 v[52:55], v133, s[20:23], s60 offen
	buffer_load_dwordx4 v[56:59], v134, s[20:23], s60 offen
	buffer_load_dwordx4 v[60:63], v135, s[20:23], s60 offen
	ds_read_b32 v128, v243 offset:512
	ds_read_b32 v129, v243 offset:544
	ds_read_b32 v130, v243 offset:576
	ds_read_b32 v131, v243 offset:608
	ds_read_b32 v132, v243 offset:640
	ds_read_b32 v133, v243 offset:672
	ds_read_b32 v134, v243 offset:704
	ds_read_b32 v135, v243 offset:736
	ds_read_b64 v[176:177], v234 offset:3840
	ds_read_b64 v[178:179], v234 offset:3872
	ds_read_b64 v[180:181], v234 offset:3904
	ds_read_b64 v[182:183], v234 offset:3936
	ds_read_b64 v[184:185], v234 offset:3968
	ds_read_b64 v[186:187], v234 offset:4000
	ds_read_b64 v[188:189], v234 offset:4032
	ds_read_b64 v[190:191], v234 offset:4064
	s_waitcnt vmcnt(28)
	v_and_b32_e32 v144, v160, v235
	v_and_b32_e32 v145, v160, v236
	v_and_b32_e32 v146, v160, v237
	v_and_b32_e32 v147, v160, v238
	v_and_b32_e32 v148, v161, v235
	v_and_b32_e32 v149, v161, v236
	v_and_b32_e32 v150, v161, v237
	v_and_b32_e32 v151, v161, v238
	s_mov_b64 vcc, s[4:5]
	v_cndmask_b32_dpp v138, v64, v66, vcc row_shl:4 row_mask:0xf bank_mask:0xf bound_ctrl:1
	v_cndmask_b32_dpp v139, v65, v67, vcc row_shl:4 row_mask:0xf bank_mask:0xf bound_ctrl:1
	s_mov_b64 vcc, s[6:7]
	v_cndmask_b32_dpp v136, v66, v64, vcc row_shr:4 row_mask:0xf bank_mask:0xf bound_ctrl:1
	v_cndmask_b32_dpp v137, v67, v65, vcc row_shr:4 row_mask:0xf bank_mask:0xf bound_ctrl:1
	v_and_b32_e32 v204, v162, v235
	v_and_b32_e32 v205, v162, v236
	v_and_b32_e32 v206, v162, v237
	v_and_b32_e32 v207, v162, v238
	v_and_b32_e32 v208, v163, v235
	v_and_b32_e32 v209, v163, v236
	v_and_b32_e32 v210, v163, v237
	v_and_b32_e32 v211, v163, v238
	s_mov_b64 vcc, s[6:7]
	v_cndmask_b32_dpp v140, v70, v68, vcc row_shr:4 row_mask:0xf bank_mask:0xf bound_ctrl:1
	v_cndmask_b32_dpp v141, v71, v69, vcc row_shr:4 row_mask:0xf bank_mask:0xf bound_ctrl:1
	s_mov_b64 vcc, s[4:5]
	v_cndmask_b32_dpp v142, v68, v70, vcc row_shl:4 row_mask:0xf bank_mask:0xf bound_ctrl:1
	v_cndmask_b32_dpp v143, v69, v71, vcc row_shl:4 row_mask:0xf bank_mask:0xf bound_ctrl:1
	v_mfma_scale_f32_16x16x128_f8f6f4 v[216:219], v[136:139], v[144:151], 0, v240, v241 op_sel_hi:[0,0,0] cbsz:4
	v_and_b32_e32 v144, v164, v235
	v_and_b32_e32 v145, v164, v236
	v_and_b32_e32 v146, v164, v237
	v_and_b32_e32 v147, v164, v238
	v_and_b32_e32 v148, v165, v235
	v_and_b32_e32 v149, v165, v236
	v_and_b32_e32 v150, v165, v237
	v_and_b32_e32 v151, v165, v238
	s_mov_b64 vcc, s[4:5]
	v_cndmask_b32_dpp v138, v72, v74, vcc row_shl:4 row_mask:0xf bank_mask:0xf bound_ctrl:1
	v_cndmask_b32_dpp v139, v73, v75, vcc row_shl:4 row_mask:0xf bank_mask:0xf bound_ctrl:1
	s_mov_b64 vcc, s[6:7]
	v_cndmask_b32_dpp v136, v74, v72, vcc row_shr:4 row_mask:0xf bank_mask:0xf bound_ctrl:1
	v_cndmask_b32_dpp v137, v75, v73, vcc row_shr:4 row_mask:0xf bank_mask:0xf bound_ctrl:1
	v_mfma_scale_f32_16x16x128_f8f6f4 v[216:219], v[140:143], v[204:211], v[216:219], v240, v241 op_sel_hi:[0,0,0] cbsz:4
	v_and_b32_e32 v204, v166, v235
	v_and_b32_e32 v205, v166, v236
	v_and_b32_e32 v206, v166, v237
	v_and_b32_e32 v207, v166, v238
	v_and_b32_e32 v208, v167, v235
	v_and_b32_e32 v209, v167, v236
	v_and_b32_e32 v210, v167, v237
	v_and_b32_e32 v211, v167, v238
	s_mov_b64 vcc, s[6:7]
	v_cndmask_b32_dpp v140, v78, v76, vcc row_shr:4 row_mask:0xf bank_mask:0xf bound_ctrl:1
	v_cndmask_b32_dpp v141, v79, v77, vcc row_shr:4 row_mask:0xf bank_mask:0xf bound_ctrl:1
	s_mov_b64 vcc, s[4:5]
	v_cndmask_b32_dpp v142, v76, v78, vcc row_shl:4 row_mask:0xf bank_mask:0xf bound_ctrl:1
	v_cndmask_b32_dpp v143, v77, v79, vcc row_shl:4 row_mask:0xf bank_mask:0xf bound_ctrl:1
	v_mfma_scale_f32_16x16x128_f8f6f4 v[216:219], v[136:139], v[144:151], v[216:219], v240, v241 op_sel_hi:[0,0,0] cbsz:4
	v_and_b32_e32 v144, v168, v235
	v_and_b32_e32 v145, v168, v236
	v_and_b32_e32 v146, v168, v237
	v_and_b32_e32 v147, v168, v238
	v_and_b32_e32 v148, v169, v235
	v_and_b32_e32 v149, v169, v236
	v_and_b32_e32 v150, v169, v237
	v_and_b32_e32 v151, v169, v238
	s_mov_b64 vcc, s[4:5]
	v_cndmask_b32_dpp v138, v80, v82, vcc row_shl:4 row_mask:0xf bank_mask:0xf bound_ctrl:1
	v_cndmask_b32_dpp v139, v81, v83, vcc row_shl:4 row_mask:0xf bank_mask:0xf bound_ctrl:1
	s_mov_b64 vcc, s[6:7]
	v_cndmask_b32_dpp v136, v82, v80, vcc row_shr:4 row_mask:0xf bank_mask:0xf bound_ctrl:1
	v_cndmask_b32_dpp v137, v83, v81, vcc row_shr:4 row_mask:0xf bank_mask:0xf bound_ctrl:1
	v_mfma_scale_f32_16x16x128_f8f6f4 v[216:219], v[140:143], v[204:211], v[216:219], v240, v241 op_sel_hi:[0,0,0] cbsz:4
	v_and_b32_e32 v204, v170, v235
	v_and_b32_e32 v205, v170, v236
	v_and_b32_e32 v206, v170, v237
	v_and_b32_e32 v207, v170, v238
	v_and_b32_e32 v208, v171, v235
	v_and_b32_e32 v209, v171, v236
	v_and_b32_e32 v210, v171, v237
	v_and_b32_e32 v211, v171, v238
	s_mov_b64 vcc, s[6:7]
	v_cndmask_b32_dpp v140, v86, v84, vcc row_shr:4 row_mask:0xf bank_mask:0xf bound_ctrl:1
	v_cndmask_b32_dpp v141, v87, v85, vcc row_shr:4 row_mask:0xf bank_mask:0xf bound_ctrl:1
	s_mov_b64 vcc, s[4:5]
	v_cndmask_b32_dpp v142, v84, v86, vcc row_shl:4 row_mask:0xf bank_mask:0xf bound_ctrl:1
	v_cndmask_b32_dpp v143, v85, v87, vcc row_shl:4 row_mask:0xf bank_mask:0xf bound_ctrl:1
	v_mfma_scale_f32_16x16x128_f8f6f4 v[216:219], v[136:139], v[144:151], v[216:219], v240, v241 op_sel_hi:[0,0,0] cbsz:4
	v_and_b32_e32 v144, v172, v235
	v_and_b32_e32 v145, v172, v236
	v_and_b32_e32 v146, v172, v237
	v_and_b32_e32 v147, v172, v238
	v_and_b32_e32 v148, v173, v235
	v_and_b32_e32 v149, v173, v236
	v_and_b32_e32 v150, v173, v237
	v_and_b32_e32 v151, v173, v238
	s_mov_b64 vcc, s[4:5]
	v_cndmask_b32_dpp v138, v88, v90, vcc row_shl:4 row_mask:0xf bank_mask:0xf bound_ctrl:1
	v_cndmask_b32_dpp v139, v89, v91, vcc row_shl:4 row_mask:0xf bank_mask:0xf bound_ctrl:1
	s_mov_b64 vcc, s[6:7]
	v_cndmask_b32_dpp v136, v90, v88, vcc row_shr:4 row_mask:0xf bank_mask:0xf bound_ctrl:1
	v_cndmask_b32_dpp v137, v91, v89, vcc row_shr:4 row_mask:0xf bank_mask:0xf bound_ctrl:1
	v_mfma_scale_f32_16x16x128_f8f6f4 v[216:219], v[140:143], v[204:211], v[216:219], v240, v241 op_sel_hi:[0,0,0] cbsz:4
	v_and_b32_e32 v204, v174, v235
	v_and_b32_e32 v205, v174, v236
	v_and_b32_e32 v206, v174, v237
	v_and_b32_e32 v207, v174, v238
	v_and_b32_e32 v208, v175, v235
	v_and_b32_e32 v209, v175, v236
	v_and_b32_e32 v210, v175, v237
	v_and_b32_e32 v211, v175, v238
	s_mov_b64 vcc, s[6:7]
	v_cndmask_b32_dpp v140, v94, v92, vcc row_shr:4 row_mask:0xf bank_mask:0xf bound_ctrl:1
	v_cndmask_b32_dpp v141, v95, v93, vcc row_shr:4 row_mask:0xf bank_mask:0xf bound_ctrl:1
	s_mov_b64 vcc, s[4:5]
	v_cndmask_b32_dpp v142, v92, v94, vcc row_shl:4 row_mask:0xf bank_mask:0xf bound_ctrl:1
	v_cndmask_b32_dpp v143, v93, v95, vcc row_shl:4 row_mask:0xf bank_mask:0xf bound_ctrl:1
	v_mfma_scale_f32_16x16x128_f8f6f4 v[216:219], v[136:139], v[144:151], v[216:219], v240, v241 op_sel_hi:[0,0,0] cbsz:4
	s_nop 0
	v_mfma_scale_f32_16x16x128_f8f6f4 v[216:219], v[140:143], v[204:211], v[216:219], v240, v241 op_sel_hi:[0,0,0] cbsz:4
	s_waitcnt lgkmcnt(0)
	v_lshl_or_b32 v128, v128, 7, v232
	v_lshl_or_b32 v129, v129, 7, v232
	v_lshl_or_b32 v130, v130, 7, v232
	v_lshl_or_b32 v131, v131, 7, v232
	v_lshl_or_b32 v132, v132, 7, v232
	v_lshl_or_b32 v133, v133, 7, v232
	v_lshl_or_b32 v134, v134, 7, v232
	v_lshl_or_b32 v135, v135, 7, v232
	buffer_load_dwordx4 v[64:67], v128, s[20:23], s60 offen
	buffer_load_dwordx4 v[68:71], v129, s[20:23], s60 offen
	buffer_load_dwordx4 v[72:75], v130, s[20:23], s60 offen
	buffer_load_dwordx4 v[76:79], v131, s[20:23], s60 offen
	buffer_load_dwordx4 v[80:83], v132, s[20:23], s60 offen
	buffer_load_dwordx4 v[84:87], v133, s[20:23], s60 offen
	buffer_load_dwordx4 v[88:91], v134, s[20:23], s60 offen
	buffer_load_dwordx4 v[92:95], v135, s[20:23], s60 offen
	ds_read_b32 v128, v243 offset:768
	ds_read_b32 v129, v243 offset:800
	ds_read_b32 v130, v243 offset:832
	ds_read_b32 v131, v243 offset:864
	ds_read_b32 v132, v243 offset:896
	ds_read_b32 v133, v243 offset:928
	ds_read_b32 v134, v243 offset:960
	ds_read_b32 v135, v243 offset:992
	ds_read_b64 v[160:161], v247 offset:0
	ds_read_b64 v[162:163], v247 offset:32
	ds_read_b64 v[164:165], v247 offset:64
	ds_read_b64 v[166:167], v247 offset:96
	ds_read_b64 v[168:169], v247 offset:128
	ds_read_b64 v[170:171], v247 offset:160
	ds_read_b64 v[172:173], v247 offset:192
	ds_read_b64 v[174:175], v247 offset:224
	s_waitcnt vmcnt(26)
	v_and_b32_e32 v144, v176, v235
	v_and_b32_e32 v145, v176, v236
	v_and_b32_e32 v146, v176, v237
	v_and_b32_e32 v147, v176, v238
	v_and_b32_e32 v148, v177, v235
	v_and_b32_e32 v149, v177, v236
	v_and_b32_e32 v150, v177, v237
	v_and_b32_e32 v151, v177, v238
	s_mov_b64 vcc, s[4:5]
	v_cndmask_b32_dpp v138, v96, v98, vcc row_shl:4 row_mask:0xf bank_mask:0xf bound_ctrl:1
	v_cndmask_b32_dpp v139, v97, v99, vcc row_shl:4 row_mask:0xf bank_mask:0xf bound_ctrl:1
	s_mov_b64 vcc, s[6:7]
	v_cndmask_b32_dpp v136, v98, v96, vcc row_shr:4 row_mask:0xf bank_mask:0xf bound_ctrl:1
	v_cndmask_b32_dpp v137, v99, v97, vcc row_shr:4 row_mask:0xf bank_mask:0xf bound_ctrl:1
	v_and_b32_e32 v204, v178, v235
	v_and_b32_e32 v205, v178, v236
	v_and_b32_e32 v206, v178, v237
	v_and_b32_e32 v207, v178, v238
	v_and_b32_e32 v208, v179, v235
	v_and_b32_e32 v209, v179, v236
	v_and_b32_e32 v210, v179, v237
	v_and_b32_e32 v211, v179, v238
	s_mov_b64 vcc, s[6:7]
	v_cndmask_b32_dpp v140, v102, v100, vcc row_shr:4 row_mask:0xf bank_mask:0xf bound_ctrl:1
	v_cndmask_b32_dpp v141, v103, v101, vcc row_shr:4 row_mask:0xf bank_mask:0xf bound_ctrl:1
	s_mov_b64 vcc, s[4:5]
	v_cndmask_b32_dpp v142, v100, v102, vcc row_shl:4 row_mask:0xf bank_mask:0xf bound_ctrl:1
	v_cndmask_b32_dpp v143, v101, v103, vcc row_shl:4 row_mask:0xf bank_mask:0xf bound_ctrl:1
	v_mfma_scale_f32_16x16x128_f8f6f4 v[216:219], v[136:139], v[144:151], v[216:219], v240, v241 op_sel_hi:[0,0,0] cbsz:4
	v_permlane16_swap_b32_e32 v212, v214
	v_permlane16_swap_b32_e32 v213, v215
	v_lshlrev_b32_e32 v252, 16, v228
	v_and_b32_e32 v144, v180, v235
	v_and_b32_e32 v145, v180, v236
	v_and_b32_e32 v146, v180, v237
	v_and_b32_e32 v147, v180, v238
	v_and_b32_e32 v148, v181, v235
	v_and_b32_e32 v149, v181, v236
	v_and_b32_e32 v150, v181, v237
	v_and_b32_e32 v151, v181, v238
	s_mov_b64 vcc, s[4:5]
	v_cndmask_b32_dpp v138, v104, v106, vcc row_shl:4 row_mask:0xf bank_mask:0xf bound_ctrl:1
	v_cndmask_b32_dpp v139, v105, v107, vcc row_shl:4 row_mask:0xf bank_mask:0xf bound_ctrl:1
	s_mov_b64 vcc, s[6:7]
	v_cndmask_b32_dpp v136, v106, v104, vcc row_shr:4 row_mask:0xf bank_mask:0xf bound_ctrl:1
	v_cndmask_b32_dpp v137, v107, v105, vcc row_shr:4 row_mask:0xf bank_mask:0xf bound_ctrl:1
	v_mfma_scale_f32_16x16x128_f8f6f4 v[216:219], v[140:143], v[204:211], v[216:219], v240, v241 op_sel_hi:[0,0,0] cbsz:4
	v_and_b32_e32 v253, 0xffff0000, v228
	v_lshlrev_b32_e32 v254, 16, v229
	v_and_b32_e32 v255, 0xffff0000, v229
	v_and_b32_e32 v204, v182, v235
	v_and_b32_e32 v205, v182, v236
	v_and_b32_e32 v206, v182, v237
	v_and_b32_e32 v207, v182, v238
	v_and_b32_e32 v208, v183, v235
	v_and_b32_e32 v209, v183, v236
	v_and_b32_e32 v210, v183, v237
	v_and_b32_e32 v211, v183, v238
	s_mov_b64 vcc, s[6:7]
	v_cndmask_b32_dpp v140, v110, v108, vcc row_shr:4 row_mask:0xf bank_mask:0xf bound_ctrl:1
	v_cndmask_b32_dpp v141, v111, v109, vcc row_shr:4 row_mask:0xf bank_mask:0xf bound_ctrl:1
	s_mov_b64 vcc, s[4:5]
	v_cndmask_b32_dpp v142, v108, v110, vcc row_shl:4 row_mask:0xf bank_mask:0xf bound_ctrl:1
	v_cndmask_b32_dpp v143, v109, v111, vcc row_shl:4 row_mask:0xf bank_mask:0xf bound_ctrl:1
	v_mfma_scale_f32_16x16x128_f8f6f4 v[216:219], v[136:139], v[144:151], v[216:219], v240, v241 op_sel_hi:[0,0,0] cbsz:4
	v_add_f32_e32 v252, v212, v252
	v_add_f32_e32 v253, v214, v253
	v_add_f32_e32 v254, v213, v254
	v_and_b32_e32 v144, v184, v235
	v_and_b32_e32 v145, v184, v236
	v_and_b32_e32 v146, v184, v237
	v_and_b32_e32 v147, v184, v238
	v_and_b32_e32 v148, v185, v235
	v_and_b32_e32 v149, v185, v236
	v_and_b32_e32 v150, v185, v237
	v_and_b32_e32 v151, v185, v238
	s_mov_b64 vcc, s[4:5]
	v_cndmask_b32_dpp v138, v112, v114, vcc row_shl:4 row_mask:0xf bank_mask:0xf bound_ctrl:1
	v_cndmask_b32_dpp v139, v113, v115, vcc row_shl:4 row_mask:0xf bank_mask:0xf bound_ctrl:1
	s_mov_b64 vcc, s[6:7]
	v_cndmask_b32_dpp v136, v114, v112, vcc row_shr:4 row_mask:0xf bank_mask:0xf bound_ctrl:1
	v_cndmask_b32_dpp v137, v115, v113, vcc row_shr:4 row_mask:0xf bank_mask:0xf bound_ctrl:1
	v_mfma_scale_f32_16x16x128_f8f6f4 v[216:219], v[140:143], v[204:211], v[216:219], v240, v241 op_sel_hi:[0,0,0] cbsz:4
	v_add_f32_e32 v255, v215, v255
	v_mul_f32_e32 v192, v252, v252
	v_mul_f32_e32 v193, v254, v254
	v_and_b32_e32 v204, v186, v235
	v_and_b32_e32 v205, v186, v236
	v_and_b32_e32 v206, v186, v237
	v_and_b32_e32 v207, v186, v238
	v_and_b32_e32 v208, v187, v235
	v_and_b32_e32 v209, v187, v236
	v_and_b32_e32 v210, v187, v237
	v_and_b32_e32 v211, v187, v238
	s_mov_b64 vcc, s[6:7]
	v_cndmask_b32_dpp v140, v118, v116, vcc row_shr:4 row_mask:0xf bank_mask:0xf bound_ctrl:1
	v_cndmask_b32_dpp v141, v119, v117, vcc row_shr:4 row_mask:0xf bank_mask:0xf bound_ctrl:1
	s_mov_b64 vcc, s[4:5]
	v_cndmask_b32_dpp v142, v116, v118, vcc row_shl:4 row_mask:0xf bank_mask:0xf bound_ctrl:1
	v_cndmask_b32_dpp v143, v117, v119, vcc row_shl:4 row_mask:0xf bank_mask:0xf bound_ctrl:1
	v_mfma_scale_f32_16x16x128_f8f6f4 v[216:219], v[136:139], v[144:151], v[216:219], v240, v241 op_sel_hi:[0,0,0] cbsz:4
	v_fmac_f32_e32 v192, v253, v253
	v_fmac_f32_e32 v193, v255, v255
	v_cvt_pk_bf16_f32 v250, v252, v253
	v_and_b32_e32 v144, v188, v235
	v_and_b32_e32 v145, v188, v236
	v_and_b32_e32 v146, v188, v237
	v_and_b32_e32 v147, v188, v238
	v_and_b32_e32 v148, v189, v235
	v_and_b32_e32 v149, v189, v236
	v_and_b32_e32 v150, v189, v237
	v_and_b32_e32 v151, v189, v238
	s_mov_b64 vcc, s[4:5]
	v_cndmask_b32_dpp v138, v120, v122, vcc row_shl:4 row_mask:0xf bank_mask:0xf bound_ctrl:1
	v_cndmask_b32_dpp v139, v121, v123, vcc row_shl:4 row_mask:0xf bank_mask:0xf bound_ctrl:1
	s_mov_b64 vcc, s[6:7]
	v_cndmask_b32_dpp v136, v122, v120, vcc row_shr:4 row_mask:0xf bank_mask:0xf bound_ctrl:1
	v_cndmask_b32_dpp v137, v123, v121, vcc row_shr:4 row_mask:0xf bank_mask:0xf bound_ctrl:1
	v_mfma_scale_f32_16x16x128_f8f6f4 v[216:219], v[140:143], v[204:211], v[216:219], v240, v241 op_sel_hi:[0,0,0] cbsz:4
	v_cvt_pk_bf16_f32 v251, v254, v255
	v_add_f32_e32 v192, v192, v193
	v_add_f32_e32 v226, v226, v192
	v_and_b32_e32 v204, v190, v235
	v_and_b32_e32 v205, v190, v236
	v_and_b32_e32 v206, v190, v237
	v_and_b32_e32 v207, v190, v238
	v_and_b32_e32 v208, v191, v235
	v_and_b32_e32 v209, v191, v236
	v_and_b32_e32 v210, v191, v237
	v_and_b32_e32 v211, v191, v238
	s_mov_b64 vcc, s[6:7]
	v_cndmask_b32_dpp v140, v126, v124, vcc row_shr:4 row_mask:0xf bank_mask:0xf bound_ctrl:1
	v_cndmask_b32_dpp v141, v127, v125, vcc row_shr:4 row_mask:0xf bank_mask:0xf bound_ctrl:1
	s_mov_b64 vcc, s[4:5]
	v_cndmask_b32_dpp v142, v124, v126, vcc row_shl:4 row_mask:0xf bank_mask:0xf bound_ctrl:1
	v_cndmask_b32_dpp v143, v125, v127, vcc row_shl:4 row_mask:0xf bank_mask:0xf bound_ctrl:1
	v_mfma_scale_f32_16x16x128_f8f6f4 v[216:219], v[136:139], v[144:151], v[216:219], v240, v241 op_sel_hi:[0,0,0] cbsz:4
	s_nop 0
	v_mfma_scale_f32_16x16x128_f8f6f4 v[216:219], v[140:143], v[204:211], v[216:219], v240, v241 op_sel_hi:[0,0,0] cbsz:4
	s_lshl_b32 s64, s0, 9
	s_add_u32 s64, s64, 0x6000
	s_add_u32 s76, s28, s64
	s_addc_u32 s77, s29, 0
	global_store_dwordx2 v239, v[250:251], s[76:77]
	s_add_u32 s0, s0, 1
	s_lshl_b32 s1, s0, 21
	s_add_u32 s60, s1, 0x200000
	s_cmp_ge_u32 s0, 3
	s_movk_i32 s65, 0x2000
	s_cselect_b32 s64, s65, 0x1000
	v_mov_b32_e32 v234, v247
	v_add_u32_e32 v247, s64, v233
	s_cmp_lt_u32 s0, 8
	s_cbranch_scc1 .LpgL0_vloopv0
	s_waitcnt vmcnt(0)
	s_nop 15
	v_permlane16_swap_b32_e32 v216, v218
	v_permlane16_swap_b32_e32 v217, v219
	v_lshlrev_b32_e32 v252, 16, v230
	v_and_b32_e32 v253, 0xffff0000, v230
	v_lshlrev_b32_e32 v254, 16, v231
	v_and_b32_e32 v255, 0xffff0000, v231
	v_add_f32_e32 v252, v216, v252
	v_add_f32_e32 v253, v218, v253
	v_add_f32_e32 v254, v217, v254
	v_add_f32_e32 v255, v219, v255
	v_mul_f32_e32 v192, v252, v252
	v_mul_f32_e32 v193, v254, v254
	v_fmac_f32_e32 v192, v253, v253
	v_fmac_f32_e32 v193, v255, v255
	v_cvt_pk_bf16_f32 v250, v252, v253
	v_cvt_pk_bf16_f32 v251, v254, v255
	v_add_f32_e32 v192, v192, v193
	v_add_f32_e32 v227, v227, v192
	s_lshl_b32 s64, s0, 9
	s_add_u32 s64, s64, 0x6e00
	s_add_u32 s76, s28, s64
	s_addc_u32 s77, s29, 0
	global_store_dwordx2 v239, v[250:251], s[76:77]
	s_nop 1
	v_add_f32_dpp v220, v220, v220 quad_perm:[1,0,3,2] row_mask:0xf bank_mask:0xf bound_ctrl:1
	s_nop 1
	v_add_f32_dpp v220, v220, v220 quad_perm:[2,3,0,1] row_mask:0xf bank_mask:0xf bound_ctrl:1
	s_nop 1
	v_add_f32_dpp v220, v220, v220 row_half_mirror row_mask:0xf bank_mask:0xf bound_ctrl:1
	s_nop 1
	v_add_f32_dpp v220, v220, v220 row_mirror row_mask:0xf bank_mask:0xf bound_ctrl:1
	v_mov_b32_e32 v249, v220
	s_nop 1
	v_permlane16_swap_b32_e32 v220, v249
	v_add_f32_e32 v220, v220, v249
	v_mov_b32_e32 v249, v220
	s_nop 1
	v_permlane32_swap_b32_e32 v220, v249
	v_add_f32_e32 v220, v220, v249
	s_nop 1
	v_add_f32_dpp v221, v221, v221 quad_perm:[1,0,3,2] row_mask:0xf bank_mask:0xf bound_ctrl:1
	s_nop 1
	v_add_f32_dpp v221, v221, v221 quad_perm:[2,3,0,1] row_mask:0xf bank_mask:0xf bound_ctrl:1
	s_nop 1
	v_add_f32_dpp v221, v221, v221 row_half_mirror row_mask:0xf bank_mask:0xf bound_ctrl:1
	s_nop 1
	v_add_f32_dpp v221, v221, v221 row_mirror row_mask:0xf bank_mask:0xf bound_ctrl:1
	v_mov_b32_e32 v249, v221
	s_nop 1
	v_permlane16_swap_b32_e32 v221, v249
	v_add_f32_e32 v221, v221, v249
	v_mov_b32_e32 v249, v221
	s_nop 1
	v_permlane32_swap_b32_e32 v221, v249
	v_add_f32_e32 v221, v221, v249
	s_nop 1
	v_add_f32_dpp v222, v222, v222 quad_perm:[1,0,3,2] row_mask:0xf bank_mask:0xf bound_ctrl:1
	s_nop 1
	v_add_f32_dpp v222, v222, v222 quad_perm:[2,3,0,1] row_mask:0xf bank_mask:0xf bound_ctrl:1
	s_nop 1
	v_add_f32_dpp v222, v222, v222 row_half_mirror row_mask:0xf bank_mask:0xf bound_ctrl:1
	s_nop 1
	v_add_f32_dpp v222, v222, v222 row_mirror row_mask:0xf bank_mask:0xf bound_ctrl:1
	v_mov_b32_e32 v249, v222
	s_nop 1
	v_permlane16_swap_b32_e32 v222, v249
	v_add_f32_e32 v222, v222, v249
	v_mov_b32_e32 v249, v222
	s_nop 1
	v_permlane32_swap_b32_e32 v222, v249
	v_add_f32_e32 v222, v222, v249
	s_nop 1
	v_add_f32_dpp v223, v223, v223 quad_perm:[1,0,3,2] row_mask:0xf bank_mask:0xf bound_ctrl:1
	s_nop 1
	v_add_f32_dpp v223, v223, v223 quad_perm:[2,3,0,1] row_mask:0xf bank_mask:0xf bound_ctrl:1
	s_nop 1
	v_add_f32_dpp v223, v223, v223 row_half_mirror row_mask:0xf bank_mask:0xf bound_ctrl:1
	s_nop 1
	v_add_f32_dpp v223, v223, v223 row_mirror row_mask:0xf bank_mask:0xf bound_ctrl:1
	v_mov_b32_e32 v249, v223
	s_nop 1
	v_permlane16_swap_b32_e32 v223, v249
	v_add_f32_e32 v223, v223, v249
	v_mov_b32_e32 v249, v223
	s_nop 1
	v_permlane32_swap_b32_e32 v223, v249
	v_add_f32_e32 v223, v223, v249
	s_nop 1
	v_add_f32_dpp v224, v224, v224 quad_perm:[1,0,3,2] row_mask:0xf bank_mask:0xf bound_ctrl:1
	s_nop 1
	v_add_f32_dpp v224, v224, v224 quad_perm:[2,3,0,1] row_mask:0xf bank_mask:0xf bound_ctrl:1
	s_nop 1
	v_add_f32_dpp v224, v224, v224 row_half_mirror row_mask:0xf bank_mask:0xf bound_ctrl:1
	s_nop 1
	v_add_f32_dpp v224, v224, v224 row_mirror row_mask:0xf bank_mask:0xf bound_ctrl:1
	v_mov_b32_e32 v249, v224
	s_nop 1
	v_permlane16_swap_b32_e32 v224, v249
	v_add_f32_e32 v224, v224, v249
	v_mov_b32_e32 v249, v224
	s_nop 1
	v_permlane32_swap_b32_e32 v224, v249
	v_add_f32_e32 v224, v224, v249
	s_nop 1
	v_add_f32_dpp v225, v225, v225 quad_perm:[1,0,3,2] row_mask:0xf bank_mask:0xf bound_ctrl:1
	s_nop 1
	v_add_f32_dpp v225, v225, v225 quad_perm:[2,3,0,1] row_mask:0xf bank_mask:0xf bound_ctrl:1
	s_nop 1
	v_add_f32_dpp v225, v225, v225 row_half_mirror row_mask:0xf bank_mask:0xf bound_ctrl:1
	s_nop 1
	v_add_f32_dpp v225, v225, v225 row_mirror row_mask:0xf bank_mask:0xf bound_ctrl:1
	v_mov_b32_e32 v249, v225
	s_nop 1
	v_permlane16_swap_b32_e32 v225, v249
	v_add_f32_e32 v225, v225, v249
	v_mov_b32_e32 v249, v225
	s_nop 1
	v_permlane32_swap_b32_e32 v225, v249
	v_add_f32_e32 v225, v225, v249
	s_nop 1
	v_add_f32_dpp v226, v226, v226 quad_perm:[1,0,3,2] row_mask:0xf bank_mask:0xf bound_ctrl:1
	s_nop 1
	v_add_f32_dpp v226, v226, v226 quad_perm:[2,3,0,1] row_mask:0xf bank_mask:0xf bound_ctrl:1
	s_nop 1
	v_add_f32_dpp v226, v226, v226 row_half_mirror row_mask:0xf bank_mask:0xf bound_ctrl:1
	s_nop 1
	v_add_f32_dpp v226, v226, v226 row_mirror row_mask:0xf bank_mask:0xf bound_ctrl:1
	v_mov_b32_e32 v249, v226
	s_nop 1
	v_permlane16_swap_b32_e32 v226, v249
	v_add_f32_e32 v226, v226, v249
	v_mov_b32_e32 v249, v226
	s_nop 1
	v_permlane32_swap_b32_e32 v226, v249
	v_add_f32_e32 v226, v226, v249
	s_nop 1
	v_add_f32_dpp v227, v227, v227 quad_perm:[1,0,3,2] row_mask:0xf bank_mask:0xf bound_ctrl:1
	s_nop 1
	v_add_f32_dpp v227, v227, v227 quad_perm:[2,3,0,1] row_mask:0xf bank_mask:0xf bound_ctrl:1
	s_nop 1
	v_add_f32_dpp v227, v227, v227 row_half_mirror row_mask:0xf bank_mask:0xf bound_ctrl:1
	s_nop 1
	v_add_f32_dpp v227, v227, v227 row_mirror row_mask:0xf bank_mask:0xf bound_ctrl:1
	v_mov_b32_e32 v249, v227
	s_nop 1
	v_permlane16_swap_b32_e32 v227, v249
	v_add_f32_e32 v227, v227, v249
	v_mov_b32_e32 v249, v227
	s_nop 1
	v_permlane32_swap_b32_e32 v227, v249
	v_add_f32_e32 v227, v227, v249
	s_mov_b64 s[78:79], exec
	s_mov_b64 exec, s[10:11]
	global_store_dword v246, v220, s[44:45] offset:0
	global_store_dword v246, v221, s[44:45] offset:4
	global_store_dword v246, v222, s[44:45] offset:8
	global_store_dword v246, v223, s[44:45] offset:12
	global_store_dword v246, v224, s[44:45] offset:16
	global_store_dword v246, v225, s[44:45] offset:20
	global_store_dword v246, v226, s[44:45] offset:24
	global_store_dword v246, v227, s[44:45] offset:28
	s_mov_b64 exec, s[78:79]
	s_add_u32 s63, s63, s90
	s_cmpk_lt_i32 s63, 0x800
	s_cbranch_scc1 .LpgL0_group
	s_setprio 0

.LBB0_1075:
	s_cmp_lt_i32 s56, 16
	s_cselect_b64 s[0:1], -1, 0
	s_and_b64 s[0:1], s[0:1], s[4:5]
	s_andn2_b64 vcc, exec, s[0:1]
	s_cbranch_vccnz .LBB0_1083
	s_cmpk_gt_i32 s33, 0x7ff
	v_mbcnt_lo_u32_b32 v0, -1, 0
	v_mbcnt_hi_u32_b32 v0, -1, v0
	s_cbranch_scc1 .LBB0_1083
	s_mov_b32 s63, s33
	v_readlane_b32 s64, v248, 0
	s_lshr_b32 s64, s64, 6
	s_cmp_ge_u32 s64, 4
	s_cbranch_scc0 .LpgL1_noprio
	s_setprio 1
.LpgL1_noprio:
.LpgL1_group:
	v_mbcnt_lo_u32_b32 v249, -1, 0
	v_mbcnt_hi_u32_b32 v249, -1, v249
	v_and_b32_e32 v250, 15, v249
	v_lshrrev_b32_e32 v251, 4, v249
	v_and_b32_e32 v252, 3, v250
	v_cmp_eq_u32_e64 s[4:5], 1, v252
	v_cmp_eq_u32_e64 s[6:7], 2, v252
	v_cmp_eq_u32_e64 s[8:9], 3, v252
	v_cmp_eq_u32_e64 s[10:11], 0, v249
	s_add_u32 s12, s54, 0x29800000
	s_addc_u32 s13, s55, 0
	s_and_b32 s13, s13, 0xffff
	s_mov_b32 s14, 0x2000000
	s_mov_b32 s15, 0x20000
	s_add_u32 s16, s54, 0x10000000
	s_addc_u32 s17, s55, 0
	s_and_b32 s17, s17, 0xffff
	s_mov_b32 s18, 0x1000000
	s_mov_b32 s19, 0x20000
	s_add_u32 s20, s54, 0x14000000
	s_addc_u32 s21, s55, 0
	s_and_b32 s21, s21, 0xffff
	s_mov_b32 s22, 0x1000000
	s_mov_b32 s23, 0x20000
	s_add_u32 s30, s54, 0xa0000
	s_addc_u32 s31, s55, 0
	s_add_u32 s34, s54, 0xe0000
	s_addc_u32 s35, s55, 0
	s_mov_b32 s94, 0xc3e00000
	s_mov_b32 s96, 0x800000
	s_mov_b32 s81, 0x1010101
	v_lshrrev_b32_e32 v253, 2, v250
	v_lshrrev_b32_e32 v254, 1, v251
	v_lshl_add_u32 v255, v253, 1, v254
	v_lshl_add_u32 v237, v255, 2, s91
	v_and_b32_e32 v255, 1, v251
	v_lshl_add_u32 v236, v255, 2, v252
	v_lshlrev_b32_e32 v236, 4, v236
	v_lshlrev_b32_e32 v254, 7, v254
	v_lshl_add_u32 v254, v252, 5, v254
	v_lshl_add_u32 v254, v255, 4, v254
	v_and_b32_e32 v253, 1, v253
	v_mov_b32_e32 v255, 0x7fff0000
	v_cmp_eq_u32_e32 vcc, 0, v253
	s_nop 1
	v_cndmask_b32_e32 v238, v255, v254, vcc
	v_cndmask_b32_e32 v239, v254, v255, vcc
	v_mov_b32_e32 v240, 0x7f7f7f7f
	v_mov_b32_e32 v255, 0x20202020
	v_cmp_gt_u32_e32 vcc, 8, v250
	s_nop 1
	v_cndmask_b32_e32 v241, v255, v240, vcc
	v_cndmask_b32_e32 v242, v240, v255, vcc
	v_lshrrev_b32_e32 v254, 3, v250
	v_lshl_add_u32 v254, v252, 1, v254
	v_lshl_add_u32 v255, v251, 1, v253
	v_lshl_add_u32 v244, v254, 3, v255
	v_lshlrev_b32_e32 v244, 2, v244
	v_add_u32_e32 v243, s91, v244
	v_and_b32_e32 v253, 3, v255
	v_lshrrev_b32_e32 v255, 2, v255
	v_lshl_add_u32 v253, v253, 1, v255
	v_lshl_add_u32 v253, v254, 3, v253
	v_lshlrev_b32_e32 v253, 2, v253
	v_add_u32_e32 v245, s91, v253
	v_add_u32_e32 v245, 0x1000, v245
	v_mov_b32_e32 v246, 0
	s_lshl_b32 s64, s63, 12
	s_add_u32 s24, s54, 0x28000000
	s_addc_u32 s25, s55, 0
	s_add_u32 s24, s24, s64
	s_addc_u32 s25, s25, 0
	s_lshl_b32 s64, s63, 12
	s_add_u32 s26, s54, 0x28800000
	s_addc_u32 s27, s55, 0
	s_add_u32 s26, s26, s64
	s_addc_u32 s27, s27, 0
	s_lshl_b32 s64, s63, 15
	s_add_u32 s28, s54, 0x18000000
	s_addc_u32 s29, s55, 0
	s_add_u32 s28, s28, s64
	s_addc_u32 s29, s29, 0
	s_lshl_b32 s64, s63, 5
	s_add_u32 s40, s54, 0x60000
	s_addc_u32 s41, s55, 0
	s_add_u32 s40, s40, s64
	s_addc_u32 s41, s41, 0
	s_lshl_b32 s64, s63, 5
	s_add_u32 s44, s54, 0x70000
	s_addc_u32 s45, s55, 0
	s_add_u32 s44, s44, s64
	s_addc_u32 s45, s45, 0
	s_lshl_b32 s64, s63, 16
	s_mov_b32 s46, s52
	s_mov_b32 s47, s53
	s_add_u32 s46, s46, s64
	s_addc_u32 s47, s47, 0
	s_lshl_b32 s61, s63, 14
	s_add_u32 s62, s61, 0x100
	v_mbcnt_lo_u32_b32 v253, -1, 0
	v_mbcnt_hi_u32_b32 v253, -1, v253
	v_lshlrev_b32_e32 v253, 2, v253
	global_load_dword v0, v253, s[24:25] offset:0 nt
	global_load_dword v1, v253, s[24:25] offset:256 nt
	global_load_dword v2, v253, s[24:25] offset:512 nt
	global_load_dword v3, v253, s[24:25] offset:768 nt
	global_load_dword v4, v253, s[24:25] offset:1024 nt
	global_load_dword v5, v253, s[24:25] offset:1280 nt
	global_load_dword v6, v253, s[24:25] offset:1536 nt
	global_load_dword v7, v253, s[24:25] offset:1792 nt
	global_load_dword v8, v253, s[24:25] offset:2048 nt
	global_load_dword v9, v253, s[24:25] offset:2304 nt
	global_load_dword v10, v253, s[24:25] offset:2560 nt
	global_load_dword v11, v253, s[24:25] offset:2816 nt
	global_load_dword v12, v253, s[24:25] offset:3072 nt
	global_load_dword v13, v253, s[24:25] offset:3328 nt
	global_load_dword v14, v253, s[24:25] offset:3584 nt
	global_load_dword v15, v253, s[24:25] offset:3840 nt
	v_add_u32_e32 v254, s91, v253
	s_waitcnt vmcnt(0)
	ds_write_b32 v254, v0 offset:0
	ds_write_b32 v254, v1 offset:256
	ds_write_b32 v254, v2 offset:512
	ds_write_b32 v254, v3 offset:768
	ds_write_b32 v254, v4 offset:1024
	ds_write_b32 v254, v5 offset:1280
	ds_write_b32 v254, v6 offset:1536
	ds_write_b32 v254, v7 offset:1792
	ds_write_b32 v254, v8 offset:2048
	ds_write_b32 v254, v9 offset:2304
	ds_write_b32 v254, v10 offset:2560
	ds_write_b32 v254, v11 offset:2816
	ds_write_b32 v254, v12 offset:3072
	ds_write_b32 v254, v13 offset:3328
	ds_write_b32 v254, v14 offset:3584
	ds_write_b32 v254, v15 offset:3840
	s_waitcnt lgkmcnt(0)
	s_lshl_b32 s61, s63, 14
	s_add_u32 s62, s61, 0x100
	v_mov_b32_e32 v204, 0
	v_mov_b32_e32 v205, 0
	v_mov_b32_e32 v206, 0
	v_mov_b32_e32 v207, 0
	v_mov_b32_e32 v208, 0
	v_mov_b32_e32 v209, 0
	v_mov_b32_e32 v210, 0
	v_mov_b32_e32 v211, 0
	v_mov_b32_e32 v212, 0
	v_mov_b32_e32 v213, 0
	v_mov_b32_e32 v214, 0
	v_mov_b32_e32 v215, 0
	v_mov_b32_e32 v216, 0
	v_mov_b32_e32 v217, 0
	v_mov_b32_e32 v218, 0
	v_mov_b32_e32 v219, 0
	v_mov_b32_e32 v176, 0
	v_mov_b32_e32 v177, 0
	v_mov_b32_e32 v178, 0
	v_mov_b32_e32 v179, 0
	v_mov_b32_e32 v180, 0
	v_mov_b32_e32 v181, 0
	v_mov_b32_e32 v182, 0
	v_mov_b32_e32 v183, 0
	v_mov_b32_e32 v184, 0
	v_mov_b32_e32 v185, 0
	v_mov_b32_e32 v186, 0
	v_mov_b32_e32 v187, 0
	v_mov_b32_e32 v188, 0
	v_mov_b32_e32 v189, 0
	v_mov_b32_e32 v190, 0
	v_mov_b32_e32 v191, 0
	s_mov_b32 s0, 0
	s_mov_b32 s1, 0
	s_mov_b32 s60, 0x200000
	ds_read_b32 v144, v237 offset:0
	ds_read_b32 v145, v237 offset:32
	ds_read_b32 v146, v237 offset:64
	ds_read_b32 v147, v237 offset:96
	ds_read_b32 v148, v237 offset:128
	ds_read_b32 v149, v237 offset:160
	ds_read_b32 v150, v237 offset:192
	ds_read_b32 v151, v237 offset:224
	s_waitcnt lgkmcnt(0)
	v_lshl_or_b32 v144, v144, 7, v236
	v_lshl_or_b32 v145, v145, 7, v236
	v_lshl_or_b32 v146, v146, 7, v236
	v_lshl_or_b32 v147, v147, 7, v236
	v_lshl_or_b32 v148, v148, 7, v236
	v_lshl_or_b32 v149, v149, 7, v236
	v_lshl_or_b32 v150, v150, 7, v236
	v_lshl_or_b32 v151, v151, 7, v236
	buffer_load_dwordx4 v[0:3], v144, s[16:19], s1 offen
	buffer_load_dwordx4 v[4:7], v145, s[16:19], s1 offen
	buffer_load_dwordx4 v[8:11], v146, s[16:19], s1 offen
	buffer_load_dwordx4 v[12:15], v147, s[16:19], s1 offen
	buffer_load_dwordx4 v[16:19], v148, s[16:19], s1 offen
	buffer_load_dwordx4 v[20:23], v149, s[16:19], s1 offen
	buffer_load_dwordx4 v[24:27], v150, s[16:19], s1 offen
	buffer_load_dwordx4 v[28:31], v151, s[16:19], s1 offen
	ds_read_b32 v144, v237 offset:256
	ds_read_b32 v145, v237 offset:288
	ds_read_b32 v146, v237 offset:320
	ds_read_b32 v147, v237 offset:352
	ds_read_b32 v148, v237 offset:384
	ds_read_b32 v149, v237 offset:416
	ds_read_b32 v150, v237 offset:448
	ds_read_b32 v151, v237 offset:480
	s_add_u32 s80, s61, 0x0
	buffer_load_dwordx4 v[128:131], v238, s[12:15], s80 offen nt
	buffer_load_dwordx4 v[132:135], v239, s[12:15], s80 offen nt
	s_waitcnt lgkmcnt(0)
	v_lshl_or_b32 v144, v144, 7, v236
	v_lshl_or_b32 v145, v145, 7, v236
	v_lshl_or_b32 v146, v146, 7, v236
	v_lshl_or_b32 v147, v147, 7, v236
	v_lshl_or_b32 v148, v148, 7, v236
	v_lshl_or_b32 v149, v149, 7, v236
	v_lshl_or_b32 v150, v150, 7, v236
	v_lshl_or_b32 v151, v151, 7, v236
	buffer_load_dwordx4 v[32:35], v144, s[16:19], s1 offen
	buffer_load_dwordx4 v[36:39], v145, s[16:19], s1 offen
	buffer_load_dwordx4 v[40:43], v146, s[16:19], s1 offen
	buffer_load_dwordx4 v[44:47], v147, s[16:19], s1 offen
	buffer_load_dwordx4 v[48:51], v148, s[16:19], s1 offen
	buffer_load_dwordx4 v[52:55], v149, s[16:19], s1 offen
	buffer_load_dwordx4 v[56:59], v150, s[16:19], s1 offen
	buffer_load_dwordx4 v[60:63], v151, s[16:19], s1 offen
	ds_read_b32 v144, v237 offset:512
	ds_read_b32 v145, v237 offset:544
	ds_read_b32 v146, v237 offset:576
	ds_read_b32 v147, v237 offset:608
	ds_read_b32 v148, v237 offset:640
	ds_read_b32 v149, v237 offset:672
	ds_read_b32 v150, v237 offset:704
	ds_read_b32 v151, v237 offset:736
	s_waitcnt lgkmcnt(0)
	v_lshl_or_b32 v144, v144, 7, v236
	v_lshl_or_b32 v145, v145, 7, v236
	v_lshl_or_b32 v146, v146, 7, v236
	v_lshl_or_b32 v147, v147, 7, v236
	v_lshl_or_b32 v148, v148, 7, v236
	v_lshl_or_b32 v149, v149, 7, v236
	v_lshl_or_b32 v150, v150, 7, v236
	v_lshl_or_b32 v151, v151, 7, v236
	buffer_load_dwordx4 v[64:67], v144, s[16:19], s1 offen
	buffer_load_dwordx4 v[68:71], v145, s[16:19], s1 offen
	buffer_load_dwordx4 v[72:75], v146, s[16:19], s1 offen
	buffer_load_dwordx4 v[76:79], v147, s[16:19], s1 offen
	buffer_load_dwordx4 v[80:83], v148, s[16:19], s1 offen
	buffer_load_dwordx4 v[84:87], v149, s[16:19], s1 offen
	buffer_load_dwordx4 v[88:91], v150, s[16:19], s1 offen
	buffer_load_dwordx4 v[92:95], v151, s[16:19], s1 offen
	ds_read_b32 v144, v237 offset:768
	ds_read_b32 v145, v237 offset:800
	ds_read_b32 v146, v237 offset:832
	ds_read_b32 v147, v237 offset:864
	ds_read_b32 v148, v237 offset:896
	ds_read_b32 v149, v237 offset:928
	ds_read_b32 v150, v237 offset:960
	ds_read_b32 v151, v237 offset:992

.LpgL1_vjoinv0:
	s_lshl_b32 s64, s0, 9
	s_add_u32 s64, s64, 0x1000
	s_add_u32 s70, s28, s64
	s_addc_u32 s71, s29, 0
	global_load_dwordx2 v[230:231], v239, s[70:71]
	s_waitcnt lgkmcnt(0)
	v_lshl_or_b32 v128, v128, 7, v232
	v_lshl_or_b32 v129, v129, 7, v232
	v_lshl_or_b32 v130, v130, 7, v232
	v_lshl_or_b32 v131, v131, 7, v232
	v_lshl_or_b32 v132, v132, 7, v232
	v_lshl_or_b32 v133, v133, 7, v232
	v_lshl_or_b32 v134, v134, 7, v232
	v_lshl_or_b32 v135, v135, 7, v232
	buffer_load_dwordx4 v[32:35], v128, s[20:23], s1 offen
	buffer_load_dwordx4 v[36:39], v129, s[20:23], s1 offen
	buffer_load_dwordx4 v[40:43], v130, s[20:23], s1 offen
	buffer_load_dwordx4 v[44:47], v131, s[20:23], s1 offen
	buffer_load_dwordx4 v[48:51], v132, s[20:23], s1 offen
	buffer_load_dwordx4 v[52:55], v133, s[20:23], s1 offen
	buffer_load_dwordx4 v[56:59], v134, s[20:23], s1 offen
	buffer_load_dwordx4 v[60:63], v135, s[20:23], s1 offen
	ds_read_b32 v128, v243 offset:1536
	ds_read_b32 v129, v243 offset:1568
	ds_read_b32 v130, v243 offset:1600
	ds_read_b32 v131, v243 offset:1632
	ds_read_b32 v132, v243 offset:1664
	ds_read_b32 v133, v243 offset:1696
	ds_read_b32 v134, v243 offset:1728
	ds_read_b32 v135, v243 offset:1760
	ds_read_b64 v[176:177], v234 offset:768
	ds_read_b64 v[178:179], v234 offset:800
	ds_read_b64 v[180:181], v234 offset:832
	ds_read_b64 v[182:183], v234 offset:864
	ds_read_b64 v[184:185], v234 offset:896
	ds_read_b64 v[186:187], v234 offset:928
	ds_read_b64 v[188:189], v234 offset:960
	ds_read_b64 v[190:191], v234 offset:992
	s_waitcnt vmcnt(28)
	v_and_b32_e32 v144, v160, v235
	v_and_b32_e32 v145, v160, v236
	v_and_b32_e32 v146, v160, v237
	v_and_b32_e32 v147, v160, v238
	v_and_b32_e32 v148, v161, v235
	v_and_b32_e32 v149, v161, v236
	v_and_b32_e32 v150, v161, v237
	v_and_b32_e32 v151, v161, v238
	s_mov_b64 vcc, s[4:5]
	v_cndmask_b32_dpp v138, v64, v66, vcc row_shl:4 row_mask:0xf bank_mask:0xf bound_ctrl:1
	v_cndmask_b32_dpp v139, v65, v67, vcc row_shl:4 row_mask:0xf bank_mask:0xf bound_ctrl:1
	s_mov_b64 vcc, s[6:7]
	v_cndmask_b32_dpp v136, v66, v64, vcc row_shr:4 row_mask:0xf bank_mask:0xf bound_ctrl:1
	v_cndmask_b32_dpp v137, v67, v65, vcc row_shr:4 row_mask:0xf bank_mask:0xf bound_ctrl:1
	v_and_b32_e32 v204, v162, v235
	v_and_b32_e32 v205, v162, v236
	v_and_b32_e32 v206, v162, v237
	v_and_b32_e32 v207, v162, v238
	v_and_b32_e32 v208, v163, v235
	v_and_b32_e32 v209, v163, v236
	v_and_b32_e32 v210, v163, v237
	v_and_b32_e32 v211, v163, v238
	s_mov_b64 vcc, s[6:7]
	v_cndmask_b32_dpp v140, v70, v68, vcc row_shr:4 row_mask:0xf bank_mask:0xf bound_ctrl:1
	v_cndmask_b32_dpp v141, v71, v69, vcc row_shr:4 row_mask:0xf bank_mask:0xf bound_ctrl:1
	s_mov_b64 vcc, s[4:5]
	v_cndmask_b32_dpp v142, v68, v70, vcc row_shl:4 row_mask:0xf bank_mask:0xf bound_ctrl:1
	v_cndmask_b32_dpp v143, v69, v71, vcc row_shl:4 row_mask:0xf bank_mask:0xf bound_ctrl:1
	v_mfma_scale_f32_16x16x128_f8f6f4 v[216:219], v[136:139], v[144:151], 0, v240, v241 op_sel_hi:[0,0,0] cbsz:4
	v_and_b32_e32 v144, v164, v235
	v_and_b32_e32 v145, v164, v236
	v_and_b32_e32 v146, v164, v237
	v_and_b32_e32 v147, v164, v238
	v_and_b32_e32 v148, v165, v235
	v_and_b32_e32 v149, v165, v236
	v_and_b32_e32 v150, v165, v237
	v_and_b32_e32 v151, v165, v238
	s_mov_b64 vcc, s[4:5]
	v_cndmask_b32_dpp v138, v72, v74, vcc row_shl:4 row_mask:0xf bank_mask:0xf bound_ctrl:1
	v_cndmask_b32_dpp v139, v73, v75, vcc row_shl:4 row_mask:0xf bank_mask:0xf bound_ctrl:1
	s_mov_b64 vcc, s[6:7]
	v_cndmask_b32_dpp v136, v74, v72, vcc row_shr:4 row_mask:0xf bank_mask:0xf bound_ctrl:1
	v_cndmask_b32_dpp v137, v75, v73, vcc row_shr:4 row_mask:0xf bank_mask:0xf bound_ctrl:1
	v_mfma_scale_f32_16x16x128_f8f6f4 v[216:219], v[140:143], v[204:211], v[216:219], v240, v241 op_sel_hi:[0,0,0] cbsz:4
	v_and_b32_e32 v204, v166, v235
	v_and_b32_e32 v205, v166, v236
	v_and_b32_e32 v206, v166, v237
	v_and_b32_e32 v207, v166, v238
	v_and_b32_e32 v208, v167, v235
	v_and_b32_e32 v209, v167, v236
	v_and_b32_e32 v210, v167, v237
	v_and_b32_e32 v211, v167, v238
	s_mov_b64 vcc, s[6:7]
	v_cndmask_b32_dpp v140, v78, v76, vcc row_shr:4 row_mask:0xf bank_mask:0xf bound_ctrl:1
	v_cndmask_b32_dpp v141, v79, v77, vcc row_shr:4 row_mask:0xf bank_mask:0xf bound_ctrl:1
	s_mov_b64 vcc, s[4:5]
	v_cndmask_b32_dpp v142, v76, v78, vcc row_shl:4 row_mask:0xf bank_mask:0xf bound_ctrl:1
	v_cndmask_b32_dpp v143, v77, v79, vcc row_shl:4 row_mask:0xf bank_mask:0xf bound_ctrl:1
	v_mfma_scale_f32_16x16x128_f8f6f4 v[216:219], v[136:139], v[144:151], v[216:219], v240, v241 op_sel_hi:[0,0,0] cbsz:4
	v_and_b32_e32 v144, v168, v235
	v_and_b32_e32 v145, v168, v236
	v_and_b32_e32 v146, v168, v237
	v_and_b32_e32 v147, v168, v238
	v_and_b32_e32 v148, v169, v235
	v_and_b32_e32 v149, v169, v236
	v_and_b32_e32 v150, v169, v237
	v_and_b32_e32 v151, v169, v238
	s_mov_b64 vcc, s[4:5]
	v_cndmask_b32_dpp v138, v80, v82, vcc row_shl:4 row_mask:0xf bank_mask:0xf bound_ctrl:1
	v_cndmask_b32_dpp v139, v81, v83, vcc row_shl:4 row_mask:0xf bank_mask:0xf bound_ctrl:1
	s_mov_b64 vcc, s[6:7]
	v_cndmask_b32_dpp v136, v82, v80, vcc row_shr:4 row_mask:0xf bank_mask:0xf bound_ctrl:1
	v_cndmask_b32_dpp v137, v83, v81, vcc row_shr:4 row_mask:0xf bank_mask:0xf bound_ctrl:1
	v_mfma_scale_f32_16x16x128_f8f6f4 v[216:219], v[140:143], v[204:211], v[216:219], v240, v241 op_sel_hi:[0,0,0] cbsz:4
	v_and_b32_e32 v204, v170, v235
	v_and_b32_e32 v205, v170, v236
	v_and_b32_e32 v206, v170, v237
	v_and_b32_e32 v207, v170, v238
	v_and_b32_e32 v208, v171, v235
	v_and_b32_e32 v209, v171, v236
	v_and_b32_e32 v210, v171, v237
	v_and_b32_e32 v211, v171, v238
	s_mov_b64 vcc, s[6:7]
	v_cndmask_b32_dpp v140, v86, v84, vcc row_shr:4 row_mask:0xf bank_mask:0xf bound_ctrl:1
	v_cndmask_b32_dpp v141, v87, v85, vcc row_shr:4 row_mask:0xf bank_mask:0xf bound_ctrl:1
	s_mov_b64 vcc, s[4:5]
	v_cndmask_b32_dpp v142, v84, v86, vcc row_shl:4 row_mask:0xf bank_mask:0xf bound_ctrl:1
	v_cndmask_b32_dpp v143, v85, v87, vcc row_shl:4 row_mask:0xf bank_mask:0xf bound_ctrl:1
	v_mfma_scale_f32_16x16x128_f8f6f4 v[216:219], v[136:139], v[144:151], v[216:219], v240, v241 op_sel_hi:[0,0,0] cbsz:4
	v_and_b32_e32 v144, v172, v235
	v_and_b32_e32 v145, v172, v236
	v_and_b32_e32 v146, v172, v237
	v_and_b32_e32 v147, v172, v238
	v_and_b32_e32 v148, v173, v235
	v_and_b32_e32 v149, v173, v236
	v_and_b32_e32 v150, v173, v237
	v_and_b32_e32 v151, v173, v238
	s_mov_b64 vcc, s[4:5]
	v_cndmask_b32_dpp v138, v88, v90, vcc row_shl:4 row_mask:0xf bank_mask:0xf bound_ctrl:1
	v_cndmask_b32_dpp v139, v89, v91, vcc row_shl:4 row_mask:0xf bank_mask:0xf bound_ctrl:1
	s_mov_b64 vcc, s[6:7]
	v_cndmask_b32_dpp v136, v90, v88, vcc row_shr:4 row_mask:0xf bank_mask:0xf bound_ctrl:1
	v_cndmask_b32_dpp v137, v91, v89, vcc row_shr:4 row_mask:0xf bank_mask:0xf bound_ctrl:1
	v_mfma_scale_f32_16x16x128_f8f6f4 v[216:219], v[140:143], v[204:211], v[216:219], v240, v241 op_sel_hi:[0,0,0] cbsz:4
	v_and_b32_e32 v204, v174, v235
	v_and_b32_e32 v205, v174, v236
	v_and_b32_e32 v206, v174, v237
	v_and_b32_e32 v207, v174, v238
	v_and_b32_e32 v208, v175, v235
	v_and_b32_e32 v209, v175, v236
	v_and_b32_e32 v210, v175, v237
	v_and_b32_e32 v211, v175, v238
	s_mov_b64 vcc, s[6:7]
	v_cndmask_b32_dpp v140, v94, v92, vcc row_shr:4 row_mask:0xf bank_mask:0xf bound_ctrl:1
	v_cndmask_b32_dpp v141, v95, v93, vcc row_shr:4 row_mask:0xf bank_mask:0xf bound_ctrl:1
	s_mov_b64 vcc, s[4:5]
	v_cndmask_b32_dpp v142, v92, v94, vcc row_shl:4 row_mask:0xf bank_mask:0xf bound_ctrl:1
	v_cndmask_b32_dpp v143, v93, v95, vcc row_shl:4 row_mask:0xf bank_mask:0xf bound_ctrl:1
	v_mfma_scale_f32_16x16x128_f8f6f4 v[216:219], v[136:139], v[144:151], v[216:219], v240, v241 op_sel_hi:[0,0,0] cbsz:4
	s_nop 0
	v_mfma_scale_f32_16x16x128_f8f6f4 v[216:219], v[140:143], v[204:211], v[216:219], v240, v241 op_sel_hi:[0,0,0] cbsz:4
	s_waitcnt lgkmcnt(0)
	v_lshl_or_b32 v128, v128, 7, v232
	v_lshl_or_b32 v129, v129, 7, v232
	v_lshl_or_b32 v130, v130, 7, v232
	v_lshl_or_b32 v131, v131, 7, v232
	v_lshl_or_b32 v132, v132, 7, v232
	v_lshl_or_b32 v133, v133, 7, v232
	v_lshl_or_b32 v134, v134, 7, v232
	v_lshl_or_b32 v135, v135, 7, v232
	buffer_load_dwordx4 v[64:67], v128, s[20:23], s1 offen
	buffer_load_dwordx4 v[68:71], v129, s[20:23], s1 offen
	buffer_load_dwordx4 v[72:75], v130, s[20:23], s1 offen
	buffer_load_dwordx4 v[76:79], v131, s[20:23], s1 offen
	buffer_load_dwordx4 v[80:83], v132, s[20:23], s1 offen
	buffer_load_dwordx4 v[84:87], v133, s[20:23], s1 offen
	buffer_load_dwordx4 v[88:91], v134, s[20:23], s1 offen
	buffer_load_dwordx4 v[92:95], v135, s[20:23], s1 offen
	ds_read_b32 v128, v243 offset:1792
	ds_read_b32 v129, v243 offset:1824
	ds_read_b32 v130, v243 offset:1856
	ds_read_b32 v131, v243 offset:1888
	ds_read_b32 v132, v243 offset:1920
	ds_read_b32 v133, v243 offset:1952
	ds_read_b32 v134, v243 offset:1984
	ds_read_b32 v135, v243 offset:2016
	ds_read_b64 v[160:161], v234 offset:1024
	ds_read_b64 v[162:163], v234 offset:1056
	ds_read_b64 v[164:165], v234 offset:1088
	ds_read_b64 v[166:167], v234 offset:1120
	ds_read_b64 v[168:169], v234 offset:1152
	ds_read_b64 v[170:171], v234 offset:1184
	ds_read_b64 v[172:173], v234 offset:1216
	ds_read_b64 v[174:175], v234 offset:1248
	s_waitcnt vmcnt(26)
	v_and_b32_e32 v144, v176, v235
	v_and_b32_e32 v145, v176, v236
	v_and_b32_e32 v146, v176, v237
	v_and_b32_e32 v147, v176, v238
	v_and_b32_e32 v148, v177, v235
	v_and_b32_e32 v149, v177, v236
	v_and_b32_e32 v150, v177, v237
	v_and_b32_e32 v151, v177, v238
	s_mov_b64 vcc, s[4:5]
	v_cndmask_b32_dpp v138, v96, v98, vcc row_shl:4 row_mask:0xf bank_mask:0xf bound_ctrl:1
	v_cndmask_b32_dpp v139, v97, v99, vcc row_shl:4 row_mask:0xf bank_mask:0xf bound_ctrl:1
	s_mov_b64 vcc, s[6:7]
	v_cndmask_b32_dpp v136, v98, v96, vcc row_shr:4 row_mask:0xf bank_mask:0xf bound_ctrl:1
	v_cndmask_b32_dpp v137, v99, v97, vcc row_shr:4 row_mask:0xf bank_mask:0xf bound_ctrl:1
	v_and_b32_e32 v204, v178, v235
	v_and_b32_e32 v205, v178, v236
	v_and_b32_e32 v206, v178, v237
	v_and_b32_e32 v207, v178, v238
	v_and_b32_e32 v208, v179, v235
	v_and_b32_e32 v209, v179, v236
	v_and_b32_e32 v210, v179, v237
	v_and_b32_e32 v211, v179, v238
	s_mov_b64 vcc, s[6:7]
	v_cndmask_b32_dpp v140, v102, v100, vcc row_shr:4 row_mask:0xf bank_mask:0xf bound_ctrl:1
	v_cndmask_b32_dpp v141, v103, v101, vcc row_shr:4 row_mask:0xf bank_mask:0xf bound_ctrl:1
	s_mov_b64 vcc, s[4:5]
	v_cndmask_b32_dpp v142, v100, v102, vcc row_shl:4 row_mask:0xf bank_mask:0xf bound_ctrl:1
	v_cndmask_b32_dpp v143, v101, v103, vcc row_shl:4 row_mask:0xf bank_mask:0xf bound_ctrl:1
	v_mfma_scale_f32_16x16x128_f8f6f4 v[216:219], v[136:139], v[144:151], v[216:219], v240, v241 op_sel_hi:[0,0,0] cbsz:4
	v_permlane16_swap_b32_e32 v212, v214
	v_permlane16_swap_b32_e32 v213, v215
	v_lshlrev_b32_e32 v252, 16, v228
	v_and_b32_e32 v144, v180, v235
	v_and_b32_e32 v145, v180, v236
	v_and_b32_e32 v146, v180, v237
	v_and_b32_e32 v147, v180, v238
	v_and_b32_e32 v148, v181, v235
	v_and_b32_e32 v149, v181, v236
	v_and_b32_e32 v150, v181, v237
	v_and_b32_e32 v151, v181, v238
	s_mov_b64 vcc, s[4:5]
	v_cndmask_b32_dpp v138, v104, v106, vcc row_shl:4 row_mask:0xf bank_mask:0xf bound_ctrl:1
	v_cndmask_b32_dpp v139, v105, v107, vcc row_shl:4 row_mask:0xf bank_mask:0xf bound_ctrl:1
	s_mov_b64 vcc, s[6:7]
	v_cndmask_b32_dpp v136, v106, v104, vcc row_shr:4 row_mask:0xf bank_mask:0xf bound_ctrl:1
	v_cndmask_b32_dpp v137, v107, v105, vcc row_shr:4 row_mask:0xf bank_mask:0xf bound_ctrl:1
	v_mfma_scale_f32_16x16x128_f8f6f4 v[216:219], v[140:143], v[204:211], v[216:219], v240, v241 op_sel_hi:[0,0,0] cbsz:4
	v_and_b32_e32 v253, 0xffff0000, v228
	v_lshlrev_b32_e32 v254, 16, v229
	v_and_b32_e32 v255, 0xffff0000, v229
	v_and_b32_e32 v204, v182, v235
	v_and_b32_e32 v205, v182, v236
	v_and_b32_e32 v206, v182, v237
	v_and_b32_e32 v207, v182, v238
	v_and_b32_e32 v208, v183, v235
	v_and_b32_e32 v209, v183, v236
	v_and_b32_e32 v210, v183, v237
	v_and_b32_e32 v211, v183, v238
	s_mov_b64 vcc, s[6:7]
	v_cndmask_b32_dpp v140, v110, v108, vcc row_shr:4 row_mask:0xf bank_mask:0xf bound_ctrl:1
	v_cndmask_b32_dpp v141, v111, v109, vcc row_shr:4 row_mask:0xf bank_mask:0xf bound_ctrl:1
	s_mov_b64 vcc, s[4:5]
	v_cndmask_b32_dpp v142, v108, v110, vcc row_shl:4 row_mask:0xf bank_mask:0xf bound_ctrl:1
	v_cndmask_b32_dpp v143, v109, v111, vcc row_shl:4 row_mask:0xf bank_mask:0xf bound_ctrl:1
	v_mfma_scale_f32_16x16x128_f8f6f4 v[216:219], v[136:139], v[144:151], v[216:219], v240, v241 op_sel_hi:[0,0,0] cbsz:4
	v_add_f32_e32 v252, v212, v252
	v_add_f32_e32 v253, v214, v253
	v_add_f32_e32 v254, v213, v254
	v_and_b32_e32 v144, v184, v235
	v_and_b32_e32 v145, v184, v236
	v_and_b32_e32 v146, v184, v237
	v_and_b32_e32 v147, v184, v238
	v_and_b32_e32 v148, v185, v235
	v_and_b32_e32 v149, v185, v236
	v_and_b32_e32 v150, v185, v237
	v_and_b32_e32 v151, v185, v238
	s_mov_b64 vcc, s[4:5]
	v_cndmask_b32_dpp v138, v112, v114, vcc row_shl:4 row_mask:0xf bank_mask:0xf bound_ctrl:1
	v_cndmask_b32_dpp v139, v113, v115, vcc row_shl:4 row_mask:0xf bank_mask:0xf bound_ctrl:1
	s_mov_b64 vcc, s[6:7]
	v_cndmask_b32_dpp v136, v114, v112, vcc row_shr:4 row_mask:0xf bank_mask:0xf bound_ctrl:1
	v_cndmask_b32_dpp v137, v115, v113, vcc row_shr:4 row_mask:0xf bank_mask:0xf bound_ctrl:1
	v_mfma_scale_f32_16x16x128_f8f6f4 v[216:219], v[140:143], v[204:211], v[216:219], v240, v241 op_sel_hi:[0,0,0] cbsz:4
	v_add_f32_e32 v255, v215, v255
	v_mul_f32_e32 v192, v252, v252
	v_mul_f32_e32 v193, v254, v254
	v_and_b32_e32 v204, v186, v235
	v_and_b32_e32 v205, v186, v236
	v_and_b32_e32 v206, v186, v237
	v_and_b32_e32 v207, v186, v238
	v_and_b32_e32 v208, v187, v235
	v_and_b32_e32 v209, v187, v236
	v_and_b32_e32 v210, v187, v237
	v_and_b32_e32 v211, v187, v238
	s_mov_b64 vcc, s[6:7]
	v_cndmask_b32_dpp v140, v118, v116, vcc row_shr:4 row_mask:0xf bank_mask:0xf bound_ctrl:1
	v_cndmask_b32_dpp v141, v119, v117, vcc row_shr:4 row_mask:0xf bank_mask:0xf bound_ctrl:1
	s_mov_b64 vcc, s[4:5]
	v_cndmask_b32_dpp v142, v116, v118, vcc row_shl:4 row_mask:0xf bank_mask:0xf bound_ctrl:1
	v_cndmask_b32_dpp v143, v117, v119, vcc row_shl:4 row_mask:0xf bank_mask:0xf bound_ctrl:1
	v_mfma_scale_f32_16x16x128_f8f6f4 v[216:219], v[136:139], v[144:151], v[216:219], v240, v241 op_sel_hi:[0,0,0] cbsz:4
	v_fmac_f32_e32 v192, v253, v253
	v_fmac_f32_e32 v193, v255, v255
	v_cvt_pk_bf16_f32 v250, v252, v253
	v_and_b32_e32 v144, v188, v235
	v_and_b32_e32 v145, v188, v236
	v_and_b32_e32 v146, v188, v237
	v_and_b32_e32 v147, v188, v238
	v_and_b32_e32 v148, v189, v235
	v_and_b32_e32 v149, v189, v236
	v_and_b32_e32 v150, v189, v237
	v_and_b32_e32 v151, v189, v238
	s_mov_b64 vcc, s[4:5]
	v_cndmask_b32_dpp v138, v120, v122, vcc row_shl:4 row_mask:0xf bank_mask:0xf bound_ctrl:1
	v_cndmask_b32_dpp v139, v121, v123, vcc row_shl:4 row_mask:0xf bank_mask:0xf bound_ctrl:1
	s_mov_b64 vcc, s[6:7]
	v_cndmask_b32_dpp v136, v122, v120, vcc row_shr:4 row_mask:0xf bank_mask:0xf bound_ctrl:1
	v_cndmask_b32_dpp v137, v123, v121, vcc row_shr:4 row_mask:0xf bank_mask:0xf bound_ctrl:1
	v_mfma_scale_f32_16x16x128_f8f6f4 v[216:219], v[140:143], v[204:211], v[216:219], v240, v241 op_sel_hi:[0,0,0] cbsz:4
	v_cvt_pk_bf16_f32 v251, v254, v255
	v_add_f32_e32 v192, v192, v193
	v_add_f32_e32 v220, v220, v192
	v_and_b32_e32 v204, v190, v235
	v_and_b32_e32 v205, v190, v236
	v_and_b32_e32 v206, v190, v237
	v_and_b32_e32 v207, v190, v238
	v_and_b32_e32 v208, v191, v235
	v_and_b32_e32 v209, v191, v236
	v_and_b32_e32 v210, v191, v237
	v_and_b32_e32 v211, v191, v238
	s_mov_b64 vcc, s[6:7]
	v_cndmask_b32_dpp v140, v126, v124, vcc row_shr:4 row_mask:0xf bank_mask:0xf bound_ctrl:1
	v_cndmask_b32_dpp v141, v127, v125, vcc row_shr:4 row_mask:0xf bank_mask:0xf bound_ctrl:1
	s_mov_b64 vcc, s[4:5]
	v_cndmask_b32_dpp v142, v124, v126, vcc row_shl:4 row_mask:0xf bank_mask:0xf bound_ctrl:1
	v_cndmask_b32_dpp v143, v125, v127, vcc row_shl:4 row_mask:0xf bank_mask:0xf bound_ctrl:1
	v_mfma_scale_f32_16x16x128_f8f6f4 v[216:219], v[136:139], v[144:151], v[216:219], v240, v241 op_sel_hi:[0,0,0] cbsz:4
	s_nop 0
	v_mfma_scale_f32_16x16x128_f8f6f4 v[216:219], v[140:143], v[204:211], v[216:219], v240, v241 op_sel_hi:[0,0,0] cbsz:4
	s_lshl_b32 s64, s0, 9
	s_add_u32 s64, s64, 0x0
	s_add_u32 s76, s28, s64
	s_addc_u32 s77, s29, 0
	global_store_dwordx2 v239, v[250:251], s[76:77]
	s_lshl_b32 s64, s0, 9
	s_add_u32 s64, s64, 0x2000
	s_add_u32 s70, s28, s64
	s_addc_u32 s71, s29, 0
	global_load_dwordx2 v[228:229], v239, s[70:71]
	s_waitcnt lgkmcnt(0)
	v_lshl_or_b32 v128, v128, 7, v232
	v_lshl_or_b32 v129, v129, 7, v232
	v_lshl_or_b32 v130, v130, 7, v232
	v_lshl_or_b32 v131, v131, 7, v232
	v_lshl_or_b32 v132, v132, 7, v232
	v_lshl_or_b32 v133, v133, 7, v232
	v_lshl_or_b32 v134, v134, 7, v232
	v_lshl_or_b32 v135, v135, 7, v232
	buffer_load_dwordx4 v[96:99], v128, s[20:23], s1 offen
	buffer_load_dwordx4 v[100:103], v129, s[20:23], s1 offen
	buffer_load_dwordx4 v[104:107], v130, s[20:23], s1 offen
	buffer_load_dwordx4 v[108:111], v131, s[20:23], s1 offen
	buffer_load_dwordx4 v[112:115], v132, s[20:23], s1 offen
	buffer_load_dwordx4 v[116:119], v133, s[20:23], s1 offen
	buffer_load_dwordx4 v[120:123], v134, s[20:23], s1 offen
	buffer_load_dwordx4 v[124:127], v135, s[20:23], s1 offen
	ds_read_b32 v128, v243 offset:2048
	ds_read_b32 v129, v243 offset:2080
	ds_read_b32 v130, v243 offset:2112
	ds_read_b32 v131, v243 offset:2144
	ds_read_b32 v132, v243 offset:2176
	ds_read_b32 v133, v243 offset:2208
	ds_read_b32 v134, v243 offset:2240
	ds_read_b32 v135, v243 offset:2272
	ds_read_b64 v[176:177], v234 offset:1280
	ds_read_b64 v[178:179], v234 offset:1312
	ds_read_b64 v[180:181], v234 offset:1344
	ds_read_b64 v[182:183], v234 offset:1376
	ds_read_b64 v[184:185], v234 offset:1408
	ds_read_b64 v[186:187], v234 offset:1440
	ds_read_b64 v[188:189], v234 offset:1472
	ds_read_b64 v[190:191], v234 offset:1504
	s_waitcnt vmcnt(28)
	v_and_b32_e32 v144, v160, v235
	v_and_b32_e32 v145, v160, v236
	v_and_b32_e32 v146, v160, v237
	v_and_b32_e32 v147, v160, v238
	v_and_b32_e32 v148, v161, v235
	v_and_b32_e32 v149, v161, v236
	v_and_b32_e32 v150, v161, v237
	v_and_b32_e32 v151, v161, v238
	s_mov_b64 vcc, s[4:5]
	v_cndmask_b32_dpp v138, v0, v2, vcc row_shl:4 row_mask:0xf bank_mask:0xf bound_ctrl:1
	v_cndmask_b32_dpp v139, v1, v3, vcc row_shl:4 row_mask:0xf bank_mask:0xf bound_ctrl:1
	s_mov_b64 vcc, s[6:7]
	v_cndmask_b32_dpp v136, v2, v0, vcc row_shr:4 row_mask:0xf bank_mask:0xf bound_ctrl:1
	v_cndmask_b32_dpp v137, v3, v1, vcc row_shr:4 row_mask:0xf bank_mask:0xf bound_ctrl:1
	v_and_b32_e32 v204, v162, v235
	v_and_b32_e32 v205, v162, v236
	v_and_b32_e32 v206, v162, v237
	v_and_b32_e32 v207, v162, v238
	v_and_b32_e32 v208, v163, v235
	v_and_b32_e32 v209, v163, v236
	v_and_b32_e32 v210, v163, v237
	v_and_b32_e32 v211, v163, v238
	s_mov_b64 vcc, s[6:7]
	v_cndmask_b32_dpp v140, v6, v4, vcc row_shr:4 row_mask:0xf bank_mask:0xf bound_ctrl:1
	v_cndmask_b32_dpp v141, v7, v5, vcc row_shr:4 row_mask:0xf bank_mask:0xf bound_ctrl:1
	s_mov_b64 vcc, s[4:5]
	v_cndmask_b32_dpp v142, v4, v6, vcc row_shl:4 row_mask:0xf bank_mask:0xf bound_ctrl:1
	v_cndmask_b32_dpp v143, v5, v7, vcc row_shl:4 row_mask:0xf bank_mask:0xf bound_ctrl:1
	v_mfma_scale_f32_16x16x128_f8f6f4 v[212:215], v[136:139], v[144:151], 0, v240, v241 op_sel_hi:[0,0,0] cbsz:4
	v_and_b32_e32 v144, v164, v235
	v_and_b32_e32 v145, v164, v236
	v_and_b32_e32 v146, v164, v237
	v_and_b32_e32 v147, v164, v238
	v_and_b32_e32 v148, v165, v235
	v_and_b32_e32 v149, v165, v236
	v_and_b32_e32 v150, v165, v237
	v_and_b32_e32 v151, v165, v238
	s_mov_b64 vcc, s[4:5]
	v_cndmask_b32_dpp v138, v8, v10, vcc row_shl:4 row_mask:0xf bank_mask:0xf bound_ctrl:1
	v_cndmask_b32_dpp v139, v9, v11, vcc row_shl:4 row_mask:0xf bank_mask:0xf bound_ctrl:1
	s_mov_b64 vcc, s[6:7]
	v_cndmask_b32_dpp v136, v10, v8, vcc row_shr:4 row_mask:0xf bank_mask:0xf bound_ctrl:1
	v_cndmask_b32_dpp v137, v11, v9, vcc row_shr:4 row_mask:0xf bank_mask:0xf bound_ctrl:1
	v_mfma_scale_f32_16x16x128_f8f6f4 v[212:215], v[140:143], v[204:211], v[212:215], v240, v241 op_sel_hi:[0,0,0] cbsz:4
	v_and_b32_e32 v204, v166, v235
	v_and_b32_e32 v205, v166, v236
	v_and_b32_e32 v206, v166, v237
	v_and_b32_e32 v207, v166, v238
	v_and_b32_e32 v208, v167, v235
	v_and_b32_e32 v209, v167, v236
	v_and_b32_e32 v210, v167, v237
	v_and_b32_e32 v211, v167, v238
	s_mov_b64 vcc, s[6:7]
	v_cndmask_b32_dpp v140, v14, v12, vcc row_shr:4 row_mask:0xf bank_mask:0xf bound_ctrl:1
	v_cndmask_b32_dpp v141, v15, v13, vcc row_shr:4 row_mask:0xf bank_mask:0xf bound_ctrl:1
	s_mov_b64 vcc, s[4:5]
	v_cndmask_b32_dpp v142, v12, v14, vcc row_shl:4 row_mask:0xf bank_mask:0xf bound_ctrl:1
	v_cndmask_b32_dpp v143, v13, v15, vcc row_shl:4 row_mask:0xf bank_mask:0xf bound_ctrl:1
	v_mfma_scale_f32_16x16x128_f8f6f4 v[212:215], v[136:139], v[144:151], v[212:215], v240, v241 op_sel_hi:[0,0,0] cbsz:4
	v_and_b32_e32 v144, v168, v235
	v_and_b32_e32 v145, v168, v236
	v_and_b32_e32 v146, v168, v237
	v_and_b32_e32 v147, v168, v238
	v_and_b32_e32 v148, v169, v235
	v_and_b32_e32 v149, v169, v236
	v_and_b32_e32 v150, v169, v237
	v_and_b32_e32 v151, v169, v238
	s_mov_b64 vcc, s[4:5]
	v_cndmask_b32_dpp v138, v16, v18, vcc row_shl:4 row_mask:0xf bank_mask:0xf bound_ctrl:1
	v_cndmask_b32_dpp v139, v17, v19, vcc row_shl:4 row_mask:0xf bank_mask:0xf bound_ctrl:1
	s_mov_b64 vcc, s[6:7]
	v_cndmask_b32_dpp v136, v18, v16, vcc row_shr:4 row_mask:0xf bank_mask:0xf bound_ctrl:1
	v_cndmask_b32_dpp v137, v19, v17, vcc row_shr:4 row_mask:0xf bank_mask:0xf bound_ctrl:1
	v_mfma_scale_f32_16x16x128_f8f6f4 v[212:215], v[140:143], v[204:211], v[212:215], v240, v241 op_sel_hi:[0,0,0] cbsz:4
	v_and_b32_e32 v204, v170, v235
	v_and_b32_e32 v205, v170, v236
	v_and_b32_e32 v206, v170, v237
	v_and_b32_e32 v207, v170, v238
	v_and_b32_e32 v208, v171, v235
	v_and_b32_e32 v209, v171, v236
	v_and_b32_e32 v210, v171, v237
	v_and_b32_e32 v211, v171, v238
	s_mov_b64 vcc, s[6:7]
	v_cndmask_b32_dpp v140, v22, v20, vcc row_shr:4 row_mask:0xf bank_mask:0xf bound_ctrl:1
	v_cndmask_b32_dpp v141, v23, v21, vcc row_shr:4 row_mask:0xf bank_mask:0xf bound_ctrl:1
	s_mov_b64 vcc, s[4:5]
	v_cndmask_b32_dpp v142, v20, v22, vcc row_shl:4 row_mask:0xf bank_mask:0xf bound_ctrl:1
	v_cndmask_b32_dpp v143, v21, v23, vcc row_shl:4 row_mask:0xf bank_mask:0xf bound_ctrl:1
	v_mfma_scale_f32_16x16x128_f8f6f4 v[212:215], v[136:139], v[144:151], v[212:215], v240, v241 op_sel_hi:[0,0,0] cbsz:4
	v_and_b32_e32 v144, v172, v235
	v_and_b32_e32 v145, v172, v236
	v_and_b32_e32 v146, v172, v237
	v_and_b32_e32 v147, v172, v238
	v_and_b32_e32 v148, v173, v235
	v_and_b32_e32 v149, v173, v236
	v_and_b32_e32 v150, v173, v237
	v_and_b32_e32 v151, v173, v238
	s_mov_b64 vcc, s[4:5]
	v_cndmask_b32_dpp v138, v24, v26, vcc row_shl:4 row_mask:0xf bank_mask:0xf bound_ctrl:1
	v_cndmask_b32_dpp v139, v25, v27, vcc row_shl:4 row_mask:0xf bank_mask:0xf bound_ctrl:1
	s_mov_b64 vcc, s[6:7]
	v_cndmask_b32_dpp v136, v26, v24, vcc row_shr:4 row_mask:0xf bank_mask:0xf bound_ctrl:1
	v_cndmask_b32_dpp v137, v27, v25, vcc row_shr:4 row_mask:0xf bank_mask:0xf bound_ctrl:1
	v_mfma_scale_f32_16x16x128_f8f6f4 v[212:215], v[140:143], v[204:211], v[212:215], v240, v241 op_sel_hi:[0,0,0] cbsz:4
	v_and_b32_e32 v204, v174, v235
	v_and_b32_e32 v205, v174, v236
	v_and_b32_e32 v206, v174, v237
	v_and_b32_e32 v207, v174, v238
	v_and_b32_e32 v208, v175, v235
	v_and_b32_e32 v209, v175, v236
	v_and_b32_e32 v210, v175, v237
	v_and_b32_e32 v211, v175, v238
	s_mov_b64 vcc, s[6:7]
	v_cndmask_b32_dpp v140, v30, v28, vcc row_shr:4 row_mask:0xf bank_mask:0xf bound_ctrl:1
	v_cndmask_b32_dpp v141, v31, v29, vcc row_shr:4 row_mask:0xf bank_mask:0xf bound_ctrl:1
	s_mov_b64 vcc, s[4:5]
	v_cndmask_b32_dpp v142, v28, v30, vcc row_shl:4 row_mask:0xf bank_mask:0xf bound_ctrl:1
	v_cndmask_b32_dpp v143, v29, v31, vcc row_shl:4 row_mask:0xf bank_mask:0xf bound_ctrl:1
	v_mfma_scale_f32_16x16x128_f8f6f4 v[212:215], v[136:139], v[144:151], v[212:215], v240, v241 op_sel_hi:[0,0,0] cbsz:4
	s_nop 0
	v_mfma_scale_f32_16x16x128_f8f6f4 v[212:215], v[140:143], v[204:211], v[212:215], v240, v241 op_sel_hi:[0,0,0] cbsz:4
	s_waitcnt lgkmcnt(0)
	v_lshl_or_b32 v128, v128, 7, v232
	v_lshl_or_b32 v129, v129, 7, v232
	v_lshl_or_b32 v130, v130, 7, v232
	v_lshl_or_b32 v131, v131, 7, v232
	v_lshl_or_b32 v132, v132, 7, v232
	v_lshl_or_b32 v133, v133, 7, v232
	v_lshl_or_b32 v134, v134, 7, v232
	v_lshl_or_b32 v135, v135, 7, v232
	buffer_load_dwordx4 v[0:3], v128, s[20:23], s1 offen
	buffer_load_dwordx4 v[4:7], v129, s[20:23], s1 offen
	buffer_load_dwordx4 v[8:11], v130, s[20:23], s1 offen
	buffer_load_dwordx4 v[12:15], v131, s[20:23], s1 offen
	buffer_load_dwordx4 v[16:19], v132, s[20:23], s1 offen
	buffer_load_dwordx4 v[20:23], v133, s[20:23], s1 offen
	buffer_load_dwordx4 v[24:27], v134, s[20:23], s1 offen
	buffer_load_dwordx4 v[28:31], v135, s[20:23], s1 offen
	ds_read_b32 v128, v243 offset:2304
	ds_read_b32 v129, v243 offset:2336
	ds_read_b32 v130, v243 offset:2368
	ds_read_b32 v131, v243 offset:2400
	ds_read_b32 v132, v243 offset:2432
	ds_read_b32 v133, v243 offset:2464
	ds_read_b32 v134, v243 offset:2496
	ds_read_b32 v135, v243 offset:2528
	ds_read_b64 v[160:161], v234 offset:1536
	ds_read_b64 v[162:163], v234 offset:1568
	ds_read_b64 v[164:165], v234 offset:1600
	ds_read_b64 v[166:167], v234 offset:1632
	ds_read_b64 v[168:169], v234 offset:1664
	ds_read_b64 v[170:171], v234 offset:1696
	ds_read_b64 v[172:173], v234 offset:1728
	ds_read_b64 v[174:175], v234 offset:1760
	s_waitcnt vmcnt(26)
	v_and_b32_e32 v144, v176, v235
	v_and_b32_e32 v145, v176, v236
	v_and_b32_e32 v146, v176, v237
	v_and_b32_e32 v147, v176, v238
	v_and_b32_e32 v148, v177, v235
	v_and_b32_e32 v149, v177, v236
	v_and_b32_e32 v150, v177, v237
	v_and_b32_e32 v151, v177, v238
	s_mov_b64 vcc, s[4:5]
	v_cndmask_b32_dpp v138, v32, v34, vcc row_shl:4 row_mask:0xf bank_mask:0xf bound_ctrl:1
	v_cndmask_b32_dpp v139, v33, v35, vcc row_shl:4 row_mask:0xf bank_mask:0xf bound_ctrl:1
	s_mov_b64 vcc, s[6:7]
	v_cndmask_b32_dpp v136, v34, v32, vcc row_shr:4 row_mask:0xf bank_mask:0xf bound_ctrl:1
	v_cndmask_b32_dpp v137, v35, v33, vcc row_shr:4 row_mask:0xf bank_mask:0xf bound_ctrl:1
	v_and_b32_e32 v204, v178, v235
	v_and_b32_e32 v205, v178, v236
	v_and_b32_e32 v206, v178, v237
	v_and_b32_e32 v207, v178, v238
	v_and_b32_e32 v208, v179, v235
	v_and_b32_e32 v209, v179, v236
	v_and_b32_e32 v210, v179, v237
	v_and_b32_e32 v211, v179, v238
	s_mov_b64 vcc, s[6:7]
	v_cndmask_b32_dpp v140, v38, v36, vcc row_shr:4 row_mask:0xf bank_mask:0xf bound_ctrl:1
	v_cndmask_b32_dpp v141, v39, v37, vcc row_shr:4 row_mask:0xf bank_mask:0xf bound_ctrl:1
	s_mov_b64 vcc, s[4:5]
	v_cndmask_b32_dpp v142, v36, v38, vcc row_shl:4 row_mask:0xf bank_mask:0xf bound_ctrl:1
	v_cndmask_b32_dpp v143, v37, v39, vcc row_shl:4 row_mask:0xf bank_mask:0xf bound_ctrl:1
	v_mfma_scale_f32_16x16x128_f8f6f4 v[212:215], v[136:139], v[144:151], v[212:215], v240, v241 op_sel_hi:[0,0,0] cbsz:4
	v_permlane16_swap_b32_e32 v216, v218
	v_permlane16_swap_b32_e32 v217, v219
	v_lshlrev_b32_e32 v252, 16, v230
	v_and_b32_e32 v144, v180, v235
	v_and_b32_e32 v145, v180, v236
	v_and_b32_e32 v146, v180, v237
	v_and_b32_e32 v147, v180, v238
	v_and_b32_e32 v148, v181, v235
	v_and_b32_e32 v149, v181, v236
	v_and_b32_e32 v150, v181, v237
	v_and_b32_e32 v151, v181, v238
	s_mov_b64 vcc, s[4:5]
	v_cndmask_b32_dpp v138, v40, v42, vcc row_shl:4 row_mask:0xf bank_mask:0xf bound_ctrl:1
	v_cndmask_b32_dpp v139, v41, v43, vcc row_shl:4 row_mask:0xf bank_mask:0xf bound_ctrl:1
	s_mov_b64 vcc, s[6:7]
	v_cndmask_b32_dpp v136, v42, v40, vcc row_shr:4 row_mask:0xf bank_mask:0xf bound_ctrl:1
	v_cndmask_b32_dpp v137, v43, v41, vcc row_shr:4 row_mask:0xf bank_mask:0xf bound_ctrl:1
	v_mfma_scale_f32_16x16x128_f8f6f4 v[212:215], v[140:143], v[204:211], v[212:215], v240, v241 op_sel_hi:[0,0,0] cbsz:4
	v_and_b32_e32 v253, 0xffff0000, v230
	v_lshlrev_b32_e32 v254, 16, v231
	v_and_b32_e32 v255, 0xffff0000, v231
	v_and_b32_e32 v204, v182, v235
	v_and_b32_e32 v205, v182, v236
	v_and_b32_e32 v206, v182, v237
	v_and_b32_e32 v207, v182, v238
	v_and_b32_e32 v208, v183, v235
	v_and_b32_e32 v209, v183, v236
	v_and_b32_e32 v210, v183, v237
	v_and_b32_e32 v211, v183, v238
	s_mov_b64 vcc, s[6:7]
	v_cndmask_b32_dpp v140, v46, v44, vcc row_shr:4 row_mask:0xf bank_mask:0xf bound_ctrl:1
	v_cndmask_b32_dpp v141, v47, v45, vcc row_shr:4 row_mask:0xf bank_mask:0xf bound_ctrl:1
	s_mov_b64 vcc, s[4:5]
	v_cndmask_b32_dpp v142, v44, v46, vcc row_shl:4 row_mask:0xf bank_mask:0xf bound_ctrl:1
	v_cndmask_b32_dpp v143, v45, v47, vcc row_shl:4 row_mask:0xf bank_mask:0xf bound_ctrl:1
	v_mfma_scale_f32_16x16x128_f8f6f4 v[212:215], v[136:139], v[144:151], v[212:215], v240, v241 op_sel_hi:[0,0,0] cbsz:4
	v_add_f32_e32 v252, v216, v252
	v_add_f32_e32 v253, v218, v253
	v_add_f32_e32 v254, v217, v254
	v_and_b32_e32 v144, v184, v235
	v_and_b32_e32 v145, v184, v236
	v_and_b32_e32 v146, v184, v237
	v_and_b32_e32 v147, v184, v238
	v_and_b32_e32 v148, v185, v235
	v_and_b32_e32 v149, v185, v236
	v_and_b32_e32 v150, v185, v237
	v_and_b32_e32 v151, v185, v238
	s_mov_b64 vcc, s[4:5]
	v_cndmask_b32_dpp v138, v48, v50, vcc row_shl:4 row_mask:0xf bank_mask:0xf bound_ctrl:1
	v_cndmask_b32_dpp v139, v49, v51, vcc row_shl:4 row_mask:0xf bank_mask:0xf bound_ctrl:1
	s_mov_b64 vcc, s[6:7]
	v_cndmask_b32_dpp v136, v50, v48, vcc row_shr:4 row_mask:0xf bank_mask:0xf bound_ctrl:1
	v_cndmask_b32_dpp v137, v51, v49, vcc row_shr:4 row_mask:0xf bank_mask:0xf bound_ctrl:1
	v_mfma_scale_f32_16x16x128_f8f6f4 v[212:215], v[140:143], v[204:211], v[212:215], v240, v241 op_sel_hi:[0,0,0] cbsz:4
	v_add_f32_e32 v255, v219, v255
	v_mul_f32_e32 v192, v252, v252
	v_mul_f32_e32 v193, v254, v254
	v_and_b32_e32 v204, v186, v235
	v_and_b32_e32 v205, v186, v236
	v_and_b32_e32 v206, v186, v237
	v_and_b32_e32 v207, v186, v238
	v_and_b32_e32 v208, v187, v235
	v_and_b32_e32 v209, v187, v236
	v_and_b32_e32 v210, v187, v237
	v_and_b32_e32 v211, v187, v238
	s_mov_b64 vcc, s[6:7]
	v_cndmask_b32_dpp v140, v54, v52, vcc row_shr:4 row_mask:0xf bank_mask:0xf bound_ctrl:1
	v_cndmask_b32_dpp v141, v55, v53, vcc row_shr:4 row_mask:0xf bank_mask:0xf bound_ctrl:1
	s_mov_b64 vcc, s[4:5]
	v_cndmask_b32_dpp v142, v52, v54, vcc row_shl:4 row_mask:0xf bank_mask:0xf bound_ctrl:1
	v_cndmask_b32_dpp v143, v53, v55, vcc row_shl:4 row_mask:0xf bank_mask:0xf bound_ctrl:1
	v_mfma_scale_f32_16x16x128_f8f6f4 v[212:215], v[136:139], v[144:151], v[212:215], v240, v241 op_sel_hi:[0,0,0] cbsz:4
	v_fmac_f32_e32 v192, v253, v253
	v_fmac_f32_e32 v193, v255, v255
	v_cvt_pk_bf16_f32 v250, v252, v253
	v_and_b32_e32 v144, v188, v235
	v_and_b32_e32 v145, v188, v236
	v_and_b32_e32 v146, v188, v237
	v_and_b32_e32 v147, v188, v238
	v_and_b32_e32 v148, v189, v235
	v_and_b32_e32 v149, v189, v236
	v_and_b32_e32 v150, v189, v237
	v_and_b32_e32 v151, v189, v238
	s_mov_b64 vcc, s[4:5]
	v_cndmask_b32_dpp v138, v56, v58, vcc row_shl:4 row_mask:0xf bank_mask:0xf bound_ctrl:1
	v_cndmask_b32_dpp v139, v57, v59, vcc row_shl:4 row_mask:0xf bank_mask:0xf bound_ctrl:1
	s_mov_b64 vcc, s[6:7]
	v_cndmask_b32_dpp v136, v58, v56, vcc row_shr:4 row_mask:0xf bank_mask:0xf bound_ctrl:1
	v_cndmask_b32_dpp v137, v59, v57, vcc row_shr:4 row_mask:0xf bank_mask:0xf bound_ctrl:1
	v_mfma_scale_f32_16x16x128_f8f6f4 v[212:215], v[140:143], v[204:211], v[212:215], v240, v241 op_sel_hi:[0,0,0] cbsz:4
	v_cvt_pk_bf16_f32 v251, v254, v255
	v_add_f32_e32 v192, v192, v193
	v_add_f32_e32 v221, v221, v192
	v_and_b32_e32 v204, v190, v235
	v_and_b32_e32 v205, v190, v236
	v_and_b32_e32 v206, v190, v237
	v_and_b32_e32 v207, v190, v238
	v_and_b32_e32 v208, v191, v235
	v_and_b32_e32 v209, v191, v236
	v_and_b32_e32 v210, v191, v237
	v_and_b32_e32 v211, v191, v238
	s_mov_b64 vcc, s[6:7]
	v_cndmask_b32_dpp v140, v62, v60, vcc row_shr:4 row_mask:0xf bank_mask:0xf bound_ctrl:1
	v_cndmask_b32_dpp v141, v63, v61, vcc row_shr:4 row_mask:0xf bank_mask:0xf bound_ctrl:1
	s_mov_b64 vcc, s[4:5]
	v_cndmask_b32_dpp v142, v60, v62, vcc row_shl:4 row_mask:0xf bank_mask:0xf bound_ctrl:1
	v_cndmask_b32_dpp v143, v61, v63, vcc row_shl:4 row_mask:0xf bank_mask:0xf bound_ctrl:1
	v_mfma_scale_f32_16x16x128_f8f6f4 v[212:215], v[136:139], v[144:151], v[212:215], v240, v241 op_sel_hi:[0,0,0] cbsz:4
	s_nop 0
	v_mfma_scale_f32_16x16x128_f8f6f4 v[212:215], v[140:143], v[204:211], v[212:215], v240, v241 op_sel_hi:[0,0,0] cbsz:4
	s_lshl_b32 s64, s0, 9
	s_add_u32 s64, s64, 0x1000
	s_add_u32 s76, s28, s64
	s_addc_u32 s77, s29, 0
	global_store_dwordx2 v239, v[250:251], s[76:77]
	s_lshl_b32 s64, s0, 9
	s_add_u32 s64, s64, 0x3000
	s_add_u32 s70, s28, s64
	s_addc_u32 s71, s29, 0
	global_load_dwordx2 v[230:231], v239, s[70:71]
	s_waitcnt lgkmcnt(0)
	v_lshl_or_b32 v128, v128, 7, v232
	v_lshl_or_b32 v129, v129, 7, v232
	v_lshl_or_b32 v130, v130, 7, v232
	v_lshl_or_b32 v131, v131, 7, v232
	v_lshl_or_b32 v132, v132, 7, v232
	v_lshl_or_b32 v133, v133, 7, v232
	v_lshl_or_b32 v134, v134, 7, v232
	v_lshl_or_b32 v135, v135, 7, v232
	buffer_load_dwordx4 v[32:35], v128, s[20:23], s1 offen
	buffer_load_dwordx4 v[36:39], v129, s[20:23], s1 offen
	buffer_load_dwordx4 v[40:43], v130, s[20:23], s1 offen
	buffer_load_dwordx4 v[44:47], v131, s[20:23], s1 offen
	buffer_load_dwordx4 v[48:51], v132, s[20:23], s1 offen
	buffer_load_dwordx4 v[52:55], v133, s[20:23], s1 offen
	buffer_load_dwordx4 v[56:59], v134, s[20:23], s1 offen
	buffer_load_dwordx4 v[60:63], v135, s[20:23], s1 offen
	ds_read_b32 v128, v243 offset:2560
	ds_read_b32 v129, v243 offset:2592
	ds_read_b32 v130, v243 offset:2624
	ds_read_b32 v131, v243 offset:2656
	ds_read_b32 v132, v243 offset:2688
	ds_read_b32 v133, v243 offset:2720
	ds_read_b32 v134, v243 offset:2752
	ds_read_b32 v135, v243 offset:2784
	ds_read_b64 v[176:177], v234 offset:1792
	ds_read_b64 v[178:179], v234 offset:1824
	ds_read_b64 v[180:181], v234 offset:1856
	ds_read_b64 v[182:183], v234 offset:1888
	ds_read_b64 v[184:185], v234 offset:1920
	ds_read_b64 v[186:187], v234 offset:1952
	ds_read_b64 v[188:189], v234 offset:1984
	ds_read_b64 v[190:191], v234 offset:2016
	s_waitcnt vmcnt(28)
	v_and_b32_e32 v144, v160, v235
	v_and_b32_e32 v145, v160, v236
	v_and_b32_e32 v146, v160, v237
	v_and_b32_e32 v147, v160, v238
	v_and_b32_e32 v148, v161, v235
	v_and_b32_e32 v149, v161, v236
	v_and_b32_e32 v150, v161, v237
	v_and_b32_e32 v151, v161, v238
	s_mov_b64 vcc, s[4:5]
	v_cndmask_b32_dpp v138, v64, v66, vcc row_shl:4 row_mask:0xf bank_mask:0xf bound_ctrl:1
	v_cndmask_b32_dpp v139, v65, v67, vcc row_shl:4 row_mask:0xf bank_mask:0xf bound_ctrl:1
	s_mov_b64 vcc, s[6:7]
	v_cndmask_b32_dpp v136, v66, v64, vcc row_shr:4 row_mask:0xf bank_mask:0xf bound_ctrl:1
	v_cndmask_b32_dpp v137, v67, v65, vcc row_shr:4 row_mask:0xf bank_mask:0xf bound_ctrl:1
	v_and_b32_e32 v204, v162, v235
	v_and_b32_e32 v205, v162, v236
	v_and_b32_e32 v206, v162, v237
	v_and_b32_e32 v207, v162, v238
	v_and_b32_e32 v208, v163, v235
	v_and_b32_e32 v209, v163, v236
	v_and_b32_e32 v210, v163, v237
	v_and_b32_e32 v211, v163, v238
	s_mov_b64 vcc, s[6:7]
	v_cndmask_b32_dpp v140, v70, v68, vcc row_shr:4 row_mask:0xf bank_mask:0xf bound_ctrl:1
	v_cndmask_b32_dpp v141, v71, v69, vcc row_shr:4 row_mask:0xf bank_mask:0xf bound_ctrl:1
	s_mov_b64 vcc, s[4:5]
	v_cndmask_b32_dpp v142, v68, v70, vcc row_shl:4 row_mask:0xf bank_mask:0xf bound_ctrl:1
	v_cndmask_b32_dpp v143, v69, v71, vcc row_shl:4 row_mask:0xf bank_mask:0xf bound_ctrl:1
	v_mfma_scale_f32_16x16x128_f8f6f4 v[216:219], v[136:139], v[144:151], 0, v240, v241 op_sel_hi:[0,0,0] cbsz:4
	v_and_b32_e32 v144, v164, v235
	v_and_b32_e32 v145, v164, v236
	v_and_b32_e32 v146, v164, v237
	v_and_b32_e32 v147, v164, v238
	v_and_b32_e32 v148, v165, v235
	v_and_b32_e32 v149, v165, v236
	v_and_b32_e32 v150, v165, v237
	v_and_b32_e32 v151, v165, v238
	s_mov_b64 vcc, s[4:5]
	v_cndmask_b32_dpp v138, v72, v74, vcc row_shl:4 row_mask:0xf bank_mask:0xf bound_ctrl:1
	v_cndmask_b32_dpp v139, v73, v75, vcc row_shl:4 row_mask:0xf bank_mask:0xf bound_ctrl:1
	s_mov_b64 vcc, s[6:7]
	v_cndmask_b32_dpp v136, v74, v72, vcc row_shr:4 row_mask:0xf bank_mask:0xf bound_ctrl:1
	v_cndmask_b32_dpp v137, v75, v73, vcc row_shr:4 row_mask:0xf bank_mask:0xf bound_ctrl:1
	v_mfma_scale_f32_16x16x128_f8f6f4 v[216:219], v[140:143], v[204:211], v[216:219], v240, v241 op_sel_hi:[0,0,0] cbsz:4
	v_and_b32_e32 v204, v166, v235
	v_and_b32_e32 v205, v166, v236
	v_and_b32_e32 v206, v166, v237
	v_and_b32_e32 v207, v166, v238
	v_and_b32_e32 v208, v167, v235
	v_and_b32_e32 v209, v167, v236
	v_and_b32_e32 v210, v167, v237
	v_and_b32_e32 v211, v167, v238
	s_mov_b64 vcc, s[6:7]
	v_cndmask_b32_dpp v140, v78, v76, vcc row_shr:4 row_mask:0xf bank_mask:0xf bound_ctrl:1
	v_cndmask_b32_dpp v141, v79, v77, vcc row_shr:4 row_mask:0xf bank_mask:0xf bound_ctrl:1
	s_mov_b64 vcc, s[4:5]
	v_cndmask_b32_dpp v142, v76, v78, vcc row_shl:4 row_mask:0xf bank_mask:0xf bound_ctrl:1
	v_cndmask_b32_dpp v143, v77, v79, vcc row_shl:4 row_mask:0xf bank_mask:0xf bound_ctrl:1
	v_mfma_scale_f32_16x16x128_f8f6f4 v[216:219], v[136:139], v[144:151], v[216:219], v240, v241 op_sel_hi:[0,0,0] cbsz:4
	v_and_b32_e32 v144, v168, v235
	v_and_b32_e32 v145, v168, v236
	v_and_b32_e32 v146, v168, v237
	v_and_b32_e32 v147, v168, v238
	v_and_b32_e32 v148, v169, v235
	v_and_b32_e32 v149, v169, v236
	v_and_b32_e32 v150, v169, v237
	v_and_b32_e32 v151, v169, v238
	s_mov_b64 vcc, s[4:5]
	v_cndmask_b32_dpp v138, v80, v82, vcc row_shl:4 row_mask:0xf bank_mask:0xf bound_ctrl:1
	v_cndmask_b32_dpp v139, v81, v83, vcc row_shl:4 row_mask:0xf bank_mask:0xf bound_ctrl:1
	s_mov_b64 vcc, s[6:7]
	v_cndmask_b32_dpp v136, v82, v80, vcc row_shr:4 row_mask:0xf bank_mask:0xf bound_ctrl:1
	v_cndmask_b32_dpp v137, v83, v81, vcc row_shr:4 row_mask:0xf bank_mask:0xf bound_ctrl:1
	v_mfma_scale_f32_16x16x128_f8f6f4 v[216:219], v[140:143], v[204:211], v[216:219], v240, v241 op_sel_hi:[0,0,0] cbsz:4
	v_and_b32_e32 v204, v170, v235
	v_and_b32_e32 v205, v170, v236
	v_and_b32_e32 v206, v170, v237
	v_and_b32_e32 v207, v170, v238
	v_and_b32_e32 v208, v171, v235
	v_and_b32_e32 v209, v171, v236
	v_and_b32_e32 v210, v171, v237
	v_and_b32_e32 v211, v171, v238
	s_mov_b64 vcc, s[6:7]
	v_cndmask_b32_dpp v140, v86, v84, vcc row_shr:4 row_mask:0xf bank_mask:0xf bound_ctrl:1
	v_cndmask_b32_dpp v141, v87, v85, vcc row_shr:4 row_mask:0xf bank_mask:0xf bound_ctrl:1
	s_mov_b64 vcc, s[4:5]
	v_cndmask_b32_dpp v142, v84, v86, vcc row_shl:4 row_mask:0xf bank_mask:0xf bound_ctrl:1
	v_cndmask_b32_dpp v143, v85, v87, vcc row_shl:4 row_mask:0xf bank_mask:0xf bound_ctrl:1
	v_mfma_scale_f32_16x16x128_f8f6f4 v[216:219], v[136:139], v[144:151], v[216:219], v240, v241 op_sel_hi:[0,0,0] cbsz:4
	v_and_b32_e32 v144, v172, v235
	v_and_b32_e32 v145, v172, v236
	v_and_b32_e32 v146, v172, v237
	v_and_b32_e32 v147, v172, v238
	v_and_b32_e32 v148, v173, v235
	v_and_b32_e32 v149, v173, v236
	v_and_b32_e32 v150, v173, v237
	v_and_b32_e32 v151, v173, v238
	s_mov_b64 vcc, s[4:5]
	v_cndmask_b32_dpp v138, v88, v90, vcc row_shl:4 row_mask:0xf bank_mask:0xf bound_ctrl:1
	v_cndmask_b32_dpp v139, v89, v91, vcc row_shl:4 row_mask:0xf bank_mask:0xf bound_ctrl:1
	s_mov_b64 vcc, s[6:7]
	v_cndmask_b32_dpp v136, v90, v88, vcc row_shr:4 row_mask:0xf bank_mask:0xf bound_ctrl:1
	v_cndmask_b32_dpp v137, v91, v89, vcc row_shr:4 row_mask:0xf bank_mask:0xf bound_ctrl:1
	v_mfma_scale_f32_16x16x128_f8f6f4 v[216:219], v[140:143], v[204:211], v[216:219], v240, v241 op_sel_hi:[0,0,0] cbsz:4
	v_and_b32_e32 v204, v174, v235
	v_and_b32_e32 v205, v174, v236
	v_and_b32_e32 v206, v174, v237
	v_and_b32_e32 v207, v174, v238
	v_and_b32_e32 v208, v175, v235
	v_and_b32_e32 v209, v175, v236
	v_and_b32_e32 v210, v175, v237
	v_and_b32_e32 v211, v175, v238
	s_mov_b64 vcc, s[6:7]
	v_cndmask_b32_dpp v140, v94, v92, vcc row_shr:4 row_mask:0xf bank_mask:0xf bound_ctrl:1
	v_cndmask_b32_dpp v141, v95, v93, vcc row_shr:4 row_mask:0xf bank_mask:0xf bound_ctrl:1
	s_mov_b64 vcc, s[4:5]
	v_cndmask_b32_dpp v142, v92, v94, vcc row_shl:4 row_mask:0xf bank_mask:0xf bound_ctrl:1
	v_cndmask_b32_dpp v143, v93, v95, vcc row_shl:4 row_mask:0xf bank_mask:0xf bound_ctrl:1
	v_mfma_scale_f32_16x16x128_f8f6f4 v[216:219], v[136:139], v[144:151], v[216:219], v240, v241 op_sel_hi:[0,0,0] cbsz:4
	s_nop 0
	v_mfma_scale_f32_16x16x128_f8f6f4 v[216:219], v[140:143], v[204:211], v[216:219], v240, v241 op_sel_hi:[0,0,0] cbsz:4
	s_waitcnt lgkmcnt(0)
	v_lshl_or_b32 v128, v128, 7, v232
	v_lshl_or_b32 v129, v129, 7, v232
	v_lshl_or_b32 v130, v130, 7, v232
	v_lshl_or_b32 v131, v131, 7, v232
	v_lshl_or_b32 v132, v132, 7, v232
	v_lshl_or_b32 v133, v133, 7, v232
	v_lshl_or_b32 v134, v134, 7, v232
	v_lshl_or_b32 v135, v135, 7, v232
	buffer_load_dwordx4 v[64:67], v128, s[20:23], s1 offen
	buffer_load_dwordx4 v[68:71], v129, s[20:23], s1 offen
	buffer_load_dwordx4 v[72:75], v130, s[20:23], s1 offen
	buffer_load_dwordx4 v[76:79], v131, s[20:23], s1 offen
	buffer_load_dwordx4 v[80:83], v132, s[20:23], s1 offen
	buffer_load_dwordx4 v[84:87], v133, s[20:23], s1 offen
	buffer_load_dwordx4 v[88:91], v134, s[20:23], s1 offen
	buffer_load_dwordx4 v[92:95], v135, s[20:23], s1 offen
	ds_read_b32 v128, v243 offset:2816
	ds_read_b32 v129, v243 offset:2848
	ds_read_b32 v130, v243 offset:2880
	ds_read_b32 v131, v243 offset:2912
	ds_read_b32 v132, v243 offset:2944
	ds_read_b32 v133, v243 offset:2976
	ds_read_b32 v134, v243 offset:3008
	ds_read_b32 v135, v243 offset:3040
	ds_read_b64 v[160:161], v234 offset:2048
	ds_read_b64 v[162:163], v234 offset:2080
	ds_read_b64 v[164:165], v234 offset:2112
	ds_read_b64 v[166:167], v234 offset:2144
	ds_read_b64 v[168:169], v234 offset:2176
	ds_read_b64 v[170:171], v234 offset:2208
	ds_read_b64 v[172:173], v234 offset:2240
	ds_read_b64 v[174:175], v234 offset:2272
	s_waitcnt vmcnt(26)
	v_and_b32_e32 v144, v176, v235
	v_and_b32_e32 v145, v176, v236
	v_and_b32_e32 v146, v176, v237
	v_and_b32_e32 v147, v176, v238
	v_and_b32_e32 v148, v177, v235
	v_and_b32_e32 v149, v177, v236
	v_and_b32_e32 v150, v177, v237
	v_and_b32_e32 v151, v177, v238
	s_mov_b64 vcc, s[4:5]
	v_cndmask_b32_dpp v138, v96, v98, vcc row_shl:4 row_mask:0xf bank_mask:0xf bound_ctrl:1
	v_cndmask_b32_dpp v139, v97, v99, vcc row_shl:4 row_mask:0xf bank_mask:0xf bound_ctrl:1
	s_mov_b64 vcc, s[6:7]
	v_cndmask_b32_dpp v136, v98, v96, vcc row_shr:4 row_mask:0xf bank_mask:0xf bound_ctrl:1
	v_cndmask_b32_dpp v137, v99, v97, vcc row_shr:4 row_mask:0xf bank_mask:0xf bound_ctrl:1
	v_and_b32_e32 v204, v178, v235
	v_and_b32_e32 v205, v178, v236
	v_and_b32_e32 v206, v178, v237
	v_and_b32_e32 v207, v178, v238
	v_and_b32_e32 v208, v179, v235
	v_and_b32_e32 v209, v179, v236
	v_and_b32_e32 v210, v179, v237
	v_and_b32_e32 v211, v179, v238
	s_mov_b64 vcc, s[6:7]
	v_cndmask_b32_dpp v140, v102, v100, vcc row_shr:4 row_mask:0xf bank_mask:0xf bound_ctrl:1
	v_cndmask_b32_dpp v141, v103, v101, vcc row_shr:4 row_mask:0xf bank_mask:0xf bound_ctrl:1
	s_mov_b64 vcc, s[4:5]
	v_cndmask_b32_dpp v142, v100, v102, vcc row_shl:4 row_mask:0xf bank_mask:0xf bound_ctrl:1
	v_cndmask_b32_dpp v143, v101, v103, vcc row_shl:4 row_mask:0xf bank_mask:0xf bound_ctrl:1
	v_mfma_scale_f32_16x16x128_f8f6f4 v[216:219], v[136:139], v[144:151], v[216:219], v240, v241 op_sel_hi:[0,0,0] cbsz:4
	v_permlane16_swap_b32_e32 v212, v214
	v_permlane16_swap_b32_e32 v213, v215
	v_lshlrev_b32_e32 v252, 16, v228
	v_and_b32_e32 v144, v180, v235
	v_and_b32_e32 v145, v180, v236
	v_and_b32_e32 v146, v180, v237
	v_and_b32_e32 v147, v180, v238
	v_and_b32_e32 v148, v181, v235
	v_and_b32_e32 v149, v181, v236
	v_and_b32_e32 v150, v181, v237
	v_and_b32_e32 v151, v181, v238
	s_mov_b64 vcc, s[4:5]
	v_cndmask_b32_dpp v138, v104, v106, vcc row_shl:4 row_mask:0xf bank_mask:0xf bound_ctrl:1
	v_cndmask_b32_dpp v139, v105, v107, vcc row_shl:4 row_mask:0xf bank_mask:0xf bound_ctrl:1
	s_mov_b64 vcc, s[6:7]
	v_cndmask_b32_dpp v136, v106, v104, vcc row_shr:4 row_mask:0xf bank_mask:0xf bound_ctrl:1
	v_cndmask_b32_dpp v137, v107, v105, vcc row_shr:4 row_mask:0xf bank_mask:0xf bound_ctrl:1
	v_mfma_scale_f32_16x16x128_f8f6f4 v[216:219], v[140:143], v[204:211], v[216:219], v240, v241 op_sel_hi:[0,0,0] cbsz:4
	v_and_b32_e32 v253, 0xffff0000, v228
	v_lshlrev_b32_e32 v254, 16, v229
	v_and_b32_e32 v255, 0xffff0000, v229
	v_and_b32_e32 v204, v182, v235
	v_and_b32_e32 v205, v182, v236
	v_and_b32_e32 v206, v182, v237
	v_and_b32_e32 v207, v182, v238
	v_and_b32_e32 v208, v183, v235
	v_and_b32_e32 v209, v183, v236
	v_and_b32_e32 v210, v183, v237
	v_and_b32_e32 v211, v183, v238
	s_mov_b64 vcc, s[6:7]
	v_cndmask_b32_dpp v140, v110, v108, vcc row_shr:4 row_mask:0xf bank_mask:0xf bound_ctrl:1
	v_cndmask_b32_dpp v141, v111, v109, vcc row_shr:4 row_mask:0xf bank_mask:0xf bound_ctrl:1
	s_mov_b64 vcc, s[4:5]
	v_cndmask_b32_dpp v142, v108, v110, vcc row_shl:4 row_mask:0xf bank_mask:0xf bound_ctrl:1
	v_cndmask_b32_dpp v143, v109, v111, vcc row_shl:4 row_mask:0xf bank_mask:0xf bound_ctrl:1
	v_mfma_scale_f32_16x16x128_f8f6f4 v[216:219], v[136:139], v[144:151], v[216:219], v240, v241 op_sel_hi:[0,0,0] cbsz:4
	v_add_f32_e32 v252, v212, v252
	v_add_f32_e32 v253, v214, v253
	v_add_f32_e32 v254, v213, v254
	v_and_b32_e32 v144, v184, v235
	v_and_b32_e32 v145, v184, v236
	v_and_b32_e32 v146, v184, v237
	v_and_b32_e32 v147, v184, v238
	v_and_b32_e32 v148, v185, v235
	v_and_b32_e32 v149, v185, v236
	v_and_b32_e32 v150, v185, v237
	v_and_b32_e32 v151, v185, v238
	s_mov_b64 vcc, s[4:5]
	v_cndmask_b32_dpp v138, v112, v114, vcc row_shl:4 row_mask:0xf bank_mask:0xf bound_ctrl:1
	v_cndmask_b32_dpp v139, v113, v115, vcc row_shl:4 row_mask:0xf bank_mask:0xf bound_ctrl:1
	s_mov_b64 vcc, s[6:7]
	v_cndmask_b32_dpp v136, v114, v112, vcc row_shr:4 row_mask:0xf bank_mask:0xf bound_ctrl:1
	v_cndmask_b32_dpp v137, v115, v113, vcc row_shr:4 row_mask:0xf bank_mask:0xf bound_ctrl:1
	v_mfma_scale_f32_16x16x128_f8f6f4 v[216:219], v[140:143], v[204:211], v[216:219], v240, v241 op_sel_hi:[0,0,0] cbsz:4
	v_add_f32_e32 v255, v215, v255
	v_mul_f32_e32 v192, v252, v252
	v_mul_f32_e32 v193, v254, v254
	v_and_b32_e32 v204, v186, v235
	v_and_b32_e32 v205, v186, v236
	v_and_b32_e32 v206, v186, v237
	v_and_b32_e32 v207, v186, v238
	v_and_b32_e32 v208, v187, v235
	v_and_b32_e32 v209, v187, v236
	v_and_b32_e32 v210, v187, v237
	v_and_b32_e32 v211, v187, v238
	s_mov_b64 vcc, s[6:7]
	v_cndmask_b32_dpp v140, v118, v116, vcc row_shr:4 row_mask:0xf bank_mask:0xf bound_ctrl:1
	v_cndmask_b32_dpp v141, v119, v117, vcc row_shr:4 row_mask:0xf bank_mask:0xf bound_ctrl:1
	s_mov_b64 vcc, s[4:5]
	v_cndmask_b32_dpp v142, v116, v118, vcc row_shl:4 row_mask:0xf bank_mask:0xf bound_ctrl:1
	v_cndmask_b32_dpp v143, v117, v119, vcc row_shl:4 row_mask:0xf bank_mask:0xf bound_ctrl:1
	v_mfma_scale_f32_16x16x128_f8f6f4 v[216:219], v[136:139], v[144:151], v[216:219], v240, v241 op_sel_hi:[0,0,0] cbsz:4
	v_fmac_f32_e32 v192, v253, v253
	v_fmac_f32_e32 v193, v255, v255
	v_cvt_pk_bf16_f32 v250, v252, v253
	v_and_b32_e32 v144, v188, v235
	v_and_b32_e32 v145, v188, v236
	v_and_b32_e32 v146, v188, v237
	v_and_b32_e32 v147, v188, v238
	v_and_b32_e32 v148, v189, v235
	v_and_b32_e32 v149, v189, v236
	v_and_b32_e32 v150, v189, v237
	v_and_b32_e32 v151, v189, v238
	s_mov_b64 vcc, s[4:5]
	v_cndmask_b32_dpp v138, v120, v122, vcc row_shl:4 row_mask:0xf bank_mask:0xf bound_ctrl:1
	v_cndmask_b32_dpp v139, v121, v123, vcc row_shl:4 row_mask:0xf bank_mask:0xf bound_ctrl:1
	s_mov_b64 vcc, s[6:7]
	v_cndmask_b32_dpp v136, v122, v120, vcc row_shr:4 row_mask:0xf bank_mask:0xf bound_ctrl:1
	v_cndmask_b32_dpp v137, v123, v121, vcc row_shr:4 row_mask:0xf bank_mask:0xf bound_ctrl:1
	v_mfma_scale_f32_16x16x128_f8f6f4 v[216:219], v[140:143], v[204:211], v[216:219], v240, v241 op_sel_hi:[0,0,0] cbsz:4
	v_cvt_pk_bf16_f32 v251, v254, v255
	v_add_f32_e32 v192, v192, v193
	v_add_f32_e32 v222, v222, v192
	v_and_b32_e32 v204, v190, v235
	v_and_b32_e32 v205, v190, v236
	v_and_b32_e32 v206, v190, v237
	v_and_b32_e32 v207, v190, v238
	v_and_b32_e32 v208, v191, v235
	v_and_b32_e32 v209, v191, v236
	v_and_b32_e32 v210, v191, v237
	v_and_b32_e32 v211, v191, v238
	s_mov_b64 vcc, s[6:7]
	v_cndmask_b32_dpp v140, v126, v124, vcc row_shr:4 row_mask:0xf bank_mask:0xf bound_ctrl:1
	v_cndmask_b32_dpp v141, v127, v125, vcc row_shr:4 row_mask:0xf bank_mask:0xf bound_ctrl:1
	s_mov_b64 vcc, s[4:5]
	v_cndmask_b32_dpp v142, v124, v126, vcc row_shl:4 row_mask:0xf bank_mask:0xf bound_ctrl:1
	v_cndmask_b32_dpp v143, v125, v127, vcc row_shl:4 row_mask:0xf bank_mask:0xf bound_ctrl:1
	v_mfma_scale_f32_16x16x128_f8f6f4 v[216:219], v[136:139], v[144:151], v[216:219], v240, v241 op_sel_hi:[0,0,0] cbsz:4
	s_nop 0
	v_mfma_scale_f32_16x16x128_f8f6f4 v[216:219], v[140:143], v[204:211], v[216:219], v240, v241 op_sel_hi:[0,0,0] cbsz:4
	s_lshl_b32 s64, s0, 9
	s_add_u32 s64, s64, 0x2000
	s_add_u32 s76, s28, s64
	s_addc_u32 s77, s29, 0
	global_store_dwordx2 v239, v[250:251], s[76:77]
	s_lshl_b32 s64, s0, 9
	s_add_u32 s64, s64, 0x4000
	s_add_u32 s70, s28, s64
	s_addc_u32 s71, s29, 0
	global_load_dwordx2 v[228:229], v239, s[70:71]
	s_waitcnt lgkmcnt(0)
	v_lshl_or_b32 v128, v128, 7, v232
	v_lshl_or_b32 v129, v129, 7, v232
	v_lshl_or_b32 v130, v130, 7, v232
	v_lshl_or_b32 v131, v131, 7, v232
	v_lshl_or_b32 v132, v132, 7, v232
	v_lshl_or_b32 v133, v133, 7, v232
	v_lshl_or_b32 v134, v134, 7, v232
	v_lshl_or_b32 v135, v135, 7, v232
	buffer_load_dwordx4 v[96:99], v128, s[20:23], s1 offen
	buffer_load_dwordx4 v[100:103], v129, s[20:23], s1 offen
	buffer_load_dwordx4 v[104:107], v130, s[20:23], s1 offen
	buffer_load_dwordx4 v[108:111], v131, s[20:23], s1 offen
	buffer_load_dwordx4 v[112:115], v132, s[20:23], s1 offen
	buffer_load_dwordx4 v[116:119], v133, s[20:23], s1 offen
	buffer_load_dwordx4 v[120:123], v134, s[20:23], s1 offen
	buffer_load_dwordx4 v[124:127], v135, s[20:23], s1 offen
	ds_read_b32 v128, v243 offset:3072
	ds_read_b32 v129, v243 offset:3104
	ds_read_b32 v130, v243 offset:3136
	ds_read_b32 v131, v243 offset:3168
	ds_read_b32 v132, v243 offset:3200
	ds_read_b32 v133, v243 offset:3232
	ds_read_b32 v134, v243 offset:3264
	ds_read_b32 v135, v243 offset:3296
	ds_read_b64 v[176:177], v234 offset:2304
	ds_read_b64 v[178:179], v234 offset:2336
	ds_read_b64 v[180:181], v234 offset:2368
	ds_read_b64 v[182:183], v234 offset:2400
	ds_read_b64 v[184:185], v234 offset:2432
	ds_read_b64 v[186:187], v234 offset:2464
	ds_read_b64 v[188:189], v234 offset:2496
	ds_read_b64 v[190:191], v234 offset:2528
	s_waitcnt vmcnt(28)
	v_and_b32_e32 v144, v160, v235
	v_and_b32_e32 v145, v160, v236
	v_and_b32_e32 v146, v160, v237
	v_and_b32_e32 v147, v160, v238
	v_and_b32_e32 v148, v161, v235
	v_and_b32_e32 v149, v161, v236
	v_and_b32_e32 v150, v161, v237
	v_and_b32_e32 v151, v161, v238
	s_mov_b64 vcc, s[4:5]
	v_cndmask_b32_dpp v138, v0, v2, vcc row_shl:4 row_mask:0xf bank_mask:0xf bound_ctrl:1
	v_cndmask_b32_dpp v139, v1, v3, vcc row_shl:4 row_mask:0xf bank_mask:0xf bound_ctrl:1
	s_mov_b64 vcc, s[6:7]
	v_cndmask_b32_dpp v136, v2, v0, vcc row_shr:4 row_mask:0xf bank_mask:0xf bound_ctrl:1
	v_cndmask_b32_dpp v137, v3, v1, vcc row_shr:4 row_mask:0xf bank_mask:0xf bound_ctrl:1
	v_and_b32_e32 v204, v162, v235
	v_and_b32_e32 v205, v162, v236
	v_and_b32_e32 v206, v162, v237
	v_and_b32_e32 v207, v162, v238
	v_and_b32_e32 v208, v163, v235
	v_and_b32_e32 v209, v163, v236
	v_and_b32_e32 v210, v163, v237
	v_and_b32_e32 v211, v163, v238
	s_mov_b64 vcc, s[6:7]
	v_cndmask_b32_dpp v140, v6, v4, vcc row_shr:4 row_mask:0xf bank_mask:0xf bound_ctrl:1
	v_cndmask_b32_dpp v141, v7, v5, vcc row_shr:4 row_mask:0xf bank_mask:0xf bound_ctrl:1
	s_mov_b64 vcc, s[4:5]
	v_cndmask_b32_dpp v142, v4, v6, vcc row_shl:4 row_mask:0xf bank_mask:0xf bound_ctrl:1
	v_cndmask_b32_dpp v143, v5, v7, vcc row_shl:4 row_mask:0xf bank_mask:0xf bound_ctrl:1
	v_mfma_scale_f32_16x16x128_f8f6f4 v[212:215], v[136:139], v[144:151], 0, v240, v241 op_sel_hi:[0,0,0] cbsz:4
	v_and_b32_e32 v144, v164, v235
	v_and_b32_e32 v145, v164, v236
	v_and_b32_e32 v146, v164, v237
	v_and_b32_e32 v147, v164, v238
	v_and_b32_e32 v148, v165, v235
	v_and_b32_e32 v149, v165, v236
	v_and_b32_e32 v150, v165, v237
	v_and_b32_e32 v151, v165, v238
	s_mov_b64 vcc, s[4:5]
	v_cndmask_b32_dpp v138, v8, v10, vcc row_shl:4 row_mask:0xf bank_mask:0xf bound_ctrl:1
	v_cndmask_b32_dpp v139, v9, v11, vcc row_shl:4 row_mask:0xf bank_mask:0xf bound_ctrl:1
	s_mov_b64 vcc, s[6:7]
	v_cndmask_b32_dpp v136, v10, v8, vcc row_shr:4 row_mask:0xf bank_mask:0xf bound_ctrl:1
	v_cndmask_b32_dpp v137, v11, v9, vcc row_shr:4 row_mask:0xf bank_mask:0xf bound_ctrl:1
	v_mfma_scale_f32_16x16x128_f8f6f4 v[212:215], v[140:143], v[204:211], v[212:215], v240, v241 op_sel_hi:[0,0,0] cbsz:4
	v_and_b32_e32 v204, v166, v235
	v_and_b32_e32 v205, v166, v236
	v_and_b32_e32 v206, v166, v237
	v_and_b32_e32 v207, v166, v238
	v_and_b32_e32 v208, v167, v235
	v_and_b32_e32 v209, v167, v236
	v_and_b32_e32 v210, v167, v237
	v_and_b32_e32 v211, v167, v238
	s_mov_b64 vcc, s[6:7]
	v_cndmask_b32_dpp v140, v14, v12, vcc row_shr:4 row_mask:0xf bank_mask:0xf bound_ctrl:1
	v_cndmask_b32_dpp v141, v15, v13, vcc row_shr:4 row_mask:0xf bank_mask:0xf bound_ctrl:1
	s_mov_b64 vcc, s[4:5]
	v_cndmask_b32_dpp v142, v12, v14, vcc row_shl:4 row_mask:0xf bank_mask:0xf bound_ctrl:1
	v_cndmask_b32_dpp v143, v13, v15, vcc row_shl:4 row_mask:0xf bank_mask:0xf bound_ctrl:1
	v_mfma_scale_f32_16x16x128_f8f6f4 v[212:215], v[136:139], v[144:151], v[212:215], v240, v241 op_sel_hi:[0,0,0] cbsz:4
	v_and_b32_e32 v144, v168, v235
	v_and_b32_e32 v145, v168, v236
	v_and_b32_e32 v146, v168, v237
	v_and_b32_e32 v147, v168, v238
	v_and_b32_e32 v148, v169, v235
	v_and_b32_e32 v149, v169, v236
	v_and_b32_e32 v150, v169, v237
	v_and_b32_e32 v151, v169, v238
	s_mov_b64 vcc, s[4:5]
	v_cndmask_b32_dpp v138, v16, v18, vcc row_shl:4 row_mask:0xf bank_mask:0xf bound_ctrl:1
	v_cndmask_b32_dpp v139, v17, v19, vcc row_shl:4 row_mask:0xf bank_mask:0xf bound_ctrl:1
	s_mov_b64 vcc, s[6:7]
	v_cndmask_b32_dpp v136, v18, v16, vcc row_shr:4 row_mask:0xf bank_mask:0xf bound_ctrl:1
	v_cndmask_b32_dpp v137, v19, v17, vcc row_shr:4 row_mask:0xf bank_mask:0xf bound_ctrl:1
	v_mfma_scale_f32_16x16x128_f8f6f4 v[212:215], v[140:143], v[204:211], v[212:215], v240, v241 op_sel_hi:[0,0,0] cbsz:4
	v_and_b32_e32 v204, v170, v235
	v_and_b32_e32 v205, v170, v236
	v_and_b32_e32 v206, v170, v237
	v_and_b32_e32 v207, v170, v238
	v_and_b32_e32 v208, v171, v235
	v_and_b32_e32 v209, v171, v236
	v_and_b32_e32 v210, v171, v237
	v_and_b32_e32 v211, v171, v238
	s_mov_b64 vcc, s[6:7]
	v_cndmask_b32_dpp v140, v22, v20, vcc row_shr:4 row_mask:0xf bank_mask:0xf bound_ctrl:1
	v_cndmask_b32_dpp v141, v23, v21, vcc row_shr:4 row_mask:0xf bank_mask:0xf bound_ctrl:1
	s_mov_b64 vcc, s[4:5]
	v_cndmask_b32_dpp v142, v20, v22, vcc row_shl:4 row_mask:0xf bank_mask:0xf bound_ctrl:1
	v_cndmask_b32_dpp v143, v21, v23, vcc row_shl:4 row_mask:0xf bank_mask:0xf bound_ctrl:1
	v_mfma_scale_f32_16x16x128_f8f6f4 v[212:215], v[136:139], v[144:151], v[212:215], v240, v241 op_sel_hi:[0,0,0] cbsz:4
	v_and_b32_e32 v144, v172, v235
	v_and_b32_e32 v145, v172, v236
	v_and_b32_e32 v146, v172, v237
	v_and_b32_e32 v147, v172, v238
	v_and_b32_e32 v148, v173, v235
	v_and_b32_e32 v149, v173, v236
	v_and_b32_e32 v150, v173, v237
	v_and_b32_e32 v151, v173, v238
	s_mov_b64 vcc, s[4:5]
	v_cndmask_b32_dpp v138, v24, v26, vcc row_shl:4 row_mask:0xf bank_mask:0xf bound_ctrl:1
	v_cndmask_b32_dpp v139, v25, v27, vcc row_shl:4 row_mask:0xf bank_mask:0xf bound_ctrl:1
	s_mov_b64 vcc, s[6:7]
	v_cndmask_b32_dpp v136, v26, v24, vcc row_shr:4 row_mask:0xf bank_mask:0xf bound_ctrl:1
	v_cndmask_b32_dpp v137, v27, v25, vcc row_shr:4 row_mask:0xf bank_mask:0xf bound_ctrl:1
	v_mfma_scale_f32_16x16x128_f8f6f4 v[212:215], v[140:143], v[204:211], v[212:215], v240, v241 op_sel_hi:[0,0,0] cbsz:4
	v_and_b32_e32 v204, v174, v235
	v_and_b32_e32 v205, v174, v236
	v_and_b32_e32 v206, v174, v237
	v_and_b32_e32 v207, v174, v238
	v_and_b32_e32 v208, v175, v235
	v_and_b32_e32 v209, v175, v236
	v_and_b32_e32 v210, v175, v237
	v_and_b32_e32 v211, v175, v238
	s_mov_b64 vcc, s[6:7]
	v_cndmask_b32_dpp v140, v30, v28, vcc row_shr:4 row_mask:0xf bank_mask:0xf bound_ctrl:1
	v_cndmask_b32_dpp v141, v31, v29, vcc row_shr:4 row_mask:0xf bank_mask:0xf bound_ctrl:1
	s_mov_b64 vcc, s[4:5]
	v_cndmask_b32_dpp v142, v28, v30, vcc row_shl:4 row_mask:0xf bank_mask:0xf bound_ctrl:1
	v_cndmask_b32_dpp v143, v29, v31, vcc row_shl:4 row_mask:0xf bank_mask:0xf bound_ctrl:1
	v_mfma_scale_f32_16x16x128_f8f6f4 v[212:215], v[136:139], v[144:151], v[212:215], v240, v241 op_sel_hi:[0,0,0] cbsz:4
	s_nop 0
	v_mfma_scale_f32_16x16x128_f8f6f4 v[212:215], v[140:143], v[204:211], v[212:215], v240, v241 op_sel_hi:[0,0,0] cbsz:4
	s_waitcnt lgkmcnt(0)
	v_lshl_or_b32 v128, v128, 7, v232
	v_lshl_or_b32 v129, v129, 7, v232
	v_lshl_or_b32 v130, v130, 7, v232
	v_lshl_or_b32 v131, v131, 7, v232
	v_lshl_or_b32 v132, v132, 7, v232
	v_lshl_or_b32 v133, v133, 7, v232
	v_lshl_or_b32 v134, v134, 7, v232
	v_lshl_or_b32 v135, v135, 7, v232
	buffer_load_dwordx4 v[0:3], v128, s[20:23], s1 offen
	buffer_load_dwordx4 v[4:7], v129, s[20:23], s1 offen
	buffer_load_dwordx4 v[8:11], v130, s[20:23], s1 offen
	buffer_load_dwordx4 v[12:15], v131, s[20:23], s1 offen
	buffer_load_dwordx4 v[16:19], v132, s[20:23], s1 offen
	buffer_load_dwordx4 v[20:23], v133, s[20:23], s1 offen
	buffer_load_dwordx4 v[24:27], v134, s[20:23], s1 offen
	buffer_load_dwordx4 v[28:31], v135, s[20:23], s1 offen
	ds_read_b32 v128, v243 offset:3328
	ds_read_b32 v129, v243 offset:3360
	ds_read_b32 v130, v243 offset:3392
	ds_read_b32 v131, v243 offset:3424
	ds_read_b32 v132, v243 offset:3456
	ds_read_b32 v133, v243 offset:3488
	ds_read_b32 v134, v243 offset:3520
	ds_read_b32 v135, v243 offset:3552
	ds_read_b64 v[160:161], v234 offset:2560
	ds_read_b64 v[162:163], v234 offset:2592
	ds_read_b64 v[164:165], v234 offset:2624
	ds_read_b64 v[166:167], v234 offset:2656
	ds_read_b64 v[168:169], v234 offset:2688
	ds_read_b64 v[170:171], v234 offset:2720
	ds_read_b64 v[172:173], v234 offset:2752
	ds_read_b64 v[174:175], v234 offset:2784
	s_waitcnt vmcnt(26)
	v_and_b32_e32 v144, v176, v235
	v_and_b32_e32 v145, v176, v236
	v_and_b32_e32 v146, v176, v237
	v_and_b32_e32 v147, v176, v238
	v_and_b32_e32 v148, v177, v235
	v_and_b32_e32 v149, v177, v236
	v_and_b32_e32 v150, v177, v237
	v_and_b32_e32 v151, v177, v238
	s_mov_b64 vcc, s[4:5]
	v_cndmask_b32_dpp v138, v32, v34, vcc row_shl:4 row_mask:0xf bank_mask:0xf bound_ctrl:1
	v_cndmask_b32_dpp v139, v33, v35, vcc row_shl:4 row_mask:0xf bank_mask:0xf bound_ctrl:1
	s_mov_b64 vcc, s[6:7]
	v_cndmask_b32_dpp v136, v34, v32, vcc row_shr:4 row_mask:0xf bank_mask:0xf bound_ctrl:1
	v_cndmask_b32_dpp v137, v35, v33, vcc row_shr:4 row_mask:0xf bank_mask:0xf bound_ctrl:1
	v_and_b32_e32 v204, v178, v235
	v_and_b32_e32 v205, v178, v236
	v_and_b32_e32 v206, v178, v237
	v_and_b32_e32 v207, v178, v238
	v_and_b32_e32 v208, v179, v235
	v_and_b32_e32 v209, v179, v236
	v_and_b32_e32 v210, v179, v237
	v_and_b32_e32 v211, v179, v238
	s_mov_b64 vcc, s[6:7]
	v_cndmask_b32_dpp v140, v38, v36, vcc row_shr:4 row_mask:0xf bank_mask:0xf bound_ctrl:1
	v_cndmask_b32_dpp v141, v39, v37, vcc row_shr:4 row_mask:0xf bank_mask:0xf bound_ctrl:1
	s_mov_b64 vcc, s[4:5]
	v_cndmask_b32_dpp v142, v36, v38, vcc row_shl:4 row_mask:0xf bank_mask:0xf bound_ctrl:1
	v_cndmask_b32_dpp v143, v37, v39, vcc row_shl:4 row_mask:0xf bank_mask:0xf bound_ctrl:1
	v_mfma_scale_f32_16x16x128_f8f6f4 v[212:215], v[136:139], v[144:151], v[212:215], v240, v241 op_sel_hi:[0,0,0] cbsz:4
	v_permlane16_swap_b32_e32 v216, v218
	v_permlane16_swap_b32_e32 v217, v219
	v_lshlrev_b32_e32 v252, 16, v230
	v_and_b32_e32 v144, v180, v235
	v_and_b32_e32 v145, v180, v236
	v_and_b32_e32 v146, v180, v237
	v_and_b32_e32 v147, v180, v238
	v_and_b32_e32 v148, v181, v235
	v_and_b32_e32 v149, v181, v236
	v_and_b32_e32 v150, v181, v237
	v_and_b32_e32 v151, v181, v238
	s_mov_b64 vcc, s[4:5]
	v_cndmask_b32_dpp v138, v40, v42, vcc row_shl:4 row_mask:0xf bank_mask:0xf bound_ctrl:1
	v_cndmask_b32_dpp v139, v41, v43, vcc row_shl:4 row_mask:0xf bank_mask:0xf bound_ctrl:1
	s_mov_b64 vcc, s[6:7]
	v_cndmask_b32_dpp v136, v42, v40, vcc row_shr:4 row_mask:0xf bank_mask:0xf bound_ctrl:1
	v_cndmask_b32_dpp v137, v43, v41, vcc row_shr:4 row_mask:0xf bank_mask:0xf bound_ctrl:1
	v_mfma_scale_f32_16x16x128_f8f6f4 v[212:215], v[140:143], v[204:211], v[212:215], v240, v241 op_sel_hi:[0,0,0] cbsz:4
	v_and_b32_e32 v253, 0xffff0000, v230
	v_lshlrev_b32_e32 v254, 16, v231
	v_and_b32_e32 v255, 0xffff0000, v231
	v_and_b32_e32 v204, v182, v235
	v_and_b32_e32 v205, v182, v236
	v_and_b32_e32 v206, v182, v237
	v_and_b32_e32 v207, v182, v238
	v_and_b32_e32 v208, v183, v235
	v_and_b32_e32 v209, v183, v236
	v_and_b32_e32 v210, v183, v237
	v_and_b32_e32 v211, v183, v238
	s_mov_b64 vcc, s[6:7]
	v_cndmask_b32_dpp v140, v46, v44, vcc row_shr:4 row_mask:0xf bank_mask:0xf bound_ctrl:1
	v_cndmask_b32_dpp v141, v47, v45, vcc row_shr:4 row_mask:0xf bank_mask:0xf bound_ctrl:1
	s_mov_b64 vcc, s[4:5]
	v_cndmask_b32_dpp v142, v44, v46, vcc row_shl:4 row_mask:0xf bank_mask:0xf bound_ctrl:1
	v_cndmask_b32_dpp v143, v45, v47, vcc row_shl:4 row_mask:0xf bank_mask:0xf bound_ctrl:1
	v_mfma_scale_f32_16x16x128_f8f6f4 v[212:215], v[136:139], v[144:151], v[212:215], v240, v241 op_sel_hi:[0,0,0] cbsz:4
	v_add_f32_e32 v252, v216, v252
	v_add_f32_e32 v253, v218, v253
	v_add_f32_e32 v254, v217, v254
	v_and_b32_e32 v144, v184, v235
	v_and_b32_e32 v145, v184, v236
	v_and_b32_e32 v146, v184, v237
	v_and_b32_e32 v147, v184, v238
	v_and_b32_e32 v148, v185, v235
	v_and_b32_e32 v149, v185, v236
	v_and_b32_e32 v150, v185, v237
	v_and_b32_e32 v151, v185, v238
	s_mov_b64 vcc, s[4:5]
	v_cndmask_b32_dpp v138, v48, v50, vcc row_shl:4 row_mask:0xf bank_mask:0xf bound_ctrl:1
	v_cndmask_b32_dpp v139, v49, v51, vcc row_shl:4 row_mask:0xf bank_mask:0xf bound_ctrl:1
	s_mov_b64 vcc, s[6:7]
	v_cndmask_b32_dpp v136, v50, v48, vcc row_shr:4 row_mask:0xf bank_mask:0xf bound_ctrl:1
	v_cndmask_b32_dpp v137, v51, v49, vcc row_shr:4 row_mask:0xf bank_mask:0xf bound_ctrl:1
	v_mfma_scale_f32_16x16x128_f8f6f4 v[212:215], v[140:143], v[204:211], v[212:215], v240, v241 op_sel_hi:[0,0,0] cbsz:4
	v_add_f32_e32 v255, v219, v255
	v_mul_f32_e32 v192, v252, v252
	v_mul_f32_e32 v193, v254, v254
	v_and_b32_e32 v204, v186, v235
	v_and_b32_e32 v205, v186, v236
	v_and_b32_e32 v206, v186, v237
	v_and_b32_e32 v207, v186, v238
	v_and_b32_e32 v208, v187, v235
	v_and_b32_e32 v209, v187, v236
	v_and_b32_e32 v210, v187, v237
	v_and_b32_e32 v211, v187, v238
	s_mov_b64 vcc, s[6:7]
	v_cndmask_b32_dpp v140, v54, v52, vcc row_shr:4 row_mask:0xf bank_mask:0xf bound_ctrl:1
	v_cndmask_b32_dpp v141, v55, v53, vcc row_shr:4 row_mask:0xf bank_mask:0xf bound_ctrl:1
	s_mov_b64 vcc, s[4:5]
	v_cndmask_b32_dpp v142, v52, v54, vcc row_shl:4 row_mask:0xf bank_mask:0xf bound_ctrl:1
	v_cndmask_b32_dpp v143, v53, v55, vcc row_shl:4 row_mask:0xf bank_mask:0xf bound_ctrl:1
	v_mfma_scale_f32_16x16x128_f8f6f4 v[212:215], v[136:139], v[144:151], v[212:215], v240, v241 op_sel_hi:[0,0,0] cbsz:4
	v_fmac_f32_e32 v192, v253, v253
	v_fmac_f32_e32 v193, v255, v255
	v_cvt_pk_bf16_f32 v250, v252, v253
	v_and_b32_e32 v144, v188, v235
	v_and_b32_e32 v145, v188, v236
	v_and_b32_e32 v146, v188, v237
	v_and_b32_e32 v147, v188, v238
	v_and_b32_e32 v148, v189, v235
	v_and_b32_e32 v149, v189, v236
	v_and_b32_e32 v150, v189, v237
	v_and_b32_e32 v151, v189, v238
	s_mov_b64 vcc, s[4:5]
	v_cndmask_b32_dpp v138, v56, v58, vcc row_shl:4 row_mask:0xf bank_mask:0xf bound_ctrl:1
	v_cndmask_b32_dpp v139, v57, v59, vcc row_shl:4 row_mask:0xf bank_mask:0xf bound_ctrl:1
	s_mov_b64 vcc, s[6:7]
	v_cndmask_b32_dpp v136, v58, v56, vcc row_shr:4 row_mask:0xf bank_mask:0xf bound_ctrl:1
	v_cndmask_b32_dpp v137, v59, v57, vcc row_shr:4 row_mask:0xf bank_mask:0xf bound_ctrl:1
	v_mfma_scale_f32_16x16x128_f8f6f4 v[212:215], v[140:143], v[204:211], v[212:215], v240, v241 op_sel_hi:[0,0,0] cbsz:4
	v_cvt_pk_bf16_f32 v251, v254, v255
	v_add_f32_e32 v192, v192, v193
	v_add_f32_e32 v223, v223, v192
	v_and_b32_e32 v204, v190, v235
	v_and_b32_e32 v205, v190, v236
	v_and_b32_e32 v206, v190, v237
	v_and_b32_e32 v207, v190, v238
	v_and_b32_e32 v208, v191, v235
	v_and_b32_e32 v209, v191, v236
	v_and_b32_e32 v210, v191, v237
	v_and_b32_e32 v211, v191, v238
	s_mov_b64 vcc, s[6:7]
	v_cndmask_b32_dpp v140, v62, v60, vcc row_shr:4 row_mask:0xf bank_mask:0xf bound_ctrl:1
	v_cndmask_b32_dpp v141, v63, v61, vcc row_shr:4 row_mask:0xf bank_mask:0xf bound_ctrl:1
	s_mov_b64 vcc, s[4:5]
	v_cndmask_b32_dpp v142, v60, v62, vcc row_shl:4 row_mask:0xf bank_mask:0xf bound_ctrl:1
	v_cndmask_b32_dpp v143, v61, v63, vcc row_shl:4 row_mask:0xf bank_mask:0xf bound_ctrl:1
	v_mfma_scale_f32_16x16x128_f8f6f4 v[212:215], v[136:139], v[144:151], v[212:215], v240, v241 op_sel_hi:[0,0,0] cbsz:4
	s_nop 0
	v_mfma_scale_f32_16x16x128_f8f6f4 v[212:215], v[140:143], v[204:211], v[212:215], v240, v241 op_sel_hi:[0,0,0] cbsz:4
	s_lshl_b32 s64, s0, 9
	s_add_u32 s64, s64, 0x3000
	s_add_u32 s76, s28, s64
	s_addc_u32 s77, s29, 0
	global_store_dwordx2 v239, v[250:251], s[76:77]
	s_lshl_b32 s64, s0, 9
	s_add_u32 s64, s64, 0x5000
	s_add_u32 s70, s28, s64
	s_addc_u32 s71, s29, 0
	global_load_dwordx2 v[230:231], v239, s[70:71]
	s_waitcnt lgkmcnt(0)
	v_lshl_or_b32 v128, v128, 7, v232
	v_lshl_or_b32 v129, v129, 7, v232
	v_lshl_or_b32 v130, v130, 7, v232
	v_lshl_or_b32 v131, v131, 7, v232
	v_lshl_or_b32 v132, v132, 7, v232
	v_lshl_or_b32 v133, v133, 7, v232
	v_lshl_or_b32 v134, v134, 7, v232
	v_lshl_or_b32 v135, v135, 7, v232
	buffer_load_dwordx4 v[32:35], v128, s[20:23], s1 offen
	buffer_load_dwordx4 v[36:39], v129, s[20:23], s1 offen
	buffer_load_dwordx4 v[40:43], v130, s[20:23], s1 offen
	buffer_load_dwordx4 v[44:47], v131, s[20:23], s1 offen
	buffer_load_dwordx4 v[48:51], v132, s[20:23], s1 offen
	buffer_load_dwordx4 v[52:55], v133, s[20:23], s1 offen
	buffer_load_dwordx4 v[56:59], v134, s[20:23], s1 offen
	buffer_load_dwordx4 v[60:63], v135, s[20:23], s1 offen
	ds_read_b32 v128, v243 offset:3584
	ds_read_b32 v129, v243 offset:3616
	ds_read_b32 v130, v243 offset:3648
	ds_read_b32 v131, v243 offset:3680
	ds_read_b32 v132, v243 offset:3712
	ds_read_b32 v133, v243 offset:3744
	ds_read_b32 v134, v243 offset:3776
	ds_read_b32 v135, v243 offset:3808
	ds_read_b64 v[176:177], v234 offset:2816
	ds_read_b64 v[178:179], v234 offset:2848
	ds_read_b64 v[180:181], v234 offset:2880
	ds_read_b64 v[182:183], v234 offset:2912
	ds_read_b64 v[184:185], v234 offset:2944
	ds_read_b64 v[186:187], v234 offset:2976
	ds_read_b64 v[188:189], v234 offset:3008
	ds_read_b64 v[190:191], v234 offset:3040
	s_waitcnt vmcnt(28)
	v_and_b32_e32 v144, v160, v235
	v_and_b32_e32 v145, v160, v236
	v_and_b32_e32 v146, v160, v237
	v_and_b32_e32 v147, v160, v238
	v_and_b32_e32 v148, v161, v235
	v_and_b32_e32 v149, v161, v236
	v_and_b32_e32 v150, v161, v237
	v_and_b32_e32 v151, v161, v238
	s_mov_b64 vcc, s[4:5]
	v_cndmask_b32_dpp v138, v64, v66, vcc row_shl:4 row_mask:0xf bank_mask:0xf bound_ctrl:1
	v_cndmask_b32_dpp v139, v65, v67, vcc row_shl:4 row_mask:0xf bank_mask:0xf bound_ctrl:1
	s_mov_b64 vcc, s[6:7]
	v_cndmask_b32_dpp v136, v66, v64, vcc row_shr:4 row_mask:0xf bank_mask:0xf bound_ctrl:1
	v_cndmask_b32_dpp v137, v67, v65, vcc row_shr:4 row_mask:0xf bank_mask:0xf bound_ctrl:1
	v_and_b32_e32 v204, v162, v235
	v_and_b32_e32 v205, v162, v236
	v_and_b32_e32 v206, v162, v237
	v_and_b32_e32 v207, v162, v238
	v_and_b32_e32 v208, v163, v235
	v_and_b32_e32 v209, v163, v236
	v_and_b32_e32 v210, v163, v237
	v_and_b32_e32 v211, v163, v238
	s_mov_b64 vcc, s[6:7]
	v_cndmask_b32_dpp v140, v70, v68, vcc row_shr:4 row_mask:0xf bank_mask:0xf bound_ctrl:1
	v_cndmask_b32_dpp v141, v71, v69, vcc row_shr:4 row_mask:0xf bank_mask:0xf bound_ctrl:1
	s_mov_b64 vcc, s[4:5]
	v_cndmask_b32_dpp v142, v68, v70, vcc row_shl:4 row_mask:0xf bank_mask:0xf bound_ctrl:1
	v_cndmask_b32_dpp v143, v69, v71, vcc row_shl:4 row_mask:0xf bank_mask:0xf bound_ctrl:1
	v_mfma_scale_f32_16x16x128_f8f6f4 v[216:219], v[136:139], v[144:151], 0, v240, v241 op_sel_hi:[0,0,0] cbsz:4
	v_and_b32_e32 v144, v164, v235
	v_and_b32_e32 v145, v164, v236
	v_and_b32_e32 v146, v164, v237
	v_and_b32_e32 v147, v164, v238
	v_and_b32_e32 v148, v165, v235
	v_and_b32_e32 v149, v165, v236
	v_and_b32_e32 v150, v165, v237
	v_and_b32_e32 v151, v165, v238
	s_mov_b64 vcc, s[4:5]
	v_cndmask_b32_dpp v138, v72, v74, vcc row_shl:4 row_mask:0xf bank_mask:0xf bound_ctrl:1
	v_cndmask_b32_dpp v139, v73, v75, vcc row_shl:4 row_mask:0xf bank_mask:0xf bound_ctrl:1
	s_mov_b64 vcc, s[6:7]
	v_cndmask_b32_dpp v136, v74, v72, vcc row_shr:4 row_mask:0xf bank_mask:0xf bound_ctrl:1
	v_cndmask_b32_dpp v137, v75, v73, vcc row_shr:4 row_mask:0xf bank_mask:0xf bound_ctrl:1
	v_mfma_scale_f32_16x16x128_f8f6f4 v[216:219], v[140:143], v[204:211], v[216:219], v240, v241 op_sel_hi:[0,0,0] cbsz:4
	v_and_b32_e32 v204, v166, v235
	v_and_b32_e32 v205, v166, v236
	v_and_b32_e32 v206, v166, v237
	v_and_b32_e32 v207, v166, v238
	v_and_b32_e32 v208, v167, v235
	v_and_b32_e32 v209, v167, v236
	v_and_b32_e32 v210, v167, v237
	v_and_b32_e32 v211, v167, v238
	s_mov_b64 vcc, s[6:7]
	v_cndmask_b32_dpp v140, v78, v76, vcc row_shr:4 row_mask:0xf bank_mask:0xf bound_ctrl:1
	v_cndmask_b32_dpp v141, v79, v77, vcc row_shr:4 row_mask:0xf bank_mask:0xf bound_ctrl:1
	s_mov_b64 vcc, s[4:5]
	v_cndmask_b32_dpp v142, v76, v78, vcc row_shl:4 row_mask:0xf bank_mask:0xf bound_ctrl:1
	v_cndmask_b32_dpp v143, v77, v79, vcc row_shl:4 row_mask:0xf bank_mask:0xf bound_ctrl:1
	v_mfma_scale_f32_16x16x128_f8f6f4 v[216:219], v[136:139], v[144:151], v[216:219], v240, v241 op_sel_hi:[0,0,0] cbsz:4
	v_and_b32_e32 v144, v168, v235
	v_and_b32_e32 v145, v168, v236
	v_and_b32_e32 v146, v168, v237
	v_and_b32_e32 v147, v168, v238
	v_and_b32_e32 v148, v169, v235
	v_and_b32_e32 v149, v169, v236
	v_and_b32_e32 v150, v169, v237
	v_and_b32_e32 v151, v169, v238
	s_mov_b64 vcc, s[4:5]
	v_cndmask_b32_dpp v138, v80, v82, vcc row_shl:4 row_mask:0xf bank_mask:0xf bound_ctrl:1
	v_cndmask_b32_dpp v139, v81, v83, vcc row_shl:4 row_mask:0xf bank_mask:0xf bound_ctrl:1
	s_mov_b64 vcc, s[6:7]
	v_cndmask_b32_dpp v136, v82, v80, vcc row_shr:4 row_mask:0xf bank_mask:0xf bound_ctrl:1
	v_cndmask_b32_dpp v137, v83, v81, vcc row_shr:4 row_mask:0xf bank_mask:0xf bound_ctrl:1
	v_mfma_scale_f32_16x16x128_f8f6f4 v[216:219], v[140:143], v[204:211], v[216:219], v240, v241 op_sel_hi:[0,0,0] cbsz:4
	v_and_b32_e32 v204, v170, v235
	v_and_b32_e32 v205, v170, v236
	v_and_b32_e32 v206, v170, v237
	v_and_b32_e32 v207, v170, v238
	v_and_b32_e32 v208, v171, v235
	v_and_b32_e32 v209, v171, v236
	v_and_b32_e32 v210, v171, v237
	v_and_b32_e32 v211, v171, v238
	s_mov_b64 vcc, s[6:7]
	v_cndmask_b32_dpp v140, v86, v84, vcc row_shr:4 row_mask:0xf bank_mask:0xf bound_ctrl:1
	v_cndmask_b32_dpp v141, v87, v85, vcc row_shr:4 row_mask:0xf bank_mask:0xf bound_ctrl:1
	s_mov_b64 vcc, s[4:5]
	v_cndmask_b32_dpp v142, v84, v86, vcc row_shl:4 row_mask:0xf bank_mask:0xf bound_ctrl:1
	v_cndmask_b32_dpp v143, v85, v87, vcc row_shl:4 row_mask:0xf bank_mask:0xf bound_ctrl:1
	v_mfma_scale_f32_16x16x128_f8f6f4 v[216:219], v[136:139], v[144:151], v[216:219], v240, v241 op_sel_hi:[0,0,0] cbsz:4
	v_and_b32_e32 v144, v172, v235
	v_and_b32_e32 v145, v172, v236
	v_and_b32_e32 v146, v172, v237
	v_and_b32_e32 v147, v172, v238
	v_and_b32_e32 v148, v173, v235
	v_and_b32_e32 v149, v173, v236
	v_and_b32_e32 v150, v173, v237
	v_and_b32_e32 v151, v173, v238
	s_mov_b64 vcc, s[4:5]
	v_cndmask_b32_dpp v138, v88, v90, vcc row_shl:4 row_mask:0xf bank_mask:0xf bound_ctrl:1
	v_cndmask_b32_dpp v139, v89, v91, vcc row_shl:4 row_mask:0xf bank_mask:0xf bound_ctrl:1
	s_mov_b64 vcc, s[6:7]
	v_cndmask_b32_dpp v136, v90, v88, vcc row_shr:4 row_mask:0xf bank_mask:0xf bound_ctrl:1
	v_cndmask_b32_dpp v137, v91, v89, vcc row_shr:4 row_mask:0xf bank_mask:0xf bound_ctrl:1
	v_mfma_scale_f32_16x16x128_f8f6f4 v[216:219], v[140:143], v[204:211], v[216:219], v240, v241 op_sel_hi:[0,0,0] cbsz:4
	v_and_b32_e32 v204, v174, v235
	v_and_b32_e32 v205, v174, v236
	v_and_b32_e32 v206, v174, v237
	v_and_b32_e32 v207, v174, v238
	v_and_b32_e32 v208, v175, v235
	v_and_b32_e32 v209, v175, v236
	v_and_b32_e32 v210, v175, v237
	v_and_b32_e32 v211, v175, v238
	s_mov_b64 vcc, s[6:7]
	v_cndmask_b32_dpp v140, v94, v92, vcc row_shr:4 row_mask:0xf bank_mask:0xf bound_ctrl:1
	v_cndmask_b32_dpp v141, v95, v93, vcc row_shr:4 row_mask:0xf bank_mask:0xf bound_ctrl:1
	s_mov_b64 vcc, s[4:5]
	v_cndmask_b32_dpp v142, v92, v94, vcc row_shl:4 row_mask:0xf bank_mask:0xf bound_ctrl:1
	v_cndmask_b32_dpp v143, v93, v95, vcc row_shl:4 row_mask:0xf bank_mask:0xf bound_ctrl:1
	v_mfma_scale_f32_16x16x128_f8f6f4 v[216:219], v[136:139], v[144:151], v[216:219], v240, v241 op_sel_hi:[0,0,0] cbsz:4
	s_nop 0
	v_mfma_scale_f32_16x16x128_f8f6f4 v[216:219], v[140:143], v[204:211], v[216:219], v240, v241 op_sel_hi:[0,0,0] cbsz:4
	s_waitcnt lgkmcnt(0)
	v_lshl_or_b32 v128, v128, 7, v232
	v_lshl_or_b32 v129, v129, 7, v232
	v_lshl_or_b32 v130, v130, 7, v232
	v_lshl_or_b32 v131, v131, 7, v232
	v_lshl_or_b32 v132, v132, 7, v232
	v_lshl_or_b32 v133, v133, 7, v232
	v_lshl_or_b32 v134, v134, 7, v232
	v_lshl_or_b32 v135, v135, 7, v232
	buffer_load_dwordx4 v[64:67], v128, s[20:23], s1 offen
	buffer_load_dwordx4 v[68:71], v129, s[20:23], s1 offen
	buffer_load_dwordx4 v[72:75], v130, s[20:23], s1 offen
	buffer_load_dwordx4 v[76:79], v131, s[20:23], s1 offen
	buffer_load_dwordx4 v[80:83], v132, s[20:23], s1 offen
	buffer_load_dwordx4 v[84:87], v133, s[20:23], s1 offen
	buffer_load_dwordx4 v[88:91], v134, s[20:23], s1 offen
	buffer_load_dwordx4 v[92:95], v135, s[20:23], s1 offen
	ds_read_b32 v128, v243 offset:3840
	ds_read_b32 v129, v243 offset:3872
	ds_read_b32 v130, v243 offset:3904
	ds_read_b32 v131, v243 offset:3936
	ds_read_b32 v132, v243 offset:3968
	ds_read_b32 v133, v243 offset:4000
	ds_read_b32 v134, v243 offset:4032
	ds_read_b32 v135, v243 offset:4064
	ds_read_b64 v[160:161], v234 offset:3072
	ds_read_b64 v[162:163], v234 offset:3104
	ds_read_b64 v[164:165], v234 offset:3136
	ds_read_b64 v[166:167], v234 offset:3168
	ds_read_b64 v[168:169], v234 offset:3200
	ds_read_b64 v[170:171], v234 offset:3232
	ds_read_b64 v[172:173], v234 offset:3264
	ds_read_b64 v[174:175], v234 offset:3296
	s_waitcnt vmcnt(26)
	v_and_b32_e32 v144, v176, v235
	v_and_b32_e32 v145, v176, v236
	v_and_b32_e32 v146, v176, v237
	v_and_b32_e32 v147, v176, v238
	v_and_b32_e32 v148, v177, v235
	v_and_b32_e32 v149, v177, v236
	v_and_b32_e32 v150, v177, v237
	v_and_b32_e32 v151, v177, v238
	s_mov_b64 vcc, s[4:5]
	v_cndmask_b32_dpp v138, v96, v98, vcc row_shl:4 row_mask:0xf bank_mask:0xf bound_ctrl:1
	v_cndmask_b32_dpp v139, v97, v99, vcc row_shl:4 row_mask:0xf bank_mask:0xf bound_ctrl:1
	s_mov_b64 vcc, s[6:7]
	v_cndmask_b32_dpp v136, v98, v96, vcc row_shr:4 row_mask:0xf bank_mask:0xf bound_ctrl:1
	v_cndmask_b32_dpp v137, v99, v97, vcc row_shr:4 row_mask:0xf bank_mask:0xf bound_ctrl:1
	v_and_b32_e32 v204, v178, v235
	v_and_b32_e32 v205, v178, v236
	v_and_b32_e32 v206, v178, v237
	v_and_b32_e32 v207, v178, v238
	v_and_b32_e32 v208, v179, v235
	v_and_b32_e32 v209, v179, v236
	v_and_b32_e32 v210, v179, v237
	v_and_b32_e32 v211, v179, v238
	s_mov_b64 vcc, s[6:7]
	v_cndmask_b32_dpp v140, v102, v100, vcc row_shr:4 row_mask:0xf bank_mask:0xf bound_ctrl:1
	v_cndmask_b32_dpp v141, v103, v101, vcc row_shr:4 row_mask:0xf bank_mask:0xf bound_ctrl:1
	s_mov_b64 vcc, s[4:5]
	v_cndmask_b32_dpp v142, v100, v102, vcc row_shl:4 row_mask:0xf bank_mask:0xf bound_ctrl:1
	v_cndmask_b32_dpp v143, v101, v103, vcc row_shl:4 row_mask:0xf bank_mask:0xf bound_ctrl:1
	v_mfma_scale_f32_16x16x128_f8f6f4 v[216:219], v[136:139], v[144:151], v[216:219], v240, v241 op_sel_hi:[0,0,0] cbsz:4
	v_permlane16_swap_b32_e32 v212, v214
	v_permlane16_swap_b32_e32 v213, v215
	v_lshlrev_b32_e32 v252, 16, v228
	v_and_b32_e32 v144, v180, v235
	v_and_b32_e32 v145, v180, v236
	v_and_b32_e32 v146, v180, v237
	v_and_b32_e32 v147, v180, v238
	v_and_b32_e32 v148, v181, v235
	v_and_b32_e32 v149, v181, v236
	v_and_b32_e32 v150, v181, v237
	v_and_b32_e32 v151, v181, v238
	s_mov_b64 vcc, s[4:5]
	v_cndmask_b32_dpp v138, v104, v106, vcc row_shl:4 row_mask:0xf bank_mask:0xf bound_ctrl:1
	v_cndmask_b32_dpp v139, v105, v107, vcc row_shl:4 row_mask:0xf bank_mask:0xf bound_ctrl:1
	s_mov_b64 vcc, s[6:7]
	v_cndmask_b32_dpp v136, v106, v104, vcc row_shr:4 row_mask:0xf bank_mask:0xf bound_ctrl:1
	v_cndmask_b32_dpp v137, v107, v105, vcc row_shr:4 row_mask:0xf bank_mask:0xf bound_ctrl:1
	v_mfma_scale_f32_16x16x128_f8f6f4 v[216:219], v[140:143], v[204:211], v[216:219], v240, v241 op_sel_hi:[0,0,0] cbsz:4
	v_and_b32_e32 v253, 0xffff0000, v228
	v_lshlrev_b32_e32 v254, 16, v229
	v_and_b32_e32 v255, 0xffff0000, v229
	v_and_b32_e32 v204, v182, v235
	v_and_b32_e32 v205, v182, v236
	v_and_b32_e32 v206, v182, v237
	v_and_b32_e32 v207, v182, v238
	v_and_b32_e32 v208, v183, v235
	v_and_b32_e32 v209, v183, v236
	v_and_b32_e32 v210, v183, v237
	v_and_b32_e32 v211, v183, v238
	s_mov_b64 vcc, s[6:7]
	v_cndmask_b32_dpp v140, v110, v108, vcc row_shr:4 row_mask:0xf bank_mask:0xf bound_ctrl:1
	v_cndmask_b32_dpp v141, v111, v109, vcc row_shr:4 row_mask:0xf bank_mask:0xf bound_ctrl:1
	s_mov_b64 vcc, s[4:5]
	v_cndmask_b32_dpp v142, v108, v110, vcc row_shl:4 row_mask:0xf bank_mask:0xf bound_ctrl:1
	v_cndmask_b32_dpp v143, v109, v111, vcc row_shl:4 row_mask:0xf bank_mask:0xf bound_ctrl:1
	v_mfma_scale_f32_16x16x128_f8f6f4 v[216:219], v[136:139], v[144:151], v[216:219], v240, v241 op_sel_hi:[0,0,0] cbsz:4
	v_add_f32_e32 v252, v212, v252
	v_add_f32_e32 v253, v214, v253
	v_add_f32_e32 v254, v213, v254
	v_and_b32_e32 v144, v184, v235
	v_and_b32_e32 v145, v184, v236
	v_and_b32_e32 v146, v184, v237
	v_and_b32_e32 v147, v184, v238
	v_and_b32_e32 v148, v185, v235
	v_and_b32_e32 v149, v185, v236
	v_and_b32_e32 v150, v185, v237
	v_and_b32_e32 v151, v185, v238
	s_mov_b64 vcc, s[4:5]
	v_cndmask_b32_dpp v138, v112, v114, vcc row_shl:4 row_mask:0xf bank_mask:0xf bound_ctrl:1
	v_cndmask_b32_dpp v139, v113, v115, vcc row_shl:4 row_mask:0xf bank_mask:0xf bound_ctrl:1
	s_mov_b64 vcc, s[6:7]
	v_cndmask_b32_dpp v136, v114, v112, vcc row_shr:4 row_mask:0xf bank_mask:0xf bound_ctrl:1
	v_cndmask_b32_dpp v137, v115, v113, vcc row_shr:4 row_mask:0xf bank_mask:0xf bound_ctrl:1
	v_mfma_scale_f32_16x16x128_f8f6f4 v[216:219], v[140:143], v[204:211], v[216:219], v240, v241 op_sel_hi:[0,0,0] cbsz:4
	v_add_f32_e32 v255, v215, v255
	v_mul_f32_e32 v192, v252, v252
	v_mul_f32_e32 v193, v254, v254
	v_and_b32_e32 v204, v186, v235
	v_and_b32_e32 v205, v186, v236
	v_and_b32_e32 v206, v186, v237
	v_and_b32_e32 v207, v186, v238
	v_and_b32_e32 v208, v187, v235
	v_and_b32_e32 v209, v187, v236
	v_and_b32_e32 v210, v187, v237
	v_and_b32_e32 v211, v187, v238
	s_mov_b64 vcc, s[6:7]
	v_cndmask_b32_dpp v140, v118, v116, vcc row_shr:4 row_mask:0xf bank_mask:0xf bound_ctrl:1
	v_cndmask_b32_dpp v141, v119, v117, vcc row_shr:4 row_mask:0xf bank_mask:0xf bound_ctrl:1
	s_mov_b64 vcc, s[4:5]
	v_cndmask_b32_dpp v142, v116, v118, vcc row_shl:4 row_mask:0xf bank_mask:0xf bound_ctrl:1
	v_cndmask_b32_dpp v143, v117, v119, vcc row_shl:4 row_mask:0xf bank_mask:0xf bound_ctrl:1
	v_mfma_scale_f32_16x16x128_f8f6f4 v[216:219], v[136:139], v[144:151], v[216:219], v240, v241 op_sel_hi:[0,0,0] cbsz:4
	v_fmac_f32_e32 v192, v253, v253
	v_fmac_f32_e32 v193, v255, v255
	v_cvt_pk_bf16_f32 v250, v252, v253
	v_and_b32_e32 v144, v188, v235
	v_and_b32_e32 v145, v188, v236
	v_and_b32_e32 v146, v188, v237
	v_and_b32_e32 v147, v188, v238
	v_and_b32_e32 v148, v189, v235
	v_and_b32_e32 v149, v189, v236
	v_and_b32_e32 v150, v189, v237
	v_and_b32_e32 v151, v189, v238
	s_mov_b64 vcc, s[4:5]
	v_cndmask_b32_dpp v138, v120, v122, vcc row_shl:4 row_mask:0xf bank_mask:0xf bound_ctrl:1
	v_cndmask_b32_dpp v139, v121, v123, vcc row_shl:4 row_mask:0xf bank_mask:0xf bound_ctrl:1
	s_mov_b64 vcc, s[6:7]
	v_cndmask_b32_dpp v136, v122, v120, vcc row_shr:4 row_mask:0xf bank_mask:0xf bound_ctrl:1
	v_cndmask_b32_dpp v137, v123, v121, vcc row_shr:4 row_mask:0xf bank_mask:0xf bound_ctrl:1
	v_mfma_scale_f32_16x16x128_f8f6f4 v[216:219], v[140:143], v[204:211], v[216:219], v240, v241 op_sel_hi:[0,0,0] cbsz:4
	v_cvt_pk_bf16_f32 v251, v254, v255
	v_add_f32_e32 v192, v192, v193
	v_add_f32_e32 v224, v224, v192
	v_and_b32_e32 v204, v190, v235
	v_and_b32_e32 v205, v190, v236
	v_and_b32_e32 v206, v190, v237
	v_and_b32_e32 v207, v190, v238
	v_and_b32_e32 v208, v191, v235
	v_and_b32_e32 v209, v191, v236
	v_and_b32_e32 v210, v191, v237
	v_and_b32_e32 v211, v191, v238
	s_mov_b64 vcc, s[6:7]
	v_cndmask_b32_dpp v140, v126, v124, vcc row_shr:4 row_mask:0xf bank_mask:0xf bound_ctrl:1
	v_cndmask_b32_dpp v141, v127, v125, vcc row_shr:4 row_mask:0xf bank_mask:0xf bound_ctrl:1
	s_mov_b64 vcc, s[4:5]
	v_cndmask_b32_dpp v142, v124, v126, vcc row_shl:4 row_mask:0xf bank_mask:0xf bound_ctrl:1
	v_cndmask_b32_dpp v143, v125, v127, vcc row_shl:4 row_mask:0xf bank_mask:0xf bound_ctrl:1
	v_mfma_scale_f32_16x16x128_f8f6f4 v[216:219], v[136:139], v[144:151], v[216:219], v240, v241 op_sel_hi:[0,0,0] cbsz:4
	s_nop 0
	v_mfma_scale_f32_16x16x128_f8f6f4 v[216:219], v[140:143], v[204:211], v[216:219], v240, v241 op_sel_hi:[0,0,0] cbsz:4
	s_lshl_b32 s64, s0, 9
	s_add_u32 s64, s64, 0x4000
	s_add_u32 s76, s28, s64
	s_addc_u32 s77, s29, 0
	global_store_dwordx2 v239, v[250:251], s[76:77]
	s_lshl_b32 s64, s0, 9
	s_add_u32 s64, s64, 0x6000
	s_add_u32 s70, s28, s64
	s_addc_u32 s71, s29, 0
	global_load_dwordx2 v[228:229], v239, s[70:71]
	s_waitcnt lgkmcnt(0)
	v_lshl_or_b32 v128, v128, 7, v232
	v_lshl_or_b32 v129, v129, 7, v232
	v_lshl_or_b32 v130, v130, 7, v232
	v_lshl_or_b32 v131, v131, 7, v232
	v_lshl_or_b32 v132, v132, 7, v232
	v_lshl_or_b32 v133, v133, 7, v232
	v_lshl_or_b32 v134, v134, 7, v232
	v_lshl_or_b32 v135, v135, 7, v232
	buffer_load_dwordx4 v[96:99], v128, s[20:23], s1 offen
	buffer_load_dwordx4 v[100:103], v129, s[20:23], s1 offen
	buffer_load_dwordx4 v[104:107], v130, s[20:23], s1 offen
	buffer_load_dwordx4 v[108:111], v131, s[20:23], s1 offen
	buffer_load_dwordx4 v[112:115], v132, s[20:23], s1 offen
	buffer_load_dwordx4 v[116:119], v133, s[20:23], s1 offen
	buffer_load_dwordx4 v[120:123], v134, s[20:23], s1 offen
	buffer_load_dwordx4 v[124:127], v135, s[20:23], s1 offen
	ds_read_b32 v128, v243 offset:0
	ds_read_b32 v129, v243 offset:32
	ds_read_b32 v130, v243 offset:64
	ds_read_b32 v131, v243 offset:96
	ds_read_b32 v132, v243 offset:128
	ds_read_b32 v133, v243 offset:160
	ds_read_b32 v134, v243 offset:192
	ds_read_b32 v135, v243 offset:224
	ds_read_b64 v[176:177], v234 offset:3328
	ds_read_b64 v[178:179], v234 offset:3360
	ds_read_b64 v[180:181], v234 offset:3392
	ds_read_b64 v[182:183], v234 offset:3424
	ds_read_b64 v[184:185], v234 offset:3456
	ds_read_b64 v[186:187], v234 offset:3488
	ds_read_b64 v[188:189], v234 offset:3520
	ds_read_b64 v[190:191], v234 offset:3552
	s_waitcnt vmcnt(28)
	v_and_b32_e32 v144, v160, v235
	v_and_b32_e32 v145, v160, v236
	v_and_b32_e32 v146, v160, v237
	v_and_b32_e32 v147, v160, v238
	v_and_b32_e32 v148, v161, v235
	v_and_b32_e32 v149, v161, v236
	v_and_b32_e32 v150, v161, v237
	v_and_b32_e32 v151, v161, v238
	s_mov_b64 vcc, s[4:5]
	v_cndmask_b32_dpp v138, v0, v2, vcc row_shl:4 row_mask:0xf bank_mask:0xf bound_ctrl:1
	v_cndmask_b32_dpp v139, v1, v3, vcc row_shl:4 row_mask:0xf bank_mask:0xf bound_ctrl:1
	s_mov_b64 vcc, s[6:7]
	v_cndmask_b32_dpp v136, v2, v0, vcc row_shr:4 row_mask:0xf bank_mask:0xf bound_ctrl:1
	v_cndmask_b32_dpp v137, v3, v1, vcc row_shr:4 row_mask:0xf bank_mask:0xf bound_ctrl:1
	v_and_b32_e32 v204, v162, v235
	v_and_b32_e32 v205, v162, v236
	v_and_b32_e32 v206, v162, v237
	v_and_b32_e32 v207, v162, v238
	v_and_b32_e32 v208, v163, v235
	v_and_b32_e32 v209, v163, v236
	v_and_b32_e32 v210, v163, v237
	v_and_b32_e32 v211, v163, v238
	s_mov_b64 vcc, s[6:7]
	v_cndmask_b32_dpp v140, v6, v4, vcc row_shr:4 row_mask:0xf bank_mask:0xf bound_ctrl:1
	v_cndmask_b32_dpp v141, v7, v5, vcc row_shr:4 row_mask:0xf bank_mask:0xf bound_ctrl:1
	s_mov_b64 vcc, s[4:5]
	v_cndmask_b32_dpp v142, v4, v6, vcc row_shl:4 row_mask:0xf bank_mask:0xf bound_ctrl:1
	v_cndmask_b32_dpp v143, v5, v7, vcc row_shl:4 row_mask:0xf bank_mask:0xf bound_ctrl:1
	v_mfma_scale_f32_16x16x128_f8f6f4 v[212:215], v[136:139], v[144:151], 0, v240, v241 op_sel_hi:[0,0,0] cbsz:4
	v_and_b32_e32 v144, v164, v235
	v_and_b32_e32 v145, v164, v236
	v_and_b32_e32 v146, v164, v237
	v_and_b32_e32 v147, v164, v238
	v_and_b32_e32 v148, v165, v235
	v_and_b32_e32 v149, v165, v236
	v_and_b32_e32 v150, v165, v237
	v_and_b32_e32 v151, v165, v238
	s_mov_b64 vcc, s[4:5]
	v_cndmask_b32_dpp v138, v8, v10, vcc row_shl:4 row_mask:0xf bank_mask:0xf bound_ctrl:1
	v_cndmask_b32_dpp v139, v9, v11, vcc row_shl:4 row_mask:0xf bank_mask:0xf bound_ctrl:1
	s_mov_b64 vcc, s[6:7]
	v_cndmask_b32_dpp v136, v10, v8, vcc row_shr:4 row_mask:0xf bank_mask:0xf bound_ctrl:1
	v_cndmask_b32_dpp v137, v11, v9, vcc row_shr:4 row_mask:0xf bank_mask:0xf bound_ctrl:1
	v_mfma_scale_f32_16x16x128_f8f6f4 v[212:215], v[140:143], v[204:211], v[212:215], v240, v241 op_sel_hi:[0,0,0] cbsz:4
	v_and_b32_e32 v204, v166, v235
	v_and_b32_e32 v205, v166, v236
	v_and_b32_e32 v206, v166, v237
	v_and_b32_e32 v207, v166, v238
	v_and_b32_e32 v208, v167, v235
	v_and_b32_e32 v209, v167, v236
	v_and_b32_e32 v210, v167, v237
	v_and_b32_e32 v211, v167, v238
	s_mov_b64 vcc, s[6:7]
	v_cndmask_b32_dpp v140, v14, v12, vcc row_shr:4 row_mask:0xf bank_mask:0xf bound_ctrl:1
	v_cndmask_b32_dpp v141, v15, v13, vcc row_shr:4 row_mask:0xf bank_mask:0xf bound_ctrl:1
	s_mov_b64 vcc, s[4:5]
	v_cndmask_b32_dpp v142, v12, v14, vcc row_shl:4 row_mask:0xf bank_mask:0xf bound_ctrl:1
	v_cndmask_b32_dpp v143, v13, v15, vcc row_shl:4 row_mask:0xf bank_mask:0xf bound_ctrl:1
	v_mfma_scale_f32_16x16x128_f8f6f4 v[212:215], v[136:139], v[144:151], v[212:215], v240, v241 op_sel_hi:[0,0,0] cbsz:4
	v_and_b32_e32 v144, v168, v235
	v_and_b32_e32 v145, v168, v236
	v_and_b32_e32 v146, v168, v237
	v_and_b32_e32 v147, v168, v238
	v_and_b32_e32 v148, v169, v235
	v_and_b32_e32 v149, v169, v236
	v_and_b32_e32 v150, v169, v237
	v_and_b32_e32 v151, v169, v238
	s_mov_b64 vcc, s[4:5]
	v_cndmask_b32_dpp v138, v16, v18, vcc row_shl:4 row_mask:0xf bank_mask:0xf bound_ctrl:1
	v_cndmask_b32_dpp v139, v17, v19, vcc row_shl:4 row_mask:0xf bank_mask:0xf bound_ctrl:1
	s_mov_b64 vcc, s[6:7]
	v_cndmask_b32_dpp v136, v18, v16, vcc row_shr:4 row_mask:0xf bank_mask:0xf bound_ctrl:1
	v_cndmask_b32_dpp v137, v19, v17, vcc row_shr:4 row_mask:0xf bank_mask:0xf bound_ctrl:1
	v_mfma_scale_f32_16x16x128_f8f6f4 v[212:215], v[140:143], v[204:211], v[212:215], v240, v241 op_sel_hi:[0,0,0] cbsz:4
	v_and_b32_e32 v204, v170, v235
	v_and_b32_e32 v205, v170, v236
	v_and_b32_e32 v206, v170, v237
	v_and_b32_e32 v207, v170, v238
	v_and_b32_e32 v208, v171, v235
	v_and_b32_e32 v209, v171, v236
	v_and_b32_e32 v210, v171, v237
	v_and_b32_e32 v211, v171, v238
	s_mov_b64 vcc, s[6:7]
	v_cndmask_b32_dpp v140, v22, v20, vcc row_shr:4 row_mask:0xf bank_mask:0xf bound_ctrl:1
	v_cndmask_b32_dpp v141, v23, v21, vcc row_shr:4 row_mask:0xf bank_mask:0xf bound_ctrl:1
	s_mov_b64 vcc, s[4:5]
	v_cndmask_b32_dpp v142, v20, v22, vcc row_shl:4 row_mask:0xf bank_mask:0xf bound_ctrl:1
	v_cndmask_b32_dpp v143, v21, v23, vcc row_shl:4 row_mask:0xf bank_mask:0xf bound_ctrl:1
	v_mfma_scale_f32_16x16x128_f8f6f4 v[212:215], v[136:139], v[144:151], v[212:215], v240, v241 op_sel_hi:[0,0,0] cbsz:4
	v_and_b32_e32 v144, v172, v235
	v_and_b32_e32 v145, v172, v236
	v_and_b32_e32 v146, v172, v237
	v_and_b32_e32 v147, v172, v238
	v_and_b32_e32 v148, v173, v235
	v_and_b32_e32 v149, v173, v236
	v_and_b32_e32 v150, v173, v237
	v_and_b32_e32 v151, v173, v238
	s_mov_b64 vcc, s[4:5]
	v_cndmask_b32_dpp v138, v24, v26, vcc row_shl:4 row_mask:0xf bank_mask:0xf bound_ctrl:1
	v_cndmask_b32_dpp v139, v25, v27, vcc row_shl:4 row_mask:0xf bank_mask:0xf bound_ctrl:1
	s_mov_b64 vcc, s[6:7]
	v_cndmask_b32_dpp v136, v26, v24, vcc row_shr:4 row_mask:0xf bank_mask:0xf bound_ctrl:1
	v_cndmask_b32_dpp v137, v27, v25, vcc row_shr:4 row_mask:0xf bank_mask:0xf bound_ctrl:1
	v_mfma_scale_f32_16x16x128_f8f6f4 v[212:215], v[140:143], v[204:211], v[212:215], v240, v241 op_sel_hi:[0,0,0] cbsz:4
	v_and_b32_e32 v204, v174, v235
	v_and_b32_e32 v205, v174, v236
	v_and_b32_e32 v206, v174, v237
	v_and_b32_e32 v207, v174, v238
	v_and_b32_e32 v208, v175, v235
	v_and_b32_e32 v209, v175, v236
	v_and_b32_e32 v210, v175, v237
	v_and_b32_e32 v211, v175, v238
	s_mov_b64 vcc, s[6:7]
	v_cndmask_b32_dpp v140, v30, v28, vcc row_shr:4 row_mask:0xf bank_mask:0xf bound_ctrl:1
	v_cndmask_b32_dpp v141, v31, v29, vcc row_shr:4 row_mask:0xf bank_mask:0xf bound_ctrl:1
	s_mov_b64 vcc, s[4:5]
	v_cndmask_b32_dpp v142, v28, v30, vcc row_shl:4 row_mask:0xf bank_mask:0xf bound_ctrl:1
	v_cndmask_b32_dpp v143, v29, v31, vcc row_shl:4 row_mask:0xf bank_mask:0xf bound_ctrl:1
	v_mfma_scale_f32_16x16x128_f8f6f4 v[212:215], v[136:139], v[144:151], v[212:215], v240, v241 op_sel_hi:[0,0,0] cbsz:4
	s_nop 0
	v_mfma_scale_f32_16x16x128_f8f6f4 v[212:215], v[140:143], v[204:211], v[212:215], v240, v241 op_sel_hi:[0,0,0] cbsz:4
	s_waitcnt lgkmcnt(0)
	v_lshl_or_b32 v128, v128, 7, v232
	v_lshl_or_b32 v129, v129, 7, v232
	v_lshl_or_b32 v130, v130, 7, v232
	v_lshl_or_b32 v131, v131, 7, v232
	v_lshl_or_b32 v132, v132, 7, v232
	v_lshl_or_b32 v133, v133, 7, v232
	v_lshl_or_b32 v134, v134, 7, v232
	v_lshl_or_b32 v135, v135, 7, v232
	buffer_load_dwordx4 v[0:3], v128, s[20:23], s60 offen
	buffer_load_dwordx4 v[4:7], v129, s[20:23], s60 offen
	buffer_load_dwordx4 v[8:11], v130, s[20:23], s60 offen
	buffer_load_dwordx4 v[12:15], v131, s[20:23], s60 offen
	buffer_load_dwordx4 v[16:19], v132, s[20:23], s60 offen
	buffer_load_dwordx4 v[20:23], v133, s[20:23], s60 offen
	buffer_load_dwordx4 v[24:27], v134, s[20:23], s60 offen
	buffer_load_dwordx4 v[28:31], v135, s[20:23], s60 offen
	ds_read_b32 v128, v243 offset:256
	ds_read_b32 v129, v243 offset:288
	ds_read_b32 v130, v243 offset:320
	ds_read_b32 v131, v243 offset:352
	ds_read_b32 v132, v243 offset:384
	ds_read_b32 v133, v243 offset:416
	ds_read_b32 v134, v243 offset:448
	ds_read_b32 v135, v243 offset:480
	ds_read_b64 v[160:161], v234 offset:3584
	ds_read_b64 v[162:163], v234 offset:3616
	ds_read_b64 v[164:165], v234 offset:3648
	ds_read_b64 v[166:167], v234 offset:3680
	ds_read_b64 v[168:169], v234 offset:3712
	ds_read_b64 v[170:171], v234 offset:3744
	ds_read_b64 v[172:173], v234 offset:3776
	ds_read_b64 v[174:175], v234 offset:3808
	s_waitcnt vmcnt(26)
	v_and_b32_e32 v144, v176, v235
	v_and_b32_e32 v145, v176, v236
	v_and_b32_e32 v146, v176, v237
	v_and_b32_e32 v147, v176, v238
	v_and_b32_e32 v148, v177, v235
	v_and_b32_e32 v149, v177, v236
	v_and_b32_e32 v150, v177, v237
	v_and_b32_e32 v151, v177, v238
	s_mov_b64 vcc, s[4:5]
	v_cndmask_b32_dpp v138, v32, v34, vcc row_shl:4 row_mask:0xf bank_mask:0xf bound_ctrl:1
	v_cndmask_b32_dpp v139, v33, v35, vcc row_shl:4 row_mask:0xf bank_mask:0xf bound_ctrl:1
	s_mov_b64 vcc, s[6:7]
	v_cndmask_b32_dpp v136, v34, v32, vcc row_shr:4 row_mask:0xf bank_mask:0xf bound_ctrl:1
	v_cndmask_b32_dpp v137, v35, v33, vcc row_shr:4 row_mask:0xf bank_mask:0xf bound_ctrl:1
	v_and_b32_e32 v204, v178, v235
	v_and_b32_e32 v205, v178, v236
	v_and_b32_e32 v206, v178, v237
	v_and_b32_e32 v207, v178, v238
	v_and_b32_e32 v208, v179, v235
	v_and_b32_e32 v209, v179, v236
	v_and_b32_e32 v210, v179, v237
	v_and_b32_e32 v211, v179, v238
	s_mov_b64 vcc, s[6:7]
	v_cndmask_b32_dpp v140, v38, v36, vcc row_shr:4 row_mask:0xf bank_mask:0xf bound_ctrl:1
	v_cndmask_b32_dpp v141, v39, v37, vcc row_shr:4 row_mask:0xf bank_mask:0xf bound_ctrl:1
	s_mov_b64 vcc, s[4:5]
	v_cndmask_b32_dpp v142, v36, v38, vcc row_shl:4 row_mask:0xf bank_mask:0xf bound_ctrl:1
	v_cndmask_b32_dpp v143, v37, v39, vcc row_shl:4 row_mask:0xf bank_mask:0xf bound_ctrl:1
	v_mfma_scale_f32_16x16x128_f8f6f4 v[212:215], v[136:139], v[144:151], v[212:215], v240, v241 op_sel_hi:[0,0,0] cbsz:4
	v_permlane16_swap_b32_e32 v216, v218
	v_permlane16_swap_b32_e32 v217, v219
	v_lshlrev_b32_e32 v252, 16, v230
	v_and_b32_e32 v144, v180, v235
	v_and_b32_e32 v145, v180, v236
	v_and_b32_e32 v146, v180, v237
	v_and_b32_e32 v147, v180, v238
	v_and_b32_e32 v148, v181, v235
	v_and_b32_e32 v149, v181, v236
	v_and_b32_e32 v150, v181, v237
	v_and_b32_e32 v151, v181, v238
	s_mov_b64 vcc, s[4:5]
	v_cndmask_b32_dpp v138, v40, v42, vcc row_shl:4 row_mask:0xf bank_mask:0xf bound_ctrl:1
	v_cndmask_b32_dpp v139, v41, v43, vcc row_shl:4 row_mask:0xf bank_mask:0xf bound_ctrl:1
	s_mov_b64 vcc, s[6:7]
	v_cndmask_b32_dpp v136, v42, v40, vcc row_shr:4 row_mask:0xf bank_mask:0xf bound_ctrl:1
	v_cndmask_b32_dpp v137, v43, v41, vcc row_shr:4 row_mask:0xf bank_mask:0xf bound_ctrl:1
	v_mfma_scale_f32_16x16x128_f8f6f4 v[212:215], v[140:143], v[204:211], v[212:215], v240, v241 op_sel_hi:[0,0,0] cbsz:4
	v_and_b32_e32 v253, 0xffff0000, v230
	v_lshlrev_b32_e32 v254, 16, v231
	v_and_b32_e32 v255, 0xffff0000, v231
	v_and_b32_e32 v204, v182, v235
	v_and_b32_e32 v205, v182, v236
	v_and_b32_e32 v206, v182, v237
	v_and_b32_e32 v207, v182, v238
	v_and_b32_e32 v208, v183, v235
	v_and_b32_e32 v209, v183, v236
	v_and_b32_e32 v210, v183, v237
	v_and_b32_e32 v211, v183, v238
	s_mov_b64 vcc, s[6:7]
	v_cndmask_b32_dpp v140, v46, v44, vcc row_shr:4 row_mask:0xf bank_mask:0xf bound_ctrl:1
	v_cndmask_b32_dpp v141, v47, v45, vcc row_shr:4 row_mask:0xf bank_mask:0xf bound_ctrl:1
	s_mov_b64 vcc, s[4:5]
	v_cndmask_b32_dpp v142, v44, v46, vcc row_shl:4 row_mask:0xf bank_mask:0xf bound_ctrl:1
	v_cndmask_b32_dpp v143, v45, v47, vcc row_shl:4 row_mask:0xf bank_mask:0xf bound_ctrl:1
	v_mfma_scale_f32_16x16x128_f8f6f4 v[212:215], v[136:139], v[144:151], v[212:215], v240, v241 op_sel_hi:[0,0,0] cbsz:4
	v_add_f32_e32 v252, v216, v252
	v_add_f32_e32 v253, v218, v253
	v_add_f32_e32 v254, v217, v254
	v_and_b32_e32 v144, v184, v235
	v_and_b32_e32 v145, v184, v236
	v_and_b32_e32 v146, v184, v237
	v_and_b32_e32 v147, v184, v238
	v_and_b32_e32 v148, v185, v235
	v_and_b32_e32 v149, v185, v236
	v_and_b32_e32 v150, v185, v237
	v_and_b32_e32 v151, v185, v238
	s_mov_b64 vcc, s[4:5]
	v_cndmask_b32_dpp v138, v48, v50, vcc row_shl:4 row_mask:0xf bank_mask:0xf bound_ctrl:1
	v_cndmask_b32_dpp v139, v49, v51, vcc row_shl:4 row_mask:0xf bank_mask:0xf bound_ctrl:1
	s_mov_b64 vcc, s[6:7]
	v_cndmask_b32_dpp v136, v50, v48, vcc row_shr:4 row_mask:0xf bank_mask:0xf bound_ctrl:1
	v_cndmask_b32_dpp v137, v51, v49, vcc row_shr:4 row_mask:0xf bank_mask:0xf bound_ctrl:1
	v_mfma_scale_f32_16x16x128_f8f6f4 v[212:215], v[140:143], v[204:211], v[212:215], v240, v241 op_sel_hi:[0,0,0] cbsz:4
	v_add_f32_e32 v255, v219, v255
	v_mul_f32_e32 v192, v252, v252
	v_mul_f32_e32 v193, v254, v254
	v_and_b32_e32 v204, v186, v235
	v_and_b32_e32 v205, v186, v236
	v_and_b32_e32 v206, v186, v237
	v_and_b32_e32 v207, v186, v238
	v_and_b32_e32 v208, v187, v235
	v_and_b32_e32 v209, v187, v236
	v_and_b32_e32 v210, v187, v237
	v_and_b32_e32 v211, v187, v238
	s_mov_b64 vcc, s[6:7]
	v_cndmask_b32_dpp v140, v54, v52, vcc row_shr:4 row_mask:0xf bank_mask:0xf bound_ctrl:1
	v_cndmask_b32_dpp v141, v55, v53, vcc row_shr:4 row_mask:0xf bank_mask:0xf bound_ctrl:1
	s_mov_b64 vcc, s[4:5]
	v_cndmask_b32_dpp v142, v52, v54, vcc row_shl:4 row_mask:0xf bank_mask:0xf bound_ctrl:1
	v_cndmask_b32_dpp v143, v53, v55, vcc row_shl:4 row_mask:0xf bank_mask:0xf bound_ctrl:1
	v_mfma_scale_f32_16x16x128_f8f6f4 v[212:215], v[136:139], v[144:151], v[212:215], v240, v241 op_sel_hi:[0,0,0] cbsz:4
	v_fmac_f32_e32 v192, v253, v253
	v_fmac_f32_e32 v193, v255, v255
	v_cvt_pk_bf16_f32 v250, v252, v253
	v_and_b32_e32 v144, v188, v235
	v_and_b32_e32 v145, v188, v236
	v_and_b32_e32 v146, v188, v237
	v_and_b32_e32 v147, v188, v238
	v_and_b32_e32 v148, v189, v235
	v_and_b32_e32 v149, v189, v236
	v_and_b32_e32 v150, v189, v237
	v_and_b32_e32 v151, v189, v238
	s_mov_b64 vcc, s[4:5]
	v_cndmask_b32_dpp v138, v56, v58, vcc row_shl:4 row_mask:0xf bank_mask:0xf bound_ctrl:1
	v_cndmask_b32_dpp v139, v57, v59, vcc row_shl:4 row_mask:0xf bank_mask:0xf bound_ctrl:1
	s_mov_b64 vcc, s[6:7]
	v_cndmask_b32_dpp v136, v58, v56, vcc row_shr:4 row_mask:0xf bank_mask:0xf bound_ctrl:1
	v_cndmask_b32_dpp v137, v59, v57, vcc row_shr:4 row_mask:0xf bank_mask:0xf bound_ctrl:1
	v_mfma_scale_f32_16x16x128_f8f6f4 v[212:215], v[140:143], v[204:211], v[212:215], v240, v241 op_sel_hi:[0,0,0] cbsz:4
	v_cvt_pk_bf16_f32 v251, v254, v255
	v_add_f32_e32 v192, v192, v193
	v_add_f32_e32 v225, v225, v192
	v_and_b32_e32 v204, v190, v235
	v_and_b32_e32 v205, v190, v236
	v_and_b32_e32 v206, v190, v237
	v_and_b32_e32 v207, v190, v238
	v_and_b32_e32 v208, v191, v235
	v_and_b32_e32 v209, v191, v236
	v_and_b32_e32 v210, v191, v237
	v_and_b32_e32 v211, v191, v238
	s_mov_b64 vcc, s[6:7]
	v_cndmask_b32_dpp v140, v62, v60, vcc row_shr:4 row_mask:0xf bank_mask:0xf bound_ctrl:1
	v_cndmask_b32_dpp v141, v63, v61, vcc row_shr:4 row_mask:0xf bank_mask:0xf bound_ctrl:1
	s_mov_b64 vcc, s[4:5]
	v_cndmask_b32_dpp v142, v60, v62, vcc row_shl:4 row_mask:0xf bank_mask:0xf bound_ctrl:1
	v_cndmask_b32_dpp v143, v61, v63, vcc row_shl:4 row_mask:0xf bank_mask:0xf bound_ctrl:1
	v_mfma_scale_f32_16x16x128_f8f6f4 v[212:215], v[136:139], v[144:151], v[212:215], v240, v241 op_sel_hi:[0,0,0] cbsz:4
	s_nop 0
	v_mfma_scale_f32_16x16x128_f8f6f4 v[212:215], v[140:143], v[204:211], v[212:215], v240, v241 op_sel_hi:[0,0,0] cbsz:4
	s_lshl_b32 s64, s0, 9
	s_add_u32 s64, s64, 0x5000
	s_add_u32 s76, s28, s64
	s_addc_u32 s77, s29, 0
	global_store_dwordx2 v239, v[250:251], s[76:77]
	s_lshl_b32 s64, s0, 9
	s_add_u32 s64, s64, 0x7000
	s_add_u32 s70, s28, s64
	s_addc_u32 s71, s29, 0
	global_load_dwordx2 v[230:231], v239, s[70:71]
	s_waitcnt lgkmcnt(0)
	v_lshl_or_b32 v128, v128, 7, v232
	v_lshl_or_b32 v129, v129, 7, v232
	v_lshl_or_b32 v130, v130, 7, v232
	v_lshl_or_b32 v131, v131, 7, v232
	v_lshl_or_b32 v132, v132, 7, v232
	v_lshl_or_b32 v133, v133, 7, v232
	v_lshl_or_b32 v134, v134, 7, v232
	v_lshl_or_b32 v135, v135, 7, v232
	buffer_load_dwordx4 v[32:35], v128, s[20:23], s60 offen
	buffer_load_dwordx4 v[36:39], v129, s[20:23], s60 offen
	buffer_load_dwordx4 v[40:43], v130, s[20:23], s60 offen
	buffer_load_dwordx4 v[44:47], v131, s[20:23], s60 offen
	buffer_load_dwordx4 v[48:51], v132, s[20:23], s60 offen
	buffer_load_dwordx4 v[52:55], v133, s[20:23], s60 offen
	buffer_load_dwordx4 v[56:59], v134, s[20:23], s60 offen
	buffer_load_dwordx4 v[60:63], v135, s[20:23], s60 offen
	ds_read_b32 v128, v243 offset:512
	ds_read_b32 v129, v243 offset:544
	ds_read_b32 v130, v243 offset:576
	ds_read_b32 v131, v243 offset:608
	ds_read_b32 v132, v243 offset:640
	ds_read_b32 v133, v243 offset:672
	ds_read_b32 v134, v243 offset:704
	ds_read_b32 v135, v243 offset:736
	ds_read_b64 v[176:177], v234 offset:3840
	ds_read_b64 v[178:179], v234 offset:3872
	ds_read_b64 v[180:181], v234 offset:3904
	ds_read_b64 v[182:183], v234 offset:3936
	ds_read_b64 v[184:185], v234 offset:3968
	ds_read_b64 v[186:187], v234 offset:4000
	ds_read_b64 v[188:189], v234 offset:4032
	ds_read_b64 v[190:191], v234 offset:4064
	s_waitcnt vmcnt(28)
	v_and_b32_e32 v144, v160, v235
	v_and_b32_e32 v145, v160, v236
	v_and_b32_e32 v146, v160, v237
	v_and_b32_e32 v147, v160, v238
	v_and_b32_e32 v148, v161, v235
	v_and_b32_e32 v149, v161, v236
	v_and_b32_e32 v150, v161, v237
	v_and_b32_e32 v151, v161, v238
	s_mov_b64 vcc, s[4:5]
	v_cndmask_b32_dpp v138, v64, v66, vcc row_shl:4 row_mask:0xf bank_mask:0xf bound_ctrl:1
	v_cndmask_b32_dpp v139, v65, v67, vcc row_shl:4 row_mask:0xf bank_mask:0xf bound_ctrl:1
	s_mov_b64 vcc, s[6:7]
	v_cndmask_b32_dpp v136, v66, v64, vcc row_shr:4 row_mask:0xf bank_mask:0xf bound_ctrl:1
	v_cndmask_b32_dpp v137, v67, v65, vcc row_shr:4 row_mask:0xf bank_mask:0xf bound_ctrl:1
	v_and_b32_e32 v204, v162, v235
	v_and_b32_e32 v205, v162, v236
	v_and_b32_e32 v206, v162, v237
	v_and_b32_e32 v207, v162, v238
	v_and_b32_e32 v208, v163, v235
	v_and_b32_e32 v209, v163, v236
	v_and_b32_e32 v210, v163, v237
	v_and_b32_e32 v211, v163, v238
	s_mov_b64 vcc, s[6:7]
	v_cndmask_b32_dpp v140, v70, v68, vcc row_shr:4 row_mask:0xf bank_mask:0xf bound_ctrl:1
	v_cndmask_b32_dpp v141, v71, v69, vcc row_shr:4 row_mask:0xf bank_mask:0xf bound_ctrl:1
	s_mov_b64 vcc, s[4:5]
	v_cndmask_b32_dpp v142, v68, v70, vcc row_shl:4 row_mask:0xf bank_mask:0xf bound_ctrl:1
	v_cndmask_b32_dpp v143, v69, v71, vcc row_shl:4 row_mask:0xf bank_mask:0xf bound_ctrl:1
	v_mfma_scale_f32_16x16x128_f8f6f4 v[216:219], v[136:139], v[144:151], 0, v240, v241 op_sel_hi:[0,0,0] cbsz:4
	v_and_b32_e32 v144, v164, v235
	v_and_b32_e32 v145, v164, v236
	v_and_b32_e32 v146, v164, v237
	v_and_b32_e32 v147, v164, v238
	v_and_b32_e32 v148, v165, v235
	v_and_b32_e32 v149, v165, v236
	v_and_b32_e32 v150, v165, v237
	v_and_b32_e32 v151, v165, v238
	s_mov_b64 vcc, s[4:5]
	v_cndmask_b32_dpp v138, v72, v74, vcc row_shl:4 row_mask:0xf bank_mask:0xf bound_ctrl:1
	v_cndmask_b32_dpp v139, v73, v75, vcc row_shl:4 row_mask:0xf bank_mask:0xf bound_ctrl:1
	s_mov_b64 vcc, s[6:7]
	v_cndmask_b32_dpp v136, v74, v72, vcc row_shr:4 row_mask:0xf bank_mask:0xf bound_ctrl:1
	v_cndmask_b32_dpp v137, v75, v73, vcc row_shr:4 row_mask:0xf bank_mask:0xf bound_ctrl:1
	v_mfma_scale_f32_16x16x128_f8f6f4 v[216:219], v[140:143], v[204:211], v[216:219], v240, v241 op_sel_hi:[0,0,0] cbsz:4
	v_and_b32_e32 v204, v166, v235
	v_and_b32_e32 v205, v166, v236
	v_and_b32_e32 v206, v166, v237
	v_and_b32_e32 v207, v166, v238
	v_and_b32_e32 v208, v167, v235
	v_and_b32_e32 v209, v167, v236
	v_and_b32_e32 v210, v167, v237
	v_and_b32_e32 v211, v167, v238
	s_mov_b64 vcc, s[6:7]
	v_cndmask_b32_dpp v140, v78, v76, vcc row_shr:4 row_mask:0xf bank_mask:0xf bound_ctrl:1
	v_cndmask_b32_dpp v141, v79, v77, vcc row_shr:4 row_mask:0xf bank_mask:0xf bound_ctrl:1
	s_mov_b64 vcc, s[4:5]
	v_cndmask_b32_dpp v142, v76, v78, vcc row_shl:4 row_mask:0xf bank_mask:0xf bound_ctrl:1
	v_cndmask_b32_dpp v143, v77, v79, vcc row_shl:4 row_mask:0xf bank_mask:0xf bound_ctrl:1
	v_mfma_scale_f32_16x16x128_f8f6f4 v[216:219], v[136:139], v[144:151], v[216:219], v240, v241 op_sel_hi:[0,0,0] cbsz:4
	v_and_b32_e32 v144, v168, v235
	v_and_b32_e32 v145, v168, v236
	v_and_b32_e32 v146, v168, v237
	v_and_b32_e32 v147, v168, v238
	v_and_b32_e32 v148, v169, v235
	v_and_b32_e32 v149, v169, v236
	v_and_b32_e32 v150, v169, v237
	v_and_b32_e32 v151, v169, v238
	s_mov_b64 vcc, s[4:5]
	v_cndmask_b32_dpp v138, v80, v82, vcc row_shl:4 row_mask:0xf bank_mask:0xf bound_ctrl:1
	v_cndmask_b32_dpp v139, v81, v83, vcc row_shl:4 row_mask:0xf bank_mask:0xf bound_ctrl:1
	s_mov_b64 vcc, s[6:7]
	v_cndmask_b32_dpp v136, v82, v80, vcc row_shr:4 row_mask:0xf bank_mask:0xf bound_ctrl:1
	v_cndmask_b32_dpp v137, v83, v81, vcc row_shr:4 row_mask:0xf bank_mask:0xf bound_ctrl:1
	v_mfma_scale_f32_16x16x128_f8f6f4 v[216:219], v[140:143], v[204:211], v[216:219], v240, v241 op_sel_hi:[0,0,0] cbsz:4
	v_and_b32_e32 v204, v170, v235
	v_and_b32_e32 v205, v170, v236
	v_and_b32_e32 v206, v170, v237
	v_and_b32_e32 v207, v170, v238
	v_and_b32_e32 v208, v171, v235
	v_and_b32_e32 v209, v171, v236
	v_and_b32_e32 v210, v171, v237
	v_and_b32_e32 v211, v171, v238
	s_mov_b64 vcc, s[6:7]
	v_cndmask_b32_dpp v140, v86, v84, vcc row_shr:4 row_mask:0xf bank_mask:0xf bound_ctrl:1
	v_cndmask_b32_dpp v141, v87, v85, vcc row_shr:4 row_mask:0xf bank_mask:0xf bound_ctrl:1
	s_mov_b64 vcc, s[4:5]
	v_cndmask_b32_dpp v142, v84, v86, vcc row_shl:4 row_mask:0xf bank_mask:0xf bound_ctrl:1
	v_cndmask_b32_dpp v143, v85, v87, vcc row_shl:4 row_mask:0xf bank_mask:0xf bound_ctrl:1
	v_mfma_scale_f32_16x16x128_f8f6f4 v[216:219], v[136:139], v[144:151], v[216:219], v240, v241 op_sel_hi:[0,0,0] cbsz:4
	v_and_b32_e32 v144, v172, v235
	v_and_b32_e32 v145, v172, v236
	v_and_b32_e32 v146, v172, v237
	v_and_b32_e32 v147, v172, v238
	v_and_b32_e32 v148, v173, v235
	v_and_b32_e32 v149, v173, v236
	v_and_b32_e32 v150, v173, v237
	v_and_b32_e32 v151, v173, v238
	s_mov_b64 vcc, s[4:5]
	v_cndmask_b32_dpp v138, v88, v90, vcc row_shl:4 row_mask:0xf bank_mask:0xf bound_ctrl:1
	v_cndmask_b32_dpp v139, v89, v91, vcc row_shl:4 row_mask:0xf bank_mask:0xf bound_ctrl:1
	s_mov_b64 vcc, s[6:7]
	v_cndmask_b32_dpp v136, v90, v88, vcc row_shr:4 row_mask:0xf bank_mask:0xf bound_ctrl:1
	v_cndmask_b32_dpp v137, v91, v89, vcc row_shr:4 row_mask:0xf bank_mask:0xf bound_ctrl:1
	v_mfma_scale_f32_16x16x128_f8f6f4 v[216:219], v[140:143], v[204:211], v[216:219], v240, v241 op_sel_hi:[0,0,0] cbsz:4
	v_and_b32_e32 v204, v174, v235
	v_and_b32_e32 v205, v174, v236
	v_and_b32_e32 v206, v174, v237
	v_and_b32_e32 v207, v174, v238
	v_and_b32_e32 v208, v175, v235
	v_and_b32_e32 v209, v175, v236
	v_and_b32_e32 v210, v175, v237
	v_and_b32_e32 v211, v175, v238
	s_mov_b64 vcc, s[6:7]
	v_cndmask_b32_dpp v140, v94, v92, vcc row_shr:4 row_mask:0xf bank_mask:0xf bound_ctrl:1
	v_cndmask_b32_dpp v141, v95, v93, vcc row_shr:4 row_mask:0xf bank_mask:0xf bound_ctrl:1
	s_mov_b64 vcc, s[4:5]
	v_cndmask_b32_dpp v142, v92, v94, vcc row_shl:4 row_mask:0xf bank_mask:0xf bound_ctrl:1
	v_cndmask_b32_dpp v143, v93, v95, vcc row_shl:4 row_mask:0xf bank_mask:0xf bound_ctrl:1
	v_mfma_scale_f32_16x16x128_f8f6f4 v[216:219], v[136:139], v[144:151], v[216:219], v240, v241 op_sel_hi:[0,0,0] cbsz:4
	s_nop 0
	v_mfma_scale_f32_16x16x128_f8f6f4 v[216:219], v[140:143], v[204:211], v[216:219], v240, v241 op_sel_hi:[0,0,0] cbsz:4
	s_waitcnt lgkmcnt(0)
	v_lshl_or_b32 v128, v128, 7, v232
	v_lshl_or_b32 v129, v129, 7, v232
	v_lshl_or_b32 v130, v130, 7, v232
	v_lshl_or_b32 v131, v131, 7, v232
	v_lshl_or_b32 v132, v132, 7, v232
	v_lshl_or_b32 v133, v133, 7, v232
	v_lshl_or_b32 v134, v134, 7, v232
	v_lshl_or_b32 v135, v135, 7, v232
	buffer_load_dwordx4 v[64:67], v128, s[20:23], s60 offen
	buffer_load_dwordx4 v[68:71], v129, s[20:23], s60 offen
	buffer_load_dwordx4 v[72:75], v130, s[20:23], s60 offen
	buffer_load_dwordx4 v[76:79], v131, s[20:23], s60 offen
	buffer_load_dwordx4 v[80:83], v132, s[20:23], s60 offen
	buffer_load_dwordx4 v[84:87], v133, s[20:23], s60 offen
	buffer_load_dwordx4 v[88:91], v134, s[20:23], s60 offen
	buffer_load_dwordx4 v[92:95], v135, s[20:23], s60 offen
	ds_read_b32 v128, v243 offset:768
	ds_read_b32 v129, v243 offset:800
	ds_read_b32 v130, v243 offset:832
	ds_read_b32 v131, v243 offset:864
	ds_read_b32 v132, v243 offset:896
	ds_read_b32 v133, v243 offset:928
	ds_read_b32 v134, v243 offset:960
	ds_read_b32 v135, v243 offset:992
	ds_read_b64 v[160:161], v247 offset:0
	ds_read_b64 v[162:163], v247 offset:32
	ds_read_b64 v[164:165], v247 offset:64
	ds_read_b64 v[166:167], v247 offset:96
	ds_read_b64 v[168:169], v247 offset:128
	ds_read_b64 v[170:171], v247 offset:160
	ds_read_b64 v[172:173], v247 offset:192
	ds_read_b64 v[174:175], v247 offset:224
	s_waitcnt vmcnt(26)
	v_and_b32_e32 v144, v176, v235
	v_and_b32_e32 v145, v176, v236
	v_and_b32_e32 v146, v176, v237
	v_and_b32_e32 v147, v176, v238
	v_and_b32_e32 v148, v177, v235
	v_and_b32_e32 v149, v177, v236
	v_and_b32_e32 v150, v177, v237
	v_and_b32_e32 v151, v177, v238
	s_mov_b64 vcc, s[4:5]
	v_cndmask_b32_dpp v138, v96, v98, vcc row_shl:4 row_mask:0xf bank_mask:0xf bound_ctrl:1
	v_cndmask_b32_dpp v139, v97, v99, vcc row_shl:4 row_mask:0xf bank_mask:0xf bound_ctrl:1
	s_mov_b64 vcc, s[6:7]
	v_cndmask_b32_dpp v136, v98, v96, vcc row_shr:4 row_mask:0xf bank_mask:0xf bound_ctrl:1
	v_cndmask_b32_dpp v137, v99, v97, vcc row_shr:4 row_mask:0xf bank_mask:0xf bound_ctrl:1
	v_and_b32_e32 v204, v178, v235
	v_and_b32_e32 v205, v178, v236
	v_and_b32_e32 v206, v178, v237
	v_and_b32_e32 v207, v178, v238
	v_and_b32_e32 v208, v179, v235
	v_and_b32_e32 v209, v179, v236
	v_and_b32_e32 v210, v179, v237
	v_and_b32_e32 v211, v179, v238
	s_mov_b64 vcc, s[6:7]
	v_cndmask_b32_dpp v140, v102, v100, vcc row_shr:4 row_mask:0xf bank_mask:0xf bound_ctrl:1
	v_cndmask_b32_dpp v141, v103, v101, vcc row_shr:4 row_mask:0xf bank_mask:0xf bound_ctrl:1
	s_mov_b64 vcc, s[4:5]
	v_cndmask_b32_dpp v142, v100, v102, vcc row_shl:4 row_mask:0xf bank_mask:0xf bound_ctrl:1
	v_cndmask_b32_dpp v143, v101, v103, vcc row_shl:4 row_mask:0xf bank_mask:0xf bound_ctrl:1
	v_mfma_scale_f32_16x16x128_f8f6f4 v[216:219], v[136:139], v[144:151], v[216:219], v240, v241 op_sel_hi:[0,0,0] cbsz:4
	v_permlane16_swap_b32_e32 v212, v214
	v_permlane16_swap_b32_e32 v213, v215
	v_lshlrev_b32_e32 v252, 16, v228
	v_and_b32_e32 v144, v180, v235
	v_and_b32_e32 v145, v180, v236
	v_and_b32_e32 v146, v180, v237
	v_and_b32_e32 v147, v180, v238
	v_and_b32_e32 v148, v181, v235
	v_and_b32_e32 v149, v181, v236
	v_and_b32_e32 v150, v181, v237
	v_and_b32_e32 v151, v181, v238
	s_mov_b64 vcc, s[4:5]
	v_cndmask_b32_dpp v138, v104, v106, vcc row_shl:4 row_mask:0xf bank_mask:0xf bound_ctrl:1
	v_cndmask_b32_dpp v139, v105, v107, vcc row_shl:4 row_mask:0xf bank_mask:0xf bound_ctrl:1
	s_mov_b64 vcc, s[6:7]
	v_cndmask_b32_dpp v136, v106, v104, vcc row_shr:4 row_mask:0xf bank_mask:0xf bound_ctrl:1
	v_cndmask_b32_dpp v137, v107, v105, vcc row_shr:4 row_mask:0xf bank_mask:0xf bound_ctrl:1
	v_mfma_scale_f32_16x16x128_f8f6f4 v[216:219], v[140:143], v[204:211], v[216:219], v240, v241 op_sel_hi:[0,0,0] cbsz:4
	v_and_b32_e32 v253, 0xffff0000, v228
	v_lshlrev_b32_e32 v254, 16, v229
	v_and_b32_e32 v255, 0xffff0000, v229
	v_and_b32_e32 v204, v182, v235
	v_and_b32_e32 v205, v182, v236
	v_and_b32_e32 v206, v182, v237
	v_and_b32_e32 v207, v182, v238
	v_and_b32_e32 v208, v183, v235
	v_and_b32_e32 v209, v183, v236
	v_and_b32_e32 v210, v183, v237
	v_and_b32_e32 v211, v183, v238
	s_mov_b64 vcc, s[6:7]
	v_cndmask_b32_dpp v140, v110, v108, vcc row_shr:4 row_mask:0xf bank_mask:0xf bound_ctrl:1
	v_cndmask_b32_dpp v141, v111, v109, vcc row_shr:4 row_mask:0xf bank_mask:0xf bound_ctrl:1
	s_mov_b64 vcc, s[4:5]
	v_cndmask_b32_dpp v142, v108, v110, vcc row_shl:4 row_mask:0xf bank_mask:0xf bound_ctrl:1
	v_cndmask_b32_dpp v143, v109, v111, vcc row_shl:4 row_mask:0xf bank_mask:0xf bound_ctrl:1
	v_mfma_scale_f32_16x16x128_f8f6f4 v[216:219], v[136:139], v[144:151], v[216:219], v240, v241 op_sel_hi:[0,0,0] cbsz:4
	v_add_f32_e32 v252, v212, v252
	v_add_f32_e32 v253, v214, v253
	v_add_f32_e32 v254, v213, v254
	v_and_b32_e32 v144, v184, v235
	v_and_b32_e32 v145, v184, v236
	v_and_b32_e32 v146, v184, v237
	v_and_b32_e32 v147, v184, v238
	v_and_b32_e32 v148, v185, v235
	v_and_b32_e32 v149, v185, v236
	v_and_b32_e32 v150, v185, v237
	v_and_b32_e32 v151, v185, v238
	s_mov_b64 vcc, s[4:5]
	v_cndmask_b32_dpp v138, v112, v114, vcc row_shl:4 row_mask:0xf bank_mask:0xf bound_ctrl:1
	v_cndmask_b32_dpp v139, v113, v115, vcc row_shl:4 row_mask:0xf bank_mask:0xf bound_ctrl:1
	s_mov_b64 vcc, s[6:7]
	v_cndmask_b32_dpp v136, v114, v112, vcc row_shr:4 row_mask:0xf bank_mask:0xf bound_ctrl:1
	v_cndmask_b32_dpp v137, v115, v113, vcc row_shr:4 row_mask:0xf bank_mask:0xf bound_ctrl:1
	v_mfma_scale_f32_16x16x128_f8f6f4 v[216:219], v[140:143], v[204:211], v[216:219], v240, v241 op_sel_hi:[0,0,0] cbsz:4
	v_add_f32_e32 v255, v215, v255
	v_mul_f32_e32 v192, v252, v252
	v_mul_f32_e32 v193, v254, v254
	v_and_b32_e32 v204, v186, v235
	v_and_b32_e32 v205, v186, v236
	v_and_b32_e32 v206, v186, v237
	v_and_b32_e32 v207, v186, v238
	v_and_b32_e32 v208, v187, v235
	v_and_b32_e32 v209, v187, v236
	v_and_b32_e32 v210, v187, v237
	v_and_b32_e32 v211, v187, v238
	s_mov_b64 vcc, s[6:7]
	v_cndmask_b32_dpp v140, v118, v116, vcc row_shr:4 row_mask:0xf bank_mask:0xf bound_ctrl:1
	v_cndmask_b32_dpp v141, v119, v117, vcc row_shr:4 row_mask:0xf bank_mask:0xf bound_ctrl:1
	s_mov_b64 vcc, s[4:5]
	v_cndmask_b32_dpp v142, v116, v118, vcc row_shl:4 row_mask:0xf bank_mask:0xf bound_ctrl:1
	v_cndmask_b32_dpp v143, v117, v119, vcc row_shl:4 row_mask:0xf bank_mask:0xf bound_ctrl:1
	v_mfma_scale_f32_16x16x128_f8f6f4 v[216:219], v[136:139], v[144:151], v[216:219], v240, v241 op_sel_hi:[0,0,0] cbsz:4
	v_fmac_f32_e32 v192, v253, v253
	v_fmac_f32_e32 v193, v255, v255
	v_cvt_pk_bf16_f32 v250, v252, v253
	v_and_b32_e32 v144, v188, v235
	v_and_b32_e32 v145, v188, v236
	v_and_b32_e32 v146, v188, v237
	v_and_b32_e32 v147, v188, v238
	v_and_b32_e32 v148, v189, v235
	v_and_b32_e32 v149, v189, v236
	v_and_b32_e32 v150, v189, v237
	v_and_b32_e32 v151, v189, v238
	s_mov_b64 vcc, s[4:5]
	v_cndmask_b32_dpp v138, v120, v122, vcc row_shl:4 row_mask:0xf bank_mask:0xf bound_ctrl:1
	v_cndmask_b32_dpp v139, v121, v123, vcc row_shl:4 row_mask:0xf bank_mask:0xf bound_ctrl:1
	s_mov_b64 vcc, s[6:7]
	v_cndmask_b32_dpp v136, v122, v120, vcc row_shr:4 row_mask:0xf bank_mask:0xf bound_ctrl:1
	v_cndmask_b32_dpp v137, v123, v121, vcc row_shr:4 row_mask:0xf bank_mask:0xf bound_ctrl:1
	v_mfma_scale_f32_16x16x128_f8f6f4 v[216:219], v[140:143], v[204:211], v[216:219], v240, v241 op_sel_hi:[0,0,0] cbsz:4
	v_cvt_pk_bf16_f32 v251, v254, v255
	v_add_f32_e32 v192, v192, v193
	v_add_f32_e32 v226, v226, v192
	v_and_b32_e32 v204, v190, v235
	v_and_b32_e32 v205, v190, v236
	v_and_b32_e32 v206, v190, v237
	v_and_b32_e32 v207, v190, v238
	v_and_b32_e32 v208, v191, v235
	v_and_b32_e32 v209, v191, v236
	v_and_b32_e32 v210, v191, v237
	v_and_b32_e32 v211, v191, v238
	s_mov_b64 vcc, s[6:7]
	v_cndmask_b32_dpp v140, v126, v124, vcc row_shr:4 row_mask:0xf bank_mask:0xf bound_ctrl:1
	v_cndmask_b32_dpp v141, v127, v125, vcc row_shr:4 row_mask:0xf bank_mask:0xf bound_ctrl:1
	s_mov_b64 vcc, s[4:5]
	v_cndmask_b32_dpp v142, v124, v126, vcc row_shl:4 row_mask:0xf bank_mask:0xf bound_ctrl:1
	v_cndmask_b32_dpp v143, v125, v127, vcc row_shl:4 row_mask:0xf bank_mask:0xf bound_ctrl:1
	v_mfma_scale_f32_16x16x128_f8f6f4 v[216:219], v[136:139], v[144:151], v[216:219], v240, v241 op_sel_hi:[0,0,0] cbsz:4
	s_nop 0
	v_mfma_scale_f32_16x16x128_f8f6f4 v[216:219], v[140:143], v[204:211], v[216:219], v240, v241 op_sel_hi:[0,0,0] cbsz:4
	s_lshl_b32 s64, s0, 9
	s_add_u32 s64, s64, 0x6000
	s_add_u32 s76, s28, s64
	s_addc_u32 s77, s29, 0
	global_store_dwordx2 v239, v[250:251], s[76:77]
	s_add_u32 s0, s0, 1
	s_lshl_b32 s1, s0, 21
	s_add_u32 s60, s1, 0x200000
	s_cmp_ge_u32 s0, 3
	s_movk_i32 s65, 0x2000
	s_cselect_b32 s64, s65, 0x1000
	v_mov_b32_e32 v234, v247
	v_add_u32_e32 v247, s64, v233
	s_cmp_lt_u32 s0, 8
	s_cbranch_scc1 .LpgL1_vloopv0
	s_waitcnt vmcnt(0)
	s_nop 15
	v_permlane16_swap_b32_e32 v216, v218
	v_permlane16_swap_b32_e32 v217, v219
	v_lshlrev_b32_e32 v252, 16, v230
	v_and_b32_e32 v253, 0xffff0000, v230
	v_lshlrev_b32_e32 v254, 16, v231
	v_and_b32_e32 v255, 0xffff0000, v231
	v_add_f32_e32 v252, v216, v252
	v_add_f32_e32 v253, v218, v253
	v_add_f32_e32 v254, v217, v254
	v_add_f32_e32 v255, v219, v255
	v_mul_f32_e32 v192, v252, v252
	v_mul_f32_e32 v193, v254, v254
	v_fmac_f32_e32 v192, v253, v253
	v_fmac_f32_e32 v193, v255, v255
	v_cvt_pk_bf16_f32 v250, v252, v253
	v_cvt_pk_bf16_f32 v251, v254, v255
	v_add_f32_e32 v192, v192, v193
	v_add_f32_e32 v227, v227, v192
	s_lshl_b32 s64, s0, 9
	s_add_u32 s64, s64, 0x6e00
	s_add_u32 s76, s28, s64
	s_addc_u32 s77, s29, 0
	global_store_dwordx2 v239, v[250:251], s[76:77]
	s_nop 1
	v_add_f32_dpp v220, v220, v220 quad_perm:[1,0,3,2] row_mask:0xf bank_mask:0xf bound_ctrl:1
	s_nop 1
	v_add_f32_dpp v220, v220, v220 quad_perm:[2,3,0,1] row_mask:0xf bank_mask:0xf bound_ctrl:1
	s_nop 1
	v_add_f32_dpp v220, v220, v220 row_half_mirror row_mask:0xf bank_mask:0xf bound_ctrl:1
	s_nop 1
	v_add_f32_dpp v220, v220, v220 row_mirror row_mask:0xf bank_mask:0xf bound_ctrl:1
	v_mov_b32_e32 v249, v220
	s_nop 1
	v_permlane16_swap_b32_e32 v220, v249
	v_add_f32_e32 v220, v220, v249
	v_mov_b32_e32 v249, v220
	s_nop 1
	v_permlane32_swap_b32_e32 v220, v249
	v_add_f32_e32 v220, v220, v249
	s_nop 1
	v_add_f32_dpp v221, v221, v221 quad_perm:[1,0,3,2] row_mask:0xf bank_mask:0xf bound_ctrl:1
	s_nop 1
	v_add_f32_dpp v221, v221, v221 quad_perm:[2,3,0,1] row_mask:0xf bank_mask:0xf bound_ctrl:1
	s_nop 1
	v_add_f32_dpp v221, v221, v221 row_half_mirror row_mask:0xf bank_mask:0xf bound_ctrl:1
	s_nop 1
	v_add_f32_dpp v221, v221, v221 row_mirror row_mask:0xf bank_mask:0xf bound_ctrl:1
	v_mov_b32_e32 v249, v221
	s_nop 1
	v_permlane16_swap_b32_e32 v221, v249
	v_add_f32_e32 v221, v221, v249
	v_mov_b32_e32 v249, v221
	s_nop 1
	v_permlane32_swap_b32_e32 v221, v249
	v_add_f32_e32 v221, v221, v249
	s_nop 1
	v_add_f32_dpp v222, v222, v222 quad_perm:[1,0,3,2] row_mask:0xf bank_mask:0xf bound_ctrl:1
	s_nop 1
	v_add_f32_dpp v222, v222, v222 quad_perm:[2,3,0,1] row_mask:0xf bank_mask:0xf bound_ctrl:1
	s_nop 1
	v_add_f32_dpp v222, v222, v222 row_half_mirror row_mask:0xf bank_mask:0xf bound_ctrl:1
	s_nop 1
	v_add_f32_dpp v222, v222, v222 row_mirror row_mask:0xf bank_mask:0xf bound_ctrl:1
	v_mov_b32_e32 v249, v222
	s_nop 1
	v_permlane16_swap_b32_e32 v222, v249
	v_add_f32_e32 v222, v222, v249
	v_mov_b32_e32 v249, v222
	s_nop 1
	v_permlane32_swap_b32_e32 v222, v249
	v_add_f32_e32 v222, v222, v249
	s_nop 1
	v_add_f32_dpp v223, v223, v223 quad_perm:[1,0,3,2] row_mask:0xf bank_mask:0xf bound_ctrl:1
	s_nop 1
	v_add_f32_dpp v223, v223, v223 quad_perm:[2,3,0,1] row_mask:0xf bank_mask:0xf bound_ctrl:1
	s_nop 1
	v_add_f32_dpp v223, v223, v223 row_half_mirror row_mask:0xf bank_mask:0xf bound_ctrl:1
	s_nop 1
	v_add_f32_dpp v223, v223, v223 row_mirror row_mask:0xf bank_mask:0xf bound_ctrl:1
	v_mov_b32_e32 v249, v223
	s_nop 1
	v_permlane16_swap_b32_e32 v223, v249
	v_add_f32_e32 v223, v223, v249
	v_mov_b32_e32 v249, v223
	s_nop 1
	v_permlane32_swap_b32_e32 v223, v249
	v_add_f32_e32 v223, v223, v249
	s_nop 1
	v_add_f32_dpp v224, v224, v224 quad_perm:[1,0,3,2] row_mask:0xf bank_mask:0xf bound_ctrl:1
	s_nop 1
	v_add_f32_dpp v224, v224, v224 quad_perm:[2,3,0,1] row_mask:0xf bank_mask:0xf bound_ctrl:1
	s_nop 1
	v_add_f32_dpp v224, v224, v224 row_half_mirror row_mask:0xf bank_mask:0xf bound_ctrl:1
	s_nop 1
	v_add_f32_dpp v224, v224, v224 row_mirror row_mask:0xf bank_mask:0xf bound_ctrl:1
	v_mov_b32_e32 v249, v224
	s_nop 1
	v_permlane16_swap_b32_e32 v224, v249
	v_add_f32_e32 v224, v224, v249
	v_mov_b32_e32 v249, v224
	s_nop 1
	v_permlane32_swap_b32_e32 v224, v249
	v_add_f32_e32 v224, v224, v249
	s_nop 1
	v_add_f32_dpp v225, v225, v225 quad_perm:[1,0,3,2] row_mask:0xf bank_mask:0xf bound_ctrl:1
	s_nop 1
	v_add_f32_dpp v225, v225, v225 quad_perm:[2,3,0,1] row_mask:0xf bank_mask:0xf bound_ctrl:1
	s_nop 1
	v_add_f32_dpp v225, v225, v225 row_half_mirror row_mask:0xf bank_mask:0xf bound_ctrl:1
	s_nop 1
	v_add_f32_dpp v225, v225, v225 row_mirror row_mask:0xf bank_mask:0xf bound_ctrl:1
	v_mov_b32_e32 v249, v225
	s_nop 1
	v_permlane16_swap_b32_e32 v225, v249
	v_add_f32_e32 v225, v225, v249
	v_mov_b32_e32 v249, v225
	s_nop 1
	v_permlane32_swap_b32_e32 v225, v249
	v_add_f32_e32 v225, v225, v249
	s_nop 1
	v_add_f32_dpp v226, v226, v226 quad_perm:[1,0,3,2] row_mask:0xf bank_mask:0xf bound_ctrl:1
	s_nop 1
	v_add_f32_dpp v226, v226, v226 quad_perm:[2,3,0,1] row_mask:0xf bank_mask:0xf bound_ctrl:1
	s_nop 1
	v_add_f32_dpp v226, v226, v226 row_half_mirror row_mask:0xf bank_mask:0xf bound_ctrl:1
	s_nop 1
	v_add_f32_dpp v226, v226, v226 row_mirror row_mask:0xf bank_mask:0xf bound_ctrl:1
	v_mov_b32_e32 v249, v226
	s_nop 1
	v_permlane16_swap_b32_e32 v226, v249
	v_add_f32_e32 v226, v226, v249
	v_mov_b32_e32 v249, v226
	s_nop 1
	v_permlane32_swap_b32_e32 v226, v249
	v_add_f32_e32 v226, v226, v249
	s_nop 1
	v_add_f32_dpp v227, v227, v227 quad_perm:[1,0,3,2] row_mask:0xf bank_mask:0xf bound_ctrl:1
	s_nop 1
	v_add_f32_dpp v227, v227, v227 quad_perm:[2,3,0,1] row_mask:0xf bank_mask:0xf bound_ctrl:1
	s_nop 1
	v_add_f32_dpp v227, v227, v227 row_half_mirror row_mask:0xf bank_mask:0xf bound_ctrl:1
	s_nop 1
	v_add_f32_dpp v227, v227, v227 row_mirror row_mask:0xf bank_mask:0xf bound_ctrl:1
	v_mov_b32_e32 v249, v227
	s_nop 1
	v_permlane16_swap_b32_e32 v227, v249
	v_add_f32_e32 v227, v227, v249
	v_mov_b32_e32 v249, v227
	s_nop 1
	v_permlane32_swap_b32_e32 v227, v249
	v_add_f32_e32 v227, v227, v249
	s_waitcnt vmcnt(0)
	v_lshlrev_b32_e32 v250, 1, v239
	v_add_u32_e32 v251, 0x1000, v250
	global_load_dwordx4 v[0:3], v250, s[66:67] offset:0
	global_load_dwordx4 v[4:7], v250, s[66:67] offset:1024
	global_load_dwordx4 v[8:11], v250, s[66:67] offset:2048
	global_load_dwordx4 v[12:15], v250, s[66:67] offset:3072
	global_load_dwordx4 v[16:19], v251, s[66:67] offset:0
	global_load_dwordx4 v[20:23], v251, s[66:67] offset:1024
	global_load_dwordx4 v[24:27], v251, s[66:67] offset:2048
	global_load_dwordx4 v[28:31], v251, s[66:67] offset:3072
	v_mov_b32_e32 v120, 0x358637bd
	v_fmamk_f32 v220, v220, 0x3a000000, v120
	v_cmp_gt_f32_e32 vcc, s96, v220
	v_mul_f32_e32 v121, 0x4b800000, v220
	s_nop 0
	v_cndmask_b32_e32 v220, v220, v121, vcc
	v_rsq_f32_e32 v220, v220
	s_nop 0
	v_mul_f32_e32 v121, 0x45800000, v220
	v_cndmask_b32_e32 v220, v220, v121, vcc
	v_fmamk_f32 v221, v221, 0x3a000000, v120
	v_cmp_gt_f32_e32 vcc, s96, v221
	v_mul_f32_e32 v121, 0x4b800000, v221
	s_nop 0
	v_cndmask_b32_e32 v221, v221, v121, vcc
	v_rsq_f32_e32 v221, v221
	s_nop 0
	v_mul_f32_e32 v121, 0x45800000, v221
	v_cndmask_b32_e32 v221, v221, v121, vcc
	v_fmamk_f32 v222, v222, 0x3a000000, v120
	v_cmp_gt_f32_e32 vcc, s96, v222
	v_mul_f32_e32 v121, 0x4b800000, v222
	s_nop 0
	v_cndmask_b32_e32 v222, v222, v121, vcc
	v_rsq_f32_e32 v222, v222
	s_nop 0
	v_mul_f32_e32 v121, 0x45800000, v222
	v_cndmask_b32_e32 v222, v222, v121, vcc
	v_fmamk_f32 v223, v223, 0x3a000000, v120
	v_cmp_gt_f32_e32 vcc, s96, v223
	v_mul_f32_e32 v121, 0x4b800000, v223
	s_nop 0
	v_cndmask_b32_e32 v223, v223, v121, vcc
	v_rsq_f32_e32 v223, v223
	s_nop 0
	v_mul_f32_e32 v121, 0x45800000, v223
	v_cndmask_b32_e32 v223, v223, v121, vcc
	v_fmamk_f32 v224, v224, 0x3a000000, v120
	v_cmp_gt_f32_e32 vcc, s96, v224
	v_mul_f32_e32 v121, 0x4b800000, v224
	s_nop 0
	v_cndmask_b32_e32 v224, v224, v121, vcc
	v_rsq_f32_e32 v224, v224
	s_nop 0
	v_mul_f32_e32 v121, 0x45800000, v224
	v_cndmask_b32_e32 v224, v224, v121, vcc
	v_fmamk_f32 v225, v225, 0x3a000000, v120
	v_cmp_gt_f32_e32 vcc, s96, v225
	v_mul_f32_e32 v121, 0x4b800000, v225
	s_nop 0
	v_cndmask_b32_e32 v225, v225, v121, vcc
	v_rsq_f32_e32 v225, v225
	s_nop 0
	v_mul_f32_e32 v121, 0x45800000, v225
	v_cndmask_b32_e32 v225, v225, v121, vcc
	v_fmamk_f32 v226, v226, 0x3a000000, v120
	v_cmp_gt_f32_e32 vcc, s96, v226
	v_mul_f32_e32 v121, 0x4b800000, v226
	s_nop 0
	v_cndmask_b32_e32 v226, v226, v121, vcc
	v_rsq_f32_e32 v226, v226
	s_nop 0
	v_mul_f32_e32 v121, 0x45800000, v226
	v_cndmask_b32_e32 v226, v226, v121, vcc
	v_fmamk_f32 v227, v227, 0x3a000000, v120
	v_cmp_gt_f32_e32 vcc, s96, v227
	v_mul_f32_e32 v121, 0x4b800000, v227
	s_nop 0
	v_cndmask_b32_e32 v227, v227, v121, vcc
	v_rsq_f32_e32 v227, v227
	s_nop 0
	v_mul_f32_e32 v121, 0x45800000, v227
	v_cndmask_b32_e32 v227, v227, v121, vcc
	s_add_u32 s70, s28, 0x0
	s_addc_u32 s71, s29, 0
	global_load_dwordx2 v[32:33], v239, s[70:71] offset:0
	global_load_dwordx2 v[34:35], v239, s[70:71] offset:512
	global_load_dwordx2 v[36:37], v239, s[70:71] offset:1024
	global_load_dwordx2 v[38:39], v239, s[70:71] offset:1536
	global_load_dwordx2 v[40:41], v239, s[70:71] offset:2048
	global_load_dwordx2 v[42:43], v239, s[70:71] offset:2560
	global_load_dwordx2 v[44:45], v239, s[70:71] offset:3072
	global_load_dwordx2 v[46:47], v239, s[70:71] offset:3584
	s_add_u32 s70, s28, 0x1000
	s_addc_u32 s71, s29, 0
	global_load_dwordx2 v[48:49], v239, s[70:71] offset:0
	global_load_dwordx2 v[50:51], v239, s[70:71] offset:512
	global_load_dwordx2 v[52:53], v239, s[70:71] offset:1024
	global_load_dwordx2 v[54:55], v239, s[70:71] offset:1536
	global_load_dwordx2 v[56:57], v239, s[70:71] offset:2048
	global_load_dwordx2 v[58:59], v239, s[70:71] offset:2560
	global_load_dwordx2 v[60:61], v239, s[70:71] offset:3072
	global_load_dwordx2 v[62:63], v239, s[70:71] offset:3584
	s_waitcnt vmcnt(8)
	s_add_u32 s76, s46, 0x0
	s_addc_u32 s77, s47, 0
	v_lshlrev_b32_e32 v64, 16, v32
	v_and_b32_e32 v65, 0xffff0000, v32
	v_lshlrev_b32_e32 v66, 16, v33
	v_and_b32_e32 v67, 0xffff0000, v33
	v_mul_f32_e32 v64, v64, v220
	v_mul_f32_e32 v65, v65, v220
	v_mul_f32_e32 v66, v66, v220
	v_mul_f32_e32 v67, v67, v220
	v_mul_f32_e32 v64, v64, v0
	v_mul_f32_e32 v65, v65, v1
	v_mul_f32_e32 v66, v66, v2
	v_mul_f32_e32 v67, v67, v3
	global_store_dwordx4 v250, v[64:67], s[76:77] offset:0 nt
	v_lshlrev_b32_e32 v68, 16, v34
	v_and_b32_e32 v69, 0xffff0000, v34
	v_lshlrev_b32_e32 v70, 16, v35
	v_and_b32_e32 v71, 0xffff0000, v35
	v_mul_f32_e32 v68, v68, v220
	v_mul_f32_e32 v69, v69, v220
	v_mul_f32_e32 v70, v70, v220
	v_mul_f32_e32 v71, v71, v220
	v_mul_f32_e32 v68, v68, v4
	v_mul_f32_e32 v69, v69, v5
	v_mul_f32_e32 v70, v70, v6
	v_mul_f32_e32 v71, v71, v7
	global_store_dwordx4 v250, v[68:71], s[76:77] offset:1024 nt
	v_lshlrev_b32_e32 v72, 16, v36
	v_and_b32_e32 v73, 0xffff0000, v36
	v_lshlrev_b32_e32 v74, 16, v37
	v_and_b32_e32 v75, 0xffff0000, v37
	v_mul_f32_e32 v72, v72, v220
	v_mul_f32_e32 v73, v73, v220
	v_mul_f32_e32 v74, v74, v220
	v_mul_f32_e32 v75, v75, v220
	v_mul_f32_e32 v72, v72, v8
	v_mul_f32_e32 v73, v73, v9
	v_mul_f32_e32 v74, v74, v10
	v_mul_f32_e32 v75, v75, v11
	global_store_dwordx4 v250, v[72:75], s[76:77] offset:2048 nt
	v_lshlrev_b32_e32 v76, 16, v38
	v_and_b32_e32 v77, 0xffff0000, v38
	v_lshlrev_b32_e32 v78, 16, v39
	v_and_b32_e32 v79, 0xffff0000, v39
	v_mul_f32_e32 v76, v76, v220
	v_mul_f32_e32 v77, v77, v220
	v_mul_f32_e32 v78, v78, v220
	v_mul_f32_e32 v79, v79, v220
	v_mul_f32_e32 v76, v76, v12
	v_mul_f32_e32 v77, v77, v13
	v_mul_f32_e32 v78, v78, v14
	v_mul_f32_e32 v79, v79, v15
	global_store_dwordx4 v250, v[76:79], s[76:77] offset:3072 nt
	v_lshlrev_b32_e32 v64, 16, v40
	v_and_b32_e32 v65, 0xffff0000, v40
	v_lshlrev_b32_e32 v66, 16, v41
	v_and_b32_e32 v67, 0xffff0000, v41
	v_mul_f32_e32 v64, v64, v220
	v_mul_f32_e32 v65, v65, v220
	v_mul_f32_e32 v66, v66, v220
	v_mul_f32_e32 v67, v67, v220
	v_mul_f32_e32 v64, v64, v16
	v_mul_f32_e32 v65, v65, v17
	v_mul_f32_e32 v66, v66, v18
	v_mul_f32_e32 v67, v67, v19
	global_store_dwordx4 v251, v[64:67], s[76:77] offset:0 nt
	v_lshlrev_b32_e32 v68, 16, v42
	v_and_b32_e32 v69, 0xffff0000, v42
	v_lshlrev_b32_e32 v70, 16, v43
	v_and_b32_e32 v71, 0xffff0000, v43
	v_mul_f32_e32 v68, v68, v220
	v_mul_f32_e32 v69, v69, v220
	v_mul_f32_e32 v70, v70, v220
	v_mul_f32_e32 v71, v71, v220
	v_mul_f32_e32 v68, v68, v20
	v_mul_f32_e32 v69, v69, v21
	v_mul_f32_e32 v70, v70, v22
	v_mul_f32_e32 v71, v71, v23
	global_store_dwordx4 v251, v[68:71], s[76:77] offset:1024 nt
	v_lshlrev_b32_e32 v72, 16, v44
	v_and_b32_e32 v73, 0xffff0000, v44
	v_lshlrev_b32_e32 v74, 16, v45
	v_and_b32_e32 v75, 0xffff0000, v45
	v_mul_f32_e32 v72, v72, v220
	v_mul_f32_e32 v73, v73, v220
	v_mul_f32_e32 v74, v74, v220
	v_mul_f32_e32 v75, v75, v220
	v_mul_f32_e32 v72, v72, v24
	v_mul_f32_e32 v73, v73, v25
	v_mul_f32_e32 v74, v74, v26
	v_mul_f32_e32 v75, v75, v27
	global_store_dwordx4 v251, v[72:75], s[76:77] offset:2048 nt
	v_lshlrev_b32_e32 v76, 16, v46
	v_and_b32_e32 v77, 0xffff0000, v46
	v_lshlrev_b32_e32 v78, 16, v47
	v_and_b32_e32 v79, 0xffff0000, v47
	v_mul_f32_e32 v76, v76, v220
	v_mul_f32_e32 v77, v77, v220
	v_mul_f32_e32 v78, v78, v220
	v_mul_f32_e32 v79, v79, v220
	v_mul_f32_e32 v76, v76, v28
	v_mul_f32_e32 v77, v77, v29
	v_mul_f32_e32 v78, v78, v30
	v_mul_f32_e32 v79, v79, v31
	global_store_dwordx4 v251, v[76:79], s[76:77] offset:3072 nt
	s_add_u32 s70, s28, 0x2000
	s_addc_u32 s71, s29, 0
	global_load_dwordx2 v[32:33], v239, s[70:71] offset:0
	global_load_dwordx2 v[34:35], v239, s[70:71] offset:512
	global_load_dwordx2 v[36:37], v239, s[70:71] offset:1024
	global_load_dwordx2 v[38:39], v239, s[70:71] offset:1536
	global_load_dwordx2 v[40:41], v239, s[70:71] offset:2048
	global_load_dwordx2 v[42:43], v239, s[70:71] offset:2560
	global_load_dwordx2 v[44:45], v239, s[70:71] offset:3072
	global_load_dwordx2 v[46:47], v239, s[70:71] offset:3584
	s_waitcnt vmcnt(16)
	s_add_u32 s76, s46, 0x2000
	s_addc_u32 s77, s47, 0
	v_lshlrev_b32_e32 v64, 16, v48
	v_and_b32_e32 v65, 0xffff0000, v48
	v_lshlrev_b32_e32 v66, 16, v49
	v_and_b32_e32 v67, 0xffff0000, v49
	v_mul_f32_e32 v64, v64, v221
	v_mul_f32_e32 v65, v65, v221
	v_mul_f32_e32 v66, v66, v221
	v_mul_f32_e32 v67, v67, v221
	v_mul_f32_e32 v64, v64, v0
	v_mul_f32_e32 v65, v65, v1
	v_mul_f32_e32 v66, v66, v2
	v_mul_f32_e32 v67, v67, v3
	global_store_dwordx4 v250, v[64:67], s[76:77] offset:0 nt
	v_lshlrev_b32_e32 v68, 16, v50
	v_and_b32_e32 v69, 0xffff0000, v50
	v_lshlrev_b32_e32 v70, 16, v51
	v_and_b32_e32 v71, 0xffff0000, v51
	v_mul_f32_e32 v68, v68, v221
	v_mul_f32_e32 v69, v69, v221
	v_mul_f32_e32 v70, v70, v221
	v_mul_f32_e32 v71, v71, v221
	v_mul_f32_e32 v68, v68, v4
	v_mul_f32_e32 v69, v69, v5
	v_mul_f32_e32 v70, v70, v6
	v_mul_f32_e32 v71, v71, v7
	global_store_dwordx4 v250, v[68:71], s[76:77] offset:1024 nt
	v_lshlrev_b32_e32 v72, 16, v52
	v_and_b32_e32 v73, 0xffff0000, v52
	v_lshlrev_b32_e32 v74, 16, v53
	v_and_b32_e32 v75, 0xffff0000, v53
	v_mul_f32_e32 v72, v72, v221
	v_mul_f32_e32 v73, v73, v221
	v_mul_f32_e32 v74, v74, v221
	v_mul_f32_e32 v75, v75, v221
	v_mul_f32_e32 v72, v72, v8
	v_mul_f32_e32 v73, v73, v9
	v_mul_f32_e32 v74, v74, v10
	v_mul_f32_e32 v75, v75, v11
	global_store_dwordx4 v250, v[72:75], s[76:77] offset:2048 nt
	v_lshlrev_b32_e32 v76, 16, v54
	v_and_b32_e32 v77, 0xffff0000, v54
	v_lshlrev_b32_e32 v78, 16, v55
	v_and_b32_e32 v79, 0xffff0000, v55
	v_mul_f32_e32 v76, v76, v221
	v_mul_f32_e32 v77, v77, v221
	v_mul_f32_e32 v78, v78, v221
	v_mul_f32_e32 v79, v79, v221
	v_mul_f32_e32 v76, v76, v12
	v_mul_f32_e32 v77, v77, v13
	v_mul_f32_e32 v78, v78, v14
	v_mul_f32_e32 v79, v79, v15
	global_store_dwordx4 v250, v[76:79], s[76:77] offset:3072 nt
	v_lshlrev_b32_e32 v64, 16, v56
	v_and_b32_e32 v65, 0xffff0000, v56
	v_lshlrev_b32_e32 v66, 16, v57
	v_and_b32_e32 v67, 0xffff0000, v57
	v_mul_f32_e32 v64, v64, v221
	v_mul_f32_e32 v65, v65, v221
	v_mul_f32_e32 v66, v66, v221
	v_mul_f32_e32 v67, v67, v221
	v_mul_f32_e32 v64, v64, v16
	v_mul_f32_e32 v65, v65, v17
	v_mul_f32_e32 v66, v66, v18
	v_mul_f32_e32 v67, v67, v19
	global_store_dwordx4 v251, v[64:67], s[76:77] offset:0 nt
	v_lshlrev_b32_e32 v68, 16, v58
	v_and_b32_e32 v69, 0xffff0000, v58
	v_lshlrev_b32_e32 v70, 16, v59
	v_and_b32_e32 v71, 0xffff0000, v59
	v_mul_f32_e32 v68, v68, v221
	v_mul_f32_e32 v69, v69, v221
	v_mul_f32_e32 v70, v70, v221
	v_mul_f32_e32 v71, v71, v221
	v_mul_f32_e32 v68, v68, v20
	v_mul_f32_e32 v69, v69, v21
	v_mul_f32_e32 v70, v70, v22
	v_mul_f32_e32 v71, v71, v23
	global_store_dwordx4 v251, v[68:71], s[76:77] offset:1024 nt
	v_lshlrev_b32_e32 v72, 16, v60
	v_and_b32_e32 v73, 0xffff0000, v60
	v_lshlrev_b32_e32 v74, 16, v61
	v_and_b32_e32 v75, 0xffff0000, v61
	v_mul_f32_e32 v72, v72, v221
	v_mul_f32_e32 v73, v73, v221
	v_mul_f32_e32 v74, v74, v221
	v_mul_f32_e32 v75, v75, v221
	v_mul_f32_e32 v72, v72, v24
	v_mul_f32_e32 v73, v73, v25
	v_mul_f32_e32 v74, v74, v26
	v_mul_f32_e32 v75, v75, v27
	global_store_dwordx4 v251, v[72:75], s[76:77] offset:2048 nt
	v_lshlrev_b32_e32 v76, 16, v62
	v_and_b32_e32 v77, 0xffff0000, v62
	v_lshlrev_b32_e32 v78, 16, v63
	v_and_b32_e32 v79, 0xffff0000, v63
	v_mul_f32_e32 v76, v76, v221
	v_mul_f32_e32 v77, v77, v221
	v_mul_f32_e32 v78, v78, v221
	v_mul_f32_e32 v79, v79, v221
	v_mul_f32_e32 v76, v76, v28
	v_mul_f32_e32 v77, v77, v29
	v_mul_f32_e32 v78, v78, v30
	v_mul_f32_e32 v79, v79, v31
	global_store_dwordx4 v251, v[76:79], s[76:77] offset:3072 nt
	s_add_u32 s70, s28, 0x3000
	s_addc_u32 s71, s29, 0
	global_load_dwordx2 v[48:49], v239, s[70:71] offset:0
	global_load_dwordx2 v[50:51], v239, s[70:71] offset:512
	global_load_dwordx2 v[52:53], v239, s[70:71] offset:1024
	global_load_dwordx2 v[54:55], v239, s[70:71] offset:1536
	global_load_dwordx2 v[56:57], v239, s[70:71] offset:2048
	global_load_dwordx2 v[58:59], v239, s[70:71] offset:2560
	global_load_dwordx2 v[60:61], v239, s[70:71] offset:3072
	global_load_dwordx2 v[62:63], v239, s[70:71] offset:3584
	s_waitcnt vmcnt(16)
	s_add_u32 s76, s46, 0x4000
	s_addc_u32 s77, s47, 0
	v_lshlrev_b32_e32 v64, 16, v32
	v_and_b32_e32 v65, 0xffff0000, v32
	v_lshlrev_b32_e32 v66, 16, v33
	v_and_b32_e32 v67, 0xffff0000, v33
	v_mul_f32_e32 v64, v64, v222
	v_mul_f32_e32 v65, v65, v222
	v_mul_f32_e32 v66, v66, v222
	v_mul_f32_e32 v67, v67, v222
	v_mul_f32_e32 v64, v64, v0
	v_mul_f32_e32 v65, v65, v1
	v_mul_f32_e32 v66, v66, v2
	v_mul_f32_e32 v67, v67, v3
	global_store_dwordx4 v250, v[64:67], s[76:77] offset:0 nt
	v_lshlrev_b32_e32 v68, 16, v34
	v_and_b32_e32 v69, 0xffff0000, v34
	v_lshlrev_b32_e32 v70, 16, v35
	v_and_b32_e32 v71, 0xffff0000, v35
	v_mul_f32_e32 v68, v68, v222
	v_mul_f32_e32 v69, v69, v222
	v_mul_f32_e32 v70, v70, v222
	v_mul_f32_e32 v71, v71, v222
	v_mul_f32_e32 v68, v68, v4
	v_mul_f32_e32 v69, v69, v5
	v_mul_f32_e32 v70, v70, v6
	v_mul_f32_e32 v71, v71, v7
	global_store_dwordx4 v250, v[68:71], s[76:77] offset:1024 nt
	v_lshlrev_b32_e32 v72, 16, v36
	v_and_b32_e32 v73, 0xffff0000, v36
	v_lshlrev_b32_e32 v74, 16, v37
	v_and_b32_e32 v75, 0xffff0000, v37
	v_mul_f32_e32 v72, v72, v222
	v_mul_f32_e32 v73, v73, v222
	v_mul_f32_e32 v74, v74, v222
	v_mul_f32_e32 v75, v75, v222
	v_mul_f32_e32 v72, v72, v8
	v_mul_f32_e32 v73, v73, v9
	v_mul_f32_e32 v74, v74, v10
	v_mul_f32_e32 v75, v75, v11
	global_store_dwordx4 v250, v[72:75], s[76:77] offset:2048 nt
	v_lshlrev_b32_e32 v76, 16, v38
	v_and_b32_e32 v77, 0xffff0000, v38
	v_lshlrev_b32_e32 v78, 16, v39
	v_and_b32_e32 v79, 0xffff0000, v39
	v_mul_f32_e32 v76, v76, v222
	v_mul_f32_e32 v77, v77, v222
	v_mul_f32_e32 v78, v78, v222
	v_mul_f32_e32 v79, v79, v222
	v_mul_f32_e32 v76, v76, v12
	v_mul_f32_e32 v77, v77, v13
	v_mul_f32_e32 v78, v78, v14
	v_mul_f32_e32 v79, v79, v15
	global_store_dwordx4 v250, v[76:79], s[76:77] offset:3072 nt
	v_lshlrev_b32_e32 v64, 16, v40
	v_and_b32_e32 v65, 0xffff0000, v40
	v_lshlrev_b32_e32 v66, 16, v41
	v_and_b32_e32 v67, 0xffff0000, v41
	v_mul_f32_e32 v64, v64, v222
	v_mul_f32_e32 v65, v65, v222
	v_mul_f32_e32 v66, v66, v222
	v_mul_f32_e32 v67, v67, v222
	v_mul_f32_e32 v64, v64, v16
	v_mul_f32_e32 v65, v65, v17
	v_mul_f32_e32 v66, v66, v18
	v_mul_f32_e32 v67, v67, v19
	global_store_dwordx4 v251, v[64:67], s[76:77] offset:0 nt
	v_lshlrev_b32_e32 v68, 16, v42
	v_and_b32_e32 v69, 0xffff0000, v42
	v_lshlrev_b32_e32 v70, 16, v43
	v_and_b32_e32 v71, 0xffff0000, v43
	v_mul_f32_e32 v68, v68, v222
	v_mul_f32_e32 v69, v69, v222
	v_mul_f32_e32 v70, v70, v222
	v_mul_f32_e32 v71, v71, v222
	v_mul_f32_e32 v68, v68, v20
	v_mul_f32_e32 v69, v69, v21
	v_mul_f32_e32 v70, v70, v22
	v_mul_f32_e32 v71, v71, v23
	global_store_dwordx4 v251, v[68:71], s[76:77] offset:1024 nt
	v_lshlrev_b32_e32 v72, 16, v44
	v_and_b32_e32 v73, 0xffff0000, v44
	v_lshlrev_b32_e32 v74, 16, v45
	v_and_b32_e32 v75, 0xffff0000, v45
	v_mul_f32_e32 v72, v72, v222
	v_mul_f32_e32 v73, v73, v222
	v_mul_f32_e32 v74, v74, v222
	v_mul_f32_e32 v75, v75, v222
	v_mul_f32_e32 v72, v72, v24
	v_mul_f32_e32 v73, v73, v25
	v_mul_f32_e32 v74, v74, v26
	v_mul_f32_e32 v75, v75, v27
	global_store_dwordx4 v251, v[72:75], s[76:77] offset:2048 nt
	v_lshlrev_b32_e32 v76, 16, v46
	v_and_b32_e32 v77, 0xffff0000, v46
	v_lshlrev_b32_e32 v78, 16, v47
	v_and_b32_e32 v79, 0xffff0000, v47
	v_mul_f32_e32 v76, v76, v222
	v_mul_f32_e32 v77, v77, v222
	v_mul_f32_e32 v78, v78, v222
	v_mul_f32_e32 v79, v79, v222
	v_mul_f32_e32 v76, v76, v28
	v_mul_f32_e32 v77, v77, v29
	v_mul_f32_e32 v78, v78, v30
	v_mul_f32_e32 v79, v79, v31
	global_store_dwordx4 v251, v[76:79], s[76:77] offset:3072 nt
	s_add_u32 s70, s28, 0x4000
	s_addc_u32 s71, s29, 0
	global_load_dwordx2 v[32:33], v239, s[70:71] offset:0
	global_load_dwordx2 v[34:35], v239, s[70:71] offset:512
	global_load_dwordx2 v[36:37], v239, s[70:71] offset:1024
	global_load_dwordx2 v[38:39], v239, s[70:71] offset:1536
	global_load_dwordx2 v[40:41], v239, s[70:71] offset:2048
	global_load_dwordx2 v[42:43], v239, s[70:71] offset:2560
	global_load_dwordx2 v[44:45], v239, s[70:71] offset:3072
	global_load_dwordx2 v[46:47], v239, s[70:71] offset:3584
	s_waitcnt vmcnt(16)
	s_add_u32 s76, s46, 0x6000
	s_addc_u32 s77, s47, 0
	v_lshlrev_b32_e32 v64, 16, v48
	v_and_b32_e32 v65, 0xffff0000, v48
	v_lshlrev_b32_e32 v66, 16, v49
	v_and_b32_e32 v67, 0xffff0000, v49
	v_mul_f32_e32 v64, v64, v223
	v_mul_f32_e32 v65, v65, v223
	v_mul_f32_e32 v66, v66, v223
	v_mul_f32_e32 v67, v67, v223
	v_mul_f32_e32 v64, v64, v0
	v_mul_f32_e32 v65, v65, v1
	v_mul_f32_e32 v66, v66, v2
	v_mul_f32_e32 v67, v67, v3
	global_store_dwordx4 v250, v[64:67], s[76:77] offset:0 nt
	v_lshlrev_b32_e32 v68, 16, v50
	v_and_b32_e32 v69, 0xffff0000, v50
	v_lshlrev_b32_e32 v70, 16, v51
	v_and_b32_e32 v71, 0xffff0000, v51
	v_mul_f32_e32 v68, v68, v223
	v_mul_f32_e32 v69, v69, v223
	v_mul_f32_e32 v70, v70, v223
	v_mul_f32_e32 v71, v71, v223
	v_mul_f32_e32 v68, v68, v4
	v_mul_f32_e32 v69, v69, v5
	v_mul_f32_e32 v70, v70, v6
	v_mul_f32_e32 v71, v71, v7
	global_store_dwordx4 v250, v[68:71], s[76:77] offset:1024 nt
	v_lshlrev_b32_e32 v72, 16, v52
	v_and_b32_e32 v73, 0xffff0000, v52
	v_lshlrev_b32_e32 v74, 16, v53
	v_and_b32_e32 v75, 0xffff0000, v53
	v_mul_f32_e32 v72, v72, v223
	v_mul_f32_e32 v73, v73, v223
	v_mul_f32_e32 v74, v74, v223
	v_mul_f32_e32 v75, v75, v223
	v_mul_f32_e32 v72, v72, v8
	v_mul_f32_e32 v73, v73, v9
	v_mul_f32_e32 v74, v74, v10
	v_mul_f32_e32 v75, v75, v11
	global_store_dwordx4 v250, v[72:75], s[76:77] offset:2048 nt
	v_lshlrev_b32_e32 v76, 16, v54
	v_and_b32_e32 v77, 0xffff0000, v54
	v_lshlrev_b32_e32 v78, 16, v55
	v_and_b32_e32 v79, 0xffff0000, v55
	v_mul_f32_e32 v76, v76, v223
	v_mul_f32_e32 v77, v77, v223
	v_mul_f32_e32 v78, v78, v223
	v_mul_f32_e32 v79, v79, v223
	v_mul_f32_e32 v76, v76, v12
	v_mul_f32_e32 v77, v77, v13
	v_mul_f32_e32 v78, v78, v14
	v_mul_f32_e32 v79, v79, v15
	global_store_dwordx4 v250, v[76:79], s[76:77] offset:3072 nt
	v_lshlrev_b32_e32 v64, 16, v56
	v_and_b32_e32 v65, 0xffff0000, v56
	v_lshlrev_b32_e32 v66, 16, v57
	v_and_b32_e32 v67, 0xffff0000, v57
	v_mul_f32_e32 v64, v64, v223
	v_mul_f32_e32 v65, v65, v223
	v_mul_f32_e32 v66, v66, v223
	v_mul_f32_e32 v67, v67, v223
	v_mul_f32_e32 v64, v64, v16
	v_mul_f32_e32 v65, v65, v17
	v_mul_f32_e32 v66, v66, v18
	v_mul_f32_e32 v67, v67, v19
	global_store_dwordx4 v251, v[64:67], s[76:77] offset:0 nt
	v_lshlrev_b32_e32 v68, 16, v58
	v_and_b32_e32 v69, 0xffff0000, v58
	v_lshlrev_b32_e32 v70, 16, v59
	v_and_b32_e32 v71, 0xffff0000, v59
	v_mul_f32_e32 v68, v68, v223
	v_mul_f32_e32 v69, v69, v223
	v_mul_f32_e32 v70, v70, v223
	v_mul_f32_e32 v71, v71, v223
	v_mul_f32_e32 v68, v68, v20
	v_mul_f32_e32 v69, v69, v21
	v_mul_f32_e32 v70, v70, v22
	v_mul_f32_e32 v71, v71, v23
	global_store_dwordx4 v251, v[68:71], s[76:77] offset:1024 nt
	v_lshlrev_b32_e32 v72, 16, v60
	v_and_b32_e32 v73, 0xffff0000, v60
	v_lshlrev_b32_e32 v74, 16, v61
	v_and_b32_e32 v75, 0xffff0000, v61
	v_mul_f32_e32 v72, v72, v223
	v_mul_f32_e32 v73, v73, v223
	v_mul_f32_e32 v74, v74, v223
	v_mul_f32_e32 v75, v75, v223
	v_mul_f32_e32 v72, v72, v24
	v_mul_f32_e32 v73, v73, v25
	v_mul_f32_e32 v74, v74, v26
	v_mul_f32_e32 v75, v75, v27
	global_store_dwordx4 v251, v[72:75], s[76:77] offset:2048 nt
	v_lshlrev_b32_e32 v76, 16, v62
	v_and_b32_e32 v77, 0xffff0000, v62
	v_lshlrev_b32_e32 v78, 16, v63
	v_and_b32_e32 v79, 0xffff0000, v63
	v_mul_f32_e32 v76, v76, v223
	v_mul_f32_e32 v77, v77, v223
	v_mul_f32_e32 v78, v78, v223
	v_mul_f32_e32 v79, v79, v223
	v_mul_f32_e32 v76, v76, v28
	v_mul_f32_e32 v77, v77, v29
	v_mul_f32_e32 v78, v78, v30
	v_mul_f32_e32 v79, v79, v31
	global_store_dwordx4 v251, v[76:79], s[76:77] offset:3072 nt
	s_add_u32 s70, s28, 0x5000
	s_addc_u32 s71, s29, 0
	global_load_dwordx2 v[48:49], v239, s[70:71] offset:0
	global_load_dwordx2 v[50:51], v239, s[70:71] offset:512
	global_load_dwordx2 v[52:53], v239, s[70:71] offset:1024
	global_load_dwordx2 v[54:55], v239, s[70:71] offset:1536
	global_load_dwordx2 v[56:57], v239, s[70:71] offset:2048
	global_load_dwordx2 v[58:59], v239, s[70:71] offset:2560
	global_load_dwordx2 v[60:61], v239, s[70:71] offset:3072
	global_load_dwordx2 v[62:63], v239, s[70:71] offset:3584
	s_waitcnt vmcnt(16)
	s_add_u32 s76, s46, 0x8000
	s_addc_u32 s77, s47, 0
	v_lshlrev_b32_e32 v64, 16, v32
	v_and_b32_e32 v65, 0xffff0000, v32
	v_lshlrev_b32_e32 v66, 16, v33
	v_and_b32_e32 v67, 0xffff0000, v33
	v_mul_f32_e32 v64, v64, v224
	v_mul_f32_e32 v65, v65, v224
	v_mul_f32_e32 v66, v66, v224
	v_mul_f32_e32 v67, v67, v224
	v_mul_f32_e32 v64, v64, v0
	v_mul_f32_e32 v65, v65, v1
	v_mul_f32_e32 v66, v66, v2
	v_mul_f32_e32 v67, v67, v3
	global_store_dwordx4 v250, v[64:67], s[76:77] offset:0 nt
	v_lshlrev_b32_e32 v68, 16, v34
	v_and_b32_e32 v69, 0xffff0000, v34
	v_lshlrev_b32_e32 v70, 16, v35
	v_and_b32_e32 v71, 0xffff0000, v35
	v_mul_f32_e32 v68, v68, v224
	v_mul_f32_e32 v69, v69, v224
	v_mul_f32_e32 v70, v70, v224
	v_mul_f32_e32 v71, v71, v224
	v_mul_f32_e32 v68, v68, v4
	v_mul_f32_e32 v69, v69, v5
	v_mul_f32_e32 v70, v70, v6
	v_mul_f32_e32 v71, v71, v7
	global_store_dwordx4 v250, v[68:71], s[76:77] offset:1024 nt
	v_lshlrev_b32_e32 v72, 16, v36
	v_and_b32_e32 v73, 0xffff0000, v36
	v_lshlrev_b32_e32 v74, 16, v37
	v_and_b32_e32 v75, 0xffff0000, v37
	v_mul_f32_e32 v72, v72, v224
	v_mul_f32_e32 v73, v73, v224
	v_mul_f32_e32 v74, v74, v224
	v_mul_f32_e32 v75, v75, v224
	v_mul_f32_e32 v72, v72, v8
	v_mul_f32_e32 v73, v73, v9
	v_mul_f32_e32 v74, v74, v10
	v_mul_f32_e32 v75, v75, v11
	global_store_dwordx4 v250, v[72:75], s[76:77] offset:2048 nt
	v_lshlrev_b32_e32 v76, 16, v38
	v_and_b32_e32 v77, 0xffff0000, v38
	v_lshlrev_b32_e32 v78, 16, v39
	v_and_b32_e32 v79, 0xffff0000, v39
	v_mul_f32_e32 v76, v76, v224
	v_mul_f32_e32 v77, v77, v224
	v_mul_f32_e32 v78, v78, v224
	v_mul_f32_e32 v79, v79, v224
	v_mul_f32_e32 v76, v76, v12
	v_mul_f32_e32 v77, v77, v13
	v_mul_f32_e32 v78, v78, v14
	v_mul_f32_e32 v79, v79, v15
	global_store_dwordx4 v250, v[76:79], s[76:77] offset:3072 nt
	v_lshlrev_b32_e32 v64, 16, v40
	v_and_b32_e32 v65, 0xffff0000, v40
	v_lshlrev_b32_e32 v66, 16, v41
	v_and_b32_e32 v67, 0xffff0000, v41
	v_mul_f32_e32 v64, v64, v224
	v_mul_f32_e32 v65, v65, v224
	v_mul_f32_e32 v66, v66, v224
	v_mul_f32_e32 v67, v67, v224
	v_mul_f32_e32 v64, v64, v16
	v_mul_f32_e32 v65, v65, v17
	v_mul_f32_e32 v66, v66, v18
	v_mul_f32_e32 v67, v67, v19
	global_store_dwordx4 v251, v[64:67], s[76:77] offset:0 nt
	v_lshlrev_b32_e32 v68, 16, v42
	v_and_b32_e32 v69, 0xffff0000, v42
	v_lshlrev_b32_e32 v70, 16, v43
	v_and_b32_e32 v71, 0xffff0000, v43
	v_mul_f32_e32 v68, v68, v224
	v_mul_f32_e32 v69, v69, v224
	v_mul_f32_e32 v70, v70, v224
	v_mul_f32_e32 v71, v71, v224
	v_mul_f32_e32 v68, v68, v20
	v_mul_f32_e32 v69, v69, v21
	v_mul_f32_e32 v70, v70, v22
	v_mul_f32_e32 v71, v71, v23
	global_store_dwordx4 v251, v[68:71], s[76:77] offset:1024 nt
	v_lshlrev_b32_e32 v72, 16, v44
	v_and_b32_e32 v73, 0xffff0000, v44
	v_lshlrev_b32_e32 v74, 16, v45
	v_and_b32_e32 v75, 0xffff0000, v45
	v_mul_f32_e32 v72, v72, v224
	v_mul_f32_e32 v73, v73, v224
	v_mul_f32_e32 v74, v74, v224
	v_mul_f32_e32 v75, v75, v224
	v_mul_f32_e32 v72, v72, v24
	v_mul_f32_e32 v73, v73, v25
	v_mul_f32_e32 v74, v74, v26
	v_mul_f32_e32 v75, v75, v27
	global_store_dwordx4 v251, v[72:75], s[76:77] offset:2048 nt
	v_lshlrev_b32_e32 v76, 16, v46
	v_and_b32_e32 v77, 0xffff0000, v46
	v_lshlrev_b32_e32 v78, 16, v47
	v_and_b32_e32 v79, 0xffff0000, v47
	v_mul_f32_e32 v76, v76, v224
	v_mul_f32_e32 v77, v77, v224
	v_mul_f32_e32 v78, v78, v224
	v_mul_f32_e32 v79, v79, v224
	v_mul_f32_e32 v76, v76, v28
	v_mul_f32_e32 v77, v77, v29
	v_mul_f32_e32 v78, v78, v30
	v_mul_f32_e32 v79, v79, v31
	global_store_dwordx4 v251, v[76:79], s[76:77] offset:3072 nt
	s_add_u32 s70, s28, 0x6000
	s_addc_u32 s71, s29, 0
	global_load_dwordx2 v[32:33], v239, s[70:71] offset:0
	global_load_dwordx2 v[34:35], v239, s[70:71] offset:512
	global_load_dwordx2 v[36:37], v239, s[70:71] offset:1024
	global_load_dwordx2 v[38:39], v239, s[70:71] offset:1536
	global_load_dwordx2 v[40:41], v239, s[70:71] offset:2048
	global_load_dwordx2 v[42:43], v239, s[70:71] offset:2560
	global_load_dwordx2 v[44:45], v239, s[70:71] offset:3072
	global_load_dwordx2 v[46:47], v239, s[70:71] offset:3584
	s_waitcnt vmcnt(16)
	s_add_u32 s76, s46, 0xa000
	s_addc_u32 s77, s47, 0
	v_lshlrev_b32_e32 v64, 16, v48
	v_and_b32_e32 v65, 0xffff0000, v48
	v_lshlrev_b32_e32 v66, 16, v49
	v_and_b32_e32 v67, 0xffff0000, v49
	v_mul_f32_e32 v64, v64, v225
	v_mul_f32_e32 v65, v65, v225
	v_mul_f32_e32 v66, v66, v225
	v_mul_f32_e32 v67, v67, v225
	v_mul_f32_e32 v64, v64, v0
	v_mul_f32_e32 v65, v65, v1
	v_mul_f32_e32 v66, v66, v2
	v_mul_f32_e32 v67, v67, v3
	global_store_dwordx4 v250, v[64:67], s[76:77] offset:0 nt
	v_lshlrev_b32_e32 v68, 16, v50
	v_and_b32_e32 v69, 0xffff0000, v50
	v_lshlrev_b32_e32 v70, 16, v51
	v_and_b32_e32 v71, 0xffff0000, v51
	v_mul_f32_e32 v68, v68, v225
	v_mul_f32_e32 v69, v69, v225
	v_mul_f32_e32 v70, v70, v225
	v_mul_f32_e32 v71, v71, v225
	v_mul_f32_e32 v68, v68, v4
	v_mul_f32_e32 v69, v69, v5
	v_mul_f32_e32 v70, v70, v6
	v_mul_f32_e32 v71, v71, v7
	global_store_dwordx4 v250, v[68:71], s[76:77] offset:1024 nt
	v_lshlrev_b32_e32 v72, 16, v52
	v_and_b32_e32 v73, 0xffff0000, v52
	v_lshlrev_b32_e32 v74, 16, v53
	v_and_b32_e32 v75, 0xffff0000, v53
	v_mul_f32_e32 v72, v72, v225
	v_mul_f32_e32 v73, v73, v225
	v_mul_f32_e32 v74, v74, v225
	v_mul_f32_e32 v75, v75, v225
	v_mul_f32_e32 v72, v72, v8
	v_mul_f32_e32 v73, v73, v9
	v_mul_f32_e32 v74, v74, v10
	v_mul_f32_e32 v75, v75, v11
	global_store_dwordx4 v250, v[72:75], s[76:77] offset:2048 nt
	v_lshlrev_b32_e32 v76, 16, v54
	v_and_b32_e32 v77, 0xffff0000, v54
	v_lshlrev_b32_e32 v78, 16, v55
	v_and_b32_e32 v79, 0xffff0000, v55
	v_mul_f32_e32 v76, v76, v225
	v_mul_f32_e32 v77, v77, v225
	v_mul_f32_e32 v78, v78, v225
	v_mul_f32_e32 v79, v79, v225
	v_mul_f32_e32 v76, v76, v12
	v_mul_f32_e32 v77, v77, v13
	v_mul_f32_e32 v78, v78, v14
	v_mul_f32_e32 v79, v79, v15
	global_store_dwordx4 v250, v[76:79], s[76:77] offset:3072 nt
	v_lshlrev_b32_e32 v64, 16, v56
	v_and_b32_e32 v65, 0xffff0000, v56
	v_lshlrev_b32_e32 v66, 16, v57
	v_and_b32_e32 v67, 0xffff0000, v57
	v_mul_f32_e32 v64, v64, v225
	v_mul_f32_e32 v65, v65, v225
	v_mul_f32_e32 v66, v66, v225
	v_mul_f32_e32 v67, v67, v225
	v_mul_f32_e32 v64, v64, v16
	v_mul_f32_e32 v65, v65, v17
	v_mul_f32_e32 v66, v66, v18
	v_mul_f32_e32 v67, v67, v19
	global_store_dwordx4 v251, v[64:67], s[76:77] offset:0 nt
	v_lshlrev_b32_e32 v68, 16, v58
	v_and_b32_e32 v69, 0xffff0000, v58
	v_lshlrev_b32_e32 v70, 16, v59
	v_and_b32_e32 v71, 0xffff0000, v59
	v_mul_f32_e32 v68, v68, v225
	v_mul_f32_e32 v69, v69, v225
	v_mul_f32_e32 v70, v70, v225
	v_mul_f32_e32 v71, v71, v225
	v_mul_f32_e32 v68, v68, v20
	v_mul_f32_e32 v69, v69, v21
	v_mul_f32_e32 v70, v70, v22
	v_mul_f32_e32 v71, v71, v23
	global_store_dwordx4 v251, v[68:71], s[76:77] offset:1024 nt
	v_lshlrev_b32_e32 v72, 16, v60
	v_and_b32_e32 v73, 0xffff0000, v60
	v_lshlrev_b32_e32 v74, 16, v61
	v_and_b32_e32 v75, 0xffff0000, v61
	v_mul_f32_e32 v72, v72, v225
	v_mul_f32_e32 v73, v73, v225
	v_mul_f32_e32 v74, v74, v225
	v_mul_f32_e32 v75, v75, v225
	v_mul_f32_e32 v72, v72, v24
	v_mul_f32_e32 v73, v73, v25
	v_mul_f32_e32 v74, v74, v26
	v_mul_f32_e32 v75, v75, v27
	global_store_dwordx4 v251, v[72:75], s[76:77] offset:2048 nt
	v_lshlrev_b32_e32 v76, 16, v62
	v_and_b32_e32 v77, 0xffff0000, v62
	v_lshlrev_b32_e32 v78, 16, v63
	v_and_b32_e32 v79, 0xffff0000, v63
	v_mul_f32_e32 v76, v76, v225
	v_mul_f32_e32 v77, v77, v225
	v_mul_f32_e32 v78, v78, v225
	v_mul_f32_e32 v79, v79, v225
	v_mul_f32_e32 v76, v76, v28
	v_mul_f32_e32 v77, v77, v29
	v_mul_f32_e32 v78, v78, v30
	v_mul_f32_e32 v79, v79, v31
	global_store_dwordx4 v251, v[76:79], s[76:77] offset:3072 nt
	s_add_u32 s70, s28, 0x7000
	s_addc_u32 s71, s29, 0
	global_load_dwordx2 v[48:49], v239, s[70:71] offset:0
	global_load_dwordx2 v[50:51], v239, s[70:71] offset:512
	global_load_dwordx2 v[52:53], v239, s[70:71] offset:1024
	global_load_dwordx2 v[54:55], v239, s[70:71] offset:1536
	global_load_dwordx2 v[56:57], v239, s[70:71] offset:2048
	global_load_dwordx2 v[58:59], v239, s[70:71] offset:2560
	global_load_dwordx2 v[60:61], v239, s[70:71] offset:3072
	global_load_dwordx2 v[62:63], v239, s[70:71] offset:3584
	s_waitcnt vmcnt(16)
	s_add_u32 s76, s46, 0xc000
	s_addc_u32 s77, s47, 0
	v_lshlrev_b32_e32 v64, 16, v32
	v_and_b32_e32 v65, 0xffff0000, v32
	v_lshlrev_b32_e32 v66, 16, v33
	v_and_b32_e32 v67, 0xffff0000, v33
	v_mul_f32_e32 v64, v64, v226
	v_mul_f32_e32 v65, v65, v226
	v_mul_f32_e32 v66, v66, v226
	v_mul_f32_e32 v67, v67, v226
	v_mul_f32_e32 v64, v64, v0
	v_mul_f32_e32 v65, v65, v1
	v_mul_f32_e32 v66, v66, v2
	v_mul_f32_e32 v67, v67, v3
	global_store_dwordx4 v250, v[64:67], s[76:77] offset:0 nt
	v_lshlrev_b32_e32 v68, 16, v34
	v_and_b32_e32 v69, 0xffff0000, v34
	v_lshlrev_b32_e32 v70, 16, v35
	v_and_b32_e32 v71, 0xffff0000, v35
	v_mul_f32_e32 v68, v68, v226
	v_mul_f32_e32 v69, v69, v226
	v_mul_f32_e32 v70, v70, v226
	v_mul_f32_e32 v71, v71, v226
	v_mul_f32_e32 v68, v68, v4
	v_mul_f32_e32 v69, v69, v5
	v_mul_f32_e32 v70, v70, v6
	v_mul_f32_e32 v71, v71, v7
	global_store_dwordx4 v250, v[68:71], s[76:77] offset:1024 nt
	v_lshlrev_b32_e32 v72, 16, v36
	v_and_b32_e32 v73, 0xffff0000, v36
	v_lshlrev_b32_e32 v74, 16, v37
	v_and_b32_e32 v75, 0xffff0000, v37
	v_mul_f32_e32 v72, v72, v226
	v_mul_f32_e32 v73, v73, v226
	v_mul_f32_e32 v74, v74, v226
	v_mul_f32_e32 v75, v75, v226
	v_mul_f32_e32 v72, v72, v8
	v_mul_f32_e32 v73, v73, v9
	v_mul_f32_e32 v74, v74, v10
	v_mul_f32_e32 v75, v75, v11
	global_store_dwordx4 v250, v[72:75], s[76:77] offset:2048 nt
	v_lshlrev_b32_e32 v76, 16, v38
	v_and_b32_e32 v77, 0xffff0000, v38
	v_lshlrev_b32_e32 v78, 16, v39
	v_and_b32_e32 v79, 0xffff0000, v39
	v_mul_f32_e32 v76, v76, v226
	v_mul_f32_e32 v77, v77, v226
	v_mul_f32_e32 v78, v78, v226
	v_mul_f32_e32 v79, v79, v226
	v_mul_f32_e32 v76, v76, v12
	v_mul_f32_e32 v77, v77, v13
	v_mul_f32_e32 v78, v78, v14
	v_mul_f32_e32 v79, v79, v15
	global_store_dwordx4 v250, v[76:79], s[76:77] offset:3072 nt
	v_lshlrev_b32_e32 v64, 16, v40
	v_and_b32_e32 v65, 0xffff0000, v40
	v_lshlrev_b32_e32 v66, 16, v41
	v_and_b32_e32 v67, 0xffff0000, v41
	v_mul_f32_e32 v64, v64, v226
	v_mul_f32_e32 v65, v65, v226
	v_mul_f32_e32 v66, v66, v226
	v_mul_f32_e32 v67, v67, v226
	v_mul_f32_e32 v64, v64, v16
	v_mul_f32_e32 v65, v65, v17
	v_mul_f32_e32 v66, v66, v18
	v_mul_f32_e32 v67, v67, v19
	global_store_dwordx4 v251, v[64:67], s[76:77] offset:0 nt
	v_lshlrev_b32_e32 v68, 16, v42
	v_and_b32_e32 v69, 0xffff0000, v42
	v_lshlrev_b32_e32 v70, 16, v43
	v_and_b32_e32 v71, 0xffff0000, v43
	v_mul_f32_e32 v68, v68, v226
	v_mul_f32_e32 v69, v69, v226
	v_mul_f32_e32 v70, v70, v226
	v_mul_f32_e32 v71, v71, v226
	v_mul_f32_e32 v68, v68, v20
	v_mul_f32_e32 v69, v69, v21
	v_mul_f32_e32 v70, v70, v22
	v_mul_f32_e32 v71, v71, v23
	global_store_dwordx4 v251, v[68:71], s[76:77] offset:1024 nt
	v_lshlrev_b32_e32 v72, 16, v44
	v_and_b32_e32 v73, 0xffff0000, v44
	v_lshlrev_b32_e32 v74, 16, v45
	v_and_b32_e32 v75, 0xffff0000, v45
	v_mul_f32_e32 v72, v72, v226
	v_mul_f32_e32 v73, v73, v226
	v_mul_f32_e32 v74, v74, v226
	v_mul_f32_e32 v75, v75, v226
	v_mul_f32_e32 v72, v72, v24
	v_mul_f32_e32 v73, v73, v25
	v_mul_f32_e32 v74, v74, v26
	v_mul_f32_e32 v75, v75, v27
	global_store_dwordx4 v251, v[72:75], s[76:77] offset:2048 nt
	v_lshlrev_b32_e32 v76, 16, v46
	v_and_b32_e32 v77, 0xffff0000, v46
	v_lshlrev_b32_e32 v78, 16, v47
	v_and_b32_e32 v79, 0xffff0000, v47
	v_mul_f32_e32 v76, v76, v226
	v_mul_f32_e32 v77, v77, v226
	v_mul_f32_e32 v78, v78, v226
	v_mul_f32_e32 v79, v79, v226
	v_mul_f32_e32 v76, v76, v28
	v_mul_f32_e32 v77, v77, v29
	v_mul_f32_e32 v78, v78, v30
	v_mul_f32_e32 v79, v79, v31
	global_store_dwordx4 v251, v[76:79], s[76:77] offset:3072 nt
	s_waitcnt vmcnt(8)
	s_add_u32 s76, s46, 0xe000
	s_addc_u32 s77, s47, 0
	v_lshlrev_b32_e32 v64, 16, v48
	v_and_b32_e32 v65, 0xffff0000, v48
	v_lshlrev_b32_e32 v66, 16, v49
	v_and_b32_e32 v67, 0xffff0000, v49
	v_mul_f32_e32 v64, v64, v227
	v_mul_f32_e32 v65, v65, v227
	v_mul_f32_e32 v66, v66, v227
	v_mul_f32_e32 v67, v67, v227
	v_mul_f32_e32 v64, v64, v0
	v_mul_f32_e32 v65, v65, v1
	v_mul_f32_e32 v66, v66, v2
	v_mul_f32_e32 v67, v67, v3
	global_store_dwordx4 v250, v[64:67], s[76:77] offset:0 nt
	v_lshlrev_b32_e32 v68, 16, v50
	v_and_b32_e32 v69, 0xffff0000, v50
	v_lshlrev_b32_e32 v70, 16, v51
	v_and_b32_e32 v71, 0xffff0000, v51
	v_mul_f32_e32 v68, v68, v227
	v_mul_f32_e32 v69, v69, v227
	v_mul_f32_e32 v70, v70, v227
	v_mul_f32_e32 v71, v71, v227
	v_mul_f32_e32 v68, v68, v4
	v_mul_f32_e32 v69, v69, v5
	v_mul_f32_e32 v70, v70, v6
	v_mul_f32_e32 v71, v71, v7
	global_store_dwordx4 v250, v[68:71], s[76:77] offset:1024 nt
	v_lshlrev_b32_e32 v72, 16, v52
	v_and_b32_e32 v73, 0xffff0000, v52
	v_lshlrev_b32_e32 v74, 16, v53
	v_and_b32_e32 v75, 0xffff0000, v53
	v_mul_f32_e32 v72, v72, v227
	v_mul_f32_e32 v73, v73, v227
	v_mul_f32_e32 v74, v74, v227
	v_mul_f32_e32 v75, v75, v227
	v_mul_f32_e32 v72, v72, v8
	v_mul_f32_e32 v73, v73, v9
	v_mul_f32_e32 v74, v74, v10
	v_mul_f32_e32 v75, v75, v11
	global_store_dwordx4 v250, v[72:75], s[76:77] offset:2048 nt
	v_lshlrev_b32_e32 v76, 16, v54
	v_and_b32_e32 v77, 0xffff0000, v54
	v_lshlrev_b32_e32 v78, 16, v55
	v_and_b32_e32 v79, 0xffff0000, v55
	v_mul_f32_e32 v76, v76, v227
	v_mul_f32_e32 v77, v77, v227
	v_mul_f32_e32 v78, v78, v227
	v_mul_f32_e32 v79, v79, v227
	v_mul_f32_e32 v76, v76, v12
	v_mul_f32_e32 v77, v77, v13
	v_mul_f32_e32 v78, v78, v14
	v_mul_f32_e32 v79, v79, v15
	global_store_dwordx4 v250, v[76:79], s[76:77] offset:3072 nt
	v_lshlrev_b32_e32 v64, 16, v56
	v_and_b32_e32 v65, 0xffff0000, v56
	v_lshlrev_b32_e32 v66, 16, v57
	v_and_b32_e32 v67, 0xffff0000, v57
	v_mul_f32_e32 v64, v64, v227
	v_mul_f32_e32 v65, v65, v227
	v_mul_f32_e32 v66, v66, v227
	v_mul_f32_e32 v67, v67, v227
	v_mul_f32_e32 v64, v64, v16
	v_mul_f32_e32 v65, v65, v17
	v_mul_f32_e32 v66, v66, v18
	v_mul_f32_e32 v67, v67, v19
	global_store_dwordx4 v251, v[64:67], s[76:77] offset:0 nt
	v_lshlrev_b32_e32 v68, 16, v58
	v_and_b32_e32 v69, 0xffff0000, v58
	v_lshlrev_b32_e32 v70, 16, v59
	v_and_b32_e32 v71, 0xffff0000, v59
	v_mul_f32_e32 v68, v68, v227
	v_mul_f32_e32 v69, v69, v227
	v_mul_f32_e32 v70, v70, v227
	v_mul_f32_e32 v71, v71, v227
	v_mul_f32_e32 v68, v68, v20
	v_mul_f32_e32 v69, v69, v21
	v_mul_f32_e32 v70, v70, v22
	v_mul_f32_e32 v71, v71, v23
	global_store_dwordx4 v251, v[68:71], s[76:77] offset:1024 nt
	v_lshlrev_b32_e32 v72, 16, v60
	v_and_b32_e32 v73, 0xffff0000, v60
	v_lshlrev_b32_e32 v74, 16, v61
	v_and_b32_e32 v75, 0xffff0000, v61
	v_mul_f32_e32 v72, v72, v227
	v_mul_f32_e32 v73, v73, v227
	v_mul_f32_e32 v74, v74, v227
	v_mul_f32_e32 v75, v75, v227
	v_mul_f32_e32 v72, v72, v24
	v_mul_f32_e32 v73, v73, v25
	v_mul_f32_e32 v74, v74, v26
	v_mul_f32_e32 v75, v75, v27
	global_store_dwordx4 v251, v[72:75], s[76:77] offset:2048 nt
	v_lshlrev_b32_e32 v76, 16, v62
	v_and_b32_e32 v77, 0xffff0000, v62
	v_lshlrev_b32_e32 v78, 16, v63
	v_and_b32_e32 v79, 0xffff0000, v63
	v_mul_f32_e32 v76, v76, v227
	v_mul_f32_e32 v77, v77, v227
	v_mul_f32_e32 v78, v78, v227
	v_mul_f32_e32 v79, v79, v227
	v_mul_f32_e32 v76, v76, v28
	v_mul_f32_e32 v77, v77, v29
	v_mul_f32_e32 v78, v78, v30
	v_mul_f32_e32 v79, v79, v31
	global_store_dwordx4 v251, v[76:79], s[76:77] offset:3072 nt
	s_add_u32 s63, s63, s90
	s_cmpk_lt_i32 s63, 0x800
	s_cbranch_scc1 .LpgL1_group
	s_setprio 0
